# attention MFMA clusters: ds_read operands hoisted into a sliding window of up to 12 reads in flight (renamed into dead registers found by liveness analysis), counted lgkmcnt waits
# speedup vs baseline: 1.0085x; 1.0085x over previous
; template <bool DO_SWA, bool DO_MEM>
; __device__ __forceinline__ void attn_unit(const Args& a, unsigned char* ws, LAS unsigned char* lds, int l, int tid_in, int lane_in, int wave, int unit) {
;     ...
;         if constexpr (DO_MEM)
; #pragma unroll
;         for (int hp = 0; hp < 2; ++hp) { const bf16* qp = UB + qrow * UBW + 1152 + (hp * 2 + g) * 64 + fq * 8; qmm[hp][0] = __builtin_nontemporal_load((const bf16x8*)qp); qmm[hp][1] = __builtin_nontemporal_load((const bf16x8*)(qp + 32)); }
;     ...
;         if constexpr (DO_MEM) {
; #pragma unroll
;             for (int i = 0; i < 8; ++i) {
;                 const int chn = tid + 512 * i;
;                 mkst[i] = DO_SWA ? *(const v4u*)(MKb + (size_t)(chn >> 4) * 256 + (chn & 15) * 8) : __builtin_nontemporal_load((const v4u*)(MKb + (size_t)(chn >> 4) * 256 + (chn & 15) * 8));
;                 mvst[i] = DO_SWA ? *(const v4u*)(MVTb + (size_t)(chn >> 5) * 256 + (chn & 31) * 8) : __builtin_nontemporal_load((const v4u*)(MVTb + (size_t)(chn >> 5) * 256 + (chn & 31) * 8));
;             }
.LBB0_257:
	s_cmpk_gt_i32 s94, 0xff
	s_mov_b64 s[0:1], -1
	s_cbranch_scc0 .LBB0_275
	s_cmpk_gt_u32 s94, 0x11f
	s_cbranch_scc0 .LBB0_262
	v_mov_b32_e32 v142, v216
	v_and_b32_e32 v175, 63, v216
	v_readlane_b32 s0, v251, 21
	s_add_i32 s0, s0, s93
	v_and_b32_e32 v141, 15, v175
	v_add_u32_e32 v0, s0, v141
	v_add_u32_e32 v140, 0xfffff7fd, v0
	v_mov_b32_e32 v0, v185
	v_ashrrev_i32_e32 v174, 4, v175
	s_movk_i32 s0, 0xb00
	v_mov_b64_e32 v[0:1], s[48:49]
	v_lshlrev_b32_e32 v2, 3, v174
	v_mad_u64_u32 v[0:1], s[0:1], v140, s0, v[0:1]
	v_ashrrev_i32_e32 v3, 31, v2
	v_readlane_b32 s6, v251, 22
	v_lshl_add_u64 v[0:1], v[2:3], 1, v[0:1]
	s_lshl_b32 s34, s6, 1
	v_lshl_add_u64 v[0:1], v[0:1], 0, s[34:35]
	s_mov_b64 s[0:1], 0xbd00900
	v_lshl_add_u64 v[2:3], v[0:1], 0, s[0:1]
	s_mov_b32 s0, 0xbd00000
	v_add_co_u32_e32 v0, vcc, s0, v0
	s_nop 1
	v_addc_co_u32_e32 v1, vcc, 0, v1, vcc
	global_load_dwordx4 v[72:75], v[2:3], off offset:64 nt
	global_load_dwordx4 v[4:7], v[2:3], off offset:256 nt
	global_load_dwordx4 v[76:79], v[0:1], off offset:2304 nt
	s_nop 0
	global_load_dwordx4 v[0:3], v[2:3], off offset:320 nt
	s_add_i32 s0, s40, s94
	s_ashr_i32 s1, s0, 31
	s_lshl_b64 s[2:3], s[0:1], 17
	s_add_u32 s0, s7, s2
	s_addc_u32 s1, s24, s3
	s_add_u32 s2, s26, s2
	s_addc_u32 s3, s27, s3
	v_lshlrev_b32_e32 v143, 4, v142
	v_and_b32_e32 v14, 0x1f0, v143
	v_mov_b32_e32 v15, v185
	v_lshl_add_u64 v[18:19], s[2:3], 0, v[14:15]
	v_add_u32_e32 v15, 0x200, v142
	v_ashrrev_i32_e32 v30, 4, v15
	v_ashrrev_i32_e32 v34, 5, v15
	v_add_u32_e32 v15, 0x400, v142
	v_ashrrev_i32_e32 v38, 4, v15
	v_ashrrev_i32_e32 v42, 5, v15
	v_add_u32_e32 v15, 0x600, v142
	v_ashrrev_i32_e32 v46, 4, v15
	v_ashrrev_i32_e32 v50, 5, v15
	v_add_u32_e32 v15, 0x800, v142
	v_ashrrev_i32_e32 v54, 4, v15
	v_ashrrev_i32_e32 v58, 5, v15
	v_add_u32_e32 v15, 0xa00, v142
	v_ashrrev_i32_e32 v62, 4, v15
	v_ashrrev_i32_e32 v66, 5, v15
	v_add_u32_e32 v15, 0xc00, v142
	v_ashrrev_i32_e32 v70, 4, v15
	v_ashrrev_i32_e32 v168, 5, v15
	v_add_u32_e32 v15, 0xe00, v142
	v_ashrrev_i32_e32 v22, 4, v142
	v_ashrrev_i32_e32 v170, 4, v15
	v_and_b32_e32 v184, 0xf0, v143
	v_ashrrev_i32_e32 v23, 31, v22
	v_ashrrev_i32_e32 v31, 31, v30
	v_ashrrev_i32_e32 v39, 31, v38
	v_ashrrev_i32_e32 v47, 31, v46
	v_ashrrev_i32_e32 v55, 31, v54
	v_ashrrev_i32_e32 v63, 31, v62
	v_ashrrev_i32_e32 v71, 31, v70
	v_ashrrev_i32_e32 v171, 31, v170
	v_lshl_add_u64 v[10:11], s[0:1], 0, v[184:185]
	v_lshlrev_b64 v[8:9], 9, v[22:23]
	v_ashrrev_i32_e32 v26, 5, v142
	v_lshlrev_b64 v[16:17], 9, v[30:31]
	v_lshlrev_b64 v[24:25], 9, v[38:39]
	v_lshlrev_b64 v[32:33], 9, v[46:47]
	v_lshlrev_b64 v[40:41], 9, v[54:55]
	v_lshlrev_b64 v[48:49], 9, v[62:63]
	v_lshlrev_b64 v[56:57], 9, v[70:71]
	v_lshlrev_b64 v[64:65], 9, v[170:171]
	v_lshl_add_u64 v[12:13], v[10:11], 0, v[8:9]
	v_ashrrev_i32_e32 v27, 31, v26
	v_lshl_add_u64 v[20:21], v[10:11], 0, v[16:17]
	v_lshl_add_u64 v[28:29], v[10:11], 0, v[24:25]
	v_lshl_add_u64 v[36:37], v[10:11], 0, v[32:33]
	v_lshl_add_u64 v[44:45], v[10:11], 0, v[40:41]
	v_lshl_add_u64 v[52:53], v[10:11], 0, v[48:49]
	v_lshl_add_u64 v[60:61], v[10:11], 0, v[56:57]
	v_lshl_add_u64 v[10:11], v[10:11], 0, v[64:65]
	s_waitcnt vmcnt(0)
	s_barrier
	global_load_dwordx4 v[80:83], v[12:13], off nt
	global_load_dwordx4 v[136:139], v[10:11], off nt
	v_lshlrev_b64 v[12:13], 9, v[26:27]
	v_lshl_add_u64 v[12:13], v[18:19], 0, v[12:13]
	v_ashrrev_i32_e32 v35, 31, v34
	global_load_dwordx4 v[84:87], v[12:13], off nt
	global_load_dwordx4 v[88:91], v[20:21], off nt
	v_lshlrev_b64 v[20:21], 9, v[34:35]
	v_lshl_add_u64 v[20:21], v[18:19], 0, v[20:21]
	v_ashrrev_i32_e32 v43, 31, v42
	global_load_dwordx4 v[92:95], v[20:21], off nt
	global_load_dwordx4 v[96:99], v[28:29], off nt
	v_lshlrev_b64 v[28:29], 9, v[42:43]
	v_lshl_add_u64 v[28:29], v[18:19], 0, v[28:29]
	v_ashrrev_i32_e32 v51, 31, v50
	global_load_dwordx4 v[100:103], v[28:29], off nt
	global_load_dwordx4 v[104:107], v[36:37], off nt
	v_lshlrev_b64 v[36:37], 9, v[50:51]
	v_lshl_add_u64 v[36:37], v[18:19], 0, v[36:37]
	v_ashrrev_i32_e32 v59, 31, v58
	global_load_dwordx4 v[108:111], v[36:37], off nt
	global_load_dwordx4 v[112:115], v[44:45], off nt
	v_lshlrev_b64 v[44:45], 9, v[58:59]
	v_lshl_add_u64 v[44:45], v[18:19], 0, v[44:45]
	v_ashrrev_i32_e32 v67, 31, v66
	v_ashrrev_i32_e32 v10, 5, v15
	global_load_dwordx4 v[116:119], v[44:45], off nt
	global_load_dwordx4 v[120:123], v[52:53], off nt
	v_lshlrev_b64 v[52:53], 9, v[66:67]
	v_ashrrev_i32_e32 v11, 31, v10
	v_lshl_add_u64 v[52:53], v[18:19], 0, v[52:53]
	v_ashrrev_i32_e32 v169, 31, v168
	v_lshlrev_b64 v[68:69], 9, v[10:11]
	v_lshlrev_b32_e32 v11, 5, v142
	global_load_dwordx4 v[124:127], v[52:53], off nt
	global_load_dwordx4 v[128:131], v[60:61], off nt
	v_lshlrev_b64 v[60:61], 9, v[168:169]
	v_and_b32_e32 v11, 0x100, v11
	v_and_b32_e32 v15, 0x70, v143
	s_add_i32 s2, 0, 0x12000
	v_lshl_add_u64 v[60:61], v[18:19], 0, v[60:61]
	v_lshl_add_u64 v[68:69], v[18:19], 0, v[68:69]
	v_add_u32_e32 v18, 0, v15
	v_add_u32_e32 v14, s2, v14
	v_add_u32_e32 v15, v11, v22
	s_movk_i32 s3, 0x90
	s_movk_i32 s8, 0x210
	v_mad_u64_u32 v[142:143], s[4:5], v15, s3, v[18:19]
	v_mad_u64_u32 v[144:145], s[4:5], v26, s8, v[14:15]
	v_add_u32_e32 v15, v30, v11
	v_mad_u64_u32 v[146:147], s[4:5], v15, s3, v[18:19]
	v_mad_u64_u32 v[148:149], s[4:5], v34, s8, v[14:15]
	v_add_u32_e32 v15, v38, v11
	v_mad_u64_u32 v[150:151], s[4:5], v15, s3, v[18:19]
	v_mad_u64_u32 v[152:153], s[4:5], v42, s8, v[14:15]
	v_add_u32_e32 v15, v46, v11
	v_mad_u64_u32 v[154:155], s[4:5], v15, s3, v[18:19]
	v_mad_u64_u32 v[156:157], s[4:5], v50, s8, v[14:15]
	v_add_u32_e32 v15, v54, v11
	v_mad_u64_u32 v[158:159], s[4:5], v15, s3, v[18:19]
; #define LAS __attribute__((address_space(3)))
; #define LAS __attribute__((address_space(3)))
; __device__ __forceinline__ f32x4 mfma16(bf16x8 a, bf16x8 b, f32x4 c) { return __builtin_amdgcn_mfma_f32_16x16x32_bf16(a, b, c, 0, 0, 0); }
; template <int NKT, int VSTR, bool SINK>
; __device__ __forceinline__ void attn_core(LAS const unsigned char* kb_, LAS const unsigned char* vb_, bf16x8 q0, bf16x8 q1, float sk, unsigned mskbits, int fr, f32x4 (&o)[4]) {
;     ...
; #pragma unroll
;     for (int kt = 0; kt < NKT; ++kt) {
;         const int key = (kt >> 1) * 32 + ((kt & 1) << 2) + krow;
;         LAS const unsigned char* kp = kb_ + key * 144;
;         const bf16x8 a0 = *(LAS const bf16x8*)kp, a1 = *(LAS const bf16x8*)(kp + 64);
;         const float bias = ((mskbits >> (kt >> 2)) & 1u) ? -1e30f : 0.f;
;         f32x4 s = mfma16(a0, q0, (f32x4){bias, bias, bias, bias});
;         s = mfma16(a1, q1, s);
;         S[kt] = s;
;     }
; template <bool DO_SWA, bool DO_MEM>
; __device__ __forceinline__ void attn_unit(const Args& a, unsigned char* ws, LAS unsigned char* lds, int l, int tid_in, int lane_in, int wave, int unit) {
;     ...
;         if constexpr (DO_MEM)
; #pragma unroll
;         for (int i = 0; i < 8; ++i) {
;             const int chn = tid + 512 * i;
;             { const int key = chn >> 4, c16 = chn & 15; *(LAS v4u*)(lds + A_KS + ((c16 >> 3) * 256 + key) * 144 + (c16 & 7) * 16) = mkst[i]; }
;             { const int col = chn >> 5, kc = chn & 31; *(LAS v4u*)(lds + A_VT2 + col * 528 + kc * 16) = mvst[i]; }
;         }
;         if constexpr (DO_MEM)
; #pragma unroll
;         for (int i = 0; i < 8; ++i) {
;             const int chn = tid + 512 * i;
;             mkst[i] = DO_SWA ? *(const v4u*)(MKb + (size_t)(chn >> 4) * 256 + 128 + (chn & 15) * 8) : __builtin_nontemporal_load((const v4u*)(MKb + (size_t)(chn >> 4) * 256 + 128 + (chn & 15) * 8));
;             mvst[i] = DO_SWA ? *(const v4u*)(MVTb + (size_t)(128 + (chn >> 5)) * 256 + (chn & 31) * 8) : __builtin_nontemporal_load((const v4u*)(MVTb + (size_t)(128 + (chn >> 5)) * 256 + (chn & 31) * 8));
	v_mad_u64_u32 v[160:161], s[4:5], v58, s8, v[14:15]
	v_add_u32_e32 v15, v62, v11
	v_mad_u64_u32 v[162:163], s[4:5], v15, s3, v[18:19]
	v_mad_u64_u32 v[164:165], s[4:5], v66, s8, v[14:15]
	v_add_u32_e32 v15, v70, v11
	v_add_u32_e32 v11, v170, v11
	v_mad_u64_u32 v[166:167], s[4:5], v15, s3, v[18:19]
	v_mad_u64_u32 v[170:171], s[4:5], v11, s3, v[18:19]
	s_mov_b32 s3, 0x10000
	v_add_co_u32_e32 v12, vcc, s3, v12
	global_load_dwordx4 v[132:135], v[60:61], off nt
	global_load_dwordx4 v[176:179], v[68:69], off nt
	v_addc_co_u32_e32 v13, vcc, 0, v13, vcc
	v_add_co_u32_e32 v20, vcc, s3, v20
	v_lshl_add_u64 v[32:33], s[0:1], 0, v[32:33]
	s_nop 0
	v_addc_co_u32_e32 v21, vcc, 0, v21, vcc
	v_add_co_u32_e32 v28, vcc, s3, v28
	v_lshl_add_u64 v[40:41], s[0:1], 0, v[40:41]
	s_nop 0
	v_addc_co_u32_e32 v29, vcc, 0, v29, vcc
	v_add_co_u32_e32 v36, vcc, s3, v36
	v_lshl_add_u64 v[8:9], s[0:1], 0, v[8:9]
	s_nop 0
	v_addc_co_u32_e32 v37, vcc, 0, v37, vcc
	v_add_co_u32_e32 v44, vcc, s3, v44
	v_lshl_add_u64 v[16:17], s[0:1], 0, v[16:17]
	s_nop 0
	v_addc_co_u32_e32 v45, vcc, 0, v45, vcc
	v_add_co_u32_e32 v52, vcc, s3, v52
	v_lshl_add_u64 v[24:25], s[0:1], 0, v[24:25]
	s_nop 0
	v_addc_co_u32_e32 v53, vcc, 0, v53, vcc
	v_add_co_u32_e32 v60, vcc, s3, v60
	v_lshl_add_u64 v[32:33], v[32:33], 0, v[184:185]
	s_nop 0
	v_addc_co_u32_e32 v61, vcc, 0, v61, vcc
	v_lshl_add_u64 v[40:41], v[40:41], 0, v[184:185]
	v_lshl_add_u64 v[48:49], s[0:1], 0, v[48:49]
	v_lshl_add_u64 v[56:57], s[0:1], 0, v[56:57]
	v_lshl_add_u64 v[64:65], s[0:1], 0, v[64:65]
	v_add_co_u32_e32 v68, vcc, s3, v68
	s_barrier
	v_lshl_add_u64 v[8:9], v[8:9], 0, v[184:185]
	v_lshl_add_u64 v[16:17], v[16:17], 0, v[184:185]
	v_lshl_add_u64 v[24:25], v[24:25], 0, v[184:185]
	global_load_dwordx4 v[32:35], v[32:33], off offset:256 nt
	v_lshl_add_u64 v[48:49], v[48:49], 0, v[184:185]
	global_load_dwordx4 v[36:39], v[36:37], off nt
	v_lshl_add_u64 v[56:57], v[56:57], 0, v[184:185]
	global_load_dwordx4 v[40:43], v[40:41], off offset:256 nt
	v_lshl_add_u64 v[64:65], v[64:65], 0, v[184:185]
	global_load_dwordx4 v[44:47], v[44:45], off nt
	v_addc_co_u32_e32 v69, vcc, 0, v69, vcc
	v_mad_u64_u32 v[168:169], s[4:5], v168, s8, v[14:15]
	v_mad_u64_u32 v[172:173], s[4:5], v10, s8, v[14:15]
	global_load_dwordx4 v[8:11], v[8:9], off offset:256 nt
	s_waitcnt vmcnt(20)
	ds_write_b128 v142, v[80:83]
	global_load_dwordx4 v[12:15], v[12:13], off nt
	s_waitcnt vmcnt(19)
	ds_write_b128 v144, v[84:87]
	global_load_dwordx4 v[16:19], v[16:17], off offset:256 nt
	s_waitcnt vmcnt(19)
	ds_write_b128 v146, v[88:91]
	global_load_dwordx4 v[20:23], v[20:21], off nt
	s_waitcnt vmcnt(19)
	ds_write_b128 v148, v[92:95]
	global_load_dwordx4 v[24:27], v[24:25], off offset:256 nt
	s_waitcnt vmcnt(19)
	ds_write_b128 v150, v[96:99]
	global_load_dwordx4 v[28:31], v[28:29], off nt
	s_waitcnt vmcnt(19)
	ds_write_b128 v152, v[100:103]
	global_load_dwordx4 v[48:51], v[48:49], off offset:256 nt
	s_waitcnt vmcnt(19)
	ds_write_b128 v154, v[104:107]
	global_load_dwordx4 v[52:55], v[52:53], off nt
	s_waitcnt vmcnt(19)
	ds_write_b128 v156, v[108:111]
	global_load_dwordx4 v[56:59], v[56:57], off offset:256 nt
	s_waitcnt vmcnt(19)
	ds_write_b128 v158, v[112:115]
	global_load_dwordx4 v[60:63], v[60:61], off nt
	s_waitcnt vmcnt(19)
	ds_write_b128 v160, v[116:119]
	global_load_dwordx4 v[64:67], v[64:65], off offset:256 nt
	s_waitcnt vmcnt(19)
	ds_write_b128 v162, v[120:123]
	global_load_dwordx4 v[68:71], v[68:69], off nt
	s_waitcnt vmcnt(19)
	ds_write_b128 v164, v[124:127]
	s_waitcnt vmcnt(18)
	ds_write_b128 v166, v[128:131]
	s_waitcnt vmcnt(17)
	ds_write_b128 v168, v[132:135]
	ds_write_b128 v170, v[136:139]
	s_waitcnt vmcnt(16)
	ds_write_b128 v172, v[176:179]
	v_or_b32_e32 v81, s6, v141
	v_and_b32_e32 v80, -16, v175
	v_mul_lo_u32 v81, v81, s8
	v_add3_u32 v143, s2, v81, v80
	v_lshlrev_b32_e32 v81, 1, v175
	v_and_b32_e32 v82, 3, v175
	v_and_or_b32 v81, v81, 24, v82
	v_mul_u32_u24_e32 v81, 0x90, v81
	v_readlane_b32 s0, v251, 23
	s_waitcnt lgkmcnt(0)
	s_barrier
	v_add3_u32 v149, s0, v80, v81
	s_waitcnt lgkmcnt(0)
	ds_read_b128 v[196:199], v149
	ds_read_b128 v[200:203], v149 offset:64
	ds_read_b128 v[204:207], v149 offset:576
	ds_read_b128 v[208:211], v149 offset:640
	ds_read_b128 v[212:215], v149 offset:4608
	ds_read_b128 v[228:231], v149 offset:4672
	ds_read_b128 v[232:235], v149 offset:5184
	ds_read_b128 v[236:239], v149 offset:5248
	ds_read_b128 v[240:243], v149 offset:9216
	ds_read_b128 v[244:247], v149 offset:9280
	s_waitcnt lgkmcnt(9)
	v_mfma_f32_16x16x32_bf16 v[80:83], v[196:199], v[76:79], 0
	s_waitcnt lgkmcnt(8)
	v_mfma_f32_16x16x32_bf16 v[136:139], v[200:203], v[72:75], v[80:83]
	ds_read_b128 v[196:199], v149 offset:9792
	ds_read_b128 v[200:203], v149 offset:9856
	s_waitcnt lgkmcnt(9)
	v_mfma_f32_16x16x32_bf16 v[80:83], v[204:207], v[76:79], 0
	s_waitcnt lgkmcnt(8)
	v_mfma_f32_16x16x32_bf16 v[132:135], v[208:211], v[72:75], v[80:83]
	ds_read_b128 v[204:207], v149 offset:13824
	ds_read_b128 v[208:211], v149 offset:13888
	s_waitcnt lgkmcnt(9)
	v_mfma_f32_16x16x32_bf16 v[80:83], v[212:215], v[76:79], 0
	s_waitcnt lgkmcnt(8)
	v_mfma_f32_16x16x32_bf16 v[128:131], v[228:231], v[72:75], v[80:83]
	ds_read_b128 v[212:215], v149 offset:14400
	ds_read_b128 v[228:231], v149 offset:14464
	s_waitcnt lgkmcnt(9)
	v_mfma_f32_16x16x32_bf16 v[80:83], v[232:235], v[76:79], 0
	s_waitcnt lgkmcnt(8)
	v_mfma_f32_16x16x32_bf16 v[124:127], v[236:239], v[72:75], v[80:83]
	ds_read_b128 v[232:235], v149 offset:18432
	ds_read_b128 v[236:239], v149 offset:18496
	s_waitcnt lgkmcnt(9)
	v_mfma_f32_16x16x32_bf16 v[80:83], v[240:243], v[76:79], 0
	s_waitcnt lgkmcnt(8)
; #define LAS __attribute__((address_space(3)))
; #define LAS __attribute__((address_space(3)))
; __device__ __forceinline__ f32x4 mfma16(bf16x8 a, bf16x8 b, f32x4 c) { return __builtin_amdgcn_mfma_f32_16x16x32_bf16(a, b, c, 0, 0, 0); }
; template <int NKT, int VSTR, bool SINK>
; __device__ __forceinline__ void attn_core(LAS const unsigned char* kb_, LAS const unsigned char* vb_, bf16x8 q0, bf16x8 q1, float sk, unsigned mskbits, int fr, f32x4 (&o)[4]) {
;     ...
; #pragma unroll
;     for (int kt = 0; kt < NKT; ++kt) {
;         const int key = (kt >> 1) * 32 + ((kt & 1) << 2) + krow;
;         LAS const unsigned char* kp = kb_ + key * 144;
;         const bf16x8 a0 = *(LAS const bf16x8*)kp, a1 = *(LAS const bf16x8*)(kp + 64);
;         const float bias = ((mskbits >> (kt >> 2)) & 1u) ? -1e30f : 0.f;
;         f32x4 s = mfma16(a0, q0, (f32x4){bias, bias, bias, bias});
;         s = mfma16(a1, q1, s);
;         S[kt] = s;
;     }
;     float mx = S[0][0];
; #pragma unroll
;     for (int kt = 0; kt < NKT; ++kt) mx = fmaxf(fmaxf(mx, fmaxf(S[kt][0], S[kt][1])), fmaxf(S[kt][2], S[kt][3]));
;     mx = fmaxf(mx, __shfl_xor(mx, 16)); mx = fmaxf(mx, __shfl_xor(mx, 32));
	v_mfma_f32_16x16x32_bf16 v[120:123], v[244:247], v[72:75], v[80:83]
	ds_read_b128 v[240:243], v149 offset:19008
	ds_read_b128 v[244:247], v149 offset:19072
	s_waitcnt lgkmcnt(9)
	v_mfma_f32_16x16x32_bf16 v[80:83], v[196:199], v[76:79], 0
	s_waitcnt lgkmcnt(8)
	v_mfma_f32_16x16x32_bf16 v[116:119], v[200:203], v[72:75], v[80:83]
	ds_read_b128 v[196:199], v149 offset:23040
	ds_read_b128 v[200:203], v149 offset:23104
	s_waitcnt lgkmcnt(9)
	v_mfma_f32_16x16x32_bf16 v[80:83], v[204:207], v[76:79], 0
	s_waitcnt lgkmcnt(8)
	v_mfma_f32_16x16x32_bf16 v[112:115], v[208:211], v[72:75], v[80:83]
	ds_read_b128 v[204:207], v149 offset:23616
	ds_read_b128 v[208:211], v149 offset:23680
	s_waitcnt lgkmcnt(9)
	v_mfma_f32_16x16x32_bf16 v[80:83], v[212:215], v[76:79], 0
	s_waitcnt lgkmcnt(8)
	v_mfma_f32_16x16x32_bf16 v[108:111], v[228:231], v[72:75], v[80:83]
	ds_read_b128 v[212:215], v149 offset:27648
	ds_read_b128 v[228:231], v149 offset:27712
	s_waitcnt lgkmcnt(9)
	v_mfma_f32_16x16x32_bf16 v[80:83], v[232:235], v[76:79], 0
	s_waitcnt lgkmcnt(8)
	v_mfma_f32_16x16x32_bf16 v[104:107], v[236:239], v[72:75], v[80:83]
	ds_read_b128 v[232:235], v149 offset:28224
	ds_read_b128 v[236:239], v149 offset:28288
	s_waitcnt lgkmcnt(9)
	v_mfma_f32_16x16x32_bf16 v[80:83], v[240:243], v[76:79], 0
	s_waitcnt lgkmcnt(8)
	v_mfma_f32_16x16x32_bf16 v[100:103], v[244:247], v[72:75], v[80:83]
	ds_read_b128 v[240:243], v149 offset:32256
	ds_read_b128 v[244:247], v149 offset:32320
	s_waitcnt lgkmcnt(9)
	v_mfma_f32_16x16x32_bf16 v[80:83], v[196:199], v[76:79], 0
	s_waitcnt lgkmcnt(8)
	v_mfma_f32_16x16x32_bf16 v[96:99], v[200:203], v[72:75], v[80:83]
	ds_read_b128 v[196:199], v149 offset:32832
	ds_read_b128 v[200:203], v149 offset:32896
	s_waitcnt lgkmcnt(9)
	v_mfma_f32_16x16x32_bf16 v[80:83], v[204:207], v[76:79], 0
	s_waitcnt lgkmcnt(8)
	v_mfma_f32_16x16x32_bf16 v[92:95], v[208:211], v[72:75], v[80:83]
	s_waitcnt lgkmcnt(7)
	v_mfma_f32_16x16x32_bf16 v[80:83], v[212:215], v[76:79], 0
	s_waitcnt lgkmcnt(6)
	v_mfma_f32_16x16x32_bf16 v[88:91], v[228:231], v[72:75], v[80:83]
	s_waitcnt lgkmcnt(5)
	v_mfma_f32_16x16x32_bf16 v[80:83], v[232:235], v[76:79], 0
	s_waitcnt lgkmcnt(4)
	v_mfma_f32_16x16x32_bf16 v[84:87], v[236:239], v[72:75], v[80:83]
	s_waitcnt lgkmcnt(3)
	v_mfma_f32_16x16x32_bf16 v[80:83], v[240:243], v[76:79], 0
	s_waitcnt lgkmcnt(2)
	v_mfma_f32_16x16x32_bf16 v[80:83], v[244:247], v[72:75], v[80:83]
	s_waitcnt lgkmcnt(1)
	v_mfma_f32_16x16x32_bf16 v[76:79], v[196:199], v[76:79], 0
	s_waitcnt lgkmcnt(0)
	v_mfma_f32_16x16x32_bf16 v[72:75], v[200:203], v[72:75], v[76:79]
	s_nop 5
	v_max_f32_e32 v76, v139, v139
	v_max_f32_e32 v77, v138, v138
	v_max_f32_e32 v76, v77, v76
	v_max_f32_e32 v77, v133, v133
	v_max_f32_e32 v78, v132, v132
	v_max_f32_e32 v77, v78, v77
	v_max_f32_e32 v78, v135, v135
	v_max_f32_e32 v79, v134, v134
	v_max3_f32 v76, v136, v137, v76
	v_max_f32_e32 v78, v79, v78
	v_max3_f32 v76, v76, v77, v78
	v_max_f32_e32 v77, v129, v129
	v_max_f32_e32 v78, v128, v128
	v_max_f32_e32 v77, v78, v77
	v_max_f32_e32 v78, v131, v131
	v_max_f32_e32 v79, v130, v130
	v_max_f32_e32 v78, v79, v78
	v_max3_f32 v76, v76, v77, v78
	v_max_f32_e32 v77, v125, v125
	v_max_f32_e32 v78, v124, v124
	v_max_f32_e32 v77, v78, v77
	v_max_f32_e32 v78, v127, v127
	v_max_f32_e32 v79, v126, v126
	v_max_f32_e32 v78, v79, v78
	v_max3_f32 v76, v76, v77, v78
	v_max_f32_e32 v77, v121, v121
	v_max_f32_e32 v78, v120, v120
	v_max_f32_e32 v77, v78, v77
	v_max_f32_e32 v78, v123, v123
	v_max_f32_e32 v79, v122, v122
	v_max_f32_e32 v78, v79, v78
	v_max3_f32 v76, v76, v77, v78
	v_max_f32_e32 v77, v117, v117
	v_max_f32_e32 v78, v116, v116
	v_max_f32_e32 v77, v78, v77
	v_max_f32_e32 v78, v119, v119
	v_max_f32_e32 v79, v118, v118
	v_max_f32_e32 v78, v79, v78
	v_max3_f32 v76, v76, v77, v78
	v_max_f32_e32 v77, v113, v113
	v_max_f32_e32 v78, v112, v112
	v_max_f32_e32 v77, v78, v77
	v_max_f32_e32 v78, v115, v115
	v_max_f32_e32 v79, v114, v114
	v_max_f32_e32 v78, v79, v78
	v_max3_f32 v76, v76, v77, v78
	v_max_f32_e32 v77, v109, v109
	v_max_f32_e32 v78, v108, v108
	v_max_f32_e32 v77, v78, v77
	v_max_f32_e32 v78, v111, v111
	v_max_f32_e32 v79, v110, v110
	v_max_f32_e32 v78, v79, v78
	v_max3_f32 v76, v76, v77, v78
	v_max_f32_e32 v77, v105, v105
	v_max_f32_e32 v78, v104, v104
	v_max_f32_e32 v77, v78, v77
	v_max_f32_e32 v78, v107, v107
	v_max_f32_e32 v79, v106, v106
	v_max_f32_e32 v78, v79, v78
	v_max3_f32 v76, v76, v77, v78
	v_max_f32_e32 v77, v101, v101
	v_max_f32_e32 v78, v100, v100
	v_max_f32_e32 v77, v78, v77
	v_max_f32_e32 v78, v103, v103
	v_max_f32_e32 v79, v102, v102
	v_max_f32_e32 v78, v79, v78
	v_max3_f32 v76, v76, v77, v78
	v_max_f32_e32 v77, v97, v97
	v_max_f32_e32 v78, v96, v96
	v_max_f32_e32 v77, v78, v77
	v_max_f32_e32 v78, v99, v99
	v_max_f32_e32 v79, v98, v98
	v_max_f32_e32 v78, v79, v78
	v_max3_f32 v76, v76, v77, v78
	v_max_f32_e32 v77, v93, v93
	v_max_f32_e32 v78, v92, v92
	v_max_f32_e32 v77, v78, v77
	v_max_f32_e32 v78, v95, v95
	v_max_f32_e32 v79, v94, v94
	v_max_f32_e32 v78, v79, v78
	v_max3_f32 v76, v76, v77, v78
	v_max_f32_e32 v77, v89, v89
	v_max_f32_e32 v78, v88, v88
	v_max_f32_e32 v77, v78, v77
	v_max_f32_e32 v78, v91, v91
	v_max_f32_e32 v79, v90, v90
	v_max_f32_e32 v78, v79, v78
	v_max3_f32 v76, v76, v77, v78
	v_max_f32_e32 v77, v85, v85
	v_max_f32_e32 v78, v84, v84
	v_max_f32_e32 v77, v78, v77
	v_max_f32_e32 v78, v87, v87
	v_max_f32_e32 v79, v86, v86
	v_max_f32_e32 v78, v79, v78
	v_max3_f32 v76, v76, v77, v78
	v_max_f32_e32 v77, v81, v81
	v_max_f32_e32 v78, v80, v80
	v_max_f32_e32 v77, v78, v77
	v_max_f32_e32 v78, v83, v83
	v_max_f32_e32 v79, v82, v82
	v_max_f32_e32 v78, v79, v78
	v_max3_f32 v76, v76, v77, v78
	v_max_f32_e32 v77, v73, v73
	v_max_f32_e32 v78, v72, v72
	v_max_f32_e32 v77, v78, v77
	v_max_f32_e32 v78, v75, v75
	v_max_f32_e32 v79, v74, v74
	v_max_f32_e32 v78, v79, v78
	v_max3_f32 v76, v76, v77, v78
	v_and_b32_e32 v78, 64, v222
	v_xor_b32_e32 v77, 16, v222
	v_add_u32_e32 v78, 64, v78
	v_cmp_lt_i32_e32 vcc, v77, v78
	s_nop 1
	v_cndmask_b32_e32 v77, v222, v77, vcc
	v_lshlrev_b32_e32 v145, 2, v77
	ds_bpermute_b32 v77, v145, v76
	s_waitcnt lgkmcnt(0)
; template <int NKT, int VSTR, bool SINK>
; __device__ __forceinline__ void attn_core(LAS const unsigned char* kb_, LAS const unsigned char* vb_, bf16x8 q0, bf16x8 q1, float sk, unsigned mskbits, int fr, f32x4 (&o)[4]) {
;     ...
;     float mx = S[0][0];
; #pragma unroll
;     for (int kt = 0; kt < NKT; ++kt) mx = fmaxf(fmaxf(mx, fmaxf(S[kt][0], S[kt][1])), fmaxf(S[kt][2], S[kt][3]));
;     mx = fmaxf(mx, __shfl_xor(mx, 16)); mx = fmaxf(mx, __shfl_xor(mx, 32));
;     if (SINK) mx = fmaxf(mx, sk);
;     float sum = 0.f;
; #pragma unroll
;     for (int kt = 0; kt < NKT; ++kt)
; #pragma unroll
;         for (int r = 0; r < 4; ++r) { const float p = __builtin_amdgcn_exp2f(S[kt][r] - mx); S[kt][r] = p; sum += p; }
;     sum += __shfl_xor(sum, 16); sum += __shfl_xor(sum, 32);
;     if (SINK) sum += __builtin_amdgcn_exp2f(sk - mx);
	v_max_f32_e32 v77, v77, v77
	v_max_f32_e32 v76, v76, v77
	v_xor_b32_e32 v77, 32, v222
	v_cmp_lt_i32_e32 vcc, v77, v78
	s_nop 1
	v_cndmask_b32_e32 v77, v222, v77, vcc
	v_lshlrev_b32_e32 v147, 2, v77
	ds_bpermute_b32 v77, v147, v76
	s_waitcnt lgkmcnt(0)
	v_max_f32_e32 v77, v77, v77
	v_max_f32_e32 v151, v76, v77
	v_sub_f32_e32 v76, v136, v151
	v_exp_f32_e32 v76, v76
	v_sub_f32_e32 v77, v137, v151
	v_exp_f32_e32 v77, v77
	v_sub_f32_e32 v132, v132, v151
	v_add_f32_e32 v78, 0, v76
	v_exp_f32_e32 v132, v132
	v_add_f32_e32 v79, v77, v78
	v_sub_f32_e32 v78, v138, v151
	v_exp_f32_e32 v78, v78
	v_sub_f32_e32 v133, v133, v151
	v_exp_f32_e32 v133, v133
	v_sub_f32_e32 v134, v134, v151
	v_add_f32_e32 v136, v78, v79
	v_sub_f32_e32 v79, v139, v151
	v_exp_f32_e32 v79, v79
	v_exp_f32_e32 v134, v134
	v_sub_f32_e32 v135, v135, v151
	v_exp_f32_e32 v135, v135
	v_add_f32_e32 v136, v79, v136
	v_sub_f32_e32 v128, v128, v151
	v_add_f32_e32 v136, v132, v136
	v_exp_f32_e32 v128, v128
	v_sub_f32_e32 v129, v129, v151
	v_add_f32_e32 v136, v133, v136
	v_exp_f32_e32 v129, v129
	v_sub_f32_e32 v130, v130, v151
	v_add_f32_e32 v136, v134, v136
	v_exp_f32_e32 v130, v130
	v_sub_f32_e32 v131, v131, v151
	v_add_f32_e32 v136, v135, v136
	v_exp_f32_e32 v131, v131
	v_sub_f32_e32 v124, v124, v151
	v_add_f32_e32 v136, v128, v136
	v_exp_f32_e32 v124, v124
	v_sub_f32_e32 v125, v125, v151
	v_add_f32_e32 v136, v129, v136
	v_exp_f32_e32 v125, v125
	v_sub_f32_e32 v126, v126, v151
	v_add_f32_e32 v136, v130, v136
	v_exp_f32_e32 v126, v126
	v_sub_f32_e32 v127, v127, v151
	v_add_f32_e32 v136, v131, v136
	v_exp_f32_e32 v127, v127
	v_sub_f32_e32 v120, v120, v151
	v_add_f32_e32 v136, v124, v136
	v_exp_f32_e32 v120, v120
	v_sub_f32_e32 v121, v121, v151
	v_add_f32_e32 v136, v125, v136
	v_exp_f32_e32 v121, v121
	v_sub_f32_e32 v122, v122, v151
	v_add_f32_e32 v136, v126, v136
	v_exp_f32_e32 v122, v122
	v_sub_f32_e32 v123, v123, v151
	v_add_f32_e32 v136, v127, v136
	v_exp_f32_e32 v123, v123
	v_sub_f32_e32 v116, v116, v151
	v_add_f32_e32 v136, v120, v136
	v_exp_f32_e32 v116, v116
	v_sub_f32_e32 v117, v117, v151
	v_add_f32_e32 v136, v121, v136
	v_exp_f32_e32 v117, v117
	v_sub_f32_e32 v118, v118, v151
	v_add_f32_e32 v136, v122, v136
	v_exp_f32_e32 v118, v118
	v_sub_f32_e32 v119, v119, v151
	v_add_f32_e32 v136, v123, v136
	v_exp_f32_e32 v119, v119
	v_sub_f32_e32 v112, v112, v151
	v_add_f32_e32 v136, v116, v136
	v_exp_f32_e32 v112, v112
	v_sub_f32_e32 v113, v113, v151
	v_add_f32_e32 v136, v117, v136
	v_exp_f32_e32 v113, v113
	v_sub_f32_e32 v114, v114, v151
	v_add_f32_e32 v136, v118, v136
	v_exp_f32_e32 v114, v114
	v_sub_f32_e32 v115, v115, v151
	v_add_f32_e32 v136, v119, v136
	v_exp_f32_e32 v115, v115
	v_sub_f32_e32 v108, v108, v151
	v_add_f32_e32 v136, v112, v136
	v_exp_f32_e32 v108, v108
	v_sub_f32_e32 v109, v109, v151
	v_add_f32_e32 v136, v113, v136
	v_exp_f32_e32 v109, v109
	v_sub_f32_e32 v110, v110, v151
	v_add_f32_e32 v136, v114, v136
	v_exp_f32_e32 v110, v110
	v_sub_f32_e32 v111, v111, v151
	v_add_f32_e32 v136, v115, v136
	v_exp_f32_e32 v111, v111
	v_sub_f32_e32 v104, v104, v151
	v_add_f32_e32 v136, v108, v136
	v_exp_f32_e32 v104, v104
	v_sub_f32_e32 v105, v105, v151
	v_add_f32_e32 v136, v109, v136
	v_exp_f32_e32 v105, v105
	v_sub_f32_e32 v106, v106, v151
	v_add_f32_e32 v136, v110, v136
	v_exp_f32_e32 v106, v106
	v_sub_f32_e32 v107, v107, v151
	v_add_f32_e32 v136, v111, v136
	v_exp_f32_e32 v107, v107
	v_sub_f32_e32 v100, v100, v151
	v_add_f32_e32 v136, v104, v136
	v_exp_f32_e32 v100, v100
	v_sub_f32_e32 v101, v101, v151
	v_add_f32_e32 v136, v105, v136
	v_exp_f32_e32 v101, v101
	v_sub_f32_e32 v102, v102, v151
	v_add_f32_e32 v136, v106, v136
	v_exp_f32_e32 v102, v102
	v_sub_f32_e32 v103, v103, v151
	v_add_f32_e32 v136, v107, v136
	v_exp_f32_e32 v103, v103
	v_sub_f32_e32 v96, v96, v151
	v_add_f32_e32 v136, v100, v136
	v_exp_f32_e32 v96, v96
	v_sub_f32_e32 v97, v97, v151
	v_add_f32_e32 v136, v101, v136
	v_exp_f32_e32 v97, v97
	v_sub_f32_e32 v98, v98, v151
	v_add_f32_e32 v136, v102, v136
	v_exp_f32_e32 v98, v98
	v_sub_f32_e32 v99, v99, v151
	v_add_f32_e32 v136, v103, v136
	v_exp_f32_e32 v99, v99
	v_sub_f32_e32 v92, v92, v151
	v_add_f32_e32 v136, v96, v136
	v_exp_f32_e32 v137, v92
	v_add_f32_e32 v136, v97, v136
	v_add_f32_e32 v136, v98, v136
	v_add_f32_e32 v136, v99, v136
	v_sub_f32_e32 v93, v93, v151
	v_add_f32_e32 v92, v137, v136
	v_exp_f32_e32 v136, v93
	v_sub_f32_e32 v93, v94, v151
	v_exp_f32_e32 v138, v93
	v_sub_f32_e32 v93, v95, v151
	v_exp_f32_e32 v95, v93
	v_sub_f32_e32 v88, v88, v151
	v_exp_f32_e32 v139, v88
	v_sub_f32_e32 v89, v89, v151
	v_add_f32_e32 v92, v136, v92
	v_exp_f32_e32 v153, v89
	v_sub_f32_e32 v89, v90, v151
	v_add_f32_e32 v92, v138, v92
	v_exp_f32_e32 v155, v89
	v_sub_f32_e32 v89, v91, v151
	v_add_f32_e32 v92, v95, v92
	v_exp_f32_e32 v157, v89
	v_sub_f32_e32 v84, v84, v151
	v_add_f32_e32 v88, v139, v92
	v_exp_f32_e32 v159, v84
	v_sub_f32_e32 v85, v85, v151
	v_add_f32_e32 v88, v153, v88
	v_exp_f32_e32 v161, v85
	v_sub_f32_e32 v85, v86, v151
	v_add_f32_e32 v88, v155, v88
	v_exp_f32_e32 v163, v85
	v_sub_f32_e32 v85, v87, v151
	v_add_f32_e32 v88, v157, v88
	v_exp_f32_e32 v165, v85
	v_sub_f32_e32 v80, v80, v151
	v_add_f32_e32 v84, v159, v88
	v_exp_f32_e32 v167, v80
	v_sub_f32_e32 v81, v81, v151
	v_add_f32_e32 v84, v161, v84
	v_exp_f32_e32 v169, v81
	v_sub_f32_e32 v81, v82, v151
	v_add_f32_e32 v84, v163, v84
	v_exp_f32_e32 v171, v81
	v_sub_f32_e32 v81, v83, v151
	v_add_f32_e32 v84, v165, v84
	v_exp_f32_e32 v173, v81
	v_sub_f32_e32 v72, v72, v151
	v_add_f32_e32 v80, v167, v84
	v_exp_f32_e32 v176, v72
	v_sub_f32_e32 v73, v73, v151
	v_add_f32_e32 v80, v169, v80
	v_exp_f32_e32 v177, v73
	v_sub_f32_e32 v73, v74, v151
	v_add_f32_e32 v80, v171, v80
	v_exp_f32_e32 v178, v73
	v_sub_f32_e32 v73, v75, v151
	v_add_f32_e32 v80, v173, v80
	v_exp_f32_e32 v151, v73
	v_add_f32_e32 v72, v176, v80
	v_add_f32_e32 v72, v177, v72
	v_add_f32_e32 v72, v178, v72
	v_add_f32_e32 v72, v151, v72
	ds_bpermute_b32 v73, v145, v72
	v_cvt_pk_bf16_f32 v84, v76, v77
	v_cvt_pk_bf16_f32 v85, v78, v79
	v_cvt_pk_bf16_f32 v86, v132, v133
	v_cvt_pk_bf16_f32 v87, v134, v135
	s_waitcnt lgkmcnt(0)
; #define LAS __attribute__((address_space(3)))
; #define LAS __attribute__((address_space(3)))
; __device__ __forceinline__ unsigned pk2(float lo, float hi) { return pg8::cvt_pk_bf16(lo, hi); }
; __device__ __forceinline__ f32x4 mfma16(bf16x8 a, bf16x8 b, f32x4 c) { return __builtin_amdgcn_mfma_f32_16x16x32_bf16(a, b, c, 0, 0, 0); }
; template <int NKT, int VSTR, bool SINK>
; __device__ __forceinline__ void attn_core(LAS const unsigned char* kb_, LAS const unsigned char* vb_, bf16x8 q0, bf16x8 q1, float sk, unsigned mskbits, int fr, f32x4 (&o)[4]) {
;     ...
;     sum += __shfl_xor(sum, 16); sum += __shfl_xor(sum, 32);
;     if (SINK) sum += __builtin_amdgcn_exp2f(sk - mx);
;     const float inv = 1.0f / sum;
;     bf16x8 pf[NKT / 2];
; #pragma unroll
;     for (int kb = 0; kb < NKT / 2; ++kb) {
;         v4u w; w.x = pk2(S[2 * kb][0], S[2 * kb][1]); w.y = pk2(S[2 * kb][2], S[2 * kb][3]); w.z = pk2(S[2 * kb + 1][0], S[2 * kb + 1][1]); w.w = pk2(S[2 * kb + 1][2], S[2 * kb + 1][3]);
;         pf[kb] = __builtin_bit_cast(bf16x8, w);
;     }
; #pragma unroll
;     for (int dt = 0; dt < 4; ++dt) {
;         f32x4 acc = (f32x4){0.f, 0.f, 0.f, 0.f};
; #pragma unroll
;         for (int kb = 0; kb < NKT / 2; ++kb) {
;             const bf16x8 vf = *(LAS const bf16x8*)(vb_ + dt * 16 * VSTR + kb * 64);
;             acc = mfma16(vf, pf[kb], acc);
;         }
;         o[dt] = acc * inv;
;     }
	v_add_f32_e32 v72, v72, v73
	ds_bpermute_b32 v73, v147, v72
	v_cvt_pk_bf16_f32 v80, v128, v129
	v_cvt_pk_bf16_f32 v81, v130, v131
	v_cvt_pk_bf16_f32 v82, v124, v125
	v_cvt_pk_bf16_f32 v83, v126, v127
	s_waitcnt lgkmcnt(0)
	v_add_f32_e32 v179, v72, v73
	v_cvt_pk_bf16_f32 v76, v120, v121
	v_cvt_pk_bf16_f32 v77, v122, v123
	v_cvt_pk_bf16_f32 v78, v116, v117
	v_cvt_pk_bf16_f32 v79, v118, v119
	v_cvt_pk_bf16_f32 v72, v112, v113
	v_cvt_pk_bf16_f32 v73, v114, v115
	v_cvt_pk_bf16_f32 v74, v108, v109
	v_cvt_pk_bf16_f32 v75, v110, v111
	v_cvt_pk_bf16_f32 v88, v104, v105
	v_div_scale_f32 v104, s[0:1], v179, v179, 1.0
	v_rcp_f32_e32 v105, v104
	v_cvt_pk_bf16_f32 v89, v106, v107
	v_cvt_pk_bf16_f32 v90, v100, v101
	v_cvt_pk_bf16_f32 v91, v102, v103
	v_cvt_pk_bf16_f32 v92, v96, v97
	v_cvt_pk_bf16_f32 v93, v98, v99
	s_nop 0
	v_fma_f32 v106, -v104, v105, 1.0
	v_fmac_f32_e32 v105, v106, v105
	v_div_scale_f32 v106, vcc, 1.0, v179, 1.0
	v_mul_f32_e32 v107, v106, v105
	v_fma_f32 v108, -v104, v107, v106
	v_fmac_f32_e32 v107, v108, v105
	v_fma_f32 v104, -v104, v107, v106
	v_div_fmas_f32 v104, v104, v105, v107
	v_cvt_pk_bf16_f32 v94, v137, v136
	v_cvt_pk_bf16_f32 v95, v138, v95
	v_cvt_pk_bf16_f32 v96, v139, v153
	v_cvt_pk_bf16_f32 v97, v155, v157
	v_cvt_pk_bf16_f32 v98, v159, v161
	v_cvt_pk_bf16_f32 v99, v163, v165
	v_cvt_pk_bf16_f32 v100, v167, v169
	v_cvt_pk_bf16_f32 v101, v171, v173
	v_cvt_pk_bf16_f32 v102, v176, v177
	v_cvt_pk_bf16_f32 v103, v178, v151
	v_div_fixup_f32 v116, v104, v179, 1.0
	s_waitcnt lgkmcnt(0)
	ds_read_b128 v[196:199], v143
	ds_read_b128 v[200:203], v143 offset:64
	ds_read_b128 v[204:207], v143 offset:8512
	ds_read_b128 v[208:211], v143 offset:16960
	ds_read_b128 v[212:215], v143 offset:128
	ds_read_b128 v[228:231], v143 offset:192
	ds_read_b128 v[232:235], v143 offset:256
	ds_read_b128 v[236:239], v143 offset:320
	ds_read_b128 v[240:243], v143 offset:384
	ds_read_b128 v[244:247], v143 offset:448
	s_waitcnt lgkmcnt(9)
	v_mfma_f32_16x16x32_bf16 v[104:107], v[196:199], v[84:87], 0
	ds_read_b128 v[196:199], v143 offset:8448
	s_waitcnt lgkmcnt(9)
	v_mfma_f32_16x16x32_bf16 v[104:107], v[200:203], v[80:83], v[104:107]
	ds_read_b128 v[200:203], v143 offset:8576
	s_waitcnt lgkmcnt(7)
	v_mfma_f32_16x16x32_bf16 v[104:107], v[212:215], v[76:79], v[104:107]
	ds_read_b128 v[212:215], v143 offset:8640
	s_waitcnt lgkmcnt(7)
	v_mfma_f32_16x16x32_bf16 v[104:107], v[228:231], v[72:75], v[104:107]
	ds_read_b128 v[228:231], v143 offset:8704
	s_waitcnt lgkmcnt(7)
	v_mfma_f32_16x16x32_bf16 v[104:107], v[232:235], v[88:91], v[104:107]
	ds_read_b128 v[232:235], v143 offset:8768
	s_waitcnt lgkmcnt(7)
	v_mfma_f32_16x16x32_bf16 v[104:107], v[236:239], v[92:95], v[104:107]
	ds_read_b128 v[236:239], v143 offset:8832
	s_waitcnt lgkmcnt(7)
	v_mfma_f32_16x16x32_bf16 v[104:107], v[240:243], v[96:99], v[104:107]
	ds_read_b128 v[240:243], v143 offset:8896
	s_waitcnt lgkmcnt(7)
	v_mfma_f32_16x16x32_bf16 v[106:109], v[244:247], v[100:103], v[104:107]
	ds_read_b128 v[244:247], v143 offset:16896
	s_nop 7
	v_pk_mul_f32 v[104:105], v[108:109], v[116:117] op_sel_hi:[1,0]
	s_waitcnt lgkmcnt(7)
	v_mfma_f32_16x16x32_bf16 v[108:111], v[196:199], v[84:87], 0
	ds_read_b128 v[196:199], v143 offset:17024
	v_mul_f32_e64 v106, v106, v116
	v_mul_f32_e64 v107, v107, v116
	v_mfma_f32_16x16x32_bf16 v[108:111], v[204:207], v[80:83], v[108:111]
	ds_read_b128 v[204:207], v143 offset:17088
	s_waitcnt lgkmcnt(8)
	v_mfma_f32_16x16x32_bf16 v[108:111], v[200:203], v[76:79], v[108:111]
	ds_read_b128 v[200:203], v143 offset:17152
	s_waitcnt lgkmcnt(8)
	v_mfma_f32_16x16x32_bf16 v[108:111], v[212:215], v[72:75], v[108:111]
	ds_read_b128 v[212:215], v143 offset:17216
	s_waitcnt lgkmcnt(8)
	v_mfma_f32_16x16x32_bf16 v[108:111], v[228:231], v[88:91], v[108:111]
	ds_read_b128 v[228:231], v143 offset:17280
	s_waitcnt lgkmcnt(8)
	v_mfma_f32_16x16x32_bf16 v[108:111], v[232:235], v[92:95], v[108:111]
	ds_read_b128 v[232:235], v143 offset:17344
	s_waitcnt lgkmcnt(8)
	v_mfma_f32_16x16x32_bf16 v[108:111], v[236:239], v[96:99], v[108:111]
	ds_read_b128 v[236:239], v143 offset:25344
	s_waitcnt lgkmcnt(8)
	v_mfma_f32_16x16x32_bf16 v[110:113], v[240:243], v[100:103], v[108:111]
	s_nop 7
	v_pk_mul_f32 v[108:109], v[112:113], v[116:117] op_sel_hi:[1,0]
	ds_read_b128 v[240:243], v143 offset:25408
	s_waitcnt lgkmcnt(8)
	v_mfma_f32_16x16x32_bf16 v[112:115], v[244:247], v[84:87], 0
	v_mul_f32_e64 v110, v110, v116
	v_mul_f32_e64 v111, v111, v116
	v_mfma_f32_16x16x32_bf16 v[112:115], v[208:211], v[80:83], v[112:115]
	ds_read_b128 v[244:247], v143 offset:25472
	s_waitcnt lgkmcnt(8)
	v_mfma_f32_16x16x32_bf16 v[112:115], v[196:199], v[76:79], v[112:115]
	ds_read_b128 v[208:211], v143 offset:25536
	s_waitcnt lgkmcnt(8)
	v_mfma_f32_16x16x32_bf16 v[112:115], v[204:207], v[72:75], v[112:115]
	ds_read_b128 v[196:199], v143 offset:25600
	s_waitcnt lgkmcnt(8)
	v_mfma_f32_16x16x32_bf16 v[112:115], v[200:203], v[88:91], v[112:115]
	ds_read_b128 v[204:207], v143 offset:25664
	s_waitcnt lgkmcnt(8)
	v_mfma_f32_16x16x32_bf16 v[112:115], v[212:215], v[92:95], v[112:115]
	ds_read_b128 v[200:203], v143 offset:25728
	s_waitcnt lgkmcnt(8)
	v_mfma_f32_16x16x32_bf16 v[112:115], v[228:231], v[96:99], v[112:115]
	s_waitcnt lgkmcnt(7)
	v_mfma_f32_16x16x32_bf16 v[118:121], v[232:235], v[100:103], v[112:115]
	s_nop 7
	v_pk_mul_f32 v[112:113], v[116:117], v[120:121] op_sel_hi:[0,1]
	v_pk_mul_f32 v[114:115], v[116:117], v[118:119] op_sel_hi:[0,1]
	s_waitcnt lgkmcnt(6)
	v_mfma_f32_16x16x32_bf16 v[84:87], v[236:239], v[84:87], 0
	s_waitcnt lgkmcnt(5)
	v_mfma_f32_16x16x32_bf16 v[80:83], v[240:243], v[80:83], v[84:87]
	s_waitcnt lgkmcnt(4)
	v_mfma_f32_16x16x32_bf16 v[76:79], v[244:247], v[76:79], v[80:83]
	s_waitcnt lgkmcnt(3)
	v_mfma_f32_16x16x32_bf16 v[72:75], v[208:211], v[72:75], v[76:79]
	s_waitcnt lgkmcnt(2)
	v_mfma_f32_16x16x32_bf16 v[72:75], v[196:199], v[88:91], v[72:75]
	s_waitcnt lgkmcnt(1)
	v_mfma_f32_16x16x32_bf16 v[72:75], v[204:207], v[92:95], v[72:75]
	s_waitcnt lgkmcnt(0)
	v_mfma_f32_16x16x32_bf16 v[72:75], v[200:203], v[96:99], v[72:75]
	ds_read_b128 v[76:79], v143 offset:25792
	s_waitcnt lgkmcnt(0)
	s_barrier
; #define LAS __attribute__((address_space(3)))
; #define LAS __attribute__((address_space(3)))
; __device__ __forceinline__ f32x4 mfma16(bf16x8 a, bf16x8 b, f32x4 c) { return __builtin_amdgcn_mfma_f32_16x16x32_bf16(a, b, c, 0, 0, 0); }
; template <int NKT, int VSTR, bool SINK>
; __device__ __forceinline__ void attn_core(LAS const unsigned char* kb_, LAS const unsigned char* vb_, bf16x8 q0, bf16x8 q1, float sk, unsigned mskbits, int fr, f32x4 (&o)[4]) {
;     ...
; #pragma unroll
;     for (int kt = 0; kt < NKT; ++kt) {
;         const int key = (kt >> 1) * 32 + ((kt & 1) << 2) + krow;
;         LAS const unsigned char* kp = kb_ + key * 144;
;         const bf16x8 a0 = *(LAS const bf16x8*)kp, a1 = *(LAS const bf16x8*)(kp + 64);
;         const float bias = ((mskbits >> (kt >> 2)) & 1u) ? -1e30f : 0.f;
;         f32x4 s = mfma16(a0, q0, (f32x4){bias, bias, bias, bias});
;         s = mfma16(a1, q1, s);
;         S[kt] = s;
;     }
; template <bool DO_SWA, bool DO_MEM>
; __device__ __forceinline__ void attn_unit(const Args& a, unsigned char* ws, LAS unsigned char* lds, int l, int tid_in, int lane_in, int wave, int unit) {
;     ...
;         if constexpr (DO_MEM)
; #pragma unroll
;         for (int i = 0; i < 8; ++i) {
;             const int chn = tid + 512 * i;
;             { const int key = chn >> 4, c16 = chn & 15; *(LAS v4u*)(lds + A_KS + ((c16 >> 3) * 256 + key) * 144 + (c16 & 7) * 16) = mkst[i]; }
;             { const int col = chn >> 5, kc = chn & 31; *(LAS v4u*)(lds + A_VT2 + col * 528 + kc * 16) = mvst[i]; }
;         }
;         __syncthreads();
;         if constexpr (DO_MEM) {
;             attn_core<16, 528, false>(lds + A_KS + g * 256 * 144 + fq * 16, lds + A_VT2 + (g * 64 + fr) * 528 + fq * 16, qmm[1][0], qmm[1][1], 0.f, 0u, fr, omem[1]);
	s_waitcnt vmcnt(11)
	ds_write_b128 v142, v[8:11]
	s_waitcnt vmcnt(10)
	ds_write_b128 v144, v[12:15]
	s_waitcnt vmcnt(9)
	ds_write_b128 v146, v[16:19]
	s_waitcnt vmcnt(8)
	ds_write_b128 v148, v[20:23]
	s_waitcnt vmcnt(7)
	ds_write_b128 v150, v[24:27]
	s_waitcnt vmcnt(6)
	ds_write_b128 v152, v[28:31]
	ds_write_b128 v154, v[32:35]
	ds_write_b128 v156, v[36:39]
	ds_write_b128 v158, v[40:43]
	ds_write_b128 v160, v[44:47]
	s_waitcnt vmcnt(5)
	ds_write_b128 v162, v[48:51]
	s_waitcnt vmcnt(4)
	ds_write_b128 v164, v[52:55]
	s_waitcnt vmcnt(3)
	ds_write_b128 v166, v[56:59]
	s_waitcnt vmcnt(2)
	ds_write_b128 v168, v[60:63]
	s_waitcnt vmcnt(1)
	ds_write_b128 v170, v[64:67]
	s_waitcnt vmcnt(0)
	ds_write_b128 v172, v[68:71]
	s_waitcnt lgkmcnt(0)
	s_barrier
	s_waitcnt lgkmcnt(0)
	ds_read_b128 v[80:83], v149
	ds_read_b128 v[84:87], v149 offset:64
	ds_read_b128 v[196:199], v149 offset:576
	ds_read_b128 v[200:203], v149 offset:640
	ds_read_b128 v[204:207], v149 offset:4608
	ds_read_b128 v[208:211], v149 offset:4672
	ds_read_b128 v[212:215], v149 offset:5184
	ds_read_b128 v[228:231], v149 offset:5248
	ds_read_b128 v[232:235], v149 offset:9216
	ds_read_b128 v[236:239], v149 offset:9280
	ds_read_b128 v[240:243], v149 offset:9792
	ds_read_b128 v[244:247], v149 offset:9856
	s_waitcnt lgkmcnt(11)
	v_mfma_f32_16x16x32_bf16 v[8:11], v[80:83], v[4:7], 0
	s_waitcnt lgkmcnt(10)
	v_mfma_f32_16x16x32_bf16 v[64:67], v[84:87], v[0:3], v[8:11]
	ds_read_b128 v[80:83], v149 offset:13824
	ds_read_b128 v[84:87], v149 offset:13888
	s_waitcnt lgkmcnt(11)
	v_mfma_f32_16x16x32_bf16 v[8:11], v[196:199], v[4:7], 0
	s_waitcnt lgkmcnt(10)
	v_mfma_f32_16x16x32_bf16 v[60:63], v[200:203], v[0:3], v[8:11]
	ds_read_b128 v[196:199], v149 offset:14400
	ds_read_b128 v[200:203], v149 offset:14464
	s_waitcnt lgkmcnt(11)
	v_mfma_f32_16x16x32_bf16 v[8:11], v[204:207], v[4:7], 0
	s_waitcnt lgkmcnt(10)
	v_mfma_f32_16x16x32_bf16 v[20:23], v[208:211], v[0:3], v[8:11]
	ds_read_b128 v[204:207], v149 offset:18432
	ds_read_b128 v[208:211], v149 offset:18496
	s_waitcnt lgkmcnt(11)
	v_mfma_f32_16x16x32_bf16 v[8:11], v[212:215], v[4:7], 0
	s_waitcnt lgkmcnt(10)
	v_mfma_f32_16x16x32_bf16 v[12:15], v[228:231], v[0:3], v[8:11]
	ds_read_b128 v[212:215], v149 offset:19008
	ds_read_b128 v[228:231], v149 offset:19072
	s_waitcnt lgkmcnt(11)
	v_mfma_f32_16x16x32_bf16 v[8:11], v[232:235], v[4:7], 0
	s_waitcnt lgkmcnt(10)
	v_mfma_f32_16x16x32_bf16 v[8:11], v[236:239], v[0:3], v[8:11]
	ds_read_b128 v[232:235], v149 offset:23040
	ds_read_b128 v[236:239], v149 offset:23104
	s_waitcnt lgkmcnt(11)
	v_mfma_f32_16x16x32_bf16 v[16:19], v[240:243], v[4:7], 0
	s_waitcnt lgkmcnt(10)
	v_mfma_f32_16x16x32_bf16 v[16:19], v[244:247], v[0:3], v[16:19]
	ds_read_b128 v[240:243], v149 offset:23616
	ds_read_b128 v[244:247], v149 offset:23680
	s_waitcnt lgkmcnt(11)
	v_mfma_f32_16x16x32_bf16 v[24:27], v[80:83], v[4:7], 0
	s_waitcnt lgkmcnt(10)
	v_mfma_f32_16x16x32_bf16 v[24:27], v[84:87], v[0:3], v[24:27]
	ds_read_b128 v[80:83], v149 offset:27648
	ds_read_b128 v[84:87], v149 offset:27712
	s_waitcnt lgkmcnt(11)
	v_mfma_f32_16x16x32_bf16 v[28:31], v[196:199], v[4:7], 0
	s_waitcnt lgkmcnt(10)
	v_mfma_f32_16x16x32_bf16 v[28:31], v[200:203], v[0:3], v[28:31]
	ds_read_b128 v[196:199], v149 offset:28224
	ds_read_b128 v[200:203], v149 offset:28288
	s_waitcnt lgkmcnt(11)
	v_mfma_f32_16x16x32_bf16 v[32:35], v[204:207], v[4:7], 0
	s_waitcnt lgkmcnt(10)
	v_mfma_f32_16x16x32_bf16 v[32:35], v[208:211], v[0:3], v[32:35]
	ds_read_b128 v[204:207], v149 offset:32256
	ds_read_b128 v[208:211], v149 offset:32320
	s_waitcnt lgkmcnt(11)
	v_mfma_f32_16x16x32_bf16 v[36:39], v[212:215], v[4:7], 0
	s_waitcnt lgkmcnt(10)
	v_mfma_f32_16x16x32_bf16 v[36:39], v[228:231], v[0:3], v[36:39]
	ds_read_b128 v[212:215], v149 offset:32832
	ds_read_b128 v[228:231], v149 offset:32896
	s_waitcnt lgkmcnt(11)
	v_mfma_f32_16x16x32_bf16 v[40:43], v[232:235], v[4:7], 0
	s_waitcnt lgkmcnt(10)
	v_mfma_f32_16x16x32_bf16 v[40:43], v[236:239], v[0:3], v[40:43]
	s_waitcnt lgkmcnt(9)
	v_mfma_f32_16x16x32_bf16 v[44:47], v[240:243], v[4:7], 0
	s_waitcnt lgkmcnt(8)
	v_mfma_f32_16x16x32_bf16 v[48:51], v[244:247], v[0:3], v[44:47]
	s_waitcnt lgkmcnt(7)
	v_mfma_f32_16x16x32_bf16 v[44:47], v[80:83], v[4:7], 0
	s_waitcnt lgkmcnt(6)
	v_mfma_f32_16x16x32_bf16 v[52:55], v[84:87], v[0:3], v[44:47]
	s_waitcnt lgkmcnt(5)
	v_mfma_f32_16x16x32_bf16 v[44:47], v[196:199], v[4:7], 0
	s_waitcnt lgkmcnt(4)
	v_mfma_f32_16x16x32_bf16 v[56:59], v[200:203], v[0:3], v[44:47]
	v_mfma_f32_16x16x32_bf16 v[74:77], v[76:79], v[100:103], v[72:75]
	s_waitcnt lgkmcnt(3)
	v_mfma_f32_16x16x32_bf16 v[44:47], v[204:207], v[4:7], 0
	s_waitcnt lgkmcnt(2)
	v_mfma_f32_16x16x32_bf16 v[44:47], v[208:211], v[0:3], v[44:47]
	s_nop 3
	v_mul_f32_e64 v72, v116, v76
	v_mul_f32_e64 v73, v116, v77
	v_pk_mul_f32 v[74:75], v[116:117], v[74:75] op_sel_hi:[0,1]
	s_waitcnt lgkmcnt(1)
	v_mfma_f32_16x16x32_bf16 v[4:7], v[212:215], v[4:7], 0
	s_waitcnt lgkmcnt(0)
; template <int NKT, int VSTR, bool SINK>
; __device__ __forceinline__ void attn_core(LAS const unsigned char* kb_, LAS const unsigned char* vb_, bf16x8 q0, bf16x8 q1, float sk, unsigned mskbits, int fr, f32x4 (&o)[4]) {
;     ...
;     float mx = S[0][0];
; #pragma unroll
;     for (int kt = 0; kt < NKT; ++kt) mx = fmaxf(fmaxf(mx, fmaxf(S[kt][0], S[kt][1])), fmaxf(S[kt][2], S[kt][3]));
;     mx = fmaxf(mx, __shfl_xor(mx, 16)); mx = fmaxf(mx, __shfl_xor(mx, 32));
;     if (SINK) mx = fmaxf(mx, sk);
;     float sum = 0.f;
; #pragma unroll
;     for (int kt = 0; kt < NKT; ++kt)
; #pragma unroll
;         for (int r = 0; r < 4; ++r) { const float p = __builtin_amdgcn_exp2f(S[kt][r] - mx); S[kt][r] = p; sum += p; }
	v_mfma_f32_16x16x32_bf16 v[0:3], v[228:231], v[0:3], v[4:7]
	s_nop 5
	v_max_f32_e32 v4, v67, v67
	v_max_f32_e32 v5, v66, v66
	v_max_f32_e32 v4, v5, v4
	v_max_f32_e32 v5, v61, v61
	v_max_f32_e32 v6, v60, v60
	v_max_f32_e32 v5, v6, v5
	v_max_f32_e32 v6, v63, v63
	v_max_f32_e32 v7, v62, v62
	v_max3_f32 v4, v64, v65, v4
	v_max_f32_e32 v6, v7, v6
	v_max3_f32 v4, v4, v5, v6
	v_max_f32_e32 v5, v21, v21
	v_max_f32_e32 v6, v20, v20
	v_max_f32_e32 v5, v6, v5
	v_max_f32_e32 v6, v23, v23
	v_max_f32_e32 v7, v22, v22
	v_max_f32_e32 v6, v7, v6
	v_max3_f32 v4, v4, v5, v6
	v_max_f32_e32 v5, v13, v13
	v_max_f32_e32 v6, v12, v12
	v_max_f32_e32 v5, v6, v5
	v_max_f32_e32 v6, v15, v15
	v_max_f32_e32 v7, v14, v14
	v_max_f32_e32 v6, v7, v6
	v_max3_f32 v4, v4, v5, v6
	v_max_f32_e32 v5, v9, v9
	v_max_f32_e32 v6, v8, v8
	v_max_f32_e32 v5, v6, v5
	v_max_f32_e32 v6, v11, v11
	v_max_f32_e32 v7, v10, v10
	v_max_f32_e32 v6, v7, v6
	v_max3_f32 v4, v4, v5, v6
	v_max_f32_e32 v5, v17, v17
	v_max_f32_e32 v6, v16, v16
	v_max_f32_e32 v5, v6, v5
	v_max_f32_e32 v6, v19, v19
	v_max_f32_e32 v7, v18, v18
	v_max_f32_e32 v6, v7, v6
	v_max3_f32 v4, v4, v5, v6
	v_max_f32_e32 v5, v25, v25
	v_max_f32_e32 v6, v24, v24
	v_max_f32_e32 v5, v6, v5
	v_max_f32_e32 v6, v27, v27
	v_max_f32_e32 v7, v26, v26
	v_max_f32_e32 v6, v7, v6
	v_max3_f32 v4, v4, v5, v6
	v_max_f32_e32 v5, v29, v29
	v_max_f32_e32 v6, v28, v28
	v_max_f32_e32 v5, v6, v5
	v_max_f32_e32 v6, v31, v31
	v_max_f32_e32 v7, v30, v30
	v_max_f32_e32 v6, v7, v6
	v_max3_f32 v4, v4, v5, v6
	v_max_f32_e32 v5, v33, v33
	v_max_f32_e32 v6, v32, v32
	v_max_f32_e32 v5, v6, v5
	v_max_f32_e32 v6, v35, v35
	v_max_f32_e32 v7, v34, v34
	v_max_f32_e32 v6, v7, v6
	v_max3_f32 v4, v4, v5, v6
	v_max_f32_e32 v5, v37, v37
	v_max_f32_e32 v6, v36, v36
	v_max_f32_e32 v5, v6, v5
	v_max_f32_e32 v6, v39, v39
	v_max_f32_e32 v7, v38, v38
	v_max_f32_e32 v6, v7, v6
	v_max3_f32 v4, v4, v5, v6
	v_max_f32_e32 v5, v41, v41
	v_max_f32_e32 v6, v40, v40
	v_max_f32_e32 v5, v6, v5
	v_max_f32_e32 v6, v43, v43
	v_max_f32_e32 v7, v42, v42
	v_max_f32_e32 v6, v7, v6
	v_max3_f32 v4, v4, v5, v6
	v_max_f32_e32 v5, v49, v49
	v_max_f32_e32 v6, v48, v48
	v_max_f32_e32 v5, v6, v5
	v_max_f32_e32 v6, v51, v51
	v_max_f32_e32 v7, v50, v50
	v_max_f32_e32 v6, v7, v6
	v_max3_f32 v4, v4, v5, v6
	v_max_f32_e32 v5, v53, v53
	v_max_f32_e32 v6, v52, v52
	v_max_f32_e32 v5, v6, v5
	v_max_f32_e32 v6, v55, v55
	v_max_f32_e32 v7, v54, v54
	v_max_f32_e32 v6, v7, v6
	v_max3_f32 v4, v4, v5, v6
	v_max_f32_e32 v5, v57, v57
	v_max_f32_e32 v6, v56, v56
	v_max_f32_e32 v5, v6, v5
	v_max_f32_e32 v6, v59, v59
	v_max_f32_e32 v7, v58, v58
	v_max_f32_e32 v6, v7, v6
	v_max3_f32 v4, v4, v5, v6
	v_max_f32_e32 v5, v45, v45
	v_max_f32_e32 v6, v44, v44
	v_max_f32_e32 v5, v6, v5
	v_max_f32_e32 v6, v47, v47
	v_max_f32_e32 v7, v46, v46
	v_max_f32_e32 v6, v7, v6
	v_max3_f32 v4, v4, v5, v6
	v_max_f32_e32 v5, v1, v1
	v_max_f32_e32 v6, v0, v0
	v_max_f32_e32 v5, v6, v5
	v_max_f32_e32 v6, v3, v3
	v_max_f32_e32 v7, v2, v2
	v_max_f32_e32 v6, v7, v6
	v_max3_f32 v4, v4, v5, v6
	ds_bpermute_b32 v5, v145, v4
	s_waitcnt lgkmcnt(0)
	v_max_f32_e32 v5, v5, v5
	v_max_f32_e32 v4, v4, v5
	ds_bpermute_b32 v5, v147, v4
	s_waitcnt lgkmcnt(0)
	v_max_f32_e32 v5, v5, v5
	v_max_f32_e32 v7, v4, v5
	v_sub_f32_e32 v4, v64, v7
	v_exp_f32_e32 v4, v4
	v_sub_f32_e32 v5, v65, v7
	v_exp_f32_e32 v5, v5
	v_sub_f32_e32 v60, v60, v7
	v_add_f32_e32 v6, 0, v4
	v_exp_f32_e32 v60, v60
	v_add_f32_e32 v64, v5, v6
	v_sub_f32_e32 v6, v66, v7
	v_exp_f32_e32 v6, v6
	v_sub_f32_e32 v61, v61, v7
	v_exp_f32_e32 v61, v61
	v_sub_f32_e32 v62, v62, v7
	v_add_f32_e32 v65, v6, v64
	v_sub_f32_e32 v64, v67, v7
	v_exp_f32_e32 v64, v64
	v_exp_f32_e32 v62, v62
	v_sub_f32_e32 v63, v63, v7
	v_exp_f32_e32 v63, v63
	v_add_f32_e32 v65, v64, v65
	v_sub_f32_e32 v20, v20, v7
	v_add_f32_e32 v65, v60, v65
	v_exp_f32_e32 v20, v20
	v_sub_f32_e32 v21, v21, v7
	v_add_f32_e32 v65, v61, v65
	v_exp_f32_e32 v21, v21
	v_sub_f32_e32 v22, v22, v7
	v_add_f32_e32 v65, v62, v65
	v_exp_f32_e32 v22, v22
	v_sub_f32_e32 v23, v23, v7
	v_add_f32_e32 v65, v63, v65
	v_exp_f32_e32 v23, v23
	v_sub_f32_e32 v12, v12, v7
	v_add_f32_e32 v65, v20, v65
	v_exp_f32_e32 v12, v12
	v_sub_f32_e32 v13, v13, v7
	v_add_f32_e32 v65, v21, v65
	v_exp_f32_e32 v13, v13
	v_sub_f32_e32 v14, v14, v7
	v_add_f32_e32 v65, v22, v65
	v_exp_f32_e32 v14, v14
	v_sub_f32_e32 v15, v15, v7
	v_add_f32_e32 v65, v23, v65
	v_exp_f32_e32 v15, v15
	v_sub_f32_e32 v8, v8, v7
	v_add_f32_e32 v65, v12, v65
	v_exp_f32_e32 v8, v8
	v_sub_f32_e32 v9, v9, v7
	v_add_f32_e32 v65, v13, v65
	v_exp_f32_e32 v9, v9
	v_sub_f32_e32 v10, v10, v7
	v_add_f32_e32 v65, v14, v65
	v_exp_f32_e32 v10, v10
	v_sub_f32_e32 v11, v11, v7
	v_add_f32_e32 v65, v15, v65
	v_exp_f32_e32 v11, v11
	v_sub_f32_e32 v16, v16, v7
	v_add_f32_e32 v65, v8, v65
	v_exp_f32_e32 v16, v16
	v_sub_f32_e32 v17, v17, v7
	v_add_f32_e32 v65, v9, v65
	v_exp_f32_e32 v17, v17
	v_sub_f32_e32 v18, v18, v7
	v_add_f32_e32 v65, v10, v65
	v_exp_f32_e32 v18, v18
	v_sub_f32_e32 v19, v19, v7
	v_add_f32_e32 v65, v11, v65
	v_exp_f32_e32 v19, v19
	v_sub_f32_e32 v24, v24, v7
	v_add_f32_e32 v65, v16, v65
	v_exp_f32_e32 v66, v24
	v_add_f32_e32 v65, v17, v65
	v_add_f32_e32 v65, v18, v65
	v_add_f32_e32 v65, v19, v65
	v_sub_f32_e32 v25, v25, v7
	v_add_f32_e32 v24, v66, v65
	v_exp_f32_e32 v65, v25
	v_sub_f32_e32 v25, v26, v7
	v_exp_f32_e32 v67, v25
	v_sub_f32_e32 v25, v27, v7
	v_exp_f32_e32 v68, v25
	v_sub_f32_e32 v25, v28, v7
	v_exp_f32_e32 v69, v25
	v_sub_f32_e32 v25, v29, v7
	v_add_f32_e32 v24, v65, v24
	v_exp_f32_e32 v70, v25
	v_sub_f32_e32 v25, v30, v7
	v_add_f32_e32 v24, v67, v24
	v_exp_f32_e32 v71, v25
	v_sub_f32_e32 v25, v31, v7
; #define LAS __attribute__((address_space(3)))
; #define LAS __attribute__((address_space(3)))
; __device__ __forceinline__ unsigned pk2(float lo, float hi) { return pg8::cvt_pk_bf16(lo, hi); }
; __device__ __forceinline__ f32x4 mfma16(bf16x8 a, bf16x8 b, f32x4 c) { return __builtin_amdgcn_mfma_f32_16x16x32_bf16(a, b, c, 0, 0, 0); }
; template <int NKT, int VSTR, bool SINK>
; __device__ __forceinline__ void attn_core(LAS const unsigned char* kb_, LAS const unsigned char* vb_, bf16x8 q0, bf16x8 q1, float sk, unsigned mskbits, int fr, f32x4 (&o)[4]) {
;     ...
; #pragma unroll
;     for (int kt = 0; kt < NKT; ++kt)
; #pragma unroll
;         for (int r = 0; r < 4; ++r) { const float p = __builtin_amdgcn_exp2f(S[kt][r] - mx); S[kt][r] = p; sum += p; }
;     sum += __shfl_xor(sum, 16); sum += __shfl_xor(sum, 32);
;     if (SINK) sum += __builtin_amdgcn_exp2f(sk - mx);
;     const float inv = 1.0f / sum;
;     bf16x8 pf[NKT / 2];
; #pragma unroll
;     for (int kb = 0; kb < NKT / 2; ++kb) {
;         v4u w; w.x = pk2(S[2 * kb][0], S[2 * kb][1]); w.y = pk2(S[2 * kb][2], S[2 * kb][3]); w.z = pk2(S[2 * kb + 1][0], S[2 * kb + 1][1]); w.w = pk2(S[2 * kb + 1][2], S[2 * kb + 1][3]);
;         pf[kb] = __builtin_bit_cast(bf16x8, w);
;     }
; #pragma unroll
;     for (int dt = 0; dt < 4; ++dt) {
;         f32x4 acc = (f32x4){0.f, 0.f, 0.f, 0.f};
; #pragma unroll
;         for (int kb = 0; kb < NKT / 2; ++kb) {
;             const bf16x8 vf = *(LAS const bf16x8*)(vb_ + dt * 16 * VSTR + kb * 64);
;             acc = mfma16(vf, pf[kb], acc);
;         }
;         o[dt] = acc * inv;
;     }
	v_add_f32_e32 v24, v68, v24
	v_exp_f32_e32 v76, v25
	v_sub_f32_e32 v25, v32, v7
	v_add_f32_e32 v24, v69, v24
	v_exp_f32_e32 v32, v25
	v_sub_f32_e32 v25, v33, v7
	v_add_f32_e32 v24, v70, v24
	v_exp_f32_e32 v33, v25
	v_sub_f32_e32 v25, v34, v7
	v_add_f32_e32 v24, v71, v24
	v_exp_f32_e32 v34, v25
	v_sub_f32_e32 v25, v35, v7
	v_add_f32_e32 v24, v76, v24
	v_exp_f32_e32 v35, v25
	v_sub_f32_e32 v25, v36, v7
	v_add_f32_e32 v24, v32, v24
	v_exp_f32_e32 v36, v25
	v_sub_f32_e32 v25, v37, v7
	v_add_f32_e32 v24, v33, v24
	v_exp_f32_e32 v37, v25
	v_sub_f32_e32 v25, v38, v7
	v_add_f32_e32 v24, v34, v24
	v_exp_f32_e32 v38, v25
	v_sub_f32_e32 v25, v39, v7
	v_add_f32_e32 v24, v35, v24
	v_exp_f32_e32 v39, v25
	v_sub_f32_e32 v25, v40, v7
	v_add_f32_e32 v24, v36, v24
	v_exp_f32_e32 v40, v25
	v_sub_f32_e32 v25, v41, v7
	v_add_f32_e32 v24, v37, v24
	v_exp_f32_e32 v41, v25
	v_sub_f32_e32 v25, v42, v7
	v_add_f32_e32 v24, v38, v24
	v_exp_f32_e32 v42, v25
	v_sub_f32_e32 v25, v43, v7
	v_add_f32_e32 v24, v39, v24
	v_exp_f32_e32 v43, v25
	v_sub_f32_e32 v25, v48, v7
	v_add_f32_e32 v24, v40, v24
	v_exp_f32_e32 v48, v25
	v_sub_f32_e32 v25, v49, v7
	v_add_f32_e32 v24, v41, v24
	v_exp_f32_e32 v49, v25
	v_sub_f32_e32 v25, v50, v7
	v_add_f32_e32 v24, v42, v24
	v_exp_f32_e32 v50, v25
	v_sub_f32_e32 v25, v51, v7
	v_add_f32_e32 v24, v43, v24
	v_exp_f32_e32 v51, v25
	v_sub_f32_e32 v25, v52, v7
	v_add_f32_e32 v24, v48, v24
	v_exp_f32_e32 v52, v25
	v_sub_f32_e32 v25, v53, v7
	v_add_f32_e32 v24, v49, v24
	v_exp_f32_e32 v53, v25
	v_sub_f32_e32 v25, v54, v7
	v_add_f32_e32 v24, v50, v24
	v_exp_f32_e32 v54, v25
	v_sub_f32_e32 v25, v55, v7
	v_add_f32_e32 v24, v51, v24
	v_exp_f32_e32 v55, v25
	v_sub_f32_e32 v25, v56, v7
	v_add_f32_e32 v24, v52, v24
	v_exp_f32_e32 v56, v25
	v_sub_f32_e32 v25, v57, v7
	v_add_f32_e32 v24, v53, v24
	v_exp_f32_e32 v57, v25
	v_sub_f32_e32 v25, v58, v7
	v_add_f32_e32 v24, v54, v24
	v_exp_f32_e32 v58, v25
	v_sub_f32_e32 v25, v59, v7
	v_add_f32_e32 v24, v55, v24
	v_exp_f32_e32 v59, v25
	v_sub_f32_e32 v25, v44, v7
	v_add_f32_e32 v24, v56, v24
	v_exp_f32_e32 v44, v25
	v_sub_f32_e32 v25, v45, v7
	v_add_f32_e32 v24, v57, v24
	v_exp_f32_e32 v45, v25
	v_sub_f32_e32 v25, v46, v7
	v_add_f32_e32 v24, v58, v24
	v_exp_f32_e32 v46, v25
	v_sub_f32_e32 v25, v47, v7
	v_add_f32_e32 v24, v59, v24
	v_exp_f32_e32 v47, v25
	v_sub_f32_e32 v0, v0, v7
	v_add_f32_e32 v24, v44, v24
	v_exp_f32_e32 v77, v0
	v_sub_f32_e32 v1, v1, v7
	v_add_f32_e32 v24, v45, v24
	v_exp_f32_e32 v78, v1
	v_sub_f32_e32 v1, v2, v7
	v_add_f32_e32 v24, v46, v24
	v_exp_f32_e32 v79, v1
	v_sub_f32_e32 v1, v3, v7
	v_add_f32_e32 v24, v47, v24
	v_exp_f32_e32 v3, v1
	v_add_f32_e32 v0, v77, v24
	v_add_f32_e32 v0, v78, v0
	v_add_f32_e32 v0, v79, v0
	v_add_f32_e32 v0, v3, v0
	ds_bpermute_b32 v1, v145, v0
	v_cvt_pk_bf16_f32 v28, v4, v5
	v_cvt_pk_bf16_f32 v29, v6, v64
	v_cvt_pk_bf16_f32 v30, v60, v61
	v_cvt_pk_bf16_f32 v31, v62, v63
	s_waitcnt lgkmcnt(0)
	v_add_f32_e32 v0, v0, v1
	ds_bpermute_b32 v1, v147, v0
	v_cvt_pk_bf16_f32 v24, v20, v21
	v_cvt_pk_bf16_f32 v25, v22, v23
	v_cvt_pk_bf16_f32 v26, v12, v13
	v_cvt_pk_bf16_f32 v27, v14, v15
	s_waitcnt lgkmcnt(0)
	v_add_f32_e32 v80, v0, v1
	v_cvt_pk_bf16_f32 v20, v8, v9
	v_cvt_pk_bf16_f32 v21, v10, v11
	v_cvt_pk_bf16_f32 v22, v16, v17
	v_cvt_pk_bf16_f32 v23, v18, v19
	v_cvt_pk_bf16_f32 v16, v66, v65
	v_cvt_pk_bf16_f32 v17, v67, v68
	v_cvt_pk_bf16_f32 v18, v69, v70
	v_cvt_pk_bf16_f32 v19, v71, v76
	v_cvt_pk_bf16_f32 v12, v32, v33
	v_div_scale_f32 v32, s[0:1], v80, v80, 1.0
	v_rcp_f32_e32 v33, v32
	v_cvt_pk_bf16_f32 v13, v34, v35
	v_cvt_pk_bf16_f32 v14, v36, v37
	v_cvt_pk_bf16_f32 v15, v38, v39
	v_cvt_pk_bf16_f32 v8, v40, v41
	v_cvt_pk_bf16_f32 v9, v42, v43
	s_nop 0
	v_fma_f32 v34, -v32, v33, 1.0
	v_fmac_f32_e32 v33, v34, v33
	v_div_scale_f32 v34, vcc, 1.0, v80, 1.0
	v_mul_f32_e32 v35, v34, v33
	v_fma_f32 v36, -v32, v35, v34
	v_fmac_f32_e32 v35, v36, v33
	v_fma_f32 v32, -v32, v35, v34
	v_div_fmas_f32 v32, v32, v33, v35
	v_cvt_pk_bf16_f32 v10, v48, v49
	v_cvt_pk_bf16_f32 v11, v50, v51
	v_cvt_pk_bf16_f32 v4, v52, v53
	v_cvt_pk_bf16_f32 v5, v54, v55
	v_cvt_pk_bf16_f32 v6, v56, v57
	v_cvt_pk_bf16_f32 v7, v58, v59
	v_cvt_pk_bf16_f32 v0, v44, v45
	v_cvt_pk_bf16_f32 v1, v46, v47
	v_cvt_pk_bf16_f32 v2, v77, v78
	v_cvt_pk_bf16_f32 v3, v79, v3
	v_div_fixup_f32 v36, v32, v80, 1.0
	s_waitcnt lgkmcnt(0)
	ds_read_b128 v[60:63], v143
	ds_read_b128 v[64:67], v143 offset:64
	ds_read_b128 v[68:71], v143 offset:8512
	ds_read_b128 v[84:87], v143 offset:16960
	ds_read_b128 v[88:91], v143 offset:128
	ds_read_b128 v[92:95], v143 offset:192
	ds_read_b128 v[196:199], v143 offset:256
	ds_read_b128 v[200:203], v143 offset:320
	ds_read_b128 v[204:207], v143 offset:384
	ds_read_b128 v[208:211], v143 offset:448
	ds_read_b128 v[212:215], v143 offset:8448
	ds_read_b128 v[228:231], v143 offset:8576
	ds_read_b128 v[232:235], v143 offset:8640
	ds_read_b128 v[236:239], v143 offset:8704
	s_waitcnt lgkmcnt(13)
	v_mfma_f32_16x16x32_bf16 v[32:35], v[60:63], v[28:31], 0
	ds_read_b128 v[240:243], v143 offset:8768
	v_cmp_gt_u32_e32 vcc, 16, v175
	s_waitcnt lgkmcnt(13)
	v_mfma_f32_16x16x32_bf16 v[32:35], v[64:67], v[24:27], v[32:35]
	ds_read_b128 v[244:247], v143 offset:8832
	s_waitcnt lgkmcnt(11)
; #define LAS __attribute__((address_space(3)))
; __device__ __forceinline__ float quad_sum(float s) { s += __shfl_xor(s, 16); s += __shfl_xor(s, 32); return s; }
; __device__ __forceinline__ float sq4(const f32x4 a) { return (a[0] * a[0] + a[1] * a[1]) + (a[2] * a[2] + a[3] * a[3]); }
; #define LAS __attribute__((address_space(3)))
; __device__ __forceinline__ f32x4 mfma16(bf16x8 a, bf16x8 b, f32x4 c) { return __builtin_amdgcn_mfma_f32_16x16x32_bf16(a, b, c, 0, 0, 0); }
; template <int NKT, int VSTR, bool SINK>
; __device__ __forceinline__ void attn_core(LAS const unsigned char* kb_, LAS const unsigned char* vb_, bf16x8 q0, bf16x8 q1, float sk, unsigned mskbits, int fr, f32x4 (&o)[4]) {
;     ...
; #pragma unroll
;     for (int dt = 0; dt < 4; ++dt) {
;         f32x4 acc = (f32x4){0.f, 0.f, 0.f, 0.f};
; #pragma unroll
;         for (int kb = 0; kb < NKT / 2; ++kb) {
;             const bf16x8 vf = *(LAS const bf16x8*)(vb_ + dt * 16 * VSTR + kb * 64);
;             acc = mfma16(vf, pf[kb], acc);
;         }
;         o[dt] = acc * inv;
;     }
; template <bool DO_SWA, bool DO_MEM>
; __device__ __forceinline__ void attn_unit(const Args& a, unsigned char* ws, LAS unsigned char* lds, int l, int tid_in, int lane_in, int wave, int unit) {
;     ...
;             float ssq = 0.f;
; #pragma unroll
;             for (int hp = 0; hp < 2; ++hp)
; #pragma unroll
;                 for (int dt = 0; dt < 4; ++dt) ssq += pg8::sq4(omem[hp][dt]);
;             ssq = pg8::quad_sum(ssq);
;             if (fq == 0) red_m[g * 64 + qs * 16 + fr] = ssq;
	v_mfma_f32_16x16x32_bf16 v[32:35], v[88:91], v[20:23], v[32:35]
	ds_read_b128 v[60:63], v143 offset:8896
	ds_read_b128 v[64:67], v143 offset:16896
	s_waitcnt lgkmcnt(12)
	v_mfma_f32_16x16x32_bf16 v[32:35], v[92:95], v[16:19], v[32:35]
	ds_read_b128 v[88:91], v143 offset:17024
	s_waitcnt lgkmcnt(12)
	v_mfma_f32_16x16x32_bf16 v[32:35], v[196:199], v[12:15], v[32:35]
	ds_read_b128 v[92:95], v143 offset:17088
	s_waitcnt lgkmcnt(12)
	v_mfma_f32_16x16x32_bf16 v[32:35], v[200:203], v[8:11], v[32:35]
	ds_read_b128 v[196:199], v143 offset:17152
	s_waitcnt lgkmcnt(12)
	v_mfma_f32_16x16x32_bf16 v[32:35], v[204:207], v[4:7], v[32:35]
	ds_read_b128 v[200:203], v143 offset:17216
	s_waitcnt lgkmcnt(12)
	v_mfma_f32_16x16x32_bf16 v[38:41], v[208:211], v[0:3], v[32:35]
	s_nop 7
	v_pk_mul_f32 v[32:33], v[40:41], v[36:37] op_sel_hi:[1,0]
	v_pk_mul_f32 v[34:35], v[38:39], v[36:37] op_sel_hi:[1,0]
	ds_read_b128 v[204:207], v143 offset:17280
	s_waitcnt lgkmcnt(12)
	v_mfma_f32_16x16x32_bf16 v[38:41], v[212:215], v[28:31], 0
	v_mfma_f32_16x16x32_bf16 v[38:41], v[68:71], v[24:27], v[38:41]
	ds_read_b128 v[208:211], v143 offset:17344
	s_waitcnt lgkmcnt(12)
	v_mfma_f32_16x16x32_bf16 v[38:41], v[228:231], v[20:23], v[38:41]
	ds_read_b128 v[212:215], v143 offset:25344
	s_waitcnt lgkmcnt(12)
	v_mfma_f32_16x16x32_bf16 v[38:41], v[232:235], v[16:19], v[38:41]
	ds_read_b128 v[68:71], v143 offset:25408
	s_waitcnt lgkmcnt(12)
	v_mfma_f32_16x16x32_bf16 v[38:41], v[236:239], v[12:15], v[38:41]
	ds_read_b128 v[228:231], v143 offset:25472
	s_waitcnt lgkmcnt(12)
	v_mfma_f32_16x16x32_bf16 v[38:41], v[240:243], v[8:11], v[38:41]
	ds_read_b128 v[232:235], v143 offset:25536
	s_waitcnt lgkmcnt(12)
	v_mfma_f32_16x16x32_bf16 v[38:41], v[244:247], v[4:7], v[38:41]
	ds_read_b128 v[236:239], v143 offset:25600
	s_waitcnt lgkmcnt(12)
	v_mfma_f32_16x16x32_bf16 v[40:43], v[60:63], v[0:3], v[38:41]
	s_nop 7
	v_pk_mul_f32 v[38:39], v[42:43], v[36:37] op_sel_hi:[1,0]
	ds_read_b128 v[240:243], v143 offset:25664
	s_waitcnt lgkmcnt(12)
	v_mfma_f32_16x16x32_bf16 v[42:45], v[64:67], v[28:31], 0
	v_mul_f32_e64 v40, v40, v36
	v_mul_f32_e64 v41, v41, v36
	v_mfma_f32_16x16x32_bf16 v[42:45], v[84:87], v[24:27], v[42:45]
	ds_read_b128 v[244:247], v143 offset:25728
	s_waitcnt lgkmcnt(12)
	v_mfma_f32_16x16x32_bf16 v[42:45], v[88:91], v[20:23], v[42:45]
	ds_read_b128 v[60:63], v143 offset:25792
	s_waitcnt lgkmcnt(12)
	v_mfma_f32_16x16x32_bf16 v[42:45], v[92:95], v[16:19], v[42:45]
	s_waitcnt lgkmcnt(11)
	v_mfma_f32_16x16x32_bf16 v[42:45], v[196:199], v[12:15], v[42:45]
	s_waitcnt lgkmcnt(10)
	v_mfma_f32_16x16x32_bf16 v[42:45], v[200:203], v[8:11], v[42:45]
	s_waitcnt lgkmcnt(9)
	v_mfma_f32_16x16x32_bf16 v[42:45], v[204:207], v[4:7], v[42:45]
	s_waitcnt lgkmcnt(8)
	v_mfma_f32_16x16x32_bf16 v[44:47], v[208:211], v[0:3], v[42:45]
	s_nop 7
	v_pk_mul_f32 v[42:43], v[36:37], v[46:47] op_sel_hi:[0,1]
	s_waitcnt lgkmcnt(7)
	v_mfma_f32_16x16x32_bf16 v[28:31], v[212:215], v[28:31], 0
	v_pk_mul_f32 v[44:45], v[36:37], v[44:45] op_sel_hi:[0,1]
	s_waitcnt lgkmcnt(6)
	v_mfma_f32_16x16x32_bf16 v[24:27], v[68:71], v[24:27], v[28:31]
	s_waitcnt lgkmcnt(5)
	v_mfma_f32_16x16x32_bf16 v[20:23], v[228:231], v[20:23], v[24:27]
	s_waitcnt lgkmcnt(4)
	v_mfma_f32_16x16x32_bf16 v[16:19], v[232:235], v[16:19], v[20:23]
	s_waitcnt lgkmcnt(3)
	v_mfma_f32_16x16x32_bf16 v[12:15], v[236:239], v[12:15], v[16:19]
	s_waitcnt lgkmcnt(2)
	v_mfma_f32_16x16x32_bf16 v[8:11], v[240:243], v[8:11], v[12:15]
	s_waitcnt lgkmcnt(1)
	v_mfma_f32_16x16x32_bf16 v[4:7], v[244:247], v[4:7], v[8:11]
	s_waitcnt lgkmcnt(0)
	v_mfma_f32_16x16x32_bf16 v[2:5], v[60:63], v[0:3], v[4:7]
	s_nop 2
	v_mul_f32_e32 v6, v109, v109
	v_fmac_f32_e32 v6, v108, v108
	s_nop 2
	v_pk_mul_f32 v[0:1], v[36:37], v[4:5] op_sel_hi:[0,1]
	v_mul_f32_e32 v4, v107, v107
	v_mul_f32_e32 v5, v105, v105
	v_fmac_f32_e32 v4, v106, v106
	v_fmac_f32_e32 v5, v104, v104
	v_add_f32_e32 v4, v4, v5
	v_mul_f32_e32 v5, v111, v111
	v_fmac_f32_e32 v5, v110, v110
	v_add_f32_e32 v5, v5, v6
	v_add_f32_e32 v4, v4, v5
	v_mul_f32_e32 v5, v115, v115
	v_mul_f32_e32 v6, v113, v113
	v_fmac_f32_e32 v5, v114, v114
	v_fmac_f32_e32 v6, v112, v112
	v_add_f32_e32 v5, v5, v6
	v_add_f32_e32 v4, v4, v5
	v_mul_f32_e32 v5, v75, v75
	v_mul_f32_e32 v6, v73, v73
	v_fmac_f32_e32 v5, v74, v74
	v_fmac_f32_e32 v6, v72, v72
	v_add_f32_e32 v5, v5, v6
	v_add_f32_e32 v4, v4, v5
	v_mul_f32_e32 v5, v35, v35
	v_mul_f32_e32 v6, v33, v33
	v_fmac_f32_e32 v5, v34, v34
	v_fmac_f32_e32 v6, v32, v32
	v_add_f32_e32 v5, v5, v6
	v_add_f32_e32 v4, v4, v5
	v_mul_f32_e32 v5, v41, v41
	v_mul_f32_e32 v6, v39, v39
	v_fmac_f32_e32 v5, v40, v40
	v_fmac_f32_e32 v6, v38, v38
	v_add_f32_e32 v5, v5, v6
	v_add_f32_e32 v4, v5, v4
	v_mul_f32_e32 v5, v45, v45
	v_mul_f32_e32 v6, v43, v43
	v_fmac_f32_e32 v5, v44, v44
	v_fmac_f32_e32 v6, v42, v42
	v_pk_mul_f32 v[2:3], v[36:37], v[2:3] op_sel_hi:[0,1]
	v_add_f32_e32 v5, v5, v6
	v_add_f32_e32 v4, v4, v5
	v_mul_f32_e32 v5, v3, v3
	v_mul_f32_e32 v6, v1, v1
	v_fmac_f32_e32 v5, v2, v2
	v_fmac_f32_e32 v6, v0, v0
	v_add_f32_e32 v5, v5, v6
	v_add_f32_e32 v4, v4, v5
	ds_bpermute_b32 v5, v145, v4
	s_waitcnt lgkmcnt(0)
	v_add_f32_e32 v4, v4, v5
	ds_bpermute_b32 v5, v147, v4
	s_and_saveexec_b64 s[0:1], vcc
	s_cbranch_execz .LBB0_261
	v_readlane_b32 s2, v251, 26
	s_waitcnt lgkmcnt(0)
	v_add_f32_e32 v4, v4, v5
	v_lshl_add_u32 v6, v175, 2, s2
	ds_write_b32 v6, v4

; template <bool DO_SWA, bool DO_MEM>
; __device__ __forceinline__ void attn_unit(const Args& a, unsigned char* ws, LAS unsigned char* lds, int l, int tid_in, int lane_in, int wave, int unit) {
;     ...
;         if constexpr (DO_SWA) {
;             const float* cw = a.in[13] + l * 768 + ch;
; #pragma unroll
;             for (int k = 0; k < 3; ++k) { cwv[2 * k] = *(const f32x4*)(cw + k * 256); cwv[2 * k + 1] = *(const f32x4*)(cw + k * 256 + 4); }
;             const bf16* ub = UB + (size_t)(row0 + t0) * UBW;
; #pragma unroll
;             for (int r = 0; r < 6; ++r) {
;                 if (r >= 2 || tg > 0 || !first) cu[r] = __builtin_nontemporal_load((const v4u*)(ub + (ptrdiff_t)(r - 2) * UBW + 896 + ch));
;                 else if (is_s) { const float* sp = a.in[5] + (size_t)(l * NBS + sb) * 512 + r * 256 + ch; const f32x4 s0 = *(const f32x4*)sp, s1 = *(const f32x4*)(sp + 4);
;                                  cu[r] = (v4u){pk2(s0[0], s0[1]), pk2(s0[2], s0[3]), pk2(s1[0], s1[1]), pk2(s1[2], s1[3])}; }
;                 else cu[r] = zero4;
;             }
; #pragma unroll
;             for (int i = 0; i < 4; ++i) ccb[i] = __builtin_nontemporal_load((const v4u*)(ub + (size_t)i * UBW + 640 + ch));
;         }
;         __builtin_amdgcn_sched_barrier(0);
;         if constexpr (DO_SWA) {
;             float w0[8], w1[8], w2[8];
; #pragma unroll
;             for (int j = 0; j < 4; ++j) { w0[j] = cwv[0][j]; w0[4 + j] = cwv[1][j]; w1[j] = cwv[2][j]; w1[4 + j] = cwv[3][j]; w2[j] = cwv[4][j]; w2[4 + j] = cwv[5][j]; }
; #pragma unroll
;             for (int i = 0; i < 4; ++i) {
;                 float ua[8], ub_[8], uc[8], cbv[8], cy[8];
;                 unpack8(cu[i], ua); unpack8(cu[i + 1], ub_); unpack8(cu[i + 2], uc); unpack8(ccb[i], cbv);
;                 float ss = 0.f;
; #pragma unroll
;                 for (int j = 0; j < 8; ++j) { const float y = ua[j] * w0[j] + ub_[j] * w1[j] + uc[j] * w2[j]; cy[j] = cbv[j] * y; ss += cy[j] * cy[j]; }
;                 ss += __shfl_xor(ss, 1); ss += __shfl_xor(ss, 2); ss += __shfl_xor(ss, 4); ss += __shfl_xor(ss, 8); ss += __shfl_xor(ss, 16);
;                 const float rs = 1.0f / sqrtf(ss * (1.0f / 256.0f) + EPS);
;                 v4u o; o.x = pk2(cy[0] * rs, cy[1] * rs); o.y = pk2(cy[2] * rs, cy[3] * rs); o.z = pk2(cy[4] * rs, cy[5] * rs); o.w = pk2(cy[6] * rs, cy[7] * rs);
.LBB0_272:
	s_or_b64 exec, exec, s[2:3]
	v_lshl_add_u64 v[108:109], v[104:105], 0, v[184:185]
	s_movk_i32 s0, 0x1000
	v_add_co_u32_e32 v110, vcc, s0, v108
	s_movk_i32 s0, 0x2000
	s_nop 0
	v_addc_co_u32_e32 v111, vcc, 0, v109, vcc
	v_add_co_u32_e32 v150, vcc, s0, v108
	v_ashrrev_i32_e32 v169, 31, v168
	s_nop 0
	v_addc_co_u32_e32 v151, vcc, 0, v109, vcc
	global_load_dwordx4 v[104:107], v[110:111], off offset:3328 nt
	global_load_dwordx4 v[116:119], v[110:111], off offset:2816
	global_load_dwordx4 v[124:127], v[110:111], off offset:512 nt
	global_load_dwordx4 v[176:179], v[110:111], off
	global_load_dwordx4 v[180:183], v[108:109], off offset:1792 nt
	global_load_dwordx4 v[146:149], v[108:109], off offset:1280
	global_load_dwordx4 v[112:115], v[150:151], off offset:1536
	s_nop 0
	global_load_dwordx4 v[108:111], v[150:151], off offset:2048 nt
	s_waitcnt vmcnt(0)
	v_lshlrev_b32_e32 v173, 16, v180
	v_lshlrev_b32_e32 v172, 16, v128
	v_mov_b32_e32 v174, v92
	v_mov_b32_e32 v175, v100
	v_pk_mul_f32 v[198:199], v[174:175], v[172:173]
	v_lshlrev_b32_e32 v155, 16, v182
	v_and_b32_e32 v151, 0xffff0000, v182
	v_lshlrev_b32_e32 v182, 16, v120
	v_lshlrev_b64 v[214:215], 11, v[168:169]
	v_fma_f32 v168, v96, v182, v198
	v_lshlrev_b32_e32 v190, 16, v146
	v_lshlrev_b32_e32 v217, 16, v147
	v_and_b32_e32 v220, 0xffff0000, v147
	v_lshlrev_b32_e32 v162, 16, v129
	v_and_b32_e32 v158, 0xffff0000, v129
	v_lshlrev_b32_e32 v147, 16, v183
	v_and_b32_e32 v129, 0xffff0000, v183
	v_lshlrev_b32_e32 v183, 16, v124
	v_add_f32_e32 v168, v168, v199
	v_and_b32_e32 v167, 0xffff0000, v180
	v_and_b32_e32 v166, 0xffff0000, v128
	v_mov_b32_e32 v170, v93
	v_mov_b32_e32 v171, v101
	v_mul_f32_e32 v190, v168, v190
	v_pk_mul_f32 v[168:169], v[174:175], v[182:183]
	v_and_b32_e32 v191, 0xffff0000, v146
	v_lshlrev_b32_e32 v223, 16, v148
	v_and_b32_e32 v224, 0xffff0000, v148
	v_lshlrev_b32_e32 v225, 16, v149
	v_and_b32_e32 v226, 0xffff0000, v149
	v_pk_mul_f32 v[200:201], v[170:171], v[166:167]
	v_lshlrev_b32_e32 v146, 16, v131
	v_mov_b32_e32 v148, v82
	v_mov_b32_e32 v149, v90
	v_fma_f32 v168, v96, v173, v168
	v_and_b32_e32 v180, 0xffff0000, v120
	v_lshlrev_b32_e32 v163, 16, v181
	v_and_b32_e32 v159, 0xffff0000, v181
	v_pk_mul_f32 v[210:211], v[148:149], v[146:147]
	v_lshlrev_b32_e32 v146, 16, v176
	v_add_f32_e32 v168, v168, v169
	v_and_b32_e32 v181, 0xffff0000, v124
	v_fma_f32 v120, v97, v180, v200
	v_mul_f32_e32 v146, v168, v146
	v_add_f32_e32 v120, v120, v201
	v_pk_mul_f32 v[168:169], v[170:171], v[180:181]
	v_mov_b32_e32 v164, v94
	v_mov_b32_e32 v165, v102
	v_lshlrev_b32_e32 v154, 16, v130
	v_mov_b32_e32 v156, v80
	v_mov_b32_e32 v157, v88
	v_mul_f32_e32 v182, v120, v191
	v_fma_f32 v120, v97, v167, v168
	v_pk_mul_f32 v[202:203], v[164:165], v[162:163]
	v_pk_mul_f32 v[206:207], v[156:157], v[154:155]
	v_and_b32_e32 v154, 0xffff0000, v176
	v_lshlrev_b32_e32 v227, 16, v178
	v_and_b32_e32 v228, 0xffff0000, v178
	v_add_f32_e32 v120, v120, v169
	v_lshlrev_b32_e32 v178, 16, v121
	v_lshlrev_b32_e32 v229, 16, v179
	v_and_b32_e32 v230, 0xffff0000, v179
	v_mul_f32_e32 v154, v120, v154
	v_lshlrev_b32_e32 v179, 16, v125
	v_fma_f32 v120, v98, v178, v202
	v_add_f32_e32 v120, v120, v203
	v_pk_mul_f32 v[168:169], v[164:165], v[178:179]
	v_mov_b32_e32 v160, v95
	v_mov_b32_e32 v161, v103
	v_mul_f32_e32 v200, v120, v217
	v_fma_f32 v120, v98, v163, v168
	v_pk_mul_f32 v[204:205], v[160:161], v[158:159]
	v_lshlrev_b32_e32 v162, 16, v177
	v_add_f32_e32 v120, v120, v169
	v_and_b32_e32 v176, 0xffff0000, v121
	v_mul_f32_e32 v162, v120, v162
	v_fma_f32 v120, v99, v176, v204
	v_add_f32_e32 v120, v120, v205
	v_lshlrev_b32_e32 v124, 16, v122
	v_and_b32_e32 v150, 0xffff0000, v130
	v_mov_b32_e32 v152, v81
	v_mov_b32_e32 v153, v89
	v_mul_f32_e32 v178, v120, v220
	v_fma_f32 v120, v84, v124, v206
	v_pk_mul_f32 v[208:209], v[152:153], v[150:151]
	v_and_b32_e32 v172, 0xffff0000, v177
	v_and_b32_e32 v177, 0xffff0000, v125
	v_add_f32_e32 v120, v120, v207
	v_and_b32_e32 v122, 0xffff0000, v122
	v_pk_mul_f32 v[198:199], v[160:161], v[176:177]
	v_mul_f32_e32 v176, v120, v223
	v_fma_f32 v120, v85, v122, v208
	v_mul_f32_e32 v191, v182, v182
	v_add_f32_e32 v120, v120, v209
	v_lshlrev_b32_e32 v168, 16, v123
	v_fmac_f32_e32 v191, v190, v190
	v_mul_f32_e32 v201, v120, v224
	v_fma_f32 v120, v86, v168, v210
	v_and_b32_e32 v128, 0xffff0000, v131
	v_mov_b32_e32 v130, v83
	v_mov_b32_e32 v131, v91
	v_fmac_f32_e32 v191, v200, v200
	v_add_f32_e32 v120, v120, v211
	v_and_b32_e32 v137, 64, v222
	v_pk_mul_f32 v[212:213], v[130:131], v[128:129]
	v_fmac_f32_e32 v191, v178, v178
	v_mul_f32_e32 v202, v120, v225
	v_and_b32_e32 v120, 0xffff0000, v123
	v_xor_b32_e32 v135, 1, v222
	v_add_u32_e32 v137, 64, v137
	v_fmac_f32_e32 v191, v176, v176
	v_fma_f32 v121, v87, v120, v212
	v_cmp_lt_i32_e32 vcc, v135, v137
	v_fmac_f32_e32 v191, v201, v201
	v_add_f32_e32 v121, v121, v213
	v_cndmask_b32_e32 v135, v222, v135, vcc
	v_fmac_f32_e32 v191, v202, v202
	v_mul_f32_e32 v203, v121, v226
	v_lshlrev_b32_e32 v145, 2, v135
	v_fmac_f32_e32 v191, v203, v203
	ds_bpermute_b32 v121, v145, v191
	v_xor_b32_e32 v135, 2, v222
	v_cmp_lt_i32_e32 vcc, v135, v137
	v_fma_f32 v123, v99, v159, v198
	v_add_f32_e32 v123, v123, v199
	v_cndmask_b32_e32 v135, v222, v135, vcc
	v_lshlrev_b32_e32 v143, 2, v135
	s_waitcnt lgkmcnt(0)
	v_add_f32_e32 v121, v191, v121
	v_mul_f32_e32 v172, v123, v172
	ds_bpermute_b32 v123, v143, v121
	v_xor_b32_e32 v135, 4, v222
	v_cmp_lt_i32_e32 vcc, v135, v137
	v_lshlrev_b32_e32 v125, 16, v126
	v_pk_mul_f32 v[198:199], v[156:157], v[124:125]
	v_cndmask_b32_e32 v135, v222, v135, vcc
	v_lshlrev_b32_e32 v141, 2, v135
	s_waitcnt lgkmcnt(0)
; __device__ __forceinline__ unsigned pk2(float lo, float hi) { return pg8::cvt_pk_bf16(lo, hi); }
; template <bool DO_SWA, bool DO_MEM>
; __device__ __forceinline__ void attn_unit(const Args& a, unsigned char* ws, LAS unsigned char* lds, int l, int tid_in, int lane_in, int wave, int unit) {
;     ...
;             for (int i = 0; i < 4; ++i) {
;                 float ua[8], ub_[8], uc[8], cbv[8], cy[8];
;                 unpack8(cu[i], ua); unpack8(cu[i + 1], ub_); unpack8(cu[i + 2], uc); unpack8(ccb[i], cbv);
;                 float ss = 0.f;
; #pragma unroll
;                 for (int j = 0; j < 8; ++j) { const float y = ua[j] * w0[j] + ub_[j] * w1[j] + uc[j] * w2[j]; cy[j] = cbv[j] * y; ss += cy[j] * cy[j]; }
;                 ss += __shfl_xor(ss, 1); ss += __shfl_xor(ss, 2); ss += __shfl_xor(ss, 4); ss += __shfl_xor(ss, 8); ss += __shfl_xor(ss, 16);
;                 const float rs = 1.0f / sqrtf(ss * (1.0f / 256.0f) + EPS);
;                 v4u o; o.x = pk2(cy[0] * rs, cy[1] * rs); o.y = pk2(cy[2] * rs, cy[3] * rs); o.z = pk2(cy[4] * rs, cy[5] * rs); o.w = pk2(cy[6] * rs, cy[7] * rs);
;                 *(v4u*)(MIX + (size_t)(row0 + t0 + i) * D + 512 + ch) = o;
	v_add_f32_e32 v121, v121, v123
	ds_bpermute_b32 v169, v141, v121
	v_xor_b32_e32 v135, 8, v222
	v_cmp_lt_i32_e32 vcc, v135, v137
	v_fma_f32 v124, v84, v155, v198
	v_and_b32_e32 v123, 0xffff0000, v126
	v_cndmask_b32_e32 v135, v222, v135, vcc
	v_lshlrev_b32_e32 v139, 2, v135
	s_waitcnt lgkmcnt(0)
	v_add_f32_e32 v121, v121, v169
	v_add_f32_e32 v124, v124, v199
	v_pk_mul_f32 v[198:199], v[152:153], v[122:123]
	ds_bpermute_b32 v122, v139, v121
	v_xor_b32_e32 v135, 16, v222
	v_cmp_lt_i32_e32 vcc, v135, v137
	s_mov_b32 s2, 0xf800000
	v_fma_f32 v126, v85, v151, v198
	v_cndmask_b32_e32 v135, v222, v135, vcc
	v_lshlrev_b32_e32 v135, 2, v135
	s_waitcnt lgkmcnt(0)
	v_add_f32_e32 v121, v121, v122
	ds_bpermute_b32 v122, v135, v121
	v_lshlrev_b32_e32 v169, 16, v127
	v_add_f32_e32 v126, v126, v199
	v_pk_mul_f32 v[198:199], v[148:149], v[168:169]
	v_mul_f32_e32 v191, v126, v228
	s_waitcnt lgkmcnt(0)
	v_add_f32_e32 v121, v121, v122
	v_fmamk_f32 v121, v121, 0x3b800000, v218
	v_mul_f32_e32 v122, 0x4f800000, v121
	v_cmp_gt_f32_e32 vcc, s2, v121
	v_fma_f32 v126, v86, v147, v198
	v_add_f32_e32 v126, v126, v199
	v_cndmask_b32_e32 v122, v121, v122, vcc
	v_sqrt_f32_e32 v168, v122
	v_mul_f32_e32 v204, v126, v229
	v_and_b32_e32 v121, 0xffff0000, v127
	v_mul_f32_e32 v180, v154, v154
	v_add_u32_e32 v126, -1, v168
	v_fma_f32 v127, -v126, v168, v122
	v_cmp_ge_f32_e64 s[0:1], 0, v127
	v_add_u32_e32 v127, 1, v168
	v_fmac_f32_e32 v180, v146, v146
	v_cndmask_b32_e64 v126, v168, v126, s[0:1]
	v_fma_f32 v168, -v127, v168, v122
	v_cmp_lt_f32_e64 s[0:1], 0, v168
	v_fmac_f32_e32 v180, v162, v162
	v_fmac_f32_e32 v180, v172, v172
	v_cndmask_b32_e64 v126, v126, v127, s[0:1]
	v_mul_f32_e32 v127, 0x37800000, v126
	v_cndmask_b32_e32 v126, v126, v127, vcc
	v_cmp_class_f32_e32 vcc, v122, v219
	v_mul_f32_e32 v124, v124, v227
	v_fmac_f32_e32 v180, v124, v124
	v_cndmask_b32_e32 v122, v126, v122, vcc
	v_pk_mul_f32 v[126:127], v[130:131], v[120:121]
	v_fmac_f32_e32 v180, v191, v191
	v_fma_f32 v120, v87, v129, v126
	v_add_f32_e32 v120, v120, v127
	v_fmac_f32_e32 v180, v204, v204
	v_mul_f32_e32 v120, v120, v230
	v_fmac_f32_e32 v180, v120, v120
	ds_bpermute_b32 v199, v145, v180
	v_div_scale_f32 v168, s[0:1], v122, v122, 1.0
	v_rcp_f32_e32 v198, v168
	v_lshl_add_u64 v[126:127], s[20:21], 0, v[214:215]
	s_waitcnt lgkmcnt(0)
	v_add_f32_e32 v180, v180, v199
	ds_bpermute_b32 v199, v143, v180
	v_fma_f32 v205, -v168, v198, 1.0
	v_fmac_f32_e32 v198, v205, v198
	v_div_scale_f32 v205, vcc, 1.0, v122, 1.0
	s_waitcnt lgkmcnt(0)
	v_add_f32_e32 v180, v180, v199
	ds_bpermute_b32 v199, v141, v180
	v_mul_f32_e32 v206, v205, v198
	v_fma_f32 v207, -v168, v206, v205
	v_fmac_f32_e32 v206, v207, v198
	v_fma_f32 v168, -v168, v206, v205
	s_waitcnt lgkmcnt(0)
	v_add_f32_e32 v180, v180, v199
	ds_bpermute_b32 v199, v139, v180
	v_div_fmas_f32 v168, v168, v198, v206
	v_div_fixup_f32 v122, v168, v122, 1.0
	v_mul_f32_e32 v168, v190, v122
	v_mul_f32_e32 v182, v182, v122
	v_cvt_pk_bf16_f32 v198, v168, v182
	s_waitcnt lgkmcnt(0)
	v_add_f32_e32 v168, v180, v199
	ds_bpermute_b32 v180, v135, v168
	v_mul_f32_e32 v178, v178, v122
	v_mul_f32_e32 v182, v200, v122
	v_cvt_pk_bf16_f32 v199, v182, v178
	v_mul_f32_e32 v176, v176, v122
	s_waitcnt lgkmcnt(0)
	v_add_f32_e32 v168, v168, v180
	v_fmamk_f32 v168, v168, 0x3b800000, v218
	v_mul_f32_e32 v178, 0x4f800000, v168
	v_cmp_gt_f32_e32 vcc, s2, v168
	v_mul_f32_e32 v180, v201, v122
	v_cvt_pk_bf16_f32 v200, v176, v180
	v_mul_f32_e32 v176, v202, v122
	v_cndmask_b32_e32 v168, v168, v178, vcc
	v_sqrt_f32_e32 v178, v168
	v_mul_f32_e32 v122, v203, v122
	v_cvt_pk_bf16_f32 v201, v176, v122
	v_lshl_add_u64 v[126:127], v[126:127], 0, v[184:185]
	v_add_u32_e32 v180, -1, v178
	v_fma_f32 v182, -v180, v178, v168
	v_cmp_ge_f32_e64 s[0:1], 0, v182
	v_add_u32_e32 v182, 1, v178
	global_store_dwordx4 v[126:127], v[198:201], off offset:1024
	v_cndmask_b32_e64 v180, v178, v180, s[0:1]
	v_fma_f32 v178, -v182, v178, v168
	v_cmp_lt_f32_e64 s[0:1], 0, v178
	v_lshlrev_b32_e32 v176, 16, v114
	s_movk_i32 s3, 0x190
	v_cndmask_b32_e64 v178, v180, v182, s[0:1]
	v_mul_f32_e32 v180, 0x37800000, v178
	v_cndmask_b32_e32 v178, v178, v180, vcc
	v_cmp_class_f32_e32 vcc, v168, v219
	v_and_b32_e32 v182, 0xffff0000, v115
	s_nop 0
	v_cndmask_b32_e32 v168, v178, v168, vcc
	v_div_scale_f32 v178, s[0:1], v168, v168, 1.0
	v_rcp_f32_e32 v180, v178
	s_nop 0
	v_fma_f32 v122, -v178, v180, 1.0
	v_fmac_f32_e32 v180, v122, v180
	v_div_scale_f32 v122, vcc, 1.0, v168, 1.0
	v_mul_f32_e32 v126, v122, v180
	v_fma_f32 v127, -v178, v126, v122
	v_fmac_f32_e32 v126, v127, v180
	v_fma_f32 v122, -v178, v126, v122
	v_div_fmas_f32 v122, v122, v180, v126
	v_div_fixup_f32 v122, v122, v168, 1.0
	v_mul_f32_e32 v126, v146, v122
	v_mul_f32_e32 v127, v154, v122
	v_cvt_pk_bf16_f32 v198, v126, v127
	v_mul_f32_e32 v126, v162, v122
	v_mul_f32_e32 v127, v172, v122
	v_lshlrev_b32_e32 v154, 16, v112
	v_and_b32_e32 v162, 0xffff0000, v112
	v_lshlrev_b32_e32 v168, 16, v113
	v_and_b32_e32 v172, 0xffff0000, v113
	v_lshlrev_b32_e32 v112, 16, v104
	v_lshlrev_b32_e32 v113, 16, v108
	v_and_b32_e32 v178, 0xffff0000, v114
	v_lshlrev_b32_e32 v180, 16, v115
	v_pk_mov_b32 v[114:115], v[172:173], v[112:113] op_sel:[1,0]
	v_mul_f32_e32 v124, v124, v122
	v_pk_mul_f32 v[114:115], v[174:175], v[114:115]
	v_mul_f32_e32 v120, v120, v122
	v_fma_f32 v114, v96, v183, v114
	v_cvt_pk_bf16_f32 v199, v126, v127
	v_mul_f32_e32 v126, v191, v122
	v_cvt_pk_bf16_f32 v200, v124, v126
	v_mul_f32_e32 v124, v204, v122
	v_cvt_pk_bf16_f32 v201, v124, v120
	v_lshlrev_b32_e32 v120, 16, v116
	v_add_f32_e32 v114, v114, v115
	v_mul_f32_e32 v120, v114, v120
	v_mov_b32_e32 v114, v96
	v_mov_b32_e32 v115, v100
; __device__ __forceinline__ unsigned pk2(float lo, float hi) { return pg8::cvt_pk_bf16(lo, hi); }
; template <bool DO_SWA, bool DO_MEM>
; __device__ __forceinline__ void attn_unit(const Args& a, unsigned char* ws, LAS unsigned char* lds, int l, int tid_in, int lane_in, int wave, int unit) {
;     ...
;             for (int i = 0; i < 4; ++i) {
;                 float ua[8], ub_[8], uc[8], cbv[8], cy[8];
;                 unpack8(cu[i], ua); unpack8(cu[i + 1], ub_); unpack8(cu[i + 2], uc); unpack8(ccb[i], cbv);
;                 float ss = 0.f;
; #pragma unroll
;                 for (int j = 0; j < 8; ++j) { const float y = ua[j] * w0[j] + ub_[j] * w1[j] + uc[j] * w2[j]; cy[j] = cbv[j] * y; ss += cy[j] * cy[j]; }
;                 ss += __shfl_xor(ss, 1); ss += __shfl_xor(ss, 2); ss += __shfl_xor(ss, 4); ss += __shfl_xor(ss, 8); ss += __shfl_xor(ss, 16);
;                 const float rs = 1.0f / sqrtf(ss * (1.0f / 256.0f) + EPS);
;                 v4u o; o.x = pk2(cy[0] * rs, cy[1] * rs); o.y = pk2(cy[2] * rs, cy[3] * rs); o.z = pk2(cy[4] * rs, cy[5] * rs); o.w = pk2(cy[6] * rs, cy[7] * rs);
;                 *(v4u*)(MIX + (size_t)(row0 + t0 + i) * D + 512 + ch) = o;
	v_pk_mul_f32 v[112:113], v[114:115], v[112:113]
	v_mov_b32_e32 v100, v97
	v_fma_f32 v92, v92, v183, v112
	v_add_f32_e32 v92, v92, v113
	v_and_b32_e32 v113, 0xffff0000, v108
	v_and_b32_e32 v112, 0xffff0000, v104
	v_pk_mov_b32 v[114:115], v[166:167], v[112:113] op_sel:[1,0]
	v_mul_f32_e32 v154, v92, v154
	v_pk_mul_f32 v[114:115], v[170:171], v[114:115]
	v_and_b32_e32 v122, 0xffff0000, v116
	v_fma_f32 v92, v97, v181, v114
	v_add_f32_e32 v92, v92, v115
	v_pk_mul_f32 v[96:97], v[100:101], v[112:113]
	v_mul_f32_e32 v104, v92, v122
	v_fma_f32 v92, v93, v181, v96
	v_add_f32_e32 v92, v92, v97
	v_mul_f32_e32 v112, v92, v162
	v_lshlrev_b32_e32 v92, 16, v105
	v_lshlrev_b32_e32 v93, 16, v109
	v_pk_mov_b32 v[96:97], v[162:163], v[92:93] op_sel:[1,0]
	v_lshlrev_b32_e32 v124, 16, v117
	v_pk_mul_f32 v[96:97], v[164:165], v[96:97]
	v_add_u32_e32 v126, -2, v144
	v_fma_f32 v96, v98, v179, v96
	v_add_f32_e32 v96, v96, v97
	v_mul_f32_e32 v114, v96, v124
	v_mov_b32_e32 v96, v98
	v_mov_b32_e32 v97, v102
	v_pk_mul_f32 v[92:93], v[96:97], v[92:93]
	v_ashrrev_i32_e32 v127, 31, v126
	v_fma_f32 v92, v94, v179, v92
	v_add_f32_e32 v92, v92, v93
	v_mul_f32_e32 v115, v92, v168
	v_and_b32_e32 v93, 0xffff0000, v109
	v_and_b32_e32 v92, 0xffff0000, v105
	v_lshlrev_b64 v[126:127], 11, v[126:127]
	v_pk_mov_b32 v[96:97], v[158:159], v[92:93] op_sel:[1,0]
	v_lshl_add_u64 v[126:127], s[20:21], 0, v[126:127]
	v_pk_mul_f32 v[96:97], v[160:161], v[96:97]
	v_lshl_add_u64 v[126:127], v[126:127], 0, v[184:185]
	v_fma_f32 v94, v99, v177, v96
	v_mov_b32_e32 v102, v99
	global_store_dwordx4 v[126:127], v[198:201], off offset:1024
	v_and_b32_e32 v126, 0xffff0000, v117
	v_add_f32_e32 v94, v94, v97
	v_pk_mul_f32 v[92:93], v[102:103], v[92:93]
	v_mul_f32_e32 v105, v94, v126
	v_fma_f32 v92, v95, v177, v92
	v_lshlrev_b32_e32 v94, 16, v106
	v_lshlrev_b32_e32 v95, 16, v110
	v_pk_mov_b32 v[96:97], v[154:155], v[94:95] op_sel:[1,0]
	v_lshlrev_b32_e32 v127, 16, v118
	v_pk_mul_f32 v[96:97], v[156:157], v[96:97]
	v_and_b32_e32 v118, 0xffff0000, v118
	v_fma_f32 v96, v84, v125, v96
	v_add_f32_e32 v96, v96, v97
	v_mul_f32_e32 v109, v96, v127
	v_and_b32_e32 v97, 0xffff0000, v110
	v_and_b32_e32 v96, 0xffff0000, v106
	v_pk_mov_b32 v[98:99], v[150:151], v[96:97] op_sel:[1,0]
	v_lshlrev_b32_e32 v146, 16, v119
	v_pk_mul_f32 v[98:99], v[152:153], v[98:99]
	v_mul_f32_e32 v108, v104, v104
	v_fma_f32 v98, v85, v123, v98
	v_add_f32_e32 v98, v98, v99
	v_mul_f32_e32 v106, v98, v118
	v_lshlrev_b32_e32 v98, 16, v107
	v_lshlrev_b32_e32 v99, 16, v111
	v_pk_mov_b32 v[100:101], v[146:147], v[98:99] op_sel:[1,0]
	v_fmac_f32_e32 v108, v120, v120
	v_pk_mul_f32 v[100:101], v[148:149], v[100:101]
	v_fmac_f32_e32 v108, v114, v114
	v_fma_f32 v100, v86, v169, v100
	v_add_f32_e32 v100, v100, v101
	v_mul_f32_e32 v110, v100, v146
	v_and_b32_e32 v101, 0xffff0000, v111
	v_and_b32_e32 v100, 0xffff0000, v107
	v_pk_mov_b32 v[102:103], v[128:129], v[100:101] op_sel:[1,0]
	v_fmac_f32_e32 v108, v105, v105
	v_pk_mul_f32 v[102:103], v[130:131], v[102:103]
	v_fmac_f32_e32 v108, v109, v109
	v_fma_f32 v102, v87, v121, v102
	v_and_b32_e32 v119, 0xffff0000, v119
	v_fmac_f32_e32 v108, v106, v106
	v_add_f32_e32 v102, v102, v103
	v_fmac_f32_e32 v108, v110, v110
	v_mul_f32_e32 v102, v102, v119
	v_fmac_f32_e32 v108, v102, v102
	ds_bpermute_b32 v103, v145, v108
	v_add_f32_e32 v92, v92, v93
	v_mul_f32_e32 v107, v92, v172
	v_mov_b32_e32 v92, v84
	v_mov_b32_e32 v93, v88
	s_waitcnt lgkmcnt(0)
	v_add_f32_e32 v84, v108, v103
	ds_bpermute_b32 v103, v143, v84
	v_pk_mul_f32 v[92:93], v[92:93], v[94:95]
	v_mov_b32_e32 v88, v85
	v_fma_f32 v80, v80, v125, v92
	v_add_f32_e32 v80, v80, v93
	s_waitcnt lgkmcnt(0)
	v_add_f32_e32 v92, v84, v103
	ds_bpermute_b32 v93, v141, v92
	v_mul_f32_e32 v94, v80, v176
	v_pk_mul_f32 v[84:85], v[88:89], v[96:97]
	v_mul_f32_e32 v113, v112, v112
	v_fma_f32 v81, v81, v123, v84
	s_waitcnt lgkmcnt(0)
	v_add_f32_e32 v80, v92, v93
	ds_bpermute_b32 v88, v139, v80
	v_add_f32_e32 v81, v81, v85
	v_mul_f32_e32 v89, v81, v178
	v_mov_b32_e32 v81, v90
	v_fmac_f32_e32 v113, v154, v154
	s_waitcnt lgkmcnt(0)
	v_add_f32_e32 v84, v80, v88
	ds_bpermute_b32 v85, v135, v84
	v_mov_b32_e32 v80, v86
	v_pk_mul_f32 v[80:81], v[80:81], v[98:99]
	v_fmac_f32_e32 v113, v115, v115
	v_fma_f32 v80, v82, v169, v80
	s_waitcnt lgkmcnt(0)
	v_add_f32_e32 v82, v84, v85
	v_fmamk_f32 v82, v82, 0x3b800000, v218
	v_mul_f32_e32 v84, 0x4f800000, v82
	v_cmp_gt_f32_e32 vcc, s2, v82
	v_add_f32_e32 v80, v80, v81
	v_mul_f32_e32 v86, v80, v180
	v_cndmask_b32_e32 v82, v82, v84, vcc
	v_sqrt_f32_e32 v84, v82
	v_mov_b32_e32 v90, v87
	v_fmac_f32_e32 v113, v107, v107
	v_fmac_f32_e32 v113, v94, v94
	v_add_u32_e32 v80, -1, v84
	v_fma_f32 v81, -v80, v84, v82
	v_cmp_ge_f32_e64 s[0:1], 0, v81
	v_add_u32_e32 v81, 1, v84
	v_fmac_f32_e32 v113, v89, v89
	v_cndmask_b32_e64 v80, v84, v80, s[0:1]
	v_fma_f32 v84, -v81, v84, v82
	v_cmp_lt_f32_e64 s[0:1], 0, v84
	v_fmac_f32_e32 v113, v86, v86
	v_add_u32_e32 v116, -1, v144
	v_cndmask_b32_e64 v80, v80, v81, s[0:1]
	v_mul_f32_e32 v81, 0x37800000, v80
	v_cndmask_b32_e32 v80, v80, v81, vcc
	v_cmp_class_f32_e32 vcc, v82, v219
	v_ashrrev_i32_e32 v117, 31, v116
	v_lshlrev_b64 v[116:117], 11, v[116:117]
	v_cndmask_b32_e32 v82, v80, v82, vcc
	v_pk_mul_f32 v[80:81], v[90:91], v[100:101]
	v_div_scale_f32 v88, s[0:1], v82, v82, 1.0
	v_fma_f32 v80, v83, v121, v80
	v_add_f32_e32 v80, v80, v81
	v_mul_f32_e32 v87, v80, v182
	v_fmac_f32_e32 v113, v87, v87
	v_rcp_f32_e32 v92, v88
	ds_bpermute_b32 v83, v145, v113
	v_lshl_add_u64 v[80:81], s[20:21], 0, v[116:117]
	v_lshl_add_u64 v[84:85], v[80:81], 0, v[184:185]
	v_fma_f32 v80, -v88, v92, 1.0
	v_fmac_f32_e32 v92, v80, v92
	s_waitcnt lgkmcnt(0)
; #define LAS __attribute__((address_space(3)))
; #define LAS __attribute__((address_space(3)))
; __device__ __forceinline__ f32x4 mfma16(bf16x8 a, bf16x8 b, f32x4 c) { return __builtin_amdgcn_mfma_f32_16x16x32_bf16(a, b, c, 0, 0, 0); }
; template <int NKT, int VSTR, bool SINK>
; __device__ __forceinline__ void attn_core(LAS const unsigned char* kb_, LAS const unsigned char* vb_, bf16x8 q0, bf16x8 q1, float sk, unsigned mskbits, int fr, f32x4 (&o)[4]) {
;     ...
; #pragma unroll
;     for (int kt = 0; kt < NKT; ++kt) {
;         const int key = (kt >> 1) * 32 + ((kt & 1) << 2) + krow;
;         LAS const unsigned char* kp = kb_ + key * 144;
;         const bf16x8 a0 = *(LAS const bf16x8*)kp, a1 = *(LAS const bf16x8*)(kp + 64);
;         const float bias = ((mskbits >> (kt >> 2)) & 1u) ? -1e30f : 0.f;
;         f32x4 s = mfma16(a0, q0, (f32x4){bias, bias, bias, bias});
;         s = mfma16(a1, q1, s);
;         S[kt] = s;
;     }
; template <bool DO_SWA, bool DO_MEM>
; __device__ __forceinline__ void attn_unit(const Args& a, unsigned char* ws, LAS unsigned char* lds, int l, int tid_in, int lane_in, int wave, int unit) {
;     ...
;         if constexpr (DO_SWA)
; #pragma unroll
;         for (int i = 0; i < 6; ++i) {
;             const int s = i >> 1, rem = tid + 512 * (i & 1);
;             { const int key = rem >> 4, c16 = rem & 15; *(LAS v4u*)(lds + A_KS + ((c16 >> 3) * 192 + s * 64 + key) * 144 + (c16 & 7) * 16) = kst[i]; }
;             { const int col = rem >> 3, kc = rem & 7; *(LAS v4u*)(lds + A_VT1 + col * 400 + (s * 64 + kc * 8) * 2) = vst[i]; }
;         }
;         const bf16* MKb = (const bf16*)(ws + WS_MK) + (size_t)(l * 40 + bb) * 65536;
;         const bf16* MVTb = (const bf16*)(ws + WS_MVT) + (size_t)(l * 40 + bb) * 65536;
;         v4u mkst[8], mvst[8];
;         __builtin_amdgcn_sched_barrier(0);
;         __syncthreads();
;         v2u osv[4][4];
;         if constexpr (DO_SWA) {
;             float ssq = 0.f;
; #pragma unroll
;             for (int hh = 0; hh < 4; ++hh) {
;                 const int h = g * 4 + hh;
;                 const float sk = a.in[12][l * 8 + h] * LOG2E;
;                 f32x4 o[4];
;                 attn_core<12, 400, true>(lds + A_KS + g * 192 * 144 + fq * 16, lds + A_VT1 + (g * 64 + fr) * 400 + fq * 16, qsw[hh][0], qsw[hh][1], sk, mskbits, fr, o);
	v_add_f32_e32 v80, v113, v83
	ds_bpermute_b32 v81, v143, v80
	v_div_scale_f32 v83, vcc, 1.0, v82, 1.0
	v_mul_f32_e32 v90, v83, v92
	v_fma_f32 v91, -v88, v90, v83
	s_waitcnt lgkmcnt(0)
	v_add_f32_e32 v80, v80, v81
	ds_bpermute_b32 v81, v141, v80
	v_fmac_f32_e32 v90, v91, v92
	v_fma_f32 v83, -v88, v90, v83
	v_div_fmas_f32 v83, v83, v92, v90
	v_div_fixup_f32 v83, v83, v82, 1.0
	s_waitcnt lgkmcnt(0)
	v_add_f32_e32 v81, v80, v81
	ds_bpermute_b32 v88, v139, v81
	v_mul_f32_e32 v80, v120, v83
	v_mul_f32_e32 v82, v104, v83
	v_cvt_pk_bf16_f32 v80, v80, v82
	v_mul_f32_e32 v90, v105, v83
	s_waitcnt lgkmcnt(0)
	v_add_f32_e32 v82, v81, v88
	ds_bpermute_b32 v88, v135, v82
	v_mul_f32_e32 v81, v114, v83
	v_cvt_pk_bf16_f32 v81, v81, v90
	v_mul_f32_e32 v90, v109, v83
	v_ashrrev_i32_e32 v145, 31, v144
	s_waitcnt lgkmcnt(0)
	v_add_f32_e32 v82, v82, v88
	v_fmamk_f32 v82, v82, 0x3b800000, v218
	v_mul_f32_e32 v88, 0x4f800000, v82
	v_cmp_gt_f32_e32 vcc, s2, v82
	s_movk_i32 s2, 0x90
	s_nop 0
	v_cndmask_b32_e32 v88, v82, v88, vcc
	v_sqrt_f32_e32 v91, v88
	v_mul_f32_e32 v82, v106, v83
	v_cvt_pk_bf16_f32 v82, v90, v82
	v_mul_f32_e32 v90, v110, v83
	v_add_u32_e32 v92, -1, v91
	v_fma_f32 v93, -v92, v91, v88
	v_cmp_ge_f32_e64 s[0:1], 0, v93
	v_add_u32_e32 v93, 1, v91
	v_mul_f32_e32 v83, v102, v83
	v_cndmask_b32_e64 v92, v91, v92, s[0:1]
	v_fma_f32 v91, -v93, v91, v88
	v_cmp_lt_f32_e64 s[0:1], 0, v91
	v_cvt_pk_bf16_f32 v83, v90, v83
	global_store_dwordx4 v[84:85], v[80:83], off offset:1024
	s_nop 0
	v_cndmask_b32_e64 v91, v92, v93, s[0:1]
	v_mul_f32_e32 v92, 0x37800000, v91
	v_cndmask_b32_e32 v91, v91, v92, vcc
	v_cmp_class_f32_e32 vcc, v88, v219
	s_nop 1
	v_cndmask_b32_e32 v88, v91, v88, vcc
	v_div_scale_f32 v91, s[0:1], v88, v88, 1.0
	v_rcp_f32_e32 v92, v91
	s_nop 0
	v_fma_f32 v80, -v91, v92, 1.0
	v_fmac_f32_e32 v92, v80, v92
	v_div_scale_f32 v80, vcc, 1.0, v88, 1.0
	v_mul_f32_e32 v81, v80, v92
	v_fma_f32 v82, -v91, v81, v80
	v_fmac_f32_e32 v81, v82, v92
	v_fma_f32 v80, -v91, v81, v80
	v_div_fmas_f32 v80, v80, v92, v81
	v_div_fixup_f32 v83, v80, v88, 1.0
	v_mul_f32_e32 v80, v154, v83
	v_mul_f32_e32 v81, v112, v83
	v_cvt_pk_bf16_f32 v80, v80, v81
	v_mul_f32_e32 v81, v115, v83
	v_mul_f32_e32 v82, v107, v83
	v_cvt_pk_bf16_f32 v81, v81, v82
	v_mul_f32_e32 v82, v94, v83
	v_mul_f32_e32 v84, v89, v83
	v_cvt_pk_bf16_f32 v82, v82, v84
	v_mul_f32_e32 v84, v86, v83
	v_mul_f32_e32 v83, v87, v83
	v_cvt_pk_bf16_f32 v83, v84, v83
	v_lshlrev_b64 v[84:85], 11, v[144:145]
	v_lshl_add_u64 v[84:85], s[20:21], 0, v[84:85]
	v_lshl_add_u64 v[84:85], v[84:85], 0, v[184:185]
	global_store_dwordx4 v[84:85], v[80:83], off offset:1024
	s_nop 1
	v_bfe_i32 v80, v196, 3, 1
	v_and_b32_e32 v81, 0xc0, v80
	v_and_b32_e32 v80, 0x70, v197
	v_add_u32_e32 v80, 0, v80
	v_add_u32_e32 v82, v81, v134
	v_mad_u64_u32 v[82:83], s[0:1], v82, s2, v[80:81]
	ds_write_b128 v82, v[36:39]
	v_mul_lo_u32 v36, v140, s3
	v_add3_u32 v36, 0, v36, v138
	ds_write_b128 v36, v[32:35] offset:55296
	v_add_u32_e32 v32, v81, v136
	v_mad_u64_u32 v[32:33], s[0:1], v32, s2, v[80:81]
	ds_write_b128 v32, v[56:59]
	v_mul_lo_u32 v32, v142, s3
	v_add_u32_e32 v35, 64, v81
	v_add3_u32 v34, 0, v32, v138
	v_add_u32_e32 v32, v35, v134
	v_mad_u64_u32 v[32:33], s[0:1], v32, s2, v[80:81]
	ds_write_b128 v34, v[68:71] offset:55296
	ds_write_b128 v32, v[52:55]
	ds_write_b128 v36, v[40:43] offset:55424
	v_add_u32_e32 v32, v35, v136
	v_mad_u64_u32 v[32:33], s[0:1], v32, s2, v[80:81]
	v_add_u32_e32 v35, 0x80, v81
	ds_write_b128 v32, v[44:47]
	ds_write_b128 v34, v[48:51] offset:55424
	v_add_u32_e32 v32, v35, v134
	v_mad_u64_u32 v[32:33], s[0:1], v32, s2, v[80:81]
	ds_write_b128 v32, v[60:63]
	ds_write_b128 v36, v[64:67] offset:55552
	v_add_u32_e32 v32, v35, v136
	v_mad_u64_u32 v[32:33], s[0:1], v32, s2, v[80:81]
	ds_write_b128 v32, v[72:75]
	ds_write_b128 v34, v[76:79] offset:55552
	v_readlane_b32 s0, v251, 22
	v_and_b32_e32 v32, -16, v133
	v_and_b32_e32 v34, 3, v133
	v_or_b32_e32 v33, s0, v195
	v_mul_lo_u32 v33, v33, s3
	v_add3_u32 v78, 0, v33, v32
	v_lshlrev_b32_e32 v33, 1, v195
	v_and_or_b32 v33, v33, 24, v34
	v_mul_u32_u24_e32 v33, 0x90, v33
	v_readlane_b32 s0, v251, 24
	s_waitcnt lgkmcnt(0)
	s_barrier
	v_add3_u32 v79, s0, v32, v33
	v_xor_b32_e32 v32, 32, v222
	v_cmp_lt_i32_e32 vcc, v32, v137
	global_load_dword v80, v185, s[12:13]
	s_nop 0
	v_cndmask_b32_e32 v32, v222, v32, vcc
	v_lshlrev_b32_e32 v76, 2, v32
	s_waitcnt lgkmcnt(0)
	ds_read_b128 v[92:95], v79
	ds_read_b128 v[196:199], v79 offset:64
	ds_read_b128 v[200:203], v79 offset:576
	ds_read_b128 v[204:207], v79 offset:640
	ds_read_b128 v[208:211], v79 offset:4608
	ds_read_b128 v[212:215], v79 offset:4672
	ds_read_b128 v[228:231], v79 offset:5184
	ds_read_b128 v[232:235], v79 offset:5248
	ds_read_b128 v[236:239], v79 offset:9216
	ds_read_b128 v[240:243], v79 offset:9280
	ds_read_b128 v[244:247], v79 offset:9792
	s_waitcnt lgkmcnt(10)
	v_mfma_f32_16x16x32_bf16 v[32:35], v[92:95], v[24:27], 0
	s_mov_b32 s2, 0x3fb8aa3b
	v_add_u32_e32 v77, 0xd800, v78
	s_waitcnt vmcnt(0)
	v_mul_f32_e32 v81, 0x3fb8aa3b, v80
	s_waitcnt lgkmcnt(9)
	v_mfma_f32_16x16x32_bf16 v[72:75], v[196:199], v[28:31], v[32:35]
	ds_read_b128 v[92:95], v79 offset:9856
	ds_read_b128 v[196:199], v79 offset:13824
	s_waitcnt lgkmcnt(10)
	v_mfma_f32_16x16x32_bf16 v[32:35], v[200:203], v[24:27], 0
	s_waitcnt lgkmcnt(9)
	v_mfma_f32_16x16x32_bf16 v[68:71], v[204:207], v[28:31], v[32:35]
	ds_read_b128 v[200:203], v79 offset:13888
	ds_read_b128 v[204:207], v79 offset:14400
	s_waitcnt lgkmcnt(10)
	v_mfma_f32_16x16x32_bf16 v[32:35], v[208:211], v[24:27], 0
	s_waitcnt lgkmcnt(9)
; #define LAS __attribute__((address_space(3)))
; #define LAS __attribute__((address_space(3)))
; __device__ __forceinline__ f32x4 mfma16(bf16x8 a, bf16x8 b, f32x4 c) { return __builtin_amdgcn_mfma_f32_16x16x32_bf16(a, b, c, 0, 0, 0); }
; template <int NKT, int VSTR, bool SINK>
; __device__ __forceinline__ void attn_core(LAS const unsigned char* kb_, LAS const unsigned char* vb_, bf16x8 q0, bf16x8 q1, float sk, unsigned mskbits, int fr, f32x4 (&o)[4]) {
;     ...
; #pragma unroll
;     for (int kt = 0; kt < NKT; ++kt) {
;         const int key = (kt >> 1) * 32 + ((kt & 1) << 2) + krow;
;         LAS const unsigned char* kp = kb_ + key * 144;
;         const bf16x8 a0 = *(LAS const bf16x8*)kp, a1 = *(LAS const bf16x8*)(kp + 64);
;         const float bias = ((mskbits >> (kt >> 2)) & 1u) ? -1e30f : 0.f;
;         f32x4 s = mfma16(a0, q0, (f32x4){bias, bias, bias, bias});
;         s = mfma16(a1, q1, s);
;         S[kt] = s;
;     }
;     float mx = S[0][0];
; #pragma unroll
;     for (int kt = 0; kt < NKT; ++kt) mx = fmaxf(fmaxf(mx, fmaxf(S[kt][0], S[kt][1])), fmaxf(S[kt][2], S[kt][3]));
;     mx = fmaxf(mx, __shfl_xor(mx, 16)); mx = fmaxf(mx, __shfl_xor(mx, 32));
	v_mfma_f32_16x16x32_bf16 v[64:67], v[212:215], v[28:31], v[32:35]
	ds_read_b128 v[208:211], v79 offset:14464
	ds_read_b128 v[212:215], v79 offset:18432
	s_waitcnt lgkmcnt(10)
	v_mfma_f32_16x16x32_bf16 v[32:35], v[228:231], v[24:27], 0
	s_waitcnt lgkmcnt(9)
	v_mfma_f32_16x16x32_bf16 v[60:63], v[232:235], v[28:31], v[32:35]
	ds_read_b128 v[228:231], v79 offset:18496
	ds_read_b128 v[232:235], v79 offset:19008
	s_waitcnt lgkmcnt(10)
	v_mfma_f32_16x16x32_bf16 v[32:35], v[236:239], v[24:27], 0
	s_waitcnt lgkmcnt(9)
	v_mfma_f32_16x16x32_bf16 v[56:59], v[240:243], v[28:31], v[32:35]
	ds_read_b128 v[236:239], v79 offset:19072
	ds_read_b128 v[240:243], v79 offset:23040
	s_waitcnt lgkmcnt(10)
	v_mfma_f32_16x16x32_bf16 v[32:35], v[244:247], v[24:27], 0
	s_waitcnt lgkmcnt(9)
	v_mfma_f32_16x16x32_bf16 v[52:55], v[92:95], v[28:31], v[32:35]
	ds_read_b128 v[244:247], v79 offset:23104
	ds_read_b128 v[92:95], v79 offset:23616
	s_waitcnt lgkmcnt(10)
	v_mfma_f32_16x16x32_bf16 v[32:35], v[196:199], v[24:27], 0
	s_waitcnt lgkmcnt(9)
	v_mfma_f32_16x16x32_bf16 v[48:51], v[200:203], v[28:31], v[32:35]
	ds_read_b128 v[196:199], v79 offset:23680
	s_waitcnt lgkmcnt(9)
	v_mfma_f32_16x16x32_bf16 v[32:35], v[204:207], v[24:27], 0
	s_waitcnt lgkmcnt(8)
	v_mfma_f32_16x16x32_bf16 v[44:47], v[208:211], v[28:31], v[32:35]
	s_waitcnt lgkmcnt(7)
	v_mfma_f32_16x16x32_bf16 v[32:35], v[212:215], v[24:27], 0
	s_waitcnt lgkmcnt(6)
	v_mfma_f32_16x16x32_bf16 v[40:43], v[228:231], v[28:31], v[32:35]
	s_waitcnt lgkmcnt(5)
	v_mfma_f32_16x16x32_bf16 v[32:35], v[232:235], v[24:27], 0
	s_waitcnt lgkmcnt(4)
	v_mfma_f32_16x16x32_bf16 v[36:39], v[236:239], v[28:31], v[32:35]
	s_waitcnt lgkmcnt(3)
	v_mfma_f32_16x16x32_bf16 v[32:35], v[240:243], v[24:27], 0
	s_waitcnt lgkmcnt(2)
	v_mfma_f32_16x16x32_bf16 v[32:35], v[244:247], v[28:31], v[32:35]
	s_waitcnt lgkmcnt(1)
	v_mfma_f32_16x16x32_bf16 v[24:27], v[92:95], v[24:27], 0
	s_waitcnt lgkmcnt(0)
	v_mfma_f32_16x16x32_bf16 v[24:27], v[196:199], v[28:31], v[24:27]
	v_max_f32_e32 v28, v75, v75
	v_max_f32_e32 v29, v74, v74
	v_max_f32_e32 v28, v29, v28
	v_max_f32_e32 v29, v69, v69
	v_max_f32_e32 v30, v68, v68
	v_max_f32_e32 v29, v30, v29
	v_max_f32_e32 v30, v71, v71
	v_max_f32_e32 v31, v70, v70
	v_max3_f32 v28, v72, v73, v28
	v_max_f32_e32 v30, v31, v30
	v_max3_f32 v28, v28, v29, v30
	v_max_f32_e32 v29, v65, v65
	v_max_f32_e32 v30, v64, v64
	v_max_f32_e32 v29, v30, v29
	v_max_f32_e32 v30, v67, v67
	v_max_f32_e32 v31, v66, v66
	v_max_f32_e32 v30, v31, v30
	v_max3_f32 v28, v28, v29, v30
	v_max_f32_e32 v29, v61, v61
	v_max_f32_e32 v30, v60, v60
	v_max_f32_e32 v29, v30, v29
	v_max_f32_e32 v30, v63, v63
	v_max_f32_e32 v31, v62, v62
	v_max_f32_e32 v30, v31, v30
	v_max3_f32 v28, v28, v29, v30
	v_max_f32_e32 v29, v57, v57
	v_max_f32_e32 v30, v56, v56
	v_max_f32_e32 v29, v30, v29
	v_max_f32_e32 v30, v59, v59
	v_max_f32_e32 v31, v58, v58
	v_max_f32_e32 v30, v31, v30
	v_max3_f32 v28, v28, v29, v30
	v_max_f32_e32 v29, v53, v53
	v_max_f32_e32 v30, v52, v52
	v_max_f32_e32 v29, v30, v29
	v_max_f32_e32 v30, v55, v55
	v_max_f32_e32 v31, v54, v54
	v_max_f32_e32 v30, v31, v30
	v_max3_f32 v28, v28, v29, v30
	v_max_f32_e32 v29, v49, v49
	v_max_f32_e32 v30, v48, v48
	v_max_f32_e32 v29, v30, v29
	v_max_f32_e32 v30, v51, v51
	v_max_f32_e32 v31, v50, v50
	v_max_f32_e32 v30, v31, v30
	v_max3_f32 v28, v28, v29, v30
	v_max_f32_e32 v29, v45, v45
	v_max_f32_e32 v30, v44, v44
	v_max_f32_e32 v29, v30, v29
	v_max_f32_e32 v30, v47, v47
	v_max_f32_e32 v31, v46, v46
	v_max_f32_e32 v30, v31, v30
	v_max3_f32 v28, v28, v29, v30
	v_max_f32_e32 v29, v41, v41
	v_max_f32_e32 v30, v40, v40
	v_max_f32_e32 v29, v30, v29
	v_max_f32_e32 v30, v43, v43
	v_max_f32_e32 v31, v42, v42
	v_max_f32_e32 v30, v31, v30
	v_max3_f32 v28, v28, v29, v30
	v_max_f32_e32 v29, v37, v37
	v_max_f32_e32 v30, v36, v36
	v_max_f32_e32 v29, v30, v29
	v_max_f32_e32 v30, v39, v39
	v_max_f32_e32 v31, v38, v38
	v_max_f32_e32 v30, v31, v30
	v_max3_f32 v28, v28, v29, v30
	v_max_f32_e32 v29, v33, v33
	v_max_f32_e32 v30, v32, v32
	v_max_f32_e32 v29, v30, v29
	v_max_f32_e32 v30, v35, v35
	v_max_f32_e32 v31, v34, v34
	v_max_f32_e32 v30, v31, v30
	v_max3_f32 v28, v28, v29, v30
	v_max_f32_e32 v29, v25, v25
	v_max_f32_e32 v30, v24, v24
	v_max_f32_e32 v29, v30, v29
	v_max_f32_e32 v30, v27, v27
	v_max_f32_e32 v31, v26, v26
	v_max_f32_e32 v30, v31, v30
	v_max3_f32 v28, v28, v29, v30
	ds_bpermute_b32 v29, v135, v28
	s_waitcnt lgkmcnt(0)
	v_max_f32_e32 v29, v29, v29
	v_max_f32_e32 v28, v28, v29
	ds_bpermute_b32 v29, v76, v28
	s_waitcnt lgkmcnt(0)
; #define LAS __attribute__((address_space(3)))
; #define LAS __attribute__((address_space(3)))
; __device__ __forceinline__ unsigned pk2(float lo, float hi) { return pg8::cvt_pk_bf16(lo, hi); }
; __device__ __forceinline__ f32x4 mfma16(bf16x8 a, bf16x8 b, f32x4 c) { return __builtin_amdgcn_mfma_f32_16x16x32_bf16(a, b, c, 0, 0, 0); }
; template <int NKT, int VSTR, bool SINK>
; __device__ __forceinline__ void attn_core(LAS const unsigned char* kb_, LAS const unsigned char* vb_, bf16x8 q0, bf16x8 q1, float sk, unsigned mskbits, int fr, f32x4 (&o)[4]) {
;     ...
;     float mx = S[0][0];
; #pragma unroll
;     for (int kt = 0; kt < NKT; ++kt) mx = fmaxf(fmaxf(mx, fmaxf(S[kt][0], S[kt][1])), fmaxf(S[kt][2], S[kt][3]));
;     mx = fmaxf(mx, __shfl_xor(mx, 16)); mx = fmaxf(mx, __shfl_xor(mx, 32));
;     if (SINK) mx = fmaxf(mx, sk);
;     float sum = 0.f;
; #pragma unroll
;     for (int kt = 0; kt < NKT; ++kt)
; #pragma unroll
;         for (int r = 0; r < 4; ++r) { const float p = __builtin_amdgcn_exp2f(S[kt][r] - mx); S[kt][r] = p; sum += p; }
;     sum += __shfl_xor(sum, 16); sum += __shfl_xor(sum, 32);
;     if (SINK) sum += __builtin_amdgcn_exp2f(sk - mx);
;     const float inv = 1.0f / sum;
;     bf16x8 pf[NKT / 2];
; #pragma unroll
;     for (int kb = 0; kb < NKT / 2; ++kb) {
;         v4u w; w.x = pk2(S[2 * kb][0], S[2 * kb][1]); w.y = pk2(S[2 * kb][2], S[2 * kb][3]); w.z = pk2(S[2 * kb + 1][0], S[2 * kb + 1][1]); w.w = pk2(S[2 * kb + 1][2], S[2 * kb + 1][3]);
;         pf[kb] = __builtin_bit_cast(bf16x8, w);
;     }
; #pragma unroll
;     for (int dt = 0; dt < 4; ++dt) {
;         f32x4 acc = (f32x4){0.f, 0.f, 0.f, 0.f};
; #pragma unroll
;         for (int kb = 0; kb < NKT / 2; ++kb) {
;             const bf16x8 vf = *(LAS const bf16x8*)(vb_ + dt * 16 * VSTR + kb * 64);
;             acc = mfma16(vf, pf[kb], acc);
;         }
;         o[dt] = acc * inv;
;     }
	v_max3_f32 v28, v28, v29, v81
	v_sub_f32_e32 v29, v72, v28
	v_exp_f32_e32 v29, v29
	v_sub_f32_e32 v31, v73, v28
	v_exp_f32_e32 v31, v31
	v_sub_f32_e32 v72, v74, v28
	v_exp_f32_e32 v72, v72
	v_sub_f32_e32 v73, v75, v28
	v_exp_f32_e32 v73, v73
	v_sub_f32_e32 v68, v68, v28
	v_add_f32_e32 v30, 0, v29
	v_exp_f32_e32 v68, v68
	v_sub_f32_e32 v69, v69, v28
	v_add_f32_e32 v30, v31, v30
	v_exp_f32_e32 v69, v69
	v_sub_f32_e32 v70, v70, v28
	v_add_f32_e32 v30, v72, v30
	v_exp_f32_e32 v70, v70
	v_sub_f32_e32 v71, v71, v28
	v_add_f32_e32 v30, v73, v30
	v_exp_f32_e32 v71, v71
	v_sub_f32_e32 v64, v64, v28
	v_add_f32_e32 v30, v68, v30
	v_exp_f32_e32 v64, v64
	v_sub_f32_e32 v65, v65, v28
	v_add_f32_e32 v30, v69, v30
	v_exp_f32_e32 v65, v65
	v_sub_f32_e32 v66, v66, v28
	v_add_f32_e32 v30, v70, v30
	v_exp_f32_e32 v66, v66
	v_sub_f32_e32 v67, v67, v28
	v_add_f32_e32 v30, v71, v30
	v_exp_f32_e32 v67, v67
	v_sub_f32_e32 v60, v60, v28
	v_add_f32_e32 v30, v64, v30
	v_exp_f32_e32 v60, v60
	v_sub_f32_e32 v61, v61, v28
	v_add_f32_e32 v30, v65, v30
	v_exp_f32_e32 v61, v61
	v_sub_f32_e32 v62, v62, v28
	v_add_f32_e32 v30, v66, v30
	v_exp_f32_e32 v62, v62
	v_sub_f32_e32 v63, v63, v28
	v_add_f32_e32 v30, v67, v30
	v_exp_f32_e32 v63, v63
	v_sub_f32_e32 v56, v56, v28
	v_add_f32_e32 v30, v60, v30
	v_exp_f32_e32 v56, v56
	v_sub_f32_e32 v57, v57, v28
	v_add_f32_e32 v30, v61, v30
	v_exp_f32_e32 v57, v57
	v_sub_f32_e32 v58, v58, v28
	v_add_f32_e32 v30, v62, v30
	v_exp_f32_e32 v58, v58
	v_sub_f32_e32 v59, v59, v28
	v_add_f32_e32 v30, v63, v30
	v_exp_f32_e32 v59, v59
	v_sub_f32_e32 v52, v52, v28
	v_add_f32_e32 v30, v56, v30
	v_exp_f32_e32 v52, v52
	v_sub_f32_e32 v53, v53, v28
	v_add_f32_e32 v30, v57, v30
	v_exp_f32_e32 v53, v53
	v_sub_f32_e32 v54, v54, v28
	v_add_f32_e32 v30, v58, v30
	v_exp_f32_e32 v54, v54
	v_sub_f32_e32 v55, v55, v28
	v_add_f32_e32 v30, v59, v30
	v_exp_f32_e32 v55, v55
	v_sub_f32_e32 v48, v48, v28
	v_add_f32_e32 v30, v52, v30
	v_exp_f32_e32 v48, v48
	v_sub_f32_e32 v49, v49, v28
	v_add_f32_e32 v30, v53, v30
	v_exp_f32_e32 v49, v49
	v_sub_f32_e32 v50, v50, v28
	v_add_f32_e32 v30, v54, v30
	v_exp_f32_e32 v50, v50
	v_sub_f32_e32 v51, v51, v28
	v_add_f32_e32 v30, v55, v30
	v_exp_f32_e32 v51, v51
	v_sub_f32_e32 v44, v44, v28
	v_add_f32_e32 v30, v48, v30
	v_exp_f32_e32 v74, v44
	v_sub_f32_e32 v44, v45, v28
	v_add_f32_e32 v30, v49, v30
	v_exp_f32_e32 v75, v44
	v_sub_f32_e32 v44, v46, v28
	v_add_f32_e32 v30, v50, v30
	v_exp_f32_e32 v81, v44
	v_sub_f32_e32 v44, v47, v28
	v_add_f32_e32 v30, v51, v30
	v_exp_f32_e32 v82, v44
	v_sub_f32_e32 v40, v40, v28
	v_add_f32_e32 v30, v74, v30
	v_exp_f32_e32 v83, v40
	v_sub_f32_e32 v40, v41, v28
	v_add_f32_e32 v30, v75, v30
	v_exp_f32_e32 v84, v40
	v_sub_f32_e32 v40, v42, v28
	v_add_f32_e32 v30, v81, v30
	v_exp_f32_e32 v85, v40
	v_sub_f32_e32 v40, v43, v28
	v_add_f32_e32 v30, v82, v30
	v_exp_f32_e32 v86, v40
	v_sub_f32_e32 v36, v36, v28
	v_add_f32_e32 v30, v83, v30
	v_exp_f32_e32 v87, v36
	v_sub_f32_e32 v36, v37, v28
	v_add_f32_e32 v30, v84, v30
	v_exp_f32_e32 v88, v36
	v_sub_f32_e32 v36, v38, v28
	v_add_f32_e32 v30, v85, v30
	v_exp_f32_e32 v89, v36
	v_sub_f32_e32 v36, v39, v28
	v_add_f32_e32 v30, v86, v30
	v_exp_f32_e32 v90, v36
	v_sub_f32_e32 v32, v32, v28
	v_add_f32_e32 v30, v87, v30
	v_exp_f32_e32 v91, v32
	v_sub_f32_e32 v32, v33, v28
	v_add_f32_e32 v30, v88, v30
	v_exp_f32_e32 v92, v32
	v_sub_f32_e32 v32, v34, v28
	v_add_f32_e32 v30, v89, v30
	v_exp_f32_e32 v93, v32
	v_sub_f32_e32 v32, v35, v28
	v_add_f32_e32 v30, v90, v30
	v_exp_f32_e32 v94, v32
	v_sub_f32_e32 v24, v24, v28
	v_add_f32_e32 v30, v91, v30
	v_exp_f32_e32 v95, v24
	v_sub_f32_e32 v25, v25, v28
	v_add_f32_e32 v30, v92, v30
	v_exp_f32_e32 v96, v25
	v_sub_f32_e32 v25, v26, v28
	v_add_f32_e32 v30, v93, v30
	v_exp_f32_e32 v97, v25
	v_sub_f32_e32 v25, v27, v28
	v_add_f32_e32 v30, v94, v30
	v_exp_f32_e32 v27, v25
	v_add_f32_e32 v24, v95, v30
	v_add_f32_e32 v24, v96, v24
	v_add_f32_e32 v24, v97, v24
	v_add_f32_e32 v24, v27, v24
	ds_bpermute_b32 v25, v135, v24
	v_cvt_pk_bf16_f32 v44, v29, v31
	v_cvt_pk_bf16_f32 v45, v72, v73
	v_cvt_pk_bf16_f32 v46, v68, v69
	v_cvt_pk_bf16_f32 v47, v70, v71
	s_waitcnt lgkmcnt(0)
	v_add_f32_e32 v24, v24, v25
	ds_bpermute_b32 v25, v76, v24
	v_cvt_pk_bf16_f32 v40, v64, v65
	v_cvt_pk_bf16_f32 v41, v66, v67
	v_cvt_pk_bf16_f32 v42, v60, v61
	v_cvt_pk_bf16_f32 v43, v62, v63
	s_waitcnt lgkmcnt(0)
	v_add_f32_e32 v24, v24, v25
	v_fma_f32 v25, v80, s2, -v28
	v_exp_f32_e32 v25, v25
	v_cvt_pk_bf16_f32 v36, v56, v57
	v_cvt_pk_bf16_f32 v37, v58, v59
	v_cvt_pk_bf16_f32 v38, v52, v53
	v_cvt_pk_bf16_f32 v39, v54, v55
	v_cvt_pk_bf16_f32 v32, v48, v49
	s_nop 0
	v_add_f32_e32 v80, v25, v24
	v_div_scale_f32 v48, s[0:1], v80, v80, 1.0
	v_rcp_f32_e32 v49, v48
	v_cvt_pk_bf16_f32 v33, v50, v51
	v_cvt_pk_bf16_f32 v34, v74, v75
	v_cvt_pk_bf16_f32 v35, v81, v82
	v_cvt_pk_bf16_f32 v28, v83, v84
	v_cvt_pk_bf16_f32 v29, v85, v86
	s_nop 0
	v_fma_f32 v50, -v48, v49, 1.0
	v_fmac_f32_e32 v49, v50, v49
	v_div_scale_f32 v50, vcc, 1.0, v80, 1.0
	v_mul_f32_e32 v51, v50, v49
	v_fma_f32 v52, -v48, v51, v50
	v_fmac_f32_e32 v51, v52, v49
	v_fma_f32 v48, -v48, v51, v50
	v_cvt_pk_bf16_f32 v30, v87, v88
	v_cvt_pk_bf16_f32 v31, v89, v90
	v_cvt_pk_bf16_f32 v24, v91, v92
	v_cvt_pk_bf16_f32 v25, v93, v94
	v_cvt_pk_bf16_f32 v26, v95, v96
	v_cvt_pk_bf16_f32 v27, v97, v27
	v_div_fmas_f32 v48, v48, v49, v51
	s_waitcnt lgkmcnt(0)
	ds_read_b128 v[196:199], v78 offset:55296
	ds_read_b128 v[200:203], v78 offset:55360
	ds_read_b128 v[204:207], v78 offset:61760
	ds_read_b128 v[208:211], v77 offset:12864
	ds_read_b128 v[212:215], v78 offset:55424
	ds_read_b128 v[228:231], v78 offset:55488
	ds_read_b128 v[232:235], v78 offset:55552
	ds_read_b128 v[236:239], v78 offset:55616
	ds_read_b128 v[240:243], v78 offset:61696
	ds_read_b128 v[244:247], v78 offset:61824
	s_waitcnt lgkmcnt(9)
; #define LAS __attribute__((address_space(3)))
; #define LAS __attribute__((address_space(3)))
; template <int NKT, int VSTR, bool SINK>
; __device__ __forceinline__ void attn_core(LAS const unsigned char* kb_, LAS const unsigned char* vb_, bf16x8 q0, bf16x8 q1, float sk, unsigned mskbits, int fr, f32x4 (&o)[4]) {
;     ...
;     for (int kt = 0; kt < NKT; ++kt) {
;         const int key = (kt >> 1) * 32 + ((kt & 1) << 2) + krow;
;         LAS const unsigned char* kp = kb_ + key * 144;
;         const bf16x8 a0 = *(LAS const bf16x8*)kp, a1 = *(LAS const bf16x8*)(kp + 64);
;         const float bias = ((mskbits >> (kt >> 2)) & 1u) ? -1e30f : 0.f;
;         f32x4 s = mfma16(a0, q0, (f32x4){bias, bias, bias, bias});
;         s = mfma16(a1, q1, s);
;         S[kt] = s;
;     }
;     float mx = S[0][0];
; #pragma unroll
;     for (int kt = 0; kt < NKT; ++kt) mx = fmaxf(fmaxf(mx, fmaxf(S[kt][0], S[kt][1])), fmaxf(S[kt][2], S[kt][3]));
;     mx = fmaxf(mx, __shfl_xor(mx, 16)); mx = fmaxf(mx, __shfl_xor(mx, 32));
;     if (SINK) mx = fmaxf(mx, sk);
;     float sum = 0.f;
; #pragma unroll
;     for (int kt = 0; kt < NKT; ++kt)
; #pragma unroll
;         for (int r = 0; r < 4; ++r) { const float p = __builtin_amdgcn_exp2f(S[kt][r] - mx); S[kt][r] = p; sum += p; }
;     sum += __shfl_xor(sum, 16); sum += __shfl_xor(sum, 32);
;     if (SINK) sum += __builtin_amdgcn_exp2f(sk - mx);
;     const float inv = 1.0f / sum;
;     bf16x8 pf[NKT / 2];
; #pragma unroll
;     for (int kb = 0; kb < NKT / 2; ++kb) {
;         v4u w; w.x = pk2(S[2 * kb][0], S[2 * kb][1]); w.y = pk2(S[2 * kb][2], S[2 * kb][3]); w.z = pk2(S[2 * kb + 1][0], S[2 * kb + 1][1]); w.w = pk2(S[2 * kb + 1][2], S[2 * kb + 1][3]);
;         pf[kb] = __builtin_bit_cast(bf16x8, w);
;     }
; #pragma unroll
;     for (int dt = 0; dt < 4; ++dt) {
;         f32x4 acc = (f32x4){0.f, 0.f, 0.f, 0.f};
; #pragma unroll
;         for (int kb = 0; kb < NKT / 2; ++kb) {
;             const bf16x8 vf = *(LAS const bf16x8*)(vb_ + dt * 16 * VSTR + kb * 64);
;             acc = mfma16(vf, pf[kb], acc);
;         }
;         o[dt] = acc * inv;
;     }
; template <bool DO_SWA, bool DO_MEM>
; __device__ __forceinline__ void attn_unit(const Args& a, unsigned char* ws, LAS unsigned char* lds, int l, int tid_in, int lane_in, int wave, int unit) {
;     ...
;                 const float sk = a.in[12][l * 8 + h] * LOG2E;
;                 f32x4 o[4];
	v_mfma_f32_16x16x32_bf16 v[50:53], v[196:199], v[44:47], 0
	ds_read_b128 v[196:199], v78 offset:61888
	v_div_fixup_f32 v48, v48, v80, 1.0
	s_waitcnt lgkmcnt(9)
	v_mfma_f32_16x16x32_bf16 v[50:53], v[200:203], v[40:43], v[50:53]
	ds_read_b128 v[200:203], v78 offset:61952
	s_waitcnt lgkmcnt(7)
	v_mfma_f32_16x16x32_bf16 v[50:53], v[212:215], v[36:39], v[50:53]
	ds_read_b128 v[212:215], v78 offset:62016
	s_waitcnt lgkmcnt(7)
	v_mfma_f32_16x16x32_bf16 v[50:53], v[228:231], v[32:35], v[50:53]
	ds_read_b128 v[228:231], v77 offset:12800
	s_waitcnt lgkmcnt(7)
	v_mfma_f32_16x16x32_bf16 v[50:53], v[232:235], v[28:31], v[50:53]
	ds_read_b128 v[232:235], v77 offset:12928
	s_waitcnt lgkmcnt(7)
	v_mfma_f32_16x16x32_bf16 v[52:55], v[236:239], v[24:27], v[50:53]
	ds_read_b128 v[236:239], v77 offset:12992
	s_nop 7
	v_pk_mul_f32 v[50:51], v[54:55], v[48:49] op_sel_hi:[1,0]
	s_waitcnt lgkmcnt(7)
	v_mfma_f32_16x16x32_bf16 v[54:57], v[240:243], v[44:47], 0
	ds_read_b128 v[240:243], v77 offset:13056
	v_mul_f32_e64 v52, v52, v48
	v_mul_f32_e64 v53, v53, v48
	v_mfma_f32_16x16x32_bf16 v[54:57], v[204:207], v[40:43], v[54:57]
	ds_read_b128 v[204:207], v77 offset:13120
	s_waitcnt lgkmcnt(8)
	v_mfma_f32_16x16x32_bf16 v[54:57], v[244:247], v[36:39], v[54:57]
	ds_read_b128 v[244:247], v77 offset:19200
	s_waitcnt lgkmcnt(8)
	v_mfma_f32_16x16x32_bf16 v[54:57], v[196:199], v[32:35], v[54:57]
	ds_read_b128 v[196:199], v77 offset:19264
	s_waitcnt lgkmcnt(8)
	v_mfma_f32_16x16x32_bf16 v[54:57], v[200:203], v[28:31], v[54:57]
	ds_read_b128 v[200:203], v77 offset:19328
	s_waitcnt lgkmcnt(8)
	v_mfma_f32_16x16x32_bf16 v[56:59], v[212:215], v[24:27], v[54:57]
	s_nop 7
	v_pk_mul_f32 v[54:55], v[58:59], v[48:49] op_sel_hi:[1,0]
	ds_read_b128 v[212:215], v77 offset:19392
	s_waitcnt lgkmcnt(8)
	v_mfma_f32_16x16x32_bf16 v[58:61], v[228:231], v[44:47], 0
	v_mul_f32_e64 v56, v56, v48
	v_mul_f32_e64 v57, v57, v48
	v_mfma_f32_16x16x32_bf16 v[58:61], v[208:211], v[40:43], v[58:61]
	ds_read_b128 v[228:231], v77 offset:19456
	s_waitcnt lgkmcnt(8)
	v_mfma_f32_16x16x32_bf16 v[58:61], v[232:235], v[36:39], v[58:61]
	ds_read_b128 v[208:211], v77 offset:19520
	s_waitcnt lgkmcnt(8)
	v_mfma_f32_16x16x32_bf16 v[58:61], v[236:239], v[32:35], v[58:61]
	s_waitcnt lgkmcnt(7)
	v_mfma_f32_16x16x32_bf16 v[58:61], v[240:243], v[28:31], v[58:61]
	s_waitcnt lgkmcnt(6)
	v_mfma_f32_16x16x32_bf16 v[60:63], v[204:207], v[24:27], v[58:61]
	s_nop 7
	v_pk_mul_f32 v[58:59], v[48:49], v[62:63] op_sel_hi:[0,1]
	s_waitcnt lgkmcnt(5)
	v_mfma_f32_16x16x32_bf16 v[44:47], v[244:247], v[44:47], 0
	v_pk_mul_f32 v[60:61], v[48:49], v[60:61] op_sel_hi:[0,1]
	s_waitcnt lgkmcnt(4)
	v_mfma_f32_16x16x32_bf16 v[40:43], v[196:199], v[40:43], v[44:47]
	s_waitcnt lgkmcnt(3)
	v_mfma_f32_16x16x32_bf16 v[36:39], v[200:203], v[36:39], v[40:43]
	s_waitcnt lgkmcnt(2)
	v_mfma_f32_16x16x32_bf16 v[32:35], v[212:215], v[32:35], v[36:39]
	s_waitcnt lgkmcnt(1)
	v_mfma_f32_16x16x32_bf16 v[28:31], v[228:231], v[28:31], v[32:35]
	v_cvt_pk_bf16_f32 v69, v52, v53
	v_cvt_pk_bf16_f32 v68, v50, v51
	s_waitcnt lgkmcnt(0)
	v_mfma_f32_16x16x32_bf16 v[24:27], v[208:211], v[24:27], v[28:31]
	s_nop 2
	v_mul_f32_e32 v28, v53, v53
	v_mul_f32_e32 v29, v51, v51
	v_fmac_f32_e32 v28, v52, v52
	v_fmac_f32_e32 v29, v50, v50
	v_add_f32_e32 v28, v28, v29
	v_mul_f32_e32 v29, v57, v57
	v_mul_f32_e32 v30, v55, v55
	v_fmac_f32_e32 v29, v56, v56
	v_fmac_f32_e32 v30, v54, v54
	v_add_f32_e32 v29, v29, v30
	v_add_f32_e32 v28, v28, v29
	v_mul_f32_e32 v29, v61, v61
	v_mul_f32_e32 v30, v59, v59
	v_fmac_f32_e32 v29, v60, v60
	v_fmac_f32_e32 v30, v58, v58
	v_pk_mul_f32 v[26:27], v[48:49], v[26:27] op_sel_hi:[0,1]
	v_pk_mul_f32 v[24:25], v[48:49], v[24:25] op_sel_hi:[0,1]
	v_add_f32_e32 v29, v29, v30
	v_add_f32_e32 v28, v29, v28
	v_mul_f32_e32 v29, v25, v25
	v_mul_f32_e32 v30, v27, v27
	v_fmac_f32_e32 v29, v24, v24
	v_fmac_f32_e32 v30, v26, v26
	v_add_f32_e32 v29, v29, v30
	v_cvt_pk_bf16_f32 v71, v56, v57
	v_cvt_pk_bf16_f32 v70, v54, v55
	v_cvt_pk_bf16_f32 v73, v60, v61
	v_cvt_pk_bf16_f32 v72, v58, v59
	v_add_f32_e32 v80, v28, v29
	v_cvt_pk_bf16_f32 v75, v24, v25
	v_cvt_pk_bf16_f32 v74, v26, v27
	global_load_dword v81, v185, s[12:13] offset:4
	s_waitcnt lgkmcnt(0)
	ds_read_b128 v[92:95], v79
	ds_read_b128 v[196:199], v79 offset:64
	ds_read_b128 v[200:203], v79 offset:576
	ds_read_b128 v[204:207], v79 offset:640
	ds_read_b128 v[208:211], v79 offset:4608
	ds_read_b128 v[212:215], v79 offset:4672
	ds_read_b128 v[228:231], v79 offset:5184
	ds_read_b128 v[232:235], v79 offset:5248
	ds_read_b128 v[236:239], v79 offset:9216
	ds_read_b128 v[240:243], v79 offset:9280
	ds_read_b128 v[244:247], v79 offset:9792
	s_waitcnt lgkmcnt(10)
	v_mfma_f32_16x16x32_bf16 v[24:27], v[92:95], v[20:23], 0
	s_waitcnt vmcnt(0)
	v_mul_f32_e32 v90, 0x3fb8aa3b, v81
	s_waitcnt lgkmcnt(9)
	v_mfma_f32_16x16x32_bf16 v[64:67], v[196:199], v[16:19], v[24:27]
	ds_read_b128 v[92:95], v79 offset:9856
	ds_read_b128 v[196:199], v79 offset:13824
	s_waitcnt lgkmcnt(10)
	v_mfma_f32_16x16x32_bf16 v[24:27], v[200:203], v[20:23], 0
	s_waitcnt lgkmcnt(9)
	v_mfma_f32_16x16x32_bf16 v[60:63], v[204:207], v[16:19], v[24:27]
	ds_read_b128 v[200:203], v79 offset:13888
	ds_read_b128 v[204:207], v79 offset:14400
	s_waitcnt lgkmcnt(10)
	v_mfma_f32_16x16x32_bf16 v[24:27], v[208:211], v[20:23], 0
	s_waitcnt lgkmcnt(9)
	v_mfma_f32_16x16x32_bf16 v[56:59], v[212:215], v[16:19], v[24:27]
	ds_read_b128 v[208:211], v79 offset:14464
	ds_read_b128 v[212:215], v79 offset:18432
	s_waitcnt lgkmcnt(10)
	v_mfma_f32_16x16x32_bf16 v[24:27], v[228:231], v[20:23], 0
	s_waitcnt lgkmcnt(9)
; #define LAS __attribute__((address_space(3)))
; #define LAS __attribute__((address_space(3)))
; __device__ __forceinline__ f32x4 mfma16(bf16x8 a, bf16x8 b, f32x4 c) { return __builtin_amdgcn_mfma_f32_16x16x32_bf16(a, b, c, 0, 0, 0); }
; template <int NKT, int VSTR, bool SINK>
; __device__ __forceinline__ void attn_core(LAS const unsigned char* kb_, LAS const unsigned char* vb_, bf16x8 q0, bf16x8 q1, float sk, unsigned mskbits, int fr, f32x4 (&o)[4]) {
;     ...
;     for (int kt = 0; kt < NKT; ++kt) {
;         const int key = (kt >> 1) * 32 + ((kt & 1) << 2) + krow;
;         LAS const unsigned char* kp = kb_ + key * 144;
;         const bf16x8 a0 = *(LAS const bf16x8*)kp, a1 = *(LAS const bf16x8*)(kp + 64);
;         const float bias = ((mskbits >> (kt >> 2)) & 1u) ? -1e30f : 0.f;
;         f32x4 s = mfma16(a0, q0, (f32x4){bias, bias, bias, bias});
;         s = mfma16(a1, q1, s);
;         S[kt] = s;
;     }
;     float mx = S[0][0];
; #pragma unroll
;     for (int kt = 0; kt < NKT; ++kt) mx = fmaxf(fmaxf(mx, fmaxf(S[kt][0], S[kt][1])), fmaxf(S[kt][2], S[kt][3]));
;     mx = fmaxf(mx, __shfl_xor(mx, 16)); mx = fmaxf(mx, __shfl_xor(mx, 32));
	v_mfma_f32_16x16x32_bf16 v[52:55], v[232:235], v[16:19], v[24:27]
	ds_read_b128 v[228:231], v79 offset:18496
	ds_read_b128 v[232:235], v79 offset:19008
	s_waitcnt lgkmcnt(10)
	v_mfma_f32_16x16x32_bf16 v[24:27], v[236:239], v[20:23], 0
	s_waitcnt lgkmcnt(9)
	v_mfma_f32_16x16x32_bf16 v[48:51], v[240:243], v[16:19], v[24:27]
	ds_read_b128 v[236:239], v79 offset:19072
	ds_read_b128 v[240:243], v79 offset:23040
	s_waitcnt lgkmcnt(10)
	v_mfma_f32_16x16x32_bf16 v[24:27], v[244:247], v[20:23], 0
	s_waitcnt lgkmcnt(9)
	v_mfma_f32_16x16x32_bf16 v[44:47], v[92:95], v[16:19], v[24:27]
	ds_read_b128 v[244:247], v79 offset:23104
	ds_read_b128 v[92:95], v79 offset:23616
	s_waitcnt lgkmcnt(10)
	v_mfma_f32_16x16x32_bf16 v[24:27], v[196:199], v[20:23], 0
	s_waitcnt lgkmcnt(9)
	v_mfma_f32_16x16x32_bf16 v[40:43], v[200:203], v[16:19], v[24:27]
	ds_read_b128 v[196:199], v79 offset:23680
	s_waitcnt lgkmcnt(9)
	v_mfma_f32_16x16x32_bf16 v[24:27], v[204:207], v[20:23], 0
	s_waitcnt lgkmcnt(8)
	v_mfma_f32_16x16x32_bf16 v[36:39], v[208:211], v[16:19], v[24:27]
	s_waitcnt lgkmcnt(7)
	v_mfma_f32_16x16x32_bf16 v[24:27], v[212:215], v[20:23], 0
	s_waitcnt lgkmcnt(6)
	v_mfma_f32_16x16x32_bf16 v[32:35], v[228:231], v[16:19], v[24:27]
	s_waitcnt lgkmcnt(5)
	v_mfma_f32_16x16x32_bf16 v[24:27], v[232:235], v[20:23], 0
	s_waitcnt lgkmcnt(4)
	v_mfma_f32_16x16x32_bf16 v[28:31], v[236:239], v[16:19], v[24:27]
	s_waitcnt lgkmcnt(3)
	v_mfma_f32_16x16x32_bf16 v[24:27], v[240:243], v[20:23], 0
	s_waitcnt lgkmcnt(2)
	v_mfma_f32_16x16x32_bf16 v[24:27], v[244:247], v[16:19], v[24:27]
	s_waitcnt lgkmcnt(1)
	v_mfma_f32_16x16x32_bf16 v[20:23], v[92:95], v[20:23], 0
	s_waitcnt lgkmcnt(0)
	v_mfma_f32_16x16x32_bf16 v[16:19], v[196:199], v[16:19], v[20:23]
	s_nop 5
	v_max_f32_e32 v20, v67, v67
	v_max_f32_e32 v21, v66, v66
	v_max_f32_e32 v20, v21, v20
	v_max_f32_e32 v21, v61, v61
	v_max_f32_e32 v22, v60, v60
	v_max_f32_e32 v21, v22, v21
	v_max_f32_e32 v22, v63, v63
	v_max_f32_e32 v23, v62, v62
	v_max3_f32 v20, v64, v65, v20
	v_max_f32_e32 v22, v23, v22
	v_max3_f32 v20, v20, v21, v22
	v_max_f32_e32 v21, v57, v57
	v_max_f32_e32 v22, v56, v56
	v_max_f32_e32 v21, v22, v21
	v_max_f32_e32 v22, v59, v59
	v_max_f32_e32 v23, v58, v58
	v_max_f32_e32 v22, v23, v22
	v_max3_f32 v20, v20, v21, v22
	v_max_f32_e32 v21, v53, v53
	v_max_f32_e32 v22, v52, v52
	v_max_f32_e32 v21, v22, v21
	v_max_f32_e32 v22, v55, v55
	v_max_f32_e32 v23, v54, v54
	v_max_f32_e32 v22, v23, v22
	v_max3_f32 v20, v20, v21, v22
	v_max_f32_e32 v21, v49, v49
	v_max_f32_e32 v22, v48, v48
	v_max_f32_e32 v21, v22, v21
	v_max_f32_e32 v22, v51, v51
	v_max_f32_e32 v23, v50, v50
	v_max_f32_e32 v22, v23, v22
	v_max3_f32 v20, v20, v21, v22
	v_max_f32_e32 v21, v45, v45
	v_max_f32_e32 v22, v44, v44
	v_max_f32_e32 v21, v22, v21
	v_max_f32_e32 v22, v47, v47
	v_max_f32_e32 v23, v46, v46
	v_max_f32_e32 v22, v23, v22
	v_max3_f32 v20, v20, v21, v22
	v_max_f32_e32 v21, v41, v41
	v_max_f32_e32 v22, v40, v40
	v_max_f32_e32 v21, v22, v21
	v_max_f32_e32 v22, v43, v43
	v_max_f32_e32 v23, v42, v42
	v_max_f32_e32 v22, v23, v22
	v_max3_f32 v20, v20, v21, v22
	v_max_f32_e32 v21, v37, v37
	v_max_f32_e32 v22, v36, v36
	v_max_f32_e32 v21, v22, v21
	v_max_f32_e32 v22, v39, v39
	v_max_f32_e32 v23, v38, v38
	v_max_f32_e32 v22, v23, v22
	v_max3_f32 v20, v20, v21, v22
	v_max_f32_e32 v21, v33, v33
	v_max_f32_e32 v22, v32, v32
	v_max_f32_e32 v21, v22, v21
	v_max_f32_e32 v22, v35, v35
	v_max_f32_e32 v23, v34, v34
	v_max_f32_e32 v22, v23, v22
	v_max3_f32 v20, v20, v21, v22
	v_max_f32_e32 v21, v29, v29
	v_max_f32_e32 v22, v28, v28
	v_max_f32_e32 v21, v22, v21
	v_max_f32_e32 v22, v31, v31
	v_max_f32_e32 v23, v30, v30
	v_max_f32_e32 v22, v23, v22
	v_max3_f32 v20, v20, v21, v22
	v_max_f32_e32 v21, v25, v25
	v_max_f32_e32 v22, v24, v24
	v_max_f32_e32 v21, v22, v21
	v_max_f32_e32 v22, v27, v27
	v_max_f32_e32 v23, v26, v26
	v_max_f32_e32 v22, v23, v22
	v_max3_f32 v20, v20, v21, v22
	v_max_f32_e32 v21, v17, v17
	v_max_f32_e32 v22, v16, v16
	v_max_f32_e32 v21, v22, v21
	v_max_f32_e32 v22, v19, v19
	v_max_f32_e32 v23, v18, v18
	v_max_f32_e32 v22, v23, v22
	v_max3_f32 v20, v20, v21, v22
	ds_bpermute_b32 v21, v135, v20
	s_waitcnt lgkmcnt(0)
	v_max_f32_e32 v21, v21, v21
	v_max_f32_e32 v20, v20, v21
	ds_bpermute_b32 v21, v76, v20
	s_waitcnt lgkmcnt(0)
; #define LAS __attribute__((address_space(3)))
; #define LAS __attribute__((address_space(3)))
; __device__ __forceinline__ unsigned pk2(float lo, float hi) { return pg8::cvt_pk_bf16(lo, hi); }
; __device__ __forceinline__ f32x4 mfma16(bf16x8 a, bf16x8 b, f32x4 c) { return __builtin_amdgcn_mfma_f32_16x16x32_bf16(a, b, c, 0, 0, 0); }
; template <int NKT, int VSTR, bool SINK>
; __device__ __forceinline__ void attn_core(LAS const unsigned char* kb_, LAS const unsigned char* vb_, bf16x8 q0, bf16x8 q1, float sk, unsigned mskbits, int fr, f32x4 (&o)[4]) {
;     ...
;     mx = fmaxf(mx, __shfl_xor(mx, 16)); mx = fmaxf(mx, __shfl_xor(mx, 32));
;     if (SINK) mx = fmaxf(mx, sk);
;     float sum = 0.f;
; #pragma unroll
;     for (int kt = 0; kt < NKT; ++kt)
; #pragma unroll
;         for (int r = 0; r < 4; ++r) { const float p = __builtin_amdgcn_exp2f(S[kt][r] - mx); S[kt][r] = p; sum += p; }
;     sum += __shfl_xor(sum, 16); sum += __shfl_xor(sum, 32);
;     if (SINK) sum += __builtin_amdgcn_exp2f(sk - mx);
;     const float inv = 1.0f / sum;
;     bf16x8 pf[NKT / 2];
; #pragma unroll
;     for (int kb = 0; kb < NKT / 2; ++kb) {
;         v4u w; w.x = pk2(S[2 * kb][0], S[2 * kb][1]); w.y = pk2(S[2 * kb][2], S[2 * kb][3]); w.z = pk2(S[2 * kb + 1][0], S[2 * kb + 1][1]); w.w = pk2(S[2 * kb + 1][2], S[2 * kb + 1][3]);
;         pf[kb] = __builtin_bit_cast(bf16x8, w);
;     }
; #pragma unroll
;     for (int dt = 0; dt < 4; ++dt) {
;         f32x4 acc = (f32x4){0.f, 0.f, 0.f, 0.f};
; #pragma unroll
;         for (int kb = 0; kb < NKT / 2; ++kb) {
;             const bf16x8 vf = *(LAS const bf16x8*)(vb_ + dt * 16 * VSTR + kb * 64);
;             acc = mfma16(vf, pf[kb], acc);
;         }
;         o[dt] = acc * inv;
;     }
	v_max3_f32 v20, v20, v21, v90
	v_sub_f32_e32 v21, v64, v20
	v_exp_f32_e32 v21, v21
	v_sub_f32_e32 v23, v65, v20
	v_exp_f32_e32 v23, v23
	v_sub_f32_e32 v64, v66, v20
	v_exp_f32_e32 v64, v64
	v_sub_f32_e32 v65, v67, v20
	v_exp_f32_e32 v65, v65
	v_sub_f32_e32 v60, v60, v20
	v_add_f32_e32 v22, 0, v21
	v_exp_f32_e32 v60, v60
	v_sub_f32_e32 v61, v61, v20
	v_add_f32_e32 v22, v23, v22
	v_exp_f32_e32 v61, v61
	v_sub_f32_e32 v62, v62, v20
	v_add_f32_e32 v22, v64, v22
	v_exp_f32_e32 v62, v62
	v_sub_f32_e32 v63, v63, v20
	v_add_f32_e32 v22, v65, v22
	v_exp_f32_e32 v63, v63
	v_sub_f32_e32 v56, v56, v20
	v_add_f32_e32 v22, v60, v22
	v_exp_f32_e32 v56, v56
	v_sub_f32_e32 v57, v57, v20
	v_add_f32_e32 v22, v61, v22
	v_exp_f32_e32 v57, v57
	v_sub_f32_e32 v58, v58, v20
	v_add_f32_e32 v22, v62, v22
	v_exp_f32_e32 v58, v58
	v_sub_f32_e32 v59, v59, v20
	v_add_f32_e32 v22, v63, v22
	v_exp_f32_e32 v59, v59
	v_sub_f32_e32 v52, v52, v20
	v_add_f32_e32 v22, v56, v22
	v_exp_f32_e32 v52, v52
	v_sub_f32_e32 v53, v53, v20
	v_add_f32_e32 v22, v57, v22
	v_exp_f32_e32 v53, v53
	v_sub_f32_e32 v54, v54, v20
	v_add_f32_e32 v22, v58, v22
	v_exp_f32_e32 v54, v54
	v_sub_f32_e32 v55, v55, v20
	v_add_f32_e32 v22, v59, v22
	v_exp_f32_e32 v55, v55
	v_sub_f32_e32 v48, v48, v20
	v_add_f32_e32 v22, v52, v22
	v_exp_f32_e32 v48, v48
	v_sub_f32_e32 v49, v49, v20
	v_add_f32_e32 v22, v53, v22
	v_exp_f32_e32 v49, v49
	v_sub_f32_e32 v50, v50, v20
	v_add_f32_e32 v22, v54, v22
	v_exp_f32_e32 v50, v50
	v_sub_f32_e32 v51, v51, v20
	v_add_f32_e32 v22, v55, v22
	v_exp_f32_e32 v51, v51
	v_sub_f32_e32 v44, v44, v20
	v_add_f32_e32 v22, v48, v22
	v_exp_f32_e32 v44, v44
	v_sub_f32_e32 v45, v45, v20
	v_add_f32_e32 v22, v49, v22
	v_exp_f32_e32 v45, v45
	v_sub_f32_e32 v46, v46, v20
	v_add_f32_e32 v22, v50, v22
	v_exp_f32_e32 v46, v46
	v_sub_f32_e32 v47, v47, v20
	v_add_f32_e32 v22, v51, v22
	v_exp_f32_e32 v47, v47
	v_sub_f32_e32 v40, v40, v20
	v_add_f32_e32 v22, v44, v22
	v_exp_f32_e32 v40, v40
	v_sub_f32_e32 v41, v41, v20
	v_add_f32_e32 v22, v45, v22
	v_exp_f32_e32 v41, v41
	v_sub_f32_e32 v42, v42, v20
	v_add_f32_e32 v22, v46, v22
	v_exp_f32_e32 v42, v42
	v_sub_f32_e32 v43, v43, v20
	v_add_f32_e32 v22, v47, v22
	v_exp_f32_e32 v43, v43
	v_sub_f32_e32 v36, v36, v20
	v_add_f32_e32 v22, v40, v22
	v_exp_f32_e32 v66, v36
	v_sub_f32_e32 v36, v37, v20
	v_add_f32_e32 v22, v41, v22
	v_exp_f32_e32 v67, v36
	v_sub_f32_e32 v36, v38, v20
	v_add_f32_e32 v22, v42, v22
	v_exp_f32_e32 v82, v36
	v_sub_f32_e32 v36, v39, v20
	v_add_f32_e32 v22, v43, v22
	v_exp_f32_e32 v83, v36
	v_sub_f32_e32 v32, v32, v20
	v_add_f32_e32 v22, v66, v22
	v_exp_f32_e32 v84, v32
	v_sub_f32_e32 v32, v33, v20
	v_add_f32_e32 v22, v67, v22
	v_exp_f32_e32 v85, v32
	v_sub_f32_e32 v32, v34, v20
	v_add_f32_e32 v22, v82, v22
	v_exp_f32_e32 v86, v32
	v_sub_f32_e32 v32, v35, v20
	v_add_f32_e32 v22, v83, v22
	v_exp_f32_e32 v87, v32
	v_sub_f32_e32 v28, v28, v20
	v_add_f32_e32 v22, v84, v22
	v_exp_f32_e32 v88, v28
	v_sub_f32_e32 v28, v29, v20
	v_add_f32_e32 v22, v85, v22
	v_exp_f32_e32 v89, v28
	v_sub_f32_e32 v28, v30, v20
	v_add_f32_e32 v22, v86, v22
	v_exp_f32_e32 v90, v28
	v_sub_f32_e32 v28, v31, v20
	v_add_f32_e32 v22, v87, v22
	v_exp_f32_e32 v91, v28
	v_sub_f32_e32 v24, v24, v20
	v_add_f32_e32 v22, v88, v22
	v_exp_f32_e32 v92, v24
	v_sub_f32_e32 v24, v25, v20
	v_add_f32_e32 v22, v89, v22
	v_exp_f32_e32 v93, v24
	v_sub_f32_e32 v24, v26, v20
	v_add_f32_e32 v22, v90, v22
	v_exp_f32_e32 v94, v24
	v_sub_f32_e32 v24, v27, v20
	v_add_f32_e32 v22, v91, v22
	v_exp_f32_e32 v95, v24
	v_sub_f32_e32 v16, v16, v20
	v_add_f32_e32 v22, v92, v22
	v_exp_f32_e32 v96, v16
	v_sub_f32_e32 v17, v17, v20
	v_add_f32_e32 v22, v93, v22
	v_exp_f32_e32 v97, v17
	v_sub_f32_e32 v17, v18, v20
	v_add_f32_e32 v22, v94, v22
	v_exp_f32_e32 v98, v17
	v_sub_f32_e32 v17, v19, v20
	v_add_f32_e32 v22, v95, v22
	v_exp_f32_e32 v19, v17
	v_add_f32_e32 v16, v96, v22
	v_add_f32_e32 v16, v97, v16
	v_add_f32_e32 v16, v98, v16
	v_add_f32_e32 v16, v19, v16
	ds_bpermute_b32 v17, v135, v16
	v_cvt_pk_bf16_f32 v36, v21, v23
	v_cvt_pk_bf16_f32 v37, v64, v65
	v_cvt_pk_bf16_f32 v38, v60, v61
	v_cvt_pk_bf16_f32 v39, v62, v63
	s_waitcnt lgkmcnt(0)
	v_add_f32_e32 v16, v16, v17
	ds_bpermute_b32 v17, v76, v16
	v_cvt_pk_bf16_f32 v32, v56, v57
	v_cvt_pk_bf16_f32 v33, v58, v59
	v_cvt_pk_bf16_f32 v34, v52, v53
	v_cvt_pk_bf16_f32 v35, v54, v55
	s_waitcnt lgkmcnt(0)
	v_add_f32_e32 v16, v16, v17
	v_fma_f32 v17, v81, s2, -v20
	v_exp_f32_e32 v17, v17
	v_cvt_pk_bf16_f32 v28, v48, v49
	v_cvt_pk_bf16_f32 v29, v50, v51
	v_cvt_pk_bf16_f32 v30, v44, v45
	v_cvt_pk_bf16_f32 v31, v46, v47
	v_cvt_pk_bf16_f32 v24, v40, v41
	s_nop 0
	v_add_f32_e32 v81, v17, v16
	v_div_scale_f32 v40, s[0:1], v81, v81, 1.0
	v_rcp_f32_e32 v41, v40
	v_cvt_pk_bf16_f32 v25, v42, v43
	v_cvt_pk_bf16_f32 v26, v66, v67
	v_cvt_pk_bf16_f32 v27, v82, v83
	v_cvt_pk_bf16_f32 v20, v84, v85
	v_cvt_pk_bf16_f32 v21, v86, v87
	s_nop 0
	v_fma_f32 v42, -v40, v41, 1.0
	v_fmac_f32_e32 v41, v42, v41
	v_div_scale_f32 v42, vcc, 1.0, v81, 1.0
	v_mul_f32_e32 v43, v42, v41
	v_fma_f32 v44, -v40, v43, v42
	v_fmac_f32_e32 v43, v44, v41
	v_fma_f32 v40, -v40, v43, v42
	v_cvt_pk_bf16_f32 v22, v88, v89
	v_cvt_pk_bf16_f32 v23, v90, v91
	v_cvt_pk_bf16_f32 v16, v92, v93
	v_cvt_pk_bf16_f32 v17, v94, v95
	v_cvt_pk_bf16_f32 v18, v96, v97
	v_cvt_pk_bf16_f32 v19, v98, v19
	v_div_fmas_f32 v40, v40, v41, v43
	s_waitcnt lgkmcnt(0)
	ds_read_b128 v[196:199], v78 offset:55296
	ds_read_b128 v[200:203], v78 offset:55360
	ds_read_b128 v[204:207], v78 offset:61760
	ds_read_b128 v[208:211], v77 offset:12864
	ds_read_b128 v[212:215], v78 offset:55424
	ds_read_b128 v[228:231], v78 offset:55488
	ds_read_b128 v[232:235], v78 offset:55552
	ds_read_b128 v[236:239], v78 offset:55616
	ds_read_b128 v[240:243], v78 offset:61696
	ds_read_b128 v[244:247], v78 offset:61824
	s_waitcnt lgkmcnt(9)
; #define LAS __attribute__((address_space(3)))
; #define LAS __attribute__((address_space(3)))
; template <int NKT, int VSTR, bool SINK>
; __device__ __forceinline__ void attn_core(LAS const unsigned char* kb_, LAS const unsigned char* vb_, bf16x8 q0, bf16x8 q1, float sk, unsigned mskbits, int fr, f32x4 (&o)[4]) {
;     ...
;     for (int kt = 0; kt < NKT; ++kt) {
;         const int key = (kt >> 1) * 32 + ((kt & 1) << 2) + krow;
;         LAS const unsigned char* kp = kb_ + key * 144;
;         const bf16x8 a0 = *(LAS const bf16x8*)kp, a1 = *(LAS const bf16x8*)(kp + 64);
;         const float bias = ((mskbits >> (kt >> 2)) & 1u) ? -1e30f : 0.f;
;         f32x4 s = mfma16(a0, q0, (f32x4){bias, bias, bias, bias});
;         s = mfma16(a1, q1, s);
;         S[kt] = s;
;     }
;     float mx = S[0][0];
; #pragma unroll
;     for (int kt = 0; kt < NKT; ++kt) mx = fmaxf(fmaxf(mx, fmaxf(S[kt][0], S[kt][1])), fmaxf(S[kt][2], S[kt][3]));
;     mx = fmaxf(mx, __shfl_xor(mx, 16)); mx = fmaxf(mx, __shfl_xor(mx, 32));
;     if (SINK) mx = fmaxf(mx, sk);
;     float sum = 0.f;
; #pragma unroll
;     for (int kt = 0; kt < NKT; ++kt)
; #pragma unroll
;         for (int r = 0; r < 4; ++r) { const float p = __builtin_amdgcn_exp2f(S[kt][r] - mx); S[kt][r] = p; sum += p; }
;     sum += __shfl_xor(sum, 16); sum += __shfl_xor(sum, 32);
;     if (SINK) sum += __builtin_amdgcn_exp2f(sk - mx);
;     const float inv = 1.0f / sum;
;     bf16x8 pf[NKT / 2];
; #pragma unroll
;     for (int kb = 0; kb < NKT / 2; ++kb) {
;         v4u w; w.x = pk2(S[2 * kb][0], S[2 * kb][1]); w.y = pk2(S[2 * kb][2], S[2 * kb][3]); w.z = pk2(S[2 * kb + 1][0], S[2 * kb + 1][1]); w.w = pk2(S[2 * kb + 1][2], S[2 * kb + 1][3]);
;         pf[kb] = __builtin_bit_cast(bf16x8, w);
;     }
; #pragma unroll
;     for (int dt = 0; dt < 4; ++dt) {
;         f32x4 acc = (f32x4){0.f, 0.f, 0.f, 0.f};
; #pragma unroll
;         for (int kb = 0; kb < NKT / 2; ++kb) {
;             const bf16x8 vf = *(LAS const bf16x8*)(vb_ + dt * 16 * VSTR + kb * 64);
;             acc = mfma16(vf, pf[kb], acc);
;         }
;         o[dt] = acc * inv;
;     }
; template <bool DO_SWA, bool DO_MEM>
; __device__ __forceinline__ void attn_unit(const Args& a, unsigned char* ws, LAS unsigned char* lds, int l, int tid_in, int lane_in, int wave, int unit) {
;     ...
;                 const float sk = a.in[12][l * 8 + h] * LOG2E;
;                 f32x4 o[4];
	v_mfma_f32_16x16x32_bf16 v[42:45], v[196:199], v[36:39], 0
	ds_read_b128 v[196:199], v78 offset:61888
	v_div_fixup_f32 v40, v40, v81, 1.0
	s_waitcnt lgkmcnt(9)
	v_mfma_f32_16x16x32_bf16 v[42:45], v[200:203], v[32:35], v[42:45]
	ds_read_b128 v[200:203], v78 offset:61952
	s_waitcnt lgkmcnt(7)
	v_mfma_f32_16x16x32_bf16 v[42:45], v[212:215], v[28:31], v[42:45]
	ds_read_b128 v[212:215], v78 offset:62016
	s_waitcnt lgkmcnt(7)
	v_mfma_f32_16x16x32_bf16 v[42:45], v[228:231], v[24:27], v[42:45]
	ds_read_b128 v[228:231], v77 offset:12800
	s_waitcnt lgkmcnt(7)
	v_mfma_f32_16x16x32_bf16 v[42:45], v[232:235], v[20:23], v[42:45]
	ds_read_b128 v[232:235], v77 offset:12928
	s_waitcnt lgkmcnt(7)
	v_mfma_f32_16x16x32_bf16 v[44:47], v[236:239], v[16:19], v[42:45]
	ds_read_b128 v[236:239], v77 offset:12992
	s_nop 7
	v_pk_mul_f32 v[42:43], v[46:47], v[40:41] op_sel_hi:[1,0]
	s_waitcnt lgkmcnt(7)
	v_mfma_f32_16x16x32_bf16 v[46:49], v[240:243], v[36:39], 0
	ds_read_b128 v[240:243], v77 offset:13056
	v_mul_f32_e64 v44, v44, v40
	v_mul_f32_e64 v45, v45, v40
	v_mfma_f32_16x16x32_bf16 v[46:49], v[204:207], v[32:35], v[46:49]
	ds_read_b128 v[204:207], v77 offset:13120
	s_waitcnt lgkmcnt(8)
	v_mfma_f32_16x16x32_bf16 v[46:49], v[244:247], v[28:31], v[46:49]
	ds_read_b128 v[244:247], v77 offset:19200
	s_waitcnt lgkmcnt(8)
	v_mfma_f32_16x16x32_bf16 v[46:49], v[196:199], v[24:27], v[46:49]
	ds_read_b128 v[196:199], v77 offset:19264
	s_waitcnt lgkmcnt(8)
	v_mfma_f32_16x16x32_bf16 v[46:49], v[200:203], v[20:23], v[46:49]
	ds_read_b128 v[200:203], v77 offset:19328
	s_waitcnt lgkmcnt(8)
	v_mfma_f32_16x16x32_bf16 v[48:51], v[212:215], v[16:19], v[46:49]
	s_nop 7
	v_pk_mul_f32 v[46:47], v[50:51], v[40:41] op_sel_hi:[1,0]
	ds_read_b128 v[212:215], v77 offset:19392
	s_waitcnt lgkmcnt(8)
	v_mfma_f32_16x16x32_bf16 v[50:53], v[228:231], v[36:39], 0
	v_mul_f32_e64 v48, v48, v40
	v_mul_f32_e64 v49, v49, v40
	v_mfma_f32_16x16x32_bf16 v[50:53], v[208:211], v[32:35], v[50:53]
	ds_read_b128 v[228:231], v77 offset:19456
	s_waitcnt lgkmcnt(8)
	v_mfma_f32_16x16x32_bf16 v[50:53], v[232:235], v[28:31], v[50:53]
	ds_read_b128 v[208:211], v77 offset:19520
	s_waitcnt lgkmcnt(8)
	v_mfma_f32_16x16x32_bf16 v[50:53], v[236:239], v[24:27], v[50:53]
	s_waitcnt lgkmcnt(7)
	v_mfma_f32_16x16x32_bf16 v[50:53], v[240:243], v[20:23], v[50:53]
	s_waitcnt lgkmcnt(6)
	v_mfma_f32_16x16x32_bf16 v[52:55], v[204:207], v[16:19], v[50:53]
	s_nop 7
	v_pk_mul_f32 v[50:51], v[40:41], v[54:55] op_sel_hi:[0,1]
	s_waitcnt lgkmcnt(5)
	v_mfma_f32_16x16x32_bf16 v[36:39], v[244:247], v[36:39], 0
	v_pk_mul_f32 v[52:53], v[40:41], v[52:53] op_sel_hi:[0,1]
	s_waitcnt lgkmcnt(4)
	v_mfma_f32_16x16x32_bf16 v[32:35], v[196:199], v[32:35], v[36:39]
	s_waitcnt lgkmcnt(3)
	v_mfma_f32_16x16x32_bf16 v[28:31], v[200:203], v[28:31], v[32:35]
	s_waitcnt lgkmcnt(2)
	v_mfma_f32_16x16x32_bf16 v[24:27], v[212:215], v[24:27], v[28:31]
	s_waitcnt lgkmcnt(1)
	v_mfma_f32_16x16x32_bf16 v[20:23], v[228:231], v[20:23], v[24:27]
	v_cvt_pk_bf16_f32 v61, v44, v45
	v_cvt_pk_bf16_f32 v60, v42, v43
	s_waitcnt lgkmcnt(0)
	v_mfma_f32_16x16x32_bf16 v[16:19], v[208:211], v[16:19], v[20:23]
	s_nop 2
	v_mul_f32_e32 v20, v45, v45
	v_mul_f32_e32 v21, v43, v43
	v_fmac_f32_e32 v20, v44, v44
	v_fmac_f32_e32 v21, v42, v42
	v_add_f32_e32 v20, v20, v21
	v_mul_f32_e32 v21, v49, v49
	v_mul_f32_e32 v22, v47, v47
	v_fmac_f32_e32 v21, v48, v48
	v_fmac_f32_e32 v22, v46, v46
	v_add_f32_e32 v20, v80, v20
	v_add_f32_e32 v21, v21, v22
	v_add_f32_e32 v20, v21, v20
	v_mul_f32_e32 v21, v53, v53
	v_mul_f32_e32 v22, v51, v51
	v_fmac_f32_e32 v21, v52, v52
	v_fmac_f32_e32 v22, v50, v50
	v_pk_mul_f32 v[18:19], v[40:41], v[18:19] op_sel_hi:[0,1]
	v_pk_mul_f32 v[16:17], v[40:41], v[16:17] op_sel_hi:[0,1]
	v_add_f32_e32 v21, v21, v22
	v_add_f32_e32 v20, v21, v20
	v_mul_f32_e32 v21, v17, v17
	v_mul_f32_e32 v22, v19, v19
	v_fmac_f32_e32 v21, v16, v16
	v_fmac_f32_e32 v22, v18, v18
	v_add_f32_e32 v21, v21, v22
	v_cvt_pk_bf16_f32 v63, v48, v49
	v_cvt_pk_bf16_f32 v62, v46, v47
	v_cvt_pk_bf16_f32 v65, v52, v53
	v_cvt_pk_bf16_f32 v64, v50, v51
	v_add_f32_e32 v80, v20, v21
	v_cvt_pk_bf16_f32 v67, v16, v17
	v_cvt_pk_bf16_f32 v66, v18, v19
	global_load_dword v81, v185, s[12:13] offset:8
	s_waitcnt lgkmcnt(0)
	ds_read_b128 v[92:95], v79
	ds_read_b128 v[196:199], v79 offset:64
	ds_read_b128 v[200:203], v79 offset:576
	ds_read_b128 v[204:207], v79 offset:640
	ds_read_b128 v[208:211], v79 offset:4608
	ds_read_b128 v[212:215], v79 offset:4672
	ds_read_b128 v[228:231], v79 offset:5184
	ds_read_b128 v[232:235], v79 offset:5248
	ds_read_b128 v[236:239], v79 offset:9216
	ds_read_b128 v[240:243], v79 offset:9280
	ds_read_b128 v[244:247], v79 offset:9792
	s_waitcnt lgkmcnt(10)
	v_mfma_f32_16x16x32_bf16 v[16:19], v[92:95], v[12:15], 0
	s_waitcnt vmcnt(0)
	v_mul_f32_e32 v90, 0x3fb8aa3b, v81
	s_waitcnt lgkmcnt(9)
	v_mfma_f32_16x16x32_bf16 v[56:59], v[196:199], v[8:11], v[16:19]
	ds_read_b128 v[92:95], v79 offset:9856
	ds_read_b128 v[196:199], v79 offset:13824
	s_waitcnt lgkmcnt(10)
	v_mfma_f32_16x16x32_bf16 v[16:19], v[200:203], v[12:15], 0
	s_waitcnt lgkmcnt(9)
	v_mfma_f32_16x16x32_bf16 v[52:55], v[204:207], v[8:11], v[16:19]
	ds_read_b128 v[200:203], v79 offset:13888
	ds_read_b128 v[204:207], v79 offset:14400
	s_waitcnt lgkmcnt(10)
	v_mfma_f32_16x16x32_bf16 v[16:19], v[208:211], v[12:15], 0
	s_waitcnt lgkmcnt(9)
	v_mfma_f32_16x16x32_bf16 v[48:51], v[212:215], v[8:11], v[16:19]
	ds_read_b128 v[208:211], v79 offset:14464
	ds_read_b128 v[212:215], v79 offset:18432
	s_waitcnt lgkmcnt(10)
	v_mfma_f32_16x16x32_bf16 v[16:19], v[228:231], v[12:15], 0
	s_waitcnt lgkmcnt(9)
; #define LAS __attribute__((address_space(3)))
; #define LAS __attribute__((address_space(3)))
; __device__ __forceinline__ f32x4 mfma16(bf16x8 a, bf16x8 b, f32x4 c) { return __builtin_amdgcn_mfma_f32_16x16x32_bf16(a, b, c, 0, 0, 0); }
; template <int NKT, int VSTR, bool SINK>
; __device__ __forceinline__ void attn_core(LAS const unsigned char* kb_, LAS const unsigned char* vb_, bf16x8 q0, bf16x8 q1, float sk, unsigned mskbits, int fr, f32x4 (&o)[4]) {
;     ...
;     for (int kt = 0; kt < NKT; ++kt) {
;         const int key = (kt >> 1) * 32 + ((kt & 1) << 2) + krow;
;         LAS const unsigned char* kp = kb_ + key * 144;
;         const bf16x8 a0 = *(LAS const bf16x8*)kp, a1 = *(LAS const bf16x8*)(kp + 64);
;         const float bias = ((mskbits >> (kt >> 2)) & 1u) ? -1e30f : 0.f;
;         f32x4 s = mfma16(a0, q0, (f32x4){bias, bias, bias, bias});
;         s = mfma16(a1, q1, s);
;         S[kt] = s;
;     }
;     float mx = S[0][0];
; #pragma unroll
;     for (int kt = 0; kt < NKT; ++kt) mx = fmaxf(fmaxf(mx, fmaxf(S[kt][0], S[kt][1])), fmaxf(S[kt][2], S[kt][3]));
;     mx = fmaxf(mx, __shfl_xor(mx, 16)); mx = fmaxf(mx, __shfl_xor(mx, 32));
	v_mfma_f32_16x16x32_bf16 v[44:47], v[232:235], v[8:11], v[16:19]
	ds_read_b128 v[228:231], v79 offset:18496
	ds_read_b128 v[232:235], v79 offset:19008
	s_waitcnt lgkmcnt(10)
	v_mfma_f32_16x16x32_bf16 v[16:19], v[236:239], v[12:15], 0
	s_waitcnt lgkmcnt(9)
	v_mfma_f32_16x16x32_bf16 v[40:43], v[240:243], v[8:11], v[16:19]
	ds_read_b128 v[236:239], v79 offset:19072
	ds_read_b128 v[240:243], v79 offset:23040
	s_waitcnt lgkmcnt(10)
	v_mfma_f32_16x16x32_bf16 v[16:19], v[244:247], v[12:15], 0
	s_waitcnt lgkmcnt(9)
	v_mfma_f32_16x16x32_bf16 v[36:39], v[92:95], v[8:11], v[16:19]
	ds_read_b128 v[244:247], v79 offset:23104
	ds_read_b128 v[92:95], v79 offset:23616
	s_waitcnt lgkmcnt(10)
	v_mfma_f32_16x16x32_bf16 v[16:19], v[196:199], v[12:15], 0
	s_waitcnt lgkmcnt(9)
	v_mfma_f32_16x16x32_bf16 v[32:35], v[200:203], v[8:11], v[16:19]
	ds_read_b128 v[196:199], v79 offset:23680
	s_waitcnt lgkmcnt(9)
	v_mfma_f32_16x16x32_bf16 v[16:19], v[204:207], v[12:15], 0
	s_waitcnt lgkmcnt(8)
	v_mfma_f32_16x16x32_bf16 v[28:31], v[208:211], v[8:11], v[16:19]
	s_waitcnt lgkmcnt(7)
	v_mfma_f32_16x16x32_bf16 v[16:19], v[212:215], v[12:15], 0
	s_waitcnt lgkmcnt(6)
	v_mfma_f32_16x16x32_bf16 v[24:27], v[228:231], v[8:11], v[16:19]
	s_waitcnt lgkmcnt(5)
	v_mfma_f32_16x16x32_bf16 v[16:19], v[232:235], v[12:15], 0
	s_waitcnt lgkmcnt(4)
	v_mfma_f32_16x16x32_bf16 v[20:23], v[236:239], v[8:11], v[16:19]
	s_waitcnt lgkmcnt(3)
	v_mfma_f32_16x16x32_bf16 v[16:19], v[240:243], v[12:15], 0
	s_waitcnt lgkmcnt(2)
	v_mfma_f32_16x16x32_bf16 v[16:19], v[244:247], v[8:11], v[16:19]
	s_waitcnt lgkmcnt(1)
	v_mfma_f32_16x16x32_bf16 v[12:15], v[92:95], v[12:15], 0
	s_waitcnt lgkmcnt(0)
	v_mfma_f32_16x16x32_bf16 v[8:11], v[196:199], v[8:11], v[12:15]
	s_nop 5
	v_max_f32_e32 v12, v59, v59
	v_max_f32_e32 v13, v58, v58
	v_max_f32_e32 v12, v13, v12
	v_max_f32_e32 v13, v53, v53
	v_max_f32_e32 v14, v52, v52
	v_max_f32_e32 v13, v14, v13
	v_max_f32_e32 v14, v55, v55
	v_max_f32_e32 v15, v54, v54
	v_max3_f32 v12, v56, v57, v12
	v_max_f32_e32 v14, v15, v14
	v_max3_f32 v12, v12, v13, v14
	v_max_f32_e32 v13, v49, v49
	v_max_f32_e32 v14, v48, v48
	v_max_f32_e32 v13, v14, v13
	v_max_f32_e32 v14, v51, v51
	v_max_f32_e32 v15, v50, v50
	v_max_f32_e32 v14, v15, v14
	v_max3_f32 v12, v12, v13, v14
	v_max_f32_e32 v13, v45, v45
	v_max_f32_e32 v14, v44, v44
	v_max_f32_e32 v13, v14, v13
	v_max_f32_e32 v14, v47, v47
	v_max_f32_e32 v15, v46, v46
	v_max_f32_e32 v14, v15, v14
	v_max3_f32 v12, v12, v13, v14
	v_max_f32_e32 v13, v41, v41
	v_max_f32_e32 v14, v40, v40
	v_max_f32_e32 v13, v14, v13
	v_max_f32_e32 v14, v43, v43
	v_max_f32_e32 v15, v42, v42
	v_max_f32_e32 v14, v15, v14
	v_max3_f32 v12, v12, v13, v14
	v_max_f32_e32 v13, v37, v37
	v_max_f32_e32 v14, v36, v36
	v_max_f32_e32 v13, v14, v13
	v_max_f32_e32 v14, v39, v39
	v_max_f32_e32 v15, v38, v38
	v_max_f32_e32 v14, v15, v14
	v_max3_f32 v12, v12, v13, v14
	v_max_f32_e32 v13, v33, v33
	v_max_f32_e32 v14, v32, v32
	v_max_f32_e32 v13, v14, v13
	v_max_f32_e32 v14, v35, v35
	v_max_f32_e32 v15, v34, v34
	v_max_f32_e32 v14, v15, v14
	v_max3_f32 v12, v12, v13, v14
	v_max_f32_e32 v13, v29, v29
	v_max_f32_e32 v14, v28, v28
	v_max_f32_e32 v13, v14, v13
	v_max_f32_e32 v14, v31, v31
	v_max_f32_e32 v15, v30, v30
	v_max_f32_e32 v14, v15, v14
	v_max3_f32 v12, v12, v13, v14
	v_max_f32_e32 v13, v25, v25
	v_max_f32_e32 v14, v24, v24
	v_max_f32_e32 v13, v14, v13
	v_max_f32_e32 v14, v27, v27
	v_max_f32_e32 v15, v26, v26
	v_max_f32_e32 v14, v15, v14
	v_max3_f32 v12, v12, v13, v14
	v_max_f32_e32 v13, v21, v21
	v_max_f32_e32 v14, v20, v20
	v_max_f32_e32 v13, v14, v13
	v_max_f32_e32 v14, v23, v23
	v_max_f32_e32 v15, v22, v22
	v_max_f32_e32 v14, v15, v14
	v_max3_f32 v12, v12, v13, v14
	v_max_f32_e32 v13, v17, v17
	v_max_f32_e32 v14, v16, v16
	v_max_f32_e32 v13, v14, v13
	v_max_f32_e32 v14, v19, v19
	v_max_f32_e32 v15, v18, v18
	v_max_f32_e32 v14, v15, v14
	v_max3_f32 v12, v12, v13, v14
	v_max_f32_e32 v13, v9, v9
	v_max_f32_e32 v14, v8, v8
	v_max_f32_e32 v13, v14, v13
	v_max_f32_e32 v14, v11, v11
	v_max_f32_e32 v15, v10, v10
	v_max_f32_e32 v14, v15, v14
	v_max3_f32 v12, v12, v13, v14
	ds_bpermute_b32 v13, v135, v12
	s_waitcnt lgkmcnt(0)
	v_max_f32_e32 v13, v13, v13
	v_max_f32_e32 v12, v12, v13
	ds_bpermute_b32 v13, v76, v12
	s_waitcnt lgkmcnt(0)
; #define LAS __attribute__((address_space(3)))
; #define LAS __attribute__((address_space(3)))
; __device__ __forceinline__ unsigned pk2(float lo, float hi) { return pg8::cvt_pk_bf16(lo, hi); }
; __device__ __forceinline__ f32x4 mfma16(bf16x8 a, bf16x8 b, f32x4 c) { return __builtin_amdgcn_mfma_f32_16x16x32_bf16(a, b, c, 0, 0, 0); }
; template <int NKT, int VSTR, bool SINK>
; __device__ __forceinline__ void attn_core(LAS const unsigned char* kb_, LAS const unsigned char* vb_, bf16x8 q0, bf16x8 q1, float sk, unsigned mskbits, int fr, f32x4 (&o)[4]) {
;     ...
;     mx = fmaxf(mx, __shfl_xor(mx, 16)); mx = fmaxf(mx, __shfl_xor(mx, 32));
;     if (SINK) mx = fmaxf(mx, sk);
;     float sum = 0.f;
; #pragma unroll
;     for (int kt = 0; kt < NKT; ++kt)
; #pragma unroll
;         for (int r = 0; r < 4; ++r) { const float p = __builtin_amdgcn_exp2f(S[kt][r] - mx); S[kt][r] = p; sum += p; }
;     sum += __shfl_xor(sum, 16); sum += __shfl_xor(sum, 32);
;     if (SINK) sum += __builtin_amdgcn_exp2f(sk - mx);
;     const float inv = 1.0f / sum;
;     bf16x8 pf[NKT / 2];
; #pragma unroll
;     for (int kb = 0; kb < NKT / 2; ++kb) {
;         v4u w; w.x = pk2(S[2 * kb][0], S[2 * kb][1]); w.y = pk2(S[2 * kb][2], S[2 * kb][3]); w.z = pk2(S[2 * kb + 1][0], S[2 * kb + 1][1]); w.w = pk2(S[2 * kb + 1][2], S[2 * kb + 1][3]);
;         pf[kb] = __builtin_bit_cast(bf16x8, w);
;     }
; #pragma unroll
;     for (int dt = 0; dt < 4; ++dt) {
;         f32x4 acc = (f32x4){0.f, 0.f, 0.f, 0.f};
; #pragma unroll
;         for (int kb = 0; kb < NKT / 2; ++kb) {
;             const bf16x8 vf = *(LAS const bf16x8*)(vb_ + dt * 16 * VSTR + kb * 64);
;             acc = mfma16(vf, pf[kb], acc);
;         }
;         o[dt] = acc * inv;
;     }
	v_max3_f32 v12, v12, v13, v90
	v_sub_f32_e32 v13, v56, v12
	v_exp_f32_e32 v13, v13
	v_sub_f32_e32 v15, v57, v12
	v_exp_f32_e32 v15, v15
	v_sub_f32_e32 v56, v58, v12
	v_exp_f32_e32 v56, v56
	v_sub_f32_e32 v57, v59, v12
	v_exp_f32_e32 v57, v57
	v_sub_f32_e32 v52, v52, v12
	v_add_f32_e32 v14, 0, v13
	v_exp_f32_e32 v52, v52
	v_sub_f32_e32 v53, v53, v12
	v_add_f32_e32 v14, v15, v14
	v_exp_f32_e32 v53, v53
	v_sub_f32_e32 v54, v54, v12
	v_add_f32_e32 v14, v56, v14
	v_exp_f32_e32 v54, v54
	v_sub_f32_e32 v55, v55, v12
	v_add_f32_e32 v14, v57, v14
	v_exp_f32_e32 v55, v55
	v_sub_f32_e32 v48, v48, v12
	v_add_f32_e32 v14, v52, v14
	v_exp_f32_e32 v48, v48
	v_sub_f32_e32 v49, v49, v12
	v_add_f32_e32 v14, v53, v14
	v_exp_f32_e32 v49, v49
	v_sub_f32_e32 v50, v50, v12
	v_add_f32_e32 v14, v54, v14
	v_exp_f32_e32 v50, v50
	v_sub_f32_e32 v51, v51, v12
	v_add_f32_e32 v14, v55, v14
	v_exp_f32_e32 v51, v51
	v_sub_f32_e32 v44, v44, v12
	v_add_f32_e32 v14, v48, v14
	v_exp_f32_e32 v44, v44
	v_sub_f32_e32 v45, v45, v12
	v_add_f32_e32 v14, v49, v14
	v_exp_f32_e32 v45, v45
	v_sub_f32_e32 v46, v46, v12
	v_add_f32_e32 v14, v50, v14
	v_exp_f32_e32 v46, v46
	v_sub_f32_e32 v47, v47, v12
	v_add_f32_e32 v14, v51, v14
	v_exp_f32_e32 v47, v47
	v_sub_f32_e32 v40, v40, v12
	v_add_f32_e32 v14, v44, v14
	v_exp_f32_e32 v40, v40
	v_sub_f32_e32 v41, v41, v12
	v_add_f32_e32 v14, v45, v14
	v_exp_f32_e32 v41, v41
	v_sub_f32_e32 v42, v42, v12
	v_add_f32_e32 v14, v46, v14
	v_exp_f32_e32 v42, v42
	v_sub_f32_e32 v43, v43, v12
	v_add_f32_e32 v14, v47, v14
	v_exp_f32_e32 v43, v43
	v_sub_f32_e32 v36, v36, v12
	v_add_f32_e32 v14, v40, v14
	v_exp_f32_e32 v36, v36
	v_sub_f32_e32 v37, v37, v12
	v_add_f32_e32 v14, v41, v14
	v_exp_f32_e32 v37, v37
	v_sub_f32_e32 v38, v38, v12
	v_add_f32_e32 v14, v42, v14
	v_exp_f32_e32 v38, v38
	v_sub_f32_e32 v39, v39, v12
	v_add_f32_e32 v14, v43, v14
	v_exp_f32_e32 v39, v39
	v_sub_f32_e32 v32, v32, v12
	v_add_f32_e32 v14, v36, v14
	v_exp_f32_e32 v32, v32
	v_sub_f32_e32 v33, v33, v12
	v_add_f32_e32 v14, v37, v14
	v_exp_f32_e32 v33, v33
	v_sub_f32_e32 v34, v34, v12
	v_add_f32_e32 v14, v38, v14
	v_exp_f32_e32 v34, v34
	v_sub_f32_e32 v35, v35, v12
	v_add_f32_e32 v14, v39, v14
	v_exp_f32_e32 v35, v35
	v_sub_f32_e32 v28, v28, v12
	v_add_f32_e32 v14, v32, v14
	v_exp_f32_e32 v58, v28
	v_sub_f32_e32 v28, v29, v12
	v_add_f32_e32 v14, v33, v14
	v_exp_f32_e32 v59, v28
	v_sub_f32_e32 v28, v30, v12
	v_add_f32_e32 v14, v34, v14
	v_exp_f32_e32 v82, v28
	v_sub_f32_e32 v28, v31, v12
	v_add_f32_e32 v14, v35, v14
	v_exp_f32_e32 v83, v28
	v_sub_f32_e32 v24, v24, v12
	v_add_f32_e32 v14, v58, v14
	v_exp_f32_e32 v84, v24
	v_sub_f32_e32 v24, v25, v12
	v_add_f32_e32 v14, v59, v14
	v_exp_f32_e32 v85, v24
	v_sub_f32_e32 v24, v26, v12
	v_add_f32_e32 v14, v82, v14
	v_exp_f32_e32 v86, v24
	v_sub_f32_e32 v24, v27, v12
	v_add_f32_e32 v14, v83, v14
	v_exp_f32_e32 v87, v24
	v_sub_f32_e32 v20, v20, v12
	v_add_f32_e32 v14, v84, v14
	v_exp_f32_e32 v88, v20
	v_sub_f32_e32 v20, v21, v12
	v_add_f32_e32 v14, v85, v14
	v_exp_f32_e32 v89, v20
	v_sub_f32_e32 v20, v22, v12
	v_add_f32_e32 v14, v86, v14
	v_exp_f32_e32 v90, v20
	v_sub_f32_e32 v20, v23, v12
	v_add_f32_e32 v14, v87, v14
	v_exp_f32_e32 v91, v20
	v_sub_f32_e32 v16, v16, v12
	v_add_f32_e32 v14, v88, v14
	v_exp_f32_e32 v92, v16
	v_sub_f32_e32 v16, v17, v12
	v_add_f32_e32 v14, v89, v14
	v_exp_f32_e32 v93, v16
	v_sub_f32_e32 v16, v18, v12
	v_add_f32_e32 v14, v90, v14
	v_exp_f32_e32 v94, v16
	v_sub_f32_e32 v16, v19, v12
	v_add_f32_e32 v14, v91, v14
	v_exp_f32_e32 v95, v16
	v_sub_f32_e32 v8, v8, v12
	v_add_f32_e32 v14, v92, v14
	v_exp_f32_e32 v96, v8
	v_sub_f32_e32 v9, v9, v12
	v_add_f32_e32 v14, v93, v14
	v_exp_f32_e32 v97, v9
	v_sub_f32_e32 v9, v10, v12
	v_add_f32_e32 v14, v94, v14
	v_exp_f32_e32 v98, v9
	v_sub_f32_e32 v9, v11, v12
	v_add_f32_e32 v14, v95, v14
	v_exp_f32_e32 v11, v9
	v_add_f32_e32 v8, v96, v14
	v_add_f32_e32 v8, v97, v8
	v_add_f32_e32 v8, v98, v8
	v_add_f32_e32 v8, v11, v8
	ds_bpermute_b32 v9, v135, v8
	v_cvt_pk_bf16_f32 v28, v13, v15
	v_cvt_pk_bf16_f32 v29, v56, v57
	v_cvt_pk_bf16_f32 v30, v52, v53
	v_cvt_pk_bf16_f32 v31, v54, v55
	s_waitcnt lgkmcnt(0)
	v_add_f32_e32 v8, v8, v9
	ds_bpermute_b32 v9, v76, v8
	v_cvt_pk_bf16_f32 v24, v48, v49
	v_cvt_pk_bf16_f32 v25, v50, v51
	v_cvt_pk_bf16_f32 v26, v44, v45
	v_cvt_pk_bf16_f32 v27, v46, v47
	s_waitcnt lgkmcnt(0)
	v_add_f32_e32 v8, v8, v9
	v_fma_f32 v9, v81, s2, -v12
	v_exp_f32_e32 v9, v9
	v_cvt_pk_bf16_f32 v20, v40, v41
	v_cvt_pk_bf16_f32 v21, v42, v43
	v_cvt_pk_bf16_f32 v22, v36, v37
	v_cvt_pk_bf16_f32 v23, v38, v39
	v_cvt_pk_bf16_f32 v16, v32, v33
	s_nop 0
	v_add_f32_e32 v81, v9, v8
	v_div_scale_f32 v32, s[0:1], v81, v81, 1.0
	v_rcp_f32_e32 v33, v32
	v_cvt_pk_bf16_f32 v17, v34, v35
	v_cvt_pk_bf16_f32 v18, v58, v59
	v_cvt_pk_bf16_f32 v19, v82, v83
	v_cvt_pk_bf16_f32 v12, v84, v85
	v_cvt_pk_bf16_f32 v13, v86, v87
	s_nop 0
	v_fma_f32 v34, -v32, v33, 1.0
	v_fmac_f32_e32 v33, v34, v33
	v_div_scale_f32 v34, vcc, 1.0, v81, 1.0
	v_mul_f32_e32 v35, v34, v33
	v_fma_f32 v36, -v32, v35, v34
	v_fmac_f32_e32 v35, v36, v33
	v_fma_f32 v32, -v32, v35, v34
	v_cvt_pk_bf16_f32 v14, v88, v89
	v_cvt_pk_bf16_f32 v15, v90, v91
	v_cvt_pk_bf16_f32 v8, v92, v93
	v_cvt_pk_bf16_f32 v9, v94, v95
	v_cvt_pk_bf16_f32 v10, v96, v97
	v_cvt_pk_bf16_f32 v11, v98, v11
	v_div_fmas_f32 v32, v32, v33, v35
	s_waitcnt lgkmcnt(0)
	ds_read_b128 v[196:199], v78 offset:55296
	ds_read_b128 v[200:203], v78 offset:55360
	ds_read_b128 v[204:207], v78 offset:61760
	ds_read_b128 v[208:211], v77 offset:12864
	ds_read_b128 v[212:215], v78 offset:55424
	ds_read_b128 v[228:231], v78 offset:55488
	ds_read_b128 v[232:235], v78 offset:55552
	ds_read_b128 v[236:239], v78 offset:55616
	ds_read_b128 v[240:243], v78 offset:61696
	ds_read_b128 v[244:247], v78 offset:61824
	s_waitcnt lgkmcnt(9)
; #define LAS __attribute__((address_space(3)))
; #define LAS __attribute__((address_space(3)))
; template <int NKT, int VSTR, bool SINK>
; __device__ __forceinline__ void attn_core(LAS const unsigned char* kb_, LAS const unsigned char* vb_, bf16x8 q0, bf16x8 q1, float sk, unsigned mskbits, int fr, f32x4 (&o)[4]) {
;     ...
;     for (int kt = 0; kt < NKT; ++kt) {
;         const int key = (kt >> 1) * 32 + ((kt & 1) << 2) + krow;
;         LAS const unsigned char* kp = kb_ + key * 144;
;         const bf16x8 a0 = *(LAS const bf16x8*)kp, a1 = *(LAS const bf16x8*)(kp + 64);
;         const float bias = ((mskbits >> (kt >> 2)) & 1u) ? -1e30f : 0.f;
;         f32x4 s = mfma16(a0, q0, (f32x4){bias, bias, bias, bias});
;         s = mfma16(a1, q1, s);
;         S[kt] = s;
;     }
;     float mx = S[0][0];
; #pragma unroll
;     for (int kt = 0; kt < NKT; ++kt) mx = fmaxf(fmaxf(mx, fmaxf(S[kt][0], S[kt][1])), fmaxf(S[kt][2], S[kt][3]));
;     mx = fmaxf(mx, __shfl_xor(mx, 16)); mx = fmaxf(mx, __shfl_xor(mx, 32));
;     if (SINK) mx = fmaxf(mx, sk);
;     float sum = 0.f;
; #pragma unroll
;     for (int kt = 0; kt < NKT; ++kt)
; #pragma unroll
;         for (int r = 0; r < 4; ++r) { const float p = __builtin_amdgcn_exp2f(S[kt][r] - mx); S[kt][r] = p; sum += p; }
;     sum += __shfl_xor(sum, 16); sum += __shfl_xor(sum, 32);
;     if (SINK) sum += __builtin_amdgcn_exp2f(sk - mx);
;     const float inv = 1.0f / sum;
;     bf16x8 pf[NKT / 2];
; #pragma unroll
;     for (int kb = 0; kb < NKT / 2; ++kb) {
;         v4u w; w.x = pk2(S[2 * kb][0], S[2 * kb][1]); w.y = pk2(S[2 * kb][2], S[2 * kb][3]); w.z = pk2(S[2 * kb + 1][0], S[2 * kb + 1][1]); w.w = pk2(S[2 * kb + 1][2], S[2 * kb + 1][3]);
;         pf[kb] = __builtin_bit_cast(bf16x8, w);
;     }
; #pragma unroll
;     for (int dt = 0; dt < 4; ++dt) {
;         f32x4 acc = (f32x4){0.f, 0.f, 0.f, 0.f};
; #pragma unroll
;         for (int kb = 0; kb < NKT / 2; ++kb) {
;             const bf16x8 vf = *(LAS const bf16x8*)(vb_ + dt * 16 * VSTR + kb * 64);
;             acc = mfma16(vf, pf[kb], acc);
;         }
;         o[dt] = acc * inv;
;     }
; template <bool DO_SWA, bool DO_MEM>
; __device__ __forceinline__ void attn_unit(const Args& a, unsigned char* ws, LAS unsigned char* lds, int l, int tid_in, int lane_in, int wave, int unit) {
;     ...
;                 const float sk = a.in[12][l * 8 + h] * LOG2E;
;                 f32x4 o[4];
	v_mfma_f32_16x16x32_bf16 v[34:37], v[196:199], v[28:31], 0
	ds_read_b128 v[196:199], v78 offset:61888
	v_div_fixup_f32 v32, v32, v81, 1.0
	s_waitcnt lgkmcnt(9)
	v_mfma_f32_16x16x32_bf16 v[34:37], v[200:203], v[24:27], v[34:37]
	ds_read_b128 v[200:203], v78 offset:61952
	s_waitcnt lgkmcnt(7)
	v_mfma_f32_16x16x32_bf16 v[34:37], v[212:215], v[20:23], v[34:37]
	ds_read_b128 v[212:215], v78 offset:62016
	s_waitcnt lgkmcnt(7)
	v_mfma_f32_16x16x32_bf16 v[34:37], v[228:231], v[16:19], v[34:37]
	ds_read_b128 v[228:231], v77 offset:12800
	s_waitcnt lgkmcnt(7)
	v_mfma_f32_16x16x32_bf16 v[34:37], v[232:235], v[12:15], v[34:37]
	ds_read_b128 v[232:235], v77 offset:12928
	s_waitcnt lgkmcnt(7)
	v_mfma_f32_16x16x32_bf16 v[36:39], v[236:239], v[8:11], v[34:37]
	ds_read_b128 v[236:239], v77 offset:12992
	s_nop 7
	v_pk_mul_f32 v[34:35], v[38:39], v[32:33] op_sel_hi:[1,0]
	s_waitcnt lgkmcnt(7)
	v_mfma_f32_16x16x32_bf16 v[38:41], v[240:243], v[28:31], 0
	ds_read_b128 v[240:243], v77 offset:13056
	v_mul_f32_e64 v36, v36, v32
	v_mul_f32_e64 v37, v37, v32
	v_mfma_f32_16x16x32_bf16 v[38:41], v[204:207], v[24:27], v[38:41]
	ds_read_b128 v[204:207], v77 offset:13120
	s_waitcnt lgkmcnt(8)
	v_mfma_f32_16x16x32_bf16 v[38:41], v[244:247], v[20:23], v[38:41]
	ds_read_b128 v[244:247], v77 offset:19200
	s_waitcnt lgkmcnt(8)
	v_mfma_f32_16x16x32_bf16 v[38:41], v[196:199], v[16:19], v[38:41]
	ds_read_b128 v[196:199], v77 offset:19264
	s_waitcnt lgkmcnt(8)
	v_mfma_f32_16x16x32_bf16 v[38:41], v[200:203], v[12:15], v[38:41]
	ds_read_b128 v[200:203], v77 offset:19328
	s_waitcnt lgkmcnt(8)
	v_mfma_f32_16x16x32_bf16 v[40:43], v[212:215], v[8:11], v[38:41]
	s_nop 7
	v_pk_mul_f32 v[38:39], v[42:43], v[32:33] op_sel_hi:[1,0]
	ds_read_b128 v[212:215], v77 offset:19392
	s_waitcnt lgkmcnt(8)
	v_mfma_f32_16x16x32_bf16 v[42:45], v[228:231], v[28:31], 0
	v_mul_f32_e64 v40, v40, v32
	v_mul_f32_e64 v41, v41, v32
	v_mfma_f32_16x16x32_bf16 v[42:45], v[208:211], v[24:27], v[42:45]
	ds_read_b128 v[228:231], v77 offset:19456
	s_waitcnt lgkmcnt(8)
	v_mfma_f32_16x16x32_bf16 v[42:45], v[232:235], v[20:23], v[42:45]
	ds_read_b128 v[208:211], v77 offset:19520
	s_waitcnt lgkmcnt(8)
	v_mfma_f32_16x16x32_bf16 v[42:45], v[236:239], v[16:19], v[42:45]
	s_waitcnt lgkmcnt(7)
	v_mfma_f32_16x16x32_bf16 v[42:45], v[240:243], v[12:15], v[42:45]
	s_waitcnt lgkmcnt(6)
	v_mfma_f32_16x16x32_bf16 v[44:47], v[204:207], v[8:11], v[42:45]
	s_nop 7
	v_pk_mul_f32 v[42:43], v[32:33], v[46:47] op_sel_hi:[0,1]
	s_waitcnt lgkmcnt(5)
	v_mfma_f32_16x16x32_bf16 v[28:31], v[244:247], v[28:31], 0
	v_pk_mul_f32 v[44:45], v[32:33], v[44:45] op_sel_hi:[0,1]
	s_waitcnt lgkmcnt(4)
	v_mfma_f32_16x16x32_bf16 v[24:27], v[196:199], v[24:27], v[28:31]
	s_waitcnt lgkmcnt(3)
	v_mfma_f32_16x16x32_bf16 v[20:23], v[200:203], v[20:23], v[24:27]
	s_waitcnt lgkmcnt(2)
	v_mfma_f32_16x16x32_bf16 v[16:19], v[212:215], v[16:19], v[20:23]
	s_waitcnt lgkmcnt(1)
	v_mfma_f32_16x16x32_bf16 v[12:15], v[228:231], v[12:15], v[16:19]
	v_cvt_pk_bf16_f32 v53, v36, v37
	v_cvt_pk_bf16_f32 v52, v34, v35
	s_waitcnt lgkmcnt(0)
	v_mfma_f32_16x16x32_bf16 v[8:11], v[208:211], v[8:11], v[12:15]
	s_nop 2
	v_mul_f32_e32 v12, v37, v37
	v_mul_f32_e32 v13, v35, v35
	v_fmac_f32_e32 v12, v36, v36
	v_fmac_f32_e32 v13, v34, v34
	v_add_f32_e32 v12, v12, v13
	v_mul_f32_e32 v13, v41, v41
	v_mul_f32_e32 v14, v39, v39
	v_fmac_f32_e32 v13, v40, v40
	v_fmac_f32_e32 v14, v38, v38
	v_add_f32_e32 v12, v80, v12
	v_add_f32_e32 v13, v13, v14
	v_add_f32_e32 v12, v13, v12
	v_mul_f32_e32 v13, v45, v45
	v_mul_f32_e32 v14, v43, v43
	v_fmac_f32_e32 v13, v44, v44
	v_fmac_f32_e32 v14, v42, v42
	v_pk_mul_f32 v[10:11], v[32:33], v[10:11] op_sel_hi:[0,1]
	v_pk_mul_f32 v[8:9], v[32:33], v[8:9] op_sel_hi:[0,1]
	v_add_f32_e32 v13, v13, v14
	v_add_f32_e32 v12, v13, v12
	v_mul_f32_e32 v13, v9, v9
	v_mul_f32_e32 v14, v11, v11
	v_fmac_f32_e32 v13, v8, v8
	v_fmac_f32_e32 v14, v10, v10
	v_add_f32_e32 v13, v13, v14
	v_cvt_pk_bf16_f32 v55, v40, v41
	v_cvt_pk_bf16_f32 v54, v38, v39
	v_cvt_pk_bf16_f32 v57, v44, v45
	v_cvt_pk_bf16_f32 v56, v42, v43
	v_add_f32_e32 v80, v12, v13
	v_cvt_pk_bf16_f32 v59, v8, v9
	v_cvt_pk_bf16_f32 v58, v10, v11
	global_load_dword v81, v185, s[12:13] offset:12
	s_waitcnt lgkmcnt(0)
	ds_read_b128 v[92:95], v79
	ds_read_b128 v[196:199], v79 offset:64
	ds_read_b128 v[200:203], v79 offset:576
	ds_read_b128 v[204:207], v79 offset:640
	ds_read_b128 v[208:211], v79 offset:4608
	ds_read_b128 v[212:215], v79 offset:4672
	ds_read_b128 v[228:231], v79 offset:5184
	ds_read_b128 v[232:235], v79 offset:5248
	ds_read_b128 v[236:239], v79 offset:9216
	ds_read_b128 v[240:243], v79 offset:9280
	ds_read_b128 v[244:247], v79 offset:9792
	s_waitcnt lgkmcnt(10)
	v_mfma_f32_16x16x32_bf16 v[8:11], v[92:95], v[4:7], 0
	s_waitcnt vmcnt(0)
	v_mul_f32_e32 v82, 0x3fb8aa3b, v81
	s_waitcnt lgkmcnt(9)
	v_mfma_f32_16x16x32_bf16 v[36:39], v[196:199], v[0:3], v[8:11]
	ds_read_b128 v[92:95], v79 offset:9856
	ds_read_b128 v[196:199], v79 offset:13824
	s_waitcnt lgkmcnt(10)
	v_mfma_f32_16x16x32_bf16 v[8:11], v[200:203], v[4:7], 0
	s_waitcnt lgkmcnt(9)
	v_mfma_f32_16x16x32_bf16 v[28:31], v[204:207], v[0:3], v[8:11]
	ds_read_b128 v[200:203], v79 offset:13888
	ds_read_b128 v[204:207], v79 offset:14400
	s_waitcnt lgkmcnt(10)
	v_mfma_f32_16x16x32_bf16 v[8:11], v[208:211], v[4:7], 0
	s_waitcnt lgkmcnt(9)
	v_mfma_f32_16x16x32_bf16 v[20:23], v[212:215], v[0:3], v[8:11]
	ds_read_b128 v[208:211], v79 offset:14464
	ds_read_b128 v[212:215], v79 offset:18432
	s_waitcnt lgkmcnt(10)
	v_mfma_f32_16x16x32_bf16 v[8:11], v[228:231], v[4:7], 0
	s_waitcnt lgkmcnt(9)
; #define LAS __attribute__((address_space(3)))
; #define LAS __attribute__((address_space(3)))
; __device__ __forceinline__ f32x4 mfma16(bf16x8 a, bf16x8 b, f32x4 c) { return __builtin_amdgcn_mfma_f32_16x16x32_bf16(a, b, c, 0, 0, 0); }
; template <int NKT, int VSTR, bool SINK>
; __device__ __forceinline__ void attn_core(LAS const unsigned char* kb_, LAS const unsigned char* vb_, bf16x8 q0, bf16x8 q1, float sk, unsigned mskbits, int fr, f32x4 (&o)[4]) {
;     ...
;     for (int kt = 0; kt < NKT; ++kt) {
;         const int key = (kt >> 1) * 32 + ((kt & 1) << 2) + krow;
;         LAS const unsigned char* kp = kb_ + key * 144;
;         const bf16x8 a0 = *(LAS const bf16x8*)kp, a1 = *(LAS const bf16x8*)(kp + 64);
;         const float bias = ((mskbits >> (kt >> 2)) & 1u) ? -1e30f : 0.f;
;         f32x4 s = mfma16(a0, q0, (f32x4){bias, bias, bias, bias});
;         s = mfma16(a1, q1, s);
;         S[kt] = s;
;     }
;     float mx = S[0][0];
; #pragma unroll
;     for (int kt = 0; kt < NKT; ++kt) mx = fmaxf(fmaxf(mx, fmaxf(S[kt][0], S[kt][1])), fmaxf(S[kt][2], S[kt][3]));
;     mx = fmaxf(mx, __shfl_xor(mx, 16)); mx = fmaxf(mx, __shfl_xor(mx, 32));
;     if (SINK) mx = fmaxf(mx, sk);
;     float sum = 0.f;
; #pragma unroll
;     for (int kt = 0; kt < NKT; ++kt)
; #pragma unroll
;         for (int r = 0; r < 4; ++r) { const float p = __builtin_amdgcn_exp2f(S[kt][r] - mx); S[kt][r] = p; sum += p; }
	v_mfma_f32_16x16x32_bf16 v[12:15], v[232:235], v[0:3], v[8:11]
	ds_read_b128 v[228:231], v79 offset:18496
	ds_read_b128 v[232:235], v79 offset:19008
	s_waitcnt lgkmcnt(10)
	v_mfma_f32_16x16x32_bf16 v[8:11], v[236:239], v[4:7], 0
	s_waitcnt lgkmcnt(9)
	v_mfma_f32_16x16x32_bf16 v[8:11], v[240:243], v[0:3], v[8:11]
	ds_read_b128 v[236:239], v79 offset:19072
	ds_read_b128 v[240:243], v79 offset:23040
	s_waitcnt lgkmcnt(10)
	v_mfma_f32_16x16x32_bf16 v[16:19], v[244:247], v[4:7], 0
	s_waitcnt lgkmcnt(9)
	v_mfma_f32_16x16x32_bf16 v[16:19], v[92:95], v[0:3], v[16:19]
	ds_read_b128 v[244:247], v79 offset:23104
	ds_read_b128 v[92:95], v79 offset:23616
	s_waitcnt lgkmcnt(10)
	v_mfma_f32_16x16x32_bf16 v[24:27], v[196:199], v[4:7], 0
	s_waitcnt lgkmcnt(9)
	v_mfma_f32_16x16x32_bf16 v[24:27], v[200:203], v[0:3], v[24:27]
	ds_read_b128 v[196:199], v79 offset:23680
	s_waitcnt lgkmcnt(9)
	v_mfma_f32_16x16x32_bf16 v[32:35], v[204:207], v[4:7], 0
	s_waitcnt lgkmcnt(8)
	v_mfma_f32_16x16x32_bf16 v[32:35], v[208:211], v[0:3], v[32:35]
	s_waitcnt lgkmcnt(7)
	v_mfma_f32_16x16x32_bf16 v[40:43], v[212:215], v[4:7], 0
	s_waitcnt lgkmcnt(6)
	v_mfma_f32_16x16x32_bf16 v[40:43], v[228:231], v[0:3], v[40:43]
	s_waitcnt lgkmcnt(5)
	v_mfma_f32_16x16x32_bf16 v[44:47], v[232:235], v[4:7], 0
	s_waitcnt lgkmcnt(4)
	v_mfma_f32_16x16x32_bf16 v[44:47], v[236:239], v[0:3], v[44:47]
	s_waitcnt lgkmcnt(3)
	v_mfma_f32_16x16x32_bf16 v[48:51], v[240:243], v[4:7], 0
	s_waitcnt lgkmcnt(2)
	v_mfma_f32_16x16x32_bf16 v[48:51], v[244:247], v[0:3], v[48:51]
	s_waitcnt lgkmcnt(1)
	v_mfma_f32_16x16x32_bf16 v[4:7], v[92:95], v[4:7], 0
	s_waitcnt lgkmcnt(0)
	v_mfma_f32_16x16x32_bf16 v[0:3], v[196:199], v[0:3], v[4:7]
	s_nop 5
	v_max_f32_e32 v4, v39, v39
	v_max_f32_e32 v5, v38, v38
	v_max_f32_e32 v4, v5, v4
	v_max_f32_e32 v5, v29, v29
	v_max_f32_e32 v6, v28, v28
	v_max_f32_e32 v5, v6, v5
	v_max_f32_e32 v6, v31, v31
	v_max_f32_e32 v7, v30, v30
	v_max3_f32 v4, v36, v37, v4
	v_max_f32_e32 v6, v7, v6
	v_max3_f32 v4, v4, v5, v6
	v_max_f32_e32 v5, v21, v21
	v_max_f32_e32 v6, v20, v20
	v_max_f32_e32 v5, v6, v5
	v_max_f32_e32 v6, v23, v23
	v_max_f32_e32 v7, v22, v22
	v_max_f32_e32 v6, v7, v6
	v_max3_f32 v4, v4, v5, v6
	v_max_f32_e32 v5, v13, v13
	v_max_f32_e32 v6, v12, v12
	v_max_f32_e32 v5, v6, v5
	v_max_f32_e32 v6, v15, v15
	v_max_f32_e32 v7, v14, v14
	v_max_f32_e32 v6, v7, v6
	v_max3_f32 v4, v4, v5, v6
	v_max_f32_e32 v5, v9, v9
	v_max_f32_e32 v6, v8, v8
	v_max_f32_e32 v5, v6, v5
	v_max_f32_e32 v6, v11, v11
	v_max_f32_e32 v7, v10, v10
	v_max_f32_e32 v6, v7, v6
	v_max3_f32 v4, v4, v5, v6
	v_max_f32_e32 v5, v17, v17
	v_max_f32_e32 v6, v16, v16
	v_max_f32_e32 v5, v6, v5
	v_max_f32_e32 v6, v19, v19
	v_max_f32_e32 v7, v18, v18
	v_max_f32_e32 v6, v7, v6
	v_max3_f32 v4, v4, v5, v6
	v_max_f32_e32 v5, v25, v25
	v_max_f32_e32 v6, v24, v24
	v_max_f32_e32 v5, v6, v5
	v_max_f32_e32 v6, v27, v27
	v_max_f32_e32 v7, v26, v26
	v_max_f32_e32 v6, v7, v6
	v_max3_f32 v4, v4, v5, v6
	v_max_f32_e32 v5, v33, v33
	v_max_f32_e32 v6, v32, v32
	v_max_f32_e32 v5, v6, v5
	v_max_f32_e32 v6, v35, v35
	v_max_f32_e32 v7, v34, v34
	v_max_f32_e32 v6, v7, v6
	v_max3_f32 v4, v4, v5, v6
	v_max_f32_e32 v5, v41, v41
	v_max_f32_e32 v6, v40, v40
	v_max_f32_e32 v5, v6, v5
	v_max_f32_e32 v6, v43, v43
	v_max_f32_e32 v7, v42, v42
	v_max_f32_e32 v6, v7, v6
	v_max3_f32 v4, v4, v5, v6
	v_max_f32_e32 v5, v45, v45
	v_max_f32_e32 v6, v44, v44
	v_max_f32_e32 v5, v6, v5
	v_max_f32_e32 v6, v47, v47
	v_max_f32_e32 v7, v46, v46
	v_max_f32_e32 v6, v7, v6
	v_max3_f32 v4, v4, v5, v6
	v_max_f32_e32 v5, v49, v49
	v_max_f32_e32 v6, v48, v48
	v_max_f32_e32 v5, v6, v5
	v_max_f32_e32 v6, v51, v51
	v_max_f32_e32 v7, v50, v50
	v_max_f32_e32 v6, v7, v6
	v_max3_f32 v4, v4, v5, v6
	v_max_f32_e32 v5, v1, v1
	v_max_f32_e32 v6, v0, v0
	v_max_f32_e32 v5, v6, v5
	v_max_f32_e32 v6, v3, v3
	v_max_f32_e32 v7, v2, v2
	v_max_f32_e32 v6, v7, v6
	v_max3_f32 v4, v4, v5, v6
	ds_bpermute_b32 v5, v135, v4
	s_waitcnt lgkmcnt(0)
	v_max_f32_e32 v5, v5, v5
	v_max_f32_e32 v4, v4, v5
	ds_bpermute_b32 v5, v76, v4
	s_waitcnt lgkmcnt(0)
	v_max3_f32 v4, v4, v5, v82
	v_sub_f32_e32 v5, v36, v4
	v_exp_f32_e32 v5, v5
	v_sub_f32_e32 v7, v37, v4
	v_exp_f32_e32 v7, v7
	v_sub_f32_e32 v36, v38, v4
	v_exp_f32_e32 v36, v36
	v_sub_f32_e32 v37, v39, v4
	v_exp_f32_e32 v37, v37
	v_sub_f32_e32 v28, v28, v4
	v_add_f32_e32 v6, 0, v5
	v_exp_f32_e32 v28, v28
	v_sub_f32_e32 v29, v29, v4
	v_add_f32_e32 v6, v7, v6
	v_exp_f32_e32 v29, v29
	v_sub_f32_e32 v30, v30, v4
	v_add_f32_e32 v6, v36, v6
	v_exp_f32_e32 v30, v30
	v_sub_f32_e32 v31, v31, v4
	v_add_f32_e32 v6, v37, v6
	v_exp_f32_e32 v31, v31
	v_sub_f32_e32 v20, v20, v4
	v_add_f32_e32 v6, v28, v6
	v_exp_f32_e32 v38, v20
	v_sub_f32_e32 v20, v21, v4
	v_add_f32_e32 v6, v29, v6
	v_exp_f32_e32 v39, v20
	v_sub_f32_e32 v20, v22, v4
	v_add_f32_e32 v6, v30, v6
	v_exp_f32_e32 v79, v20
	v_sub_f32_e32 v20, v23, v4
	v_add_f32_e32 v6, v31, v6
	v_exp_f32_e32 v82, v20
	v_sub_f32_e32 v12, v12, v4
	v_add_f32_e32 v6, v38, v6
	v_exp_f32_e32 v12, v12
	v_sub_f32_e32 v13, v13, v4
	v_add_f32_e32 v6, v39, v6
	v_exp_f32_e32 v13, v13
	v_sub_f32_e32 v14, v14, v4
	v_add_f32_e32 v6, v79, v6
	v_exp_f32_e32 v14, v14
	v_sub_f32_e32 v15, v15, v4
	v_add_f32_e32 v6, v82, v6
	v_exp_f32_e32 v15, v15
	v_sub_f32_e32 v8, v8, v4
	v_add_f32_e32 v6, v12, v6
	v_exp_f32_e32 v8, v8
	v_sub_f32_e32 v9, v9, v4
	v_add_f32_e32 v6, v13, v6
	v_exp_f32_e32 v9, v9
	v_sub_f32_e32 v10, v10, v4
	v_add_f32_e32 v6, v14, v6
	v_exp_f32_e32 v10, v10
	v_sub_f32_e32 v11, v11, v4
	v_add_f32_e32 v6, v15, v6
	v_exp_f32_e32 v11, v11
	v_sub_f32_e32 v16, v16, v4
	v_add_f32_e32 v6, v8, v6
	v_exp_f32_e32 v83, v16
	v_sub_f32_e32 v16, v17, v4
; #define LAS __attribute__((address_space(3)))
; #define LAS __attribute__((address_space(3)))
; __device__ __forceinline__ unsigned pk2(float lo, float hi) { return pg8::cvt_pk_bf16(lo, hi); }
; __device__ __forceinline__ f32x4 mfma16(bf16x8 a, bf16x8 b, f32x4 c) { return __builtin_amdgcn_mfma_f32_16x16x32_bf16(a, b, c, 0, 0, 0); }
; template <int NKT, int VSTR, bool SINK>
; __device__ __forceinline__ void attn_core(LAS const unsigned char* kb_, LAS const unsigned char* vb_, bf16x8 q0, bf16x8 q1, float sk, unsigned mskbits, int fr, f32x4 (&o)[4]) {
;     ...
;     for (int kt = 0; kt < NKT; ++kt)
; #pragma unroll
;         for (int r = 0; r < 4; ++r) { const float p = __builtin_amdgcn_exp2f(S[kt][r] - mx); S[kt][r] = p; sum += p; }
;     sum += __shfl_xor(sum, 16); sum += __shfl_xor(sum, 32);
;     if (SINK) sum += __builtin_amdgcn_exp2f(sk - mx);
;     const float inv = 1.0f / sum;
;     bf16x8 pf[NKT / 2];
; #pragma unroll
;     for (int kb = 0; kb < NKT / 2; ++kb) {
;         v4u w; w.x = pk2(S[2 * kb][0], S[2 * kb][1]); w.y = pk2(S[2 * kb][2], S[2 * kb][3]); w.z = pk2(S[2 * kb + 1][0], S[2 * kb + 1][1]); w.w = pk2(S[2 * kb + 1][2], S[2 * kb + 1][3]);
;         pf[kb] = __builtin_bit_cast(bf16x8, w);
;     }
; #pragma unroll
;     for (int dt = 0; dt < 4; ++dt) {
;         f32x4 acc = (f32x4){0.f, 0.f, 0.f, 0.f};
; #pragma unroll
;         for (int kb = 0; kb < NKT / 2; ++kb) {
;             const bf16x8 vf = *(LAS const bf16x8*)(vb_ + dt * 16 * VSTR + kb * 64);
;             acc = mfma16(vf, pf[kb], acc);
;         }
;         o[dt] = acc * inv;
;     }
	v_add_f32_e32 v6, v9, v6
	v_exp_f32_e32 v84, v16
	v_sub_f32_e32 v16, v18, v4
	v_add_f32_e32 v6, v10, v6
	v_exp_f32_e32 v85, v16
	v_sub_f32_e32 v16, v19, v4
	v_add_f32_e32 v6, v11, v6
	v_exp_f32_e32 v86, v16
	v_sub_f32_e32 v16, v24, v4
	v_add_f32_e32 v6, v83, v6
	v_exp_f32_e32 v24, v16
	v_sub_f32_e32 v16, v25, v4
	v_add_f32_e32 v6, v84, v6
	v_exp_f32_e32 v25, v16
	v_sub_f32_e32 v16, v26, v4
	v_add_f32_e32 v6, v85, v6
	v_exp_f32_e32 v26, v16
	v_sub_f32_e32 v16, v27, v4
	v_add_f32_e32 v6, v86, v6
	v_exp_f32_e32 v27, v16
	v_sub_f32_e32 v16, v32, v4
	v_add_f32_e32 v6, v24, v6
	v_exp_f32_e32 v32, v16
	v_sub_f32_e32 v16, v33, v4
	v_add_f32_e32 v6, v25, v6
	v_exp_f32_e32 v33, v16
	v_sub_f32_e32 v16, v34, v4
	v_add_f32_e32 v6, v26, v6
	v_exp_f32_e32 v34, v16
	v_sub_f32_e32 v16, v35, v4
	v_add_f32_e32 v6, v27, v6
	v_exp_f32_e32 v35, v16
	v_sub_f32_e32 v16, v40, v4
	v_add_f32_e32 v6, v32, v6
	v_exp_f32_e32 v40, v16
	v_sub_f32_e32 v16, v41, v4
	v_add_f32_e32 v6, v33, v6
	v_exp_f32_e32 v41, v16
	v_sub_f32_e32 v16, v42, v4
	v_add_f32_e32 v6, v34, v6
	v_exp_f32_e32 v42, v16
	v_sub_f32_e32 v16, v43, v4
	v_add_f32_e32 v6, v35, v6
	v_exp_f32_e32 v43, v16
	v_sub_f32_e32 v16, v44, v4
	v_add_f32_e32 v6, v40, v6
	v_exp_f32_e32 v44, v16
	v_sub_f32_e32 v16, v45, v4
	v_add_f32_e32 v6, v41, v6
	v_exp_f32_e32 v45, v16
	v_sub_f32_e32 v16, v46, v4
	v_add_f32_e32 v6, v42, v6
	v_exp_f32_e32 v46, v16
	v_sub_f32_e32 v16, v47, v4
	v_add_f32_e32 v6, v43, v6
	v_exp_f32_e32 v47, v16
	v_sub_f32_e32 v16, v48, v4
	v_add_f32_e32 v6, v44, v6
	v_exp_f32_e32 v48, v16
	v_sub_f32_e32 v16, v49, v4
	v_add_f32_e32 v6, v45, v6
	v_exp_f32_e32 v49, v16
	v_sub_f32_e32 v16, v50, v4
	v_add_f32_e32 v6, v46, v6
	v_exp_f32_e32 v50, v16
	v_sub_f32_e32 v16, v51, v4
	v_add_f32_e32 v6, v47, v6
	v_exp_f32_e32 v51, v16
	v_sub_f32_e32 v0, v0, v4
	v_add_f32_e32 v6, v48, v6
	v_exp_f32_e32 v87, v0
	v_sub_f32_e32 v1, v1, v4
	v_add_f32_e32 v6, v49, v6
	v_exp_f32_e32 v88, v1
	v_sub_f32_e32 v1, v2, v4
	v_add_f32_e32 v6, v50, v6
	v_exp_f32_e32 v89, v1
	v_sub_f32_e32 v1, v3, v4
	v_add_f32_e32 v6, v51, v6
	v_exp_f32_e32 v3, v1
	v_add_f32_e32 v0, v87, v6
	v_add_f32_e32 v0, v88, v0
	v_add_f32_e32 v0, v89, v0
	v_add_f32_e32 v0, v3, v0
	ds_bpermute_b32 v1, v135, v0
	v_cvt_pk_bf16_f32 v20, v5, v7
	v_cvt_pk_bf16_f32 v21, v36, v37
	v_cvt_pk_bf16_f32 v22, v28, v29
	v_cvt_pk_bf16_f32 v23, v30, v31
	s_waitcnt lgkmcnt(0)
	v_add_f32_e32 v0, v0, v1
	ds_bpermute_b32 v1, v76, v0
	v_cvt_pk_bf16_f32 v16, v38, v39
	v_cvt_pk_bf16_f32 v17, v79, v82
	v_cvt_pk_bf16_f32 v18, v12, v13
	v_cvt_pk_bf16_f32 v19, v14, v15
	s_waitcnt lgkmcnt(0)
	v_add_f32_e32 v0, v0, v1
	v_fma_f32 v1, v81, s2, -v4
	v_exp_f32_e32 v1, v1
	v_cvt_pk_bf16_f32 v12, v8, v9
	v_cvt_pk_bf16_f32 v13, v10, v11
	v_cvt_pk_bf16_f32 v14, v83, v84
	v_cvt_pk_bf16_f32 v15, v85, v86
	v_cvt_pk_bf16_f32 v8, v24, v25
	s_nop 0
	v_add_f32_e32 v81, v1, v0
	v_div_scale_f32 v24, s[0:1], v81, v81, 1.0
	v_rcp_f32_e32 v25, v24
	v_cvt_pk_bf16_f32 v9, v26, v27
	v_cvt_pk_bf16_f32 v10, v32, v33
	v_cvt_pk_bf16_f32 v11, v34, v35
	v_cvt_pk_bf16_f32 v4, v40, v41
	v_cvt_pk_bf16_f32 v5, v42, v43
	s_nop 0
	v_fma_f32 v26, -v24, v25, 1.0
	v_fmac_f32_e32 v25, v26, v25
	v_div_scale_f32 v26, vcc, 1.0, v81, 1.0
	v_mul_f32_e32 v27, v26, v25
	v_fma_f32 v28, -v24, v27, v26
	v_fmac_f32_e32 v27, v28, v25
	v_fma_f32 v24, -v24, v27, v26
	v_cvt_pk_bf16_f32 v6, v44, v45
	v_cvt_pk_bf16_f32 v7, v46, v47
	v_cvt_pk_bf16_f32 v0, v48, v49
	v_cvt_pk_bf16_f32 v1, v50, v51
	v_cvt_pk_bf16_f32 v2, v87, v88
	v_cvt_pk_bf16_f32 v3, v89, v3
	v_div_fmas_f32 v24, v24, v25, v27
	s_waitcnt lgkmcnt(0)
	ds_read_b128 v[92:95], v78 offset:55296
	ds_read_b128 v[196:199], v78 offset:55360
	ds_read_b128 v[200:203], v78 offset:61760
	ds_read_b128 v[204:207], v77 offset:12864
	ds_read_b128 v[208:211], v78 offset:55424
	ds_read_b128 v[212:215], v78 offset:55488
	ds_read_b128 v[228:231], v78 offset:55552
	ds_read_b128 v[232:235], v78 offset:55616
	ds_read_b128 v[236:239], v78 offset:61696
	ds_read_b128 v[240:243], v78 offset:61824
	ds_read_b128 v[244:247], v78 offset:61888
	s_waitcnt lgkmcnt(10)
	v_mfma_f32_16x16x32_bf16 v[26:29], v[92:95], v[20:23], 0
	ds_read_b128 v[92:95], v78 offset:61952
	v_div_fixup_f32 v24, v24, v81, 1.0
	s_waitcnt lgkmcnt(10)
; #define LAS __attribute__((address_space(3)))
; __device__ __forceinline__ float quad_sum(float s) { s += __shfl_xor(s, 16); s += __shfl_xor(s, 32); return s; }
; __device__ __forceinline__ float sq4(const f32x4 a) { return (a[0] * a[0] + a[1] * a[1]) + (a[2] * a[2] + a[3] * a[3]); }
; #define LAS __attribute__((address_space(3)))
; __device__ __forceinline__ unsigned pk2(float lo, float hi) { return pg8::cvt_pk_bf16(lo, hi); }
; __device__ __forceinline__ f32x4 mfma16(bf16x8 a, bf16x8 b, f32x4 c) { return __builtin_amdgcn_mfma_f32_16x16x32_bf16(a, b, c, 0, 0, 0); }
; template <int NKT, int VSTR, bool SINK>
; __device__ __forceinline__ void attn_core(LAS const unsigned char* kb_, LAS const unsigned char* vb_, bf16x8 q0, bf16x8 q1, float sk, unsigned mskbits, int fr, f32x4 (&o)[4]) {
;     ...
; #pragma unroll
;     for (int dt = 0; dt < 4; ++dt) {
;         f32x4 acc = (f32x4){0.f, 0.f, 0.f, 0.f};
; #pragma unroll
;         for (int kb = 0; kb < NKT / 2; ++kb) {
;             const bf16x8 vf = *(LAS const bf16x8*)(vb_ + dt * 16 * VSTR + kb * 64);
;             acc = mfma16(vf, pf[kb], acc);
;         }
;         o[dt] = acc * inv;
;     }
; template <bool DO_SWA, bool DO_MEM>
; __device__ __forceinline__ void attn_unit(const Args& a, unsigned char* ws, LAS unsigned char* lds, int l, int tid_in, int lane_in, int wave, int unit) {
;     ...
;                 for (int dt = 0; dt < 4; ++dt) { ssq += pg8::sq4(o[dt]); osv[hh][dt] = (v2u){pk2(o[dt][0], o[dt][1]), pk2(o[dt][2], o[dt][3])}; }
;             }
;             ssq = pg8::quad_sum(ssq);
;             if (fq == 0) red_a[g * 64 + qs * 16 + fr] = ssq;
	v_mfma_f32_16x16x32_bf16 v[26:29], v[196:199], v[16:19], v[26:29]
	ds_read_b128 v[196:199], v78 offset:62016
	v_cmp_gt_u32_e32 vcc, 16, v133
	s_waitcnt lgkmcnt(8)
	v_mfma_f32_16x16x32_bf16 v[26:29], v[208:211], v[12:15], v[26:29]
	ds_read_b128 v[208:211], v77 offset:12800
	s_waitcnt lgkmcnt(8)
	v_mfma_f32_16x16x32_bf16 v[26:29], v[212:215], v[8:11], v[26:29]
	ds_read_b128 v[212:215], v77 offset:12928
	s_waitcnt lgkmcnt(8)
	v_mfma_f32_16x16x32_bf16 v[26:29], v[228:231], v[4:7], v[26:29]
	ds_read_b128 v[228:231], v77 offset:12992
	s_waitcnt lgkmcnt(8)
	v_mfma_f32_16x16x32_bf16 v[28:31], v[232:235], v[0:3], v[26:29]
	ds_read_b128 v[232:235], v77 offset:13056
	s_nop 7
	v_pk_mul_f32 v[26:27], v[30:31], v[24:25] op_sel_hi:[1,0]
	s_waitcnt lgkmcnt(8)
	v_mfma_f32_16x16x32_bf16 v[30:33], v[236:239], v[20:23], 0
	ds_read_b128 v[236:239], v77 offset:13120
	v_mul_f32_e64 v28, v28, v24
	v_mul_f32_e64 v29, v29, v24
	v_mfma_f32_16x16x32_bf16 v[30:33], v[200:203], v[16:19], v[30:33]
	ds_read_b128 v[200:203], v77 offset:19200
	s_waitcnt lgkmcnt(9)
	v_mfma_f32_16x16x32_bf16 v[30:33], v[240:243], v[12:15], v[30:33]
	ds_read_b128 v[240:243], v77 offset:19264
	s_waitcnt lgkmcnt(9)
	v_mfma_f32_16x16x32_bf16 v[30:33], v[244:247], v[8:11], v[30:33]
	ds_read_b128 v[244:247], v77 offset:19328
	s_waitcnt lgkmcnt(9)
	v_mfma_f32_16x16x32_bf16 v[30:33], v[92:95], v[4:7], v[30:33]
	ds_read_b128 v[92:95], v77 offset:19392
	s_waitcnt lgkmcnt(9)
	v_mfma_f32_16x16x32_bf16 v[32:35], v[196:199], v[0:3], v[30:33]
	s_nop 7
	v_pk_mul_f32 v[30:31], v[34:35], v[24:25] op_sel_hi:[1,0]
	ds_read_b128 v[196:199], v77 offset:19456
	s_waitcnt lgkmcnt(9)
	v_mfma_f32_16x16x32_bf16 v[34:37], v[208:211], v[20:23], 0
	v_mul_f32_e64 v32, v32, v24
	v_mul_f32_e64 v33, v33, v24
	v_mfma_f32_16x16x32_bf16 v[34:37], v[204:207], v[16:19], v[34:37]
	ds_read_b128 v[208:211], v77 offset:19520
	s_waitcnt lgkmcnt(9)
	v_mfma_f32_16x16x32_bf16 v[34:37], v[212:215], v[12:15], v[34:37]
	s_waitcnt lgkmcnt(8)
	v_mfma_f32_16x16x32_bf16 v[34:37], v[228:231], v[8:11], v[34:37]
	s_waitcnt lgkmcnt(7)
	v_mfma_f32_16x16x32_bf16 v[34:37], v[232:235], v[4:7], v[34:37]
	s_waitcnt lgkmcnt(6)
	v_mfma_f32_16x16x32_bf16 v[34:37], v[236:239], v[0:3], v[34:37]
	s_nop 7
	v_pk_mul_f32 v[38:39], v[24:25], v[36:37] op_sel_hi:[0,1]
	v_pk_mul_f32 v[40:41], v[24:25], v[34:35] op_sel_hi:[0,1]
	s_waitcnt lgkmcnt(5)
	v_mfma_f32_16x16x32_bf16 v[20:23], v[200:203], v[20:23], 0
	s_waitcnt lgkmcnt(4)
	v_mfma_f32_16x16x32_bf16 v[16:19], v[240:243], v[16:19], v[20:23]
	s_waitcnt lgkmcnt(3)
	v_mfma_f32_16x16x32_bf16 v[12:15], v[244:247], v[12:15], v[16:19]
	s_waitcnt lgkmcnt(2)
	v_mfma_f32_16x16x32_bf16 v[8:11], v[92:95], v[8:11], v[12:15]
	s_waitcnt lgkmcnt(1)
	v_mfma_f32_16x16x32_bf16 v[4:7], v[196:199], v[4:7], v[8:11]
	s_waitcnt lgkmcnt(0)
	v_mfma_f32_16x16x32_bf16 v[0:3], v[208:211], v[0:3], v[4:7]
	s_nop 2
	v_mul_f32_e32 v4, v31, v31
	v_fmac_f32_e32 v4, v30, v30
	v_mul_f32_e32 v5, v41, v41
	s_nop 1
	v_pk_mul_f32 v[6:7], v[24:25], v[0:1] op_sel_hi:[0,1]
	v_mul_f32_e32 v0, v29, v29
	v_mul_f32_e32 v1, v27, v27
	v_pk_mul_f32 v[8:9], v[24:25], v[2:3] op_sel_hi:[0,1]
	v_fmac_f32_e32 v0, v28, v28
	v_fmac_f32_e32 v1, v26, v26
	v_mul_f32_e32 v3, v33, v33
	v_add_f32_e32 v0, v0, v1
	v_fmac_f32_e32 v3, v32, v32
	v_mul_f32_e32 v10, v39, v39
	v_add_f32_e32 v2, v80, v0
	v_add_f32_e32 v3, v3, v4
	v_fmac_f32_e32 v5, v40, v40
	v_fmac_f32_e32 v10, v38, v38
	v_mul_f32_e32 v11, v7, v7
	v_mul_f32_e32 v12, v9, v9
	v_add_f32_e32 v4, v3, v2
	v_add_f32_e32 v5, v5, v10
	v_fmac_f32_e32 v11, v6, v6
	v_fmac_f32_e32 v12, v8, v8
	v_add_f32_e32 v10, v5, v4
	v_add_f32_e32 v11, v11, v12
	v_add_f32_e32 v10, v10, v11
	v_cvt_pk_bf16_f32 v1, v28, v29
	v_cvt_pk_bf16_f32 v0, v26, v27
	v_cvt_pk_bf16_f32 v3, v32, v33
	v_cvt_pk_bf16_f32 v2, v30, v31
	v_cvt_pk_bf16_f32 v5, v40, v41
	v_cvt_pk_bf16_f32 v4, v38, v39
	v_cvt_pk_bf16_f32 v7, v6, v7
	v_cvt_pk_bf16_f32 v6, v8, v9
	ds_bpermute_b32 v8, v135, v10
	s_waitcnt lgkmcnt(0)
	v_add_f32_e32 v8, v10, v8
	ds_bpermute_b32 v9, v76, v8
	s_and_saveexec_b64 s[0:1], vcc
	s_cbranch_execz .LBB0_274
	v_readlane_b32 s2, v251, 30
	s_waitcnt lgkmcnt(0)
	v_add_f32_e32 v8, v8, v9
	v_lshl_add_u32 v10, v133, 2, s2
	ds_write_b32 v10, v8

; __device__ __forceinline__ unsigned pk2(float lo, float hi) { return pg8::cvt_pk_bf16(lo, hi); }
; template <bool DO_SWA, bool DO_MEM>
; __device__ __forceinline__ void attn_unit(const Args& a, unsigned char* ws, LAS unsigned char* lds, int l, int tid_in, int lane_in, int wave, int unit) {
;     ...
;             float w0[8], w1[8], w2[8];
; #pragma unroll
;             for (int j = 0; j < 4; ++j) { w0[j] = cwv[0][j]; w0[4 + j] = cwv[1][j]; w1[j] = cwv[2][j]; w1[4 + j] = cwv[3][j]; w2[j] = cwv[4][j]; w2[4 + j] = cwv[5][j]; }
; #pragma unroll
;             for (int i = 0; i < 4; ++i) {
;                 float ua[8], ub_[8], uc[8], cbv[8], cy[8];
;                 unpack8(cu[i], ua); unpack8(cu[i + 1], ub_); unpack8(cu[i + 2], uc); unpack8(ccb[i], cbv);
;                 float ss = 0.f;
; #pragma unroll
;                 for (int j = 0; j < 8; ++j) { const float y = ua[j] * w0[j] + ub_[j] * w1[j] + uc[j] * w2[j]; cy[j] = cbv[j] * y; ss += cy[j] * cy[j]; }
;                 ss += __shfl_xor(ss, 1); ss += __shfl_xor(ss, 2); ss += __shfl_xor(ss, 4); ss += __shfl_xor(ss, 8); ss += __shfl_xor(ss, 16);
;                 const float rs = 1.0f / sqrtf(ss * (1.0f / 256.0f) + EPS);
;                 v4u o; o.x = pk2(cy[0] * rs, cy[1] * rs); o.y = pk2(cy[2] * rs, cy[3] * rs); o.z = pk2(cy[4] * rs, cy[5] * rs); o.w = pk2(cy[6] * rs, cy[7] * rs);
;                 *(v4u*)(MIX + (size_t)(row0 + t0 + i) * D + 512 + ch) = o;
.LBB0_290:
	s_or_b64 exec, exec, s[4:5]
	v_lshl_add_u64 v[124:125], v[124:125], 0, v[184:185]
	s_movk_i32 s0, 0x1000
	v_add_co_u32_e32 v128, vcc, s0, v124
	s_movk_i32 s0, 0x2000
	s_nop 0
	v_addc_co_u32_e32 v129, vcc, 0, v125, vcc
	v_add_co_u32_e32 v132, vcc, s0, v124
	v_ashrrev_i32_e32 v153, 31, v152
	s_nop 0
	v_addc_co_u32_e32 v133, vcc, 0, v125, vcc
	global_load_dwordx4 v[202:205], v[124:125], off offset:1792 nt
	global_load_dwordx4 v[162:165], v[124:125], off offset:1280 nt
	global_load_dwordx4 v[140:143], v[128:129], off offset:512 nt
	global_load_dwordx4 v[206:209], v[128:129], off nt
	s_nop 0
	global_load_dwordx4 v[124:127], v[128:129], off offset:3328 nt
	global_load_dwordx4 v[136:139], v[128:129], off offset:2816 nt
	s_nop 0
	global_load_dwordx4 v[128:131], v[132:133], off offset:2048 nt
	s_nop 0
	global_load_dwordx4 v[132:135], v[132:133], off offset:1536 nt
	v_ashrrev_i32_e32 v149, 31, v148
	v_ashrrev_i32_e32 v161, 31, v160
	s_waitcnt vmcnt(0)
	v_lshlrev_b32_e32 v199, 16, v202
	v_lshlrev_b32_e32 v198, 16, v144
	v_mov_b32_e32 v200, v112
	v_mov_b32_e32 v201, v120
	v_pk_mul_f32 v[194:195], v[200:201], v[198:199]
	v_lshlrev_b32_e32 v198, 16, v208
	v_and_b32_e32 v220, 0xffff0000, v208
	v_lshlrev_b32_e32 v208, 16, v108
	v_and_b32_e32 v151, 64, v222
	v_fma_f32 v194, v116, v208, v194
	v_xor_b32_e32 v159, 1, v222
	v_add_u32_e32 v151, 64, v151
	v_lshlrev_b32_e32 v226, 16, v162
	v_lshlrev_b32_e32 v190, 16, v209
	v_and_b32_e32 v191, 0xffff0000, v209
	v_lshlrev_b32_e32 v209, 16, v140
	v_add_f32_e32 v194, v194, v195
	v_cmp_lt_i32_e32 vcc, v159, v151
	v_and_b32_e32 v246, 0xffff0000, v162
	v_lshlrev_b32_e32 v247, 16, v163
	v_and_b32_e32 v248, 0xffff0000, v163
	v_lshlrev_b32_e32 v249, 16, v164
	v_and_b32_e32 v223, 0xffff0000, v164
	v_lshlrev_b32_e32 v250, 16, v165
	v_and_b32_e32 v217, 0xffff0000, v165
	v_and_b32_e32 v183, 0xffff0000, v202
	v_and_b32_e32 v182, 0xffff0000, v144
	v_mov_b32_e32 v196, v113
	v_mov_b32_e32 v197, v121
	v_lshlrev_b32_e32 v163, 16, v205
	v_lshlrev_b32_e32 v162, 16, v147
	v_mov_b32_e32 v164, v98
	v_mov_b32_e32 v165, v106
	v_mul_f32_e32 v226, v194, v226
	v_pk_mul_f32 v[194:195], v[200:201], v[208:209]
	v_cndmask_b32_e32 v159, v222, v159, vcc
	v_pk_mul_f32 v[224:225], v[196:197], v[182:183]
	v_lshlrev_b32_e32 v179, 16, v203
	v_lshlrev_b32_e32 v178, 16, v145
	v_mov_b32_e32 v180, v114
	v_mov_b32_e32 v181, v122
	v_lshlrev_b32_e32 v171, 16, v204
	v_lshlrev_b32_e32 v170, 16, v146
	v_mov_b32_e32 v172, v96
	v_mov_b32_e32 v173, v104
	v_pk_mul_f32 v[240:241], v[164:165], v[162:163]
	v_lshlrev_b64 v[244:245], 11, v[160:161]
	v_lshlrev_b32_e32 v161, 16, v206
	v_and_b32_e32 v162, 0xffff0000, v206
	v_fma_f32 v194, v116, v199, v194
	v_and_b32_e32 v206, 0xffff0000, v108
	v_lshlrev_b32_e32 v231, 2, v159
	v_xor_b32_e32 v159, 2, v222
	v_pk_mul_f32 v[232:233], v[180:181], v[178:179]
	v_pk_mul_f32 v[236:237], v[172:173], v[170:171]
	v_lshlrev_b32_e32 v170, 16, v207
	v_and_b32_e32 v178, 0xffff0000, v207
	v_add_f32_e32 v194, v194, v195
	v_and_b32_e32 v207, 0xffff0000, v140
	v_fma_f32 v108, v117, v206, v224
	v_cmp_lt_i32_e32 vcc, v159, v151
	v_mul_f32_e32 v161, v194, v161
	v_add_f32_e32 v108, v108, v225
	v_pk_mul_f32 v[194:195], v[196:197], v[206:207]
	v_cndmask_b32_e32 v159, v222, v159, vcc
	v_mul_f32_e32 v208, v108, v246
	v_fma_f32 v108, v117, v183, v194
	v_lshlrev_b32_e32 v230, 2, v159
	v_xor_b32_e32 v159, 4, v222
	v_and_b32_e32 v167, 0xffff0000, v204
	v_add_f32_e32 v108, v108, v195
	v_lshlrev_b32_e32 v204, 16, v109
	v_cmp_lt_i32_e32 vcc, v159, v151
	v_and_b32_e32 v174, 0xffff0000, v145
	v_and_b32_e32 v145, 0xffff0000, v205
	v_mul_f32_e32 v162, v108, v162
	v_lshlrev_b32_e32 v205, 16, v141
	v_fma_f32 v108, v118, v204, v232
	v_cndmask_b32_e32 v159, v222, v159, vcc
	v_add_f32_e32 v108, v108, v233
	v_pk_mul_f32 v[194:195], v[180:181], v[204:205]
	v_lshlrev_b32_e32 v229, 2, v159
	v_xor_b32_e32 v159, 8, v222
	v_and_b32_e32 v175, 0xffff0000, v203
	v_mov_b32_e32 v176, v115
	v_mov_b32_e32 v177, v123
	v_mul_f32_e32 v233, v108, v247
	v_fma_f32 v108, v118, v179, v194
	v_cmp_lt_i32_e32 vcc, v159, v151
	v_xor_b32_e32 v166, 16, v222
	v_pk_mul_f32 v[234:235], v[176:177], v[174:175]
	v_add_f32_e32 v108, v108, v195
	v_and_b32_e32 v202, 0xffff0000, v109
	v_cndmask_b32_e32 v159, v222, v159, vcc
	v_cmp_lt_i32_e32 vcc, v166, v151
	v_mul_f32_e32 v170, v108, v170
	v_fma_f32 v108, v119, v202, v234
	v_cndmask_b32_e32 v166, v222, v166, vcc
	v_add_f32_e32 v108, v108, v235
	v_lshlrev_b32_e32 v140, 16, v110
	v_lshlrev_b32_e32 v212, 2, v166
	v_and_b32_e32 v166, 0xffff0000, v146
	v_mov_b32_e32 v168, v97
	v_mov_b32_e32 v169, v105
	v_mul_f32_e32 v204, v108, v248
	v_fma_f32 v108, v100, v140, v236
	v_pk_mul_f32 v[238:239], v[168:169], v[166:167]
	v_and_b32_e32 v203, 0xffff0000, v141
	v_add_f32_e32 v108, v108, v237
	v_and_b32_e32 v110, 0xffff0000, v110
	v_pk_mul_f32 v[224:225], v[176:177], v[202:203]
	v_mul_f32_e32 v202, v108, v249
	v_fma_f32 v108, v101, v110, v238
	v_mul_f32_e32 v246, v208, v208
	v_add_f32_e32 v108, v108, v239
	v_lshlrev_b32_e32 v194, 16, v111
	v_fmac_f32_e32 v246, v226, v226
	v_mul_f32_e32 v223, v108, v223
	v_fma_f32 v108, v102, v194, v240
	v_and_b32_e32 v144, 0xffff0000, v147
	v_mov_b32_e32 v146, v99
	v_mov_b32_e32 v147, v107
	v_fmac_f32_e32 v246, v233, v233
	v_add_f32_e32 v108, v108, v241
	v_pk_mul_f32 v[242:243], v[146:147], v[144:145]
	v_fmac_f32_e32 v246, v204, v204
	v_mul_f32_e32 v235, v108, v250
	v_and_b32_e32 v108, 0xffff0000, v111
	v_fmac_f32_e32 v246, v202, v202
	v_fma_f32 v109, v103, v108, v242
	v_fmac_f32_e32 v246, v223, v223
	v_add_f32_e32 v109, v109, v243
	v_fmac_f32_e32 v246, v235, v235
	v_mul_f32_e32 v217, v109, v217
	v_fmac_f32_e32 v246, v217, v217
	ds_bpermute_b32 v109, v231, v246
	v_fma_f32 v111, v119, v175, v224
	v_add_f32_e32 v111, v111, v225
	v_mul_f32_e32 v178, v111, v178
	v_lshlrev_b32_e32 v141, 16, v142
	s_waitcnt lgkmcnt(0)
; __device__ __forceinline__ unsigned pk2(float lo, float hi) { return pg8::cvt_pk_bf16(lo, hi); }
; template <bool DO_SWA, bool DO_MEM>
; __device__ __forceinline__ void attn_unit(const Args& a, unsigned char* ws, LAS unsigned char* lds, int l, int tid_in, int lane_in, int wave, int unit) {
;     ...
;             for (int i = 0; i < 4; ++i) {
;                 float ua[8], ub_[8], uc[8], cbv[8], cy[8];
;                 unpack8(cu[i], ua); unpack8(cu[i + 1], ub_); unpack8(cu[i + 2], uc); unpack8(ccb[i], cbv);
;                 float ss = 0.f;
; #pragma unroll
;                 for (int j = 0; j < 8; ++j) { const float y = ua[j] * w0[j] + ub_[j] * w1[j] + uc[j] * w2[j]; cy[j] = cbv[j] * y; ss += cy[j] * cy[j]; }
;                 ss += __shfl_xor(ss, 1); ss += __shfl_xor(ss, 2); ss += __shfl_xor(ss, 4); ss += __shfl_xor(ss, 8); ss += __shfl_xor(ss, 16);
;                 const float rs = 1.0f / sqrtf(ss * (1.0f / 256.0f) + EPS);
;                 v4u o; o.x = pk2(cy[0] * rs, cy[1] * rs); o.y = pk2(cy[2] * rs, cy[3] * rs); o.z = pk2(cy[4] * rs, cy[5] * rs); o.w = pk2(cy[6] * rs, cy[7] * rs);
;                 *(v4u*)(MIX + (size_t)(row0 + t0 + i) * D + 512 + ch) = o;
	v_add_f32_e32 v109, v246, v109
	ds_bpermute_b32 v111, v230, v109
	v_pk_mul_f32 v[224:225], v[172:173], v[140:141]
	v_lshlrev_b32_e32 v159, 2, v159
	v_fma_f32 v140, v100, v171, v224
	v_add_f32_e32 v140, v140, v225
	s_waitcnt lgkmcnt(0)
	v_add_f32_e32 v109, v109, v111
	ds_bpermute_b32 v195, v229, v109
	v_and_b32_e32 v111, 0xffff0000, v142
	v_pk_mul_f32 v[224:225], v[168:169], v[110:111]
	s_mov_b32 s4, 0xf800000
	v_fma_f32 v142, v101, v167, v224
	s_waitcnt lgkmcnt(0)
	v_add_f32_e32 v109, v109, v195
	ds_bpermute_b32 v110, v159, v109
	v_lshlrev_b32_e32 v195, 16, v143
	v_add_f32_e32 v142, v142, v225
	v_pk_mul_f32 v[224:225], v[164:165], v[194:195]
	v_mul_f32_e32 v140, v140, v198
	s_waitcnt lgkmcnt(0)
	v_add_f32_e32 v109, v109, v110
	ds_bpermute_b32 v110, v212, v109
	v_mul_f32_e32 v198, v142, v220
	v_fma_f32 v142, v102, v163, v224
	v_add_f32_e32 v142, v142, v225
	v_mul_f32_e32 v190, v142, v190
	s_waitcnt lgkmcnt(0)
	v_add_f32_e32 v109, v109, v110
	v_fmamk_f32 v109, v109, 0x3b800000, v218
	v_mul_f32_e32 v110, 0x4f800000, v109
	v_cmp_gt_f32_e32 vcc, s4, v109
	v_mul_f32_e32 v206, v162, v162
	v_fmac_f32_e32 v206, v161, v161
	v_cndmask_b32_e32 v110, v109, v110, vcc
	v_sqrt_f32_e32 v194, v110
	v_and_b32_e32 v109, 0xffff0000, v143
	v_fmac_f32_e32 v206, v170, v170
	v_fmac_f32_e32 v206, v178, v178
	v_add_u32_e32 v142, -1, v194
	v_fma_f32 v143, -v142, v194, v110
	v_cmp_ge_f32_e64 s[0:1], 0, v143
	v_add_u32_e32 v143, 1, v194
	v_fmac_f32_e32 v206, v140, v140
	v_cndmask_b32_e64 v142, v194, v142, s[0:1]
	v_fma_f32 v194, -v143, v194, v110
	v_cmp_lt_f32_e64 s[0:1], 0, v194
	v_fmac_f32_e32 v206, v198, v198
	v_fmac_f32_e32 v206, v190, v190
	v_cndmask_b32_e64 v142, v142, v143, s[0:1]
	v_mul_f32_e32 v143, 0x37800000, v142
	v_cndmask_b32_e32 v142, v142, v143, vcc
	v_cmp_class_f32_e32 vcc, v110, v219
	s_movk_i32 s5, 0x190
	s_nop 0
	v_cndmask_b32_e32 v110, v142, v110, vcc
	v_pk_mul_f32 v[142:143], v[146:147], v[108:109]
	v_div_scale_f32 v194, s[0:1], v110, v110, 1.0
	v_fma_f32 v108, v103, v145, v142
	v_add_f32_e32 v108, v108, v143
	v_mul_f32_e32 v108, v108, v191
	v_fmac_f32_e32 v206, v108, v108
	ds_bpermute_b32 v191, v231, v206
	v_rcp_f32_e32 v220, v194
	v_lshl_add_u64 v[142:143], s[20:21], 0, v[244:245]
	v_lshl_add_u64 v[142:143], v[142:143], 0, v[184:185]
	s_waitcnt lgkmcnt(0)
	v_add_f32_e32 v191, v206, v191
	ds_bpermute_b32 v206, v230, v191
	v_fma_f32 v224, -v194, v220, 1.0
	v_fmac_f32_e32 v220, v224, v220
	v_div_scale_f32 v224, vcc, 1.0, v110, 1.0
	s_waitcnt lgkmcnt(0)
	v_add_f32_e32 v191, v191, v206
	ds_bpermute_b32 v206, v229, v191
	v_mul_f32_e32 v225, v224, v220
	v_fma_f32 v232, -v194, v225, v224
	v_fmac_f32_e32 v225, v232, v220
	v_fma_f32 v194, -v194, v225, v224
	s_waitcnt lgkmcnt(0)
	v_add_f32_e32 v191, v191, v206
	ds_bpermute_b32 v206, v159, v191
	v_div_fmas_f32 v194, v194, v220, v225
	v_div_fixup_f32 v110, v194, v110, 1.0
	v_mul_f32_e32 v194, v226, v110
	v_mul_f32_e32 v208, v208, v110
	s_waitcnt lgkmcnt(0)
	v_add_f32_e32 v191, v191, v206
	v_cvt_pk_bf16_f32 v232, v194, v208
	ds_bpermute_b32 v194, v212, v191
	v_mul_f32_e32 v204, v204, v110
	v_mul_f32_e32 v206, v233, v110
	v_cvt_pk_bf16_f32 v233, v206, v204
	v_mul_f32_e32 v204, v223, v110
	s_waitcnt lgkmcnt(0)
	v_add_f32_e32 v191, v191, v194
	v_fmamk_f32 v191, v191, 0x3b800000, v218
	v_mul_f32_e32 v194, 0x4f800000, v191
	v_cmp_gt_f32_e32 vcc, s4, v191
	v_mul_f32_e32 v202, v202, v110
	v_cvt_pk_bf16_f32 v234, v202, v204
	v_mul_f32_e32 v202, v235, v110
	v_cndmask_b32_e32 v191, v191, v194, vcc
	v_sqrt_f32_e32 v194, v191
	v_mul_f32_e32 v110, v217, v110
	v_cvt_pk_bf16_f32 v235, v202, v110
	global_store_dwordx4 v[142:143], v[232:235], off offset:1024
	v_add_u32_e32 v204, -1, v194
	v_fma_f32 v206, -v204, v194, v191
	v_cmp_ge_f32_e64 s[0:1], 0, v206
	v_add_u32_e32 v206, 1, v194
	v_and_b32_e32 v202, 0xffff0000, v135
	v_cndmask_b32_e64 v204, v194, v204, s[0:1]
	v_fma_f32 v194, -v206, v194, v191
	v_cmp_lt_f32_e64 s[0:1], 0, v194
	s_nop 1
	v_cndmask_b32_e64 v194, v204, v206, s[0:1]
	v_mul_f32_e32 v204, 0x37800000, v194
	v_cndmask_b32_e32 v194, v194, v204, vcc
	v_cmp_class_f32_e32 vcc, v191, v219
	s_nop 1
	v_cndmask_b32_e32 v191, v194, v191, vcc
	v_div_scale_f32 v194, s[0:1], v191, v191, 1.0
	v_rcp_f32_e32 v204, v194
	s_nop 0
	v_fma_f32 v110, -v194, v204, 1.0
	v_fmac_f32_e32 v204, v110, v204
	v_div_scale_f32 v110, vcc, 1.0, v191, 1.0
	v_mul_f32_e32 v142, v110, v204
	v_fma_f32 v143, -v194, v142, v110
	v_fmac_f32_e32 v142, v143, v204
	v_fma_f32 v110, -v194, v142, v110
	v_div_fmas_f32 v110, v110, v204, v142
	v_div_fixup_f32 v110, v110, v191, 1.0
	v_mul_f32_e32 v142, v161, v110
	v_mul_f32_e32 v143, v162, v110
	v_cvt_pk_bf16_f32 v232, v142, v143
	v_mul_f32_e32 v142, v170, v110
	v_mul_f32_e32 v140, v140, v110
	v_mul_f32_e32 v143, v178, v110
	v_cvt_pk_bf16_f32 v233, v142, v143
	v_mul_f32_e32 v142, v198, v110
	v_cvt_pk_bf16_f32 v234, v140, v142
	v_mul_f32_e32 v140, v190, v110
	v_lshlrev_b32_e32 v162, 16, v132
	v_and_b32_e32 v170, 0xffff0000, v132
	v_lshlrev_b32_e32 v178, 16, v133
	v_and_b32_e32 v190, 0xffff0000, v133
	v_lshlrev_b32_e32 v198, 16, v135
	v_lshlrev_b32_e32 v132, 16, v124
	v_lshlrev_b32_e32 v133, 16, v128
	v_lshlrev_b32_e32 v191, 16, v134
	v_and_b32_e32 v194, 0xffff0000, v134
	v_pk_mov_b32 v[134:135], v[198:199], v[132:133] op_sel:[1,0]
	v_mul_f32_e32 v108, v108, v110
	v_pk_mul_f32 v[134:135], v[200:201], v[134:135]
	v_cvt_pk_bf16_f32 v235, v140, v108
	v_lshlrev_b32_e32 v108, 16, v136
	v_fma_f32 v134, v116, v209, v134
	v_add_f32_e32 v134, v134, v135
	v_mul_f32_e32 v108, v134, v108
	v_mov_b32_e32 v134, v116
	v_mov_b32_e32 v135, v120
	v_pk_mul_f32 v[132:133], v[134:135], v[132:133]
	v_mov_b32_e32 v120, v117
; __device__ __forceinline__ unsigned pk2(float lo, float hi) { return pg8::cvt_pk_bf16(lo, hi); }
; template <bool DO_SWA, bool DO_MEM>
; __device__ __forceinline__ void attn_unit(const Args& a, unsigned char* ws, LAS unsigned char* lds, int l, int tid_in, int lane_in, int wave, int unit) {
;     ...
;             for (int i = 0; i < 4; ++i) {
;                 float ua[8], ub_[8], uc[8], cbv[8], cy[8];
;                 unpack8(cu[i], ua); unpack8(cu[i + 1], ub_); unpack8(cu[i + 2], uc); unpack8(ccb[i], cbv);
;                 float ss = 0.f;
; #pragma unroll
;                 for (int j = 0; j < 8; ++j) { const float y = ua[j] * w0[j] + ub_[j] * w1[j] + uc[j] * w2[j]; cy[j] = cbv[j] * y; ss += cy[j] * cy[j]; }
;                 ss += __shfl_xor(ss, 1); ss += __shfl_xor(ss, 2); ss += __shfl_xor(ss, 4); ss += __shfl_xor(ss, 8); ss += __shfl_xor(ss, 16);
;                 const float rs = 1.0f / sqrtf(ss * (1.0f / 256.0f) + EPS);
;                 v4u o; o.x = pk2(cy[0] * rs, cy[1] * rs); o.y = pk2(cy[2] * rs, cy[3] * rs); o.z = pk2(cy[4] * rs, cy[5] * rs); o.w = pk2(cy[6] * rs, cy[7] * rs);
;                 *(v4u*)(MIX + (size_t)(row0 + t0 + i) * D + 512 + ch) = o;
	v_fma_f32 v112, v112, v209, v132
	v_add_f32_e32 v112, v112, v133
	v_and_b32_e32 v133, 0xffff0000, v128
	v_and_b32_e32 v132, 0xffff0000, v124
	v_pk_mov_b32 v[134:135], v[182:183], v[132:133] op_sel:[1,0]
	v_mul_f32_e32 v162, v112, v162
	v_pk_mul_f32 v[134:135], v[196:197], v[134:135]
	v_and_b32_e32 v110, 0xffff0000, v136
	v_fma_f32 v112, v117, v207, v134
	v_add_f32_e32 v112, v112, v135
	v_pk_mul_f32 v[116:117], v[120:121], v[132:133]
	v_mul_f32_e32 v110, v112, v110
	v_fma_f32 v112, v113, v207, v116
	v_add_f32_e32 v112, v112, v117
	v_mul_f32_e32 v128, v112, v170
	v_lshlrev_b32_e32 v112, 16, v125
	v_lshlrev_b32_e32 v113, 16, v129
	v_pk_mov_b32 v[116:117], v[178:179], v[112:113] op_sel:[1,0]
	v_lshlrev_b32_e32 v140, 16, v137
	v_pk_mul_f32 v[116:117], v[180:181], v[116:117]
	v_or_b32_e32 v142, 1, v160
	v_fma_f32 v116, v118, v205, v116
	v_add_f32_e32 v116, v116, v117
	v_mul_f32_e32 v133, v116, v140
	v_mov_b32_e32 v116, v118
	v_mov_b32_e32 v117, v122
	v_pk_mul_f32 v[112:113], v[116:117], v[112:113]
	v_ashrrev_i32_e32 v143, 31, v142
	v_fma_f32 v112, v114, v205, v112
	v_add_f32_e32 v112, v112, v113
	v_mul_f32_e32 v134, v112, v178
	v_and_b32_e32 v113, 0xffff0000, v129
	v_and_b32_e32 v112, 0xffff0000, v125
	v_lshlrev_b64 v[142:143], 11, v[142:143]
	v_pk_mov_b32 v[116:117], v[174:175], v[112:113] op_sel:[1,0]
	v_lshl_add_u64 v[142:143], s[20:21], 0, v[142:143]
	v_pk_mul_f32 v[116:117], v[176:177], v[116:117]
	v_lshl_add_u64 v[142:143], v[142:143], 0, v[184:185]
	v_fma_f32 v114, v119, v203, v116
	v_mov_b32_e32 v122, v119
	global_store_dwordx4 v[142:143], v[232:235], off offset:1024
	v_and_b32_e32 v142, 0xffff0000, v137
	v_add_f32_e32 v114, v114, v117
	v_pk_mul_f32 v[112:113], v[122:123], v[112:113]
	v_mul_f32_e32 v125, v114, v142
	v_fma_f32 v112, v115, v203, v112
	v_lshlrev_b32_e32 v114, 16, v126
	v_lshlrev_b32_e32 v115, 16, v130
	v_pk_mov_b32 v[116:117], v[170:171], v[114:115] op_sel:[1,0]
	v_lshlrev_b32_e32 v143, 16, v138
	v_pk_mul_f32 v[116:117], v[172:173], v[116:117]
	v_and_b32_e32 v138, 0xffff0000, v138
	v_fma_f32 v116, v100, v141, v116
	v_add_f32_e32 v116, v116, v117
	v_mul_f32_e32 v129, v116, v143
	v_and_b32_e32 v117, 0xffff0000, v130
	v_and_b32_e32 v116, 0xffff0000, v126
	v_pk_mov_b32 v[118:119], v[166:167], v[116:117] op_sel:[1,0]
	v_lshlrev_b32_e32 v161, 16, v139
	v_pk_mul_f32 v[118:119], v[168:169], v[118:119]
	v_mul_f32_e32 v124, v110, v110
	v_fma_f32 v118, v101, v111, v118
	v_add_f32_e32 v118, v118, v119
	v_mul_f32_e32 v126, v118, v138
	v_lshlrev_b32_e32 v118, 16, v127
	v_lshlrev_b32_e32 v119, 16, v131
	v_pk_mov_b32 v[120:121], v[162:163], v[118:119] op_sel:[1,0]
	v_fmac_f32_e32 v124, v108, v108
	v_pk_mul_f32 v[120:121], v[164:165], v[120:121]
	v_fmac_f32_e32 v124, v133, v133
	v_fma_f32 v120, v102, v195, v120
	v_add_f32_e32 v120, v120, v121
	v_mul_f32_e32 v130, v120, v161
	v_and_b32_e32 v121, 0xffff0000, v131
	v_and_b32_e32 v120, 0xffff0000, v127
	v_pk_mov_b32 v[122:123], v[144:145], v[120:121] op_sel:[1,0]
	v_fmac_f32_e32 v124, v125, v125
	v_pk_mul_f32 v[122:123], v[146:147], v[122:123]
	v_fmac_f32_e32 v124, v129, v129
	v_fma_f32 v122, v103, v109, v122
	v_and_b32_e32 v139, 0xffff0000, v139
	v_fmac_f32_e32 v124, v126, v126
	v_add_f32_e32 v122, v122, v123
	v_fmac_f32_e32 v124, v130, v130
	v_mul_f32_e32 v122, v122, v139
	v_fmac_f32_e32 v124, v122, v122
	ds_bpermute_b32 v123, v231, v124
	v_add_f32_e32 v112, v112, v113
	v_mul_f32_e32 v127, v112, v190
	v_mov_b32_e32 v112, v100
	v_mov_b32_e32 v113, v104
	s_waitcnt lgkmcnt(0)
	v_add_f32_e32 v100, v124, v123
	ds_bpermute_b32 v123, v230, v100
	v_pk_mul_f32 v[112:113], v[112:113], v[114:115]
	v_mov_b32_e32 v104, v101
	v_fma_f32 v96, v96, v141, v112
	v_add_f32_e32 v96, v96, v113
	s_waitcnt lgkmcnt(0)
	v_add_f32_e32 v112, v100, v123
	ds_bpermute_b32 v113, v229, v112
	v_mul_f32_e32 v114, v96, v191
	v_pk_mul_f32 v[100:101], v[104:105], v[116:117]
	v_mul_f32_e32 v132, v128, v128
	v_fma_f32 v97, v97, v111, v100
	s_waitcnt lgkmcnt(0)
	v_add_f32_e32 v96, v112, v113
	ds_bpermute_b32 v104, v159, v96
	v_add_f32_e32 v97, v97, v101
	v_mul_f32_e32 v105, v97, v194
	v_mov_b32_e32 v97, v106
	v_fmac_f32_e32 v132, v162, v162
	s_waitcnt lgkmcnt(0)
	v_add_f32_e32 v100, v96, v104
	ds_bpermute_b32 v101, v212, v100
	v_mov_b32_e32 v96, v102
	v_pk_mul_f32 v[96:97], v[96:97], v[118:119]
	v_fmac_f32_e32 v132, v134, v134
	v_fma_f32 v96, v98, v195, v96
	s_waitcnt lgkmcnt(0)
	v_add_f32_e32 v98, v100, v101
	v_fmamk_f32 v98, v98, 0x3b800000, v218
	v_mul_f32_e32 v100, 0x4f800000, v98
	v_cmp_gt_f32_e32 vcc, s4, v98
	v_add_f32_e32 v96, v96, v97
	v_mul_f32_e32 v102, v96, v198
	v_cndmask_b32_e32 v98, v98, v100, vcc
	v_sqrt_f32_e32 v100, v98
	v_mov_b32_e32 v106, v103
	v_fmac_f32_e32 v132, v127, v127
	v_fmac_f32_e32 v132, v114, v114
	v_add_u32_e32 v96, -1, v100
	v_fma_f32 v97, -v96, v100, v98
	v_cmp_ge_f32_e64 s[0:1], 0, v97
	v_add_u32_e32 v97, 1, v100
	v_fmac_f32_e32 v132, v105, v105
	v_cndmask_b32_e64 v96, v100, v96, s[0:1]
	v_fma_f32 v100, -v97, v100, v98
	v_cmp_lt_f32_e64 s[0:1], 0, v100
	v_fmac_f32_e32 v132, v102, v102
	v_or_b32_e32 v136, 2, v160
	v_cndmask_b32_e64 v96, v96, v97, s[0:1]
	v_mul_f32_e32 v97, 0x37800000, v96
	v_cndmask_b32_e32 v96, v96, v97, vcc
	v_cmp_class_f32_e32 vcc, v98, v219
	v_ashrrev_i32_e32 v137, 31, v136
	v_lshlrev_b64 v[136:137], 11, v[136:137]
	v_cndmask_b32_e32 v98, v96, v98, vcc
	v_pk_mul_f32 v[96:97], v[106:107], v[120:121]
	v_div_scale_f32 v104, s[0:1], v98, v98, 1.0
	v_fma_f32 v96, v99, v109, v96
	v_add_f32_e32 v96, v96, v97
	v_mul_f32_e32 v103, v96, v202
	v_fmac_f32_e32 v132, v103, v103
	v_rcp_f32_e32 v111, v104
	ds_bpermute_b32 v99, v231, v132
	v_lshl_add_u64 v[96:97], s[20:21], 0, v[136:137]
	v_lshl_add_u64 v[100:101], v[96:97], 0, v[184:185]
	v_fma_f32 v96, -v104, v111, 1.0
	v_fmac_f32_e32 v111, v96, v111
	s_waitcnt lgkmcnt(0)
; #define LAS __attribute__((address_space(3)))
; #define LAS __attribute__((address_space(3)))
; __device__ __forceinline__ unsigned pk2(float lo, float hi) { return pg8::cvt_pk_bf16(lo, hi); }
; template <bool DO_SWA, bool DO_MEM>
; __device__ __forceinline__ void attn_unit(const Args& a, unsigned char* ws, LAS unsigned char* lds, int l, int tid_in, int lane_in, int wave, int unit) {
;     ...
;                 const float rs = 1.0f / sqrtf(ss * (1.0f / 256.0f) + EPS);
;                 v4u o; o.x = pk2(cy[0] * rs, cy[1] * rs); o.y = pk2(cy[2] * rs, cy[3] * rs); o.z = pk2(cy[4] * rs, cy[5] * rs); o.w = pk2(cy[6] * rs, cy[7] * rs);
;                 *(v4u*)(MIX + (size_t)(row0 + t0 + i) * D + 512 + ch) = o;
;             }
;         }
;         if constexpr (DO_SWA)
; #pragma unroll
;         for (int i = 0; i < 6; ++i) {
;             const int s = i >> 1, rem = tid + 512 * (i & 1);
;             { const int key = rem >> 4, c16 = rem & 15; *(LAS v4u*)(lds + A_KS + ((c16 >> 3) * 192 + s * 64 + key) * 144 + (c16 & 7) * 16) = kst[i]; }
;             { const int col = rem >> 3, kc = rem & 7; *(LAS v4u*)(lds + A_VT1 + col * 400 + (s * 64 + kc * 8) * 2) = vst[i]; }
;         }
;         const bf16* MKb = (const bf16*)(ws + WS_MK) + (size_t)(l * 40 + bb) * 65536;
;         const bf16* MVTb = (const bf16*)(ws + WS_MVT) + (size_t)(l * 40 + bb) * 65536;
;         v4u mkst[8], mvst[8];
;         __builtin_amdgcn_sched_barrier(0);
;         __syncthreads();
	v_add_f32_e32 v96, v132, v99
	ds_bpermute_b32 v97, v230, v96
	v_div_scale_f32 v99, vcc, 1.0, v98, 1.0
	v_mul_f32_e32 v106, v99, v111
	v_fma_f32 v107, -v104, v106, v99
	s_waitcnt lgkmcnt(0)
	v_add_f32_e32 v96, v96, v97
	ds_bpermute_b32 v97, v229, v96
	v_fmac_f32_e32 v106, v107, v111
	v_fma_f32 v99, -v104, v106, v99
	v_div_fmas_f32 v99, v99, v111, v106
	v_div_fixup_f32 v99, v99, v98, 1.0
	s_waitcnt lgkmcnt(0)
	v_add_f32_e32 v97, v96, v97
	ds_bpermute_b32 v104, v159, v97
	v_mul_f32_e32 v96, v108, v99
	v_mul_f32_e32 v98, v110, v99
	v_cvt_pk_bf16_f32 v96, v96, v98
	v_mul_f32_e32 v106, v125, v99
	s_waitcnt lgkmcnt(0)
	v_add_f32_e32 v98, v97, v104
	ds_bpermute_b32 v104, v212, v98
	v_mul_f32_e32 v97, v133, v99
	v_cvt_pk_bf16_f32 v97, v97, v106
	v_mul_f32_e32 v106, v129, v99
	s_waitcnt lgkmcnt(0)
	v_add_f32_e32 v98, v98, v104
	v_fmamk_f32 v98, v98, 0x3b800000, v218
	v_mul_f32_e32 v104, 0x4f800000, v98
	v_cmp_gt_f32_e32 vcc, s4, v98
	s_movk_i32 s4, 0x90
	s_nop 0
	v_cndmask_b32_e32 v104, v98, v104, vcc
	v_sqrt_f32_e32 v107, v104
	v_mul_f32_e32 v98, v126, v99
	v_cvt_pk_bf16_f32 v98, v106, v98
	v_mul_f32_e32 v106, v130, v99
	v_add_u32_e32 v108, -1, v107
	v_fma_f32 v109, -v108, v107, v104
	v_cmp_ge_f32_e64 s[0:1], 0, v109
	v_add_u32_e32 v109, 1, v107
	v_mul_f32_e32 v99, v122, v99
	v_cndmask_b32_e64 v108, v107, v108, s[0:1]
	v_fma_f32 v107, -v109, v107, v104
	v_cmp_lt_f32_e64 s[0:1], 0, v107
	v_cvt_pk_bf16_f32 v99, v106, v99
	global_store_dwordx4 v[100:101], v[96:99], off offset:1024
	s_nop 0
	v_cndmask_b32_e64 v107, v108, v109, s[0:1]
	v_mul_f32_e32 v108, 0x37800000, v107
	v_cndmask_b32_e32 v107, v107, v108, vcc
	v_cmp_class_f32_e32 vcc, v104, v219
	s_nop 1
	v_cndmask_b32_e32 v104, v107, v104, vcc
	v_div_scale_f32 v107, s[0:1], v104, v104, 1.0
	v_rcp_f32_e32 v108, v107
	s_nop 0
	v_fma_f32 v96, -v107, v108, 1.0
	v_fmac_f32_e32 v108, v96, v108
	v_div_scale_f32 v96, vcc, 1.0, v104, 1.0
	v_mul_f32_e32 v97, v96, v108
	v_fma_f32 v98, -v107, v97, v96
	v_fmac_f32_e32 v97, v98, v108
	v_fma_f32 v96, -v107, v97, v96
	v_div_fmas_f32 v96, v96, v108, v97
	v_div_fixup_f32 v99, v96, v104, 1.0
	v_mul_f32_e32 v96, v162, v99
	v_mul_f32_e32 v97, v128, v99
	v_cvt_pk_bf16_f32 v96, v96, v97
	v_mul_f32_e32 v97, v134, v99
	v_mul_f32_e32 v98, v127, v99
	v_cvt_pk_bf16_f32 v97, v97, v98
	v_mul_f32_e32 v98, v114, v99
	v_mul_f32_e32 v100, v105, v99
	v_cvt_pk_bf16_f32 v98, v98, v100
	v_mul_f32_e32 v100, v102, v99
	v_mul_f32_e32 v99, v103, v99
	v_cvt_pk_bf16_f32 v99, v100, v99
	v_or_b32_e32 v100, 3, v160
	v_ashrrev_i32_e32 v101, 31, v100
	v_lshlrev_b64 v[100:101], 11, v[100:101]
	v_lshl_add_u64 v[100:101], s[20:21], 0, v[100:101]
	v_lshl_add_u64 v[100:101], v[100:101], 0, v[184:185]
	global_store_dwordx4 v[100:101], v[96:99], off offset:1024
	v_lshlrev_b32_e32 v104, 4, v213
	s_nop 0
	v_bfe_i32 v96, v213, 3, 1
	v_and_b32_e32 v98, 0xc0, v96
	v_and_b32_e32 v96, 0x70, v104
	v_add_u32_e32 v100, 0, v96
	v_add_u32_e32 v96, v98, v148
	v_mad_u64_u32 v[96:97], s[0:1], v96, s4, v[100:101]
	ds_write_b128 v96, v[28:31]
	v_mul_lo_u32 v28, v157, s5
	v_add3_u32 v28, 0, v28, v158
	ds_write_b128 v28, v[24:27] offset:55296
	v_add_u32_e32 v24, v98, v152
	v_mad_u64_u32 v[24:25], s[0:1], v24, s4, v[100:101]
	ds_write_b128 v24, v[60:63]
	v_mul_lo_u32 v24, v227, s5
	v_add_u32_e32 v27, 64, v98
	v_add3_u32 v26, 0, v24, v158
	v_add_u32_e32 v24, v27, v148
	v_mad_u64_u32 v[24:25], s[0:1], v24, s4, v[100:101]
	ds_write_b128 v26, v[56:59] offset:55296
	ds_write_b128 v24, v[68:71]
	ds_write_b128 v28, v[64:67] offset:55424
	v_add_u32_e32 v24, v27, v152
	v_mad_u64_u32 v[24:25], s[0:1], v24, s4, v[100:101]
	v_add_u32_e32 v27, 0x80, v98
	ds_write_b128 v24, v[72:75]
	ds_write_b128 v26, v[76:79] offset:55424
	v_add_u32_e32 v24, v27, v148
	v_mad_u64_u32 v[24:25], s[0:1], v24, s4, v[100:101]
	ds_write_b128 v24, v[80:83]
	ds_write_b128 v28, v[84:87] offset:55552
	v_add_u32_e32 v24, v27, v152
	v_mad_u64_u32 v[24:25], s[0:1], v24, s4, v[100:101]
	ds_write_b128 v24, v[88:91]
	ds_write_b128 v26, v[92:95] offset:55552
	v_readlane_b32 s0, v251, 22
	v_and_b32_e32 v101, -16, v210
	v_and_b32_e32 v25, 3, v210
	v_or_b32_e32 v102, s0, v228
	v_mul_lo_u32 v24, v102, s5
	v_add3_u32 v106, 0, v24, v101
	v_lshlrev_b32_e32 v24, 1, v228
	v_and_or_b32 v24, v24, 24, v25
	v_xor_b32_e32 v56, 32, v222
	v_mul_u32_u24_e32 v103, 0x90, v24
	v_readlane_b32 s0, v251, 24
	v_cmp_lt_i32_e32 vcc, v56, v151
	s_waitcnt lgkmcnt(0)
	v_add3_u32 v107, s0, v101, v103
	v_cndmask_b32_e32 v56, v222, v56, vcc
	s_barrier
; #define LAS __attribute__((address_space(3)))
; #define LAS __attribute__((address_space(3)))
; __device__ __forceinline__ f32x4 mfma16(bf16x8 a, bf16x8 b, f32x4 c) { return __builtin_amdgcn_mfma_f32_16x16x32_bf16(a, b, c, 0, 0, 0); }
; template <int NKT, int VSTR, bool SINK>
; __device__ __forceinline__ void attn_core(LAS const unsigned char* kb_, LAS const unsigned char* vb_, bf16x8 q0, bf16x8 q1, float sk, unsigned mskbits, int fr, f32x4 (&o)[4]) {
;     ...
;     const int krow = ((fr >> 2) << 3) + (fr & 3);
; #pragma unroll
;     for (int kt = 0; kt < NKT; ++kt) {
;         const int key = (kt >> 1) * 32 + ((kt & 1) << 2) + krow;
;         LAS const unsigned char* kp = kb_ + key * 144;
;         const bf16x8 a0 = *(LAS const bf16x8*)kp, a1 = *(LAS const bf16x8*)(kp + 64);
;         const float bias = ((mskbits >> (kt >> 2)) & 1u) ? -1e30f : 0.f;
;         f32x4 s = mfma16(a0, q0, (f32x4){bias, bias, bias, bias});
;         s = mfma16(a1, q1, s);
;         S[kt] = s;
;     }
;     float mx = S[0][0];
; #pragma unroll
;     for (int kt = 0; kt < NKT; ++kt) mx = fmaxf(fmaxf(mx, fmaxf(S[kt][0], S[kt][1])), fmaxf(S[kt][2], S[kt][3]));
;     mx = fmaxf(mx, __shfl_xor(mx, 16)); mx = fmaxf(mx, __shfl_xor(mx, 32));
	v_lshlrev_b32_e32 v176, 2, v56
	global_load_dword v108, v185, s[12:13]
	s_waitcnt lgkmcnt(0)
	ds_read_b128 v[120:123], v107
	ds_read_b128 v[124:127], v107 offset:64
	ds_read_b128 v[128:131], v107 offset:576
	ds_read_b128 v[132:135], v107 offset:640
	ds_read_b128 v[136:139], v107 offset:4608
	ds_read_b128 v[140:143], v107 offset:4672
	ds_read_b128 v[144:147], v107 offset:5184
	ds_read_b128 v[160:163], v107 offset:5248
	ds_read_b128 v[164:167], v107 offset:9216
	ds_read_b128 v[168:171], v107 offset:9280
	ds_read_b128 v[172:175], v107 offset:9792
	ds_read_b128 v[180:183], v107 offset:9856
	ds_read_b128 v[196:199], v107 offset:13824
	ds_read_b128 v[200:203], v107 offset:13888
	v_mov_b32_e32 v24, 0xf149f2ca
	v_cndmask_b32_e64 v28, v24, 0, s[2:3]
	v_mov_b32_e32 v29, v28
	v_mov_b32_e32 v30, v28
	v_mov_b32_e32 v31, v28
	v_cndmask_b32_e64 v24, 0, v24, s[36:37]
	v_mov_b32_e32 v25, v24
	s_waitcnt lgkmcnt(13)
	v_mfma_f32_16x16x32_bf16 v[56:59], v[120:123], v[48:51], v[28:31]
	v_mov_b32_e32 v26, v24
	v_mov_b32_e32 v27, v24
	s_mov_b32 s2, 0x3fb8aa3b
	s_waitcnt lgkmcnt(12)
	v_mfma_f32_16x16x32_bf16 v[96:99], v[124:127], v[52:55], v[56:59]
	ds_read_b128 v[204:207], v107 offset:14400
	ds_read_b128 v[224:227], v107 offset:14464
	v_add_u32_e32 v105, 0xd800, v106
	v_cmp_gt_u32_e64 s[36:37], 16, v210
	s_waitcnt lgkmcnt(13)
	v_mfma_f32_16x16x32_bf16 v[56:59], v[128:131], v[48:51], v[28:31]
	s_waitcnt vmcnt(0)
	v_mul_f32_e32 v109, 0x3fb8aa3b, v108
	s_waitcnt lgkmcnt(12)
	v_mfma_f32_16x16x32_bf16 v[92:95], v[132:135], v[52:55], v[56:59]
	ds_read_b128 v[232:235], v107 offset:18432
	ds_read_b128 v[236:239], v107 offset:18496
	s_waitcnt lgkmcnt(13)
	v_mfma_f32_16x16x32_bf16 v[56:59], v[136:139], v[48:51], v[28:31]
	s_waitcnt lgkmcnt(12)
	v_mfma_f32_16x16x32_bf16 v[88:91], v[140:143], v[52:55], v[56:59]
	ds_read_b128 v[240:243], v107 offset:19008
	ds_read_b128 v[244:247], v107 offset:19072
	s_waitcnt lgkmcnt(13)
	v_mfma_f32_16x16x32_bf16 v[56:59], v[144:147], v[48:51], v[28:31]
	s_waitcnt lgkmcnt(12)
	v_mfma_f32_16x16x32_bf16 v[84:87], v[160:163], v[52:55], v[56:59]
	ds_read_b128 v[120:123], v107 offset:23040
	ds_read_b128 v[124:127], v107 offset:23104
	s_waitcnt lgkmcnt(13)
	v_mfma_f32_16x16x32_bf16 v[56:59], v[164:167], v[48:51], v[24:27]
	s_waitcnt lgkmcnt(12)
	v_mfma_f32_16x16x32_bf16 v[80:83], v[168:171], v[52:55], v[56:59]
	ds_read_b128 v[128:131], v107 offset:23616
	ds_read_b128 v[132:135], v107 offset:23680
	s_waitcnt lgkmcnt(13)
	v_mfma_f32_16x16x32_bf16 v[56:59], v[172:175], v[48:51], v[24:27]
	s_waitcnt lgkmcnt(12)
	v_mfma_f32_16x16x32_bf16 v[76:79], v[180:183], v[52:55], v[56:59]
	s_waitcnt lgkmcnt(11)
	v_mfma_f32_16x16x32_bf16 v[56:59], v[196:199], v[48:51], v[24:27]
	s_waitcnt lgkmcnt(10)
	v_mfma_f32_16x16x32_bf16 v[72:75], v[200:203], v[52:55], v[56:59]
	s_waitcnt lgkmcnt(9)
	v_mfma_f32_16x16x32_bf16 v[56:59], v[204:207], v[48:51], v[24:27]
	s_waitcnt lgkmcnt(8)
	v_mfma_f32_16x16x32_bf16 v[68:71], v[224:227], v[52:55], v[56:59]
	s_waitcnt lgkmcnt(7)
	v_mfma_f32_16x16x32_bf16 v[56:59], v[232:235], v[48:51], 0
	s_waitcnt lgkmcnt(6)
	v_mfma_f32_16x16x32_bf16 v[64:67], v[236:239], v[52:55], v[56:59]
	s_waitcnt lgkmcnt(5)
	v_mfma_f32_16x16x32_bf16 v[56:59], v[240:243], v[48:51], 0
	s_waitcnt lgkmcnt(4)
	v_mfma_f32_16x16x32_bf16 v[60:63], v[244:247], v[52:55], v[56:59]
	s_waitcnt lgkmcnt(3)
	v_mfma_f32_16x16x32_bf16 v[56:59], v[120:123], v[48:51], 0
	s_waitcnt lgkmcnt(2)
	v_mfma_f32_16x16x32_bf16 v[56:59], v[124:127], v[52:55], v[56:59]
	s_waitcnt lgkmcnt(1)
	v_mfma_f32_16x16x32_bf16 v[48:51], v[128:131], v[48:51], 0
	s_waitcnt lgkmcnt(0)
	v_mfma_f32_16x16x32_bf16 v[48:51], v[132:135], v[52:55], v[48:51]
	v_max_f32_e32 v52, v99, v99
	v_max_f32_e32 v53, v98, v98
	v_max_f32_e32 v52, v53, v52
	v_max_f32_e32 v53, v93, v93
	v_max_f32_e32 v54, v92, v92
	v_max_f32_e32 v53, v54, v53
	v_max_f32_e32 v54, v95, v95
	v_max_f32_e32 v55, v94, v94
	v_max3_f32 v52, v96, v97, v52
	v_max_f32_e32 v54, v55, v54
	v_max3_f32 v52, v52, v53, v54
	v_max_f32_e32 v53, v89, v89
	v_max_f32_e32 v54, v88, v88
	v_max_f32_e32 v53, v54, v53
	v_max_f32_e32 v54, v91, v91
	v_max_f32_e32 v55, v90, v90
	v_max_f32_e32 v54, v55, v54
	v_max3_f32 v52, v52, v53, v54
	v_max_f32_e32 v53, v85, v85
	v_max_f32_e32 v54, v84, v84
	v_max_f32_e32 v53, v54, v53
	v_max_f32_e32 v54, v87, v87
	v_max_f32_e32 v55, v86, v86
	v_max_f32_e32 v54, v55, v54
	v_max3_f32 v52, v52, v53, v54
	v_max_f32_e32 v53, v81, v81
	v_max_f32_e32 v54, v80, v80
	v_max_f32_e32 v53, v54, v53
	v_max_f32_e32 v54, v83, v83
	v_max_f32_e32 v55, v82, v82
	v_max_f32_e32 v54, v55, v54
	v_max3_f32 v52, v52, v53, v54
	v_max_f32_e32 v53, v77, v77
	v_max_f32_e32 v54, v76, v76
	v_max_f32_e32 v53, v54, v53
	v_max_f32_e32 v54, v79, v79
	v_max_f32_e32 v55, v78, v78
	v_max_f32_e32 v54, v55, v54
	v_max3_f32 v52, v52, v53, v54
	v_max_f32_e32 v53, v73, v73
	v_max_f32_e32 v54, v72, v72
	v_max_f32_e32 v53, v54, v53
	v_max_f32_e32 v54, v75, v75
	v_max_f32_e32 v55, v74, v74
	v_max_f32_e32 v54, v55, v54
	v_max3_f32 v52, v52, v53, v54
	v_max_f32_e32 v53, v69, v69
	v_max_f32_e32 v54, v68, v68
	v_max_f32_e32 v53, v54, v53
	v_max_f32_e32 v54, v71, v71
	v_max_f32_e32 v55, v70, v70
	v_max_f32_e32 v54, v55, v54
	v_max3_f32 v52, v52, v53, v54
	v_max_f32_e32 v53, v65, v65
	v_max_f32_e32 v54, v64, v64
	v_max_f32_e32 v53, v54, v53
	v_max_f32_e32 v54, v67, v67
	v_max_f32_e32 v55, v66, v66
	v_max_f32_e32 v54, v55, v54
	v_max3_f32 v52, v52, v53, v54
	v_max_f32_e32 v53, v61, v61
	v_max_f32_e32 v54, v60, v60
	v_max_f32_e32 v53, v54, v53
	v_max_f32_e32 v54, v63, v63
	v_max_f32_e32 v55, v62, v62
	v_max_f32_e32 v54, v55, v54
	v_max3_f32 v52, v52, v53, v54
	v_max_f32_e32 v53, v57, v57
	v_max_f32_e32 v54, v56, v56
	v_max_f32_e32 v53, v54, v53
	v_max_f32_e32 v54, v59, v59
	v_max_f32_e32 v55, v58, v58
	v_max_f32_e32 v54, v55, v54
	v_max3_f32 v52, v52, v53, v54
	v_max_f32_e32 v53, v49, v49
	v_max_f32_e32 v54, v48, v48
	v_max_f32_e32 v53, v54, v53
	v_max_f32_e32 v54, v51, v51
	v_max_f32_e32 v55, v50, v50
	v_max_f32_e32 v54, v55, v54
	v_max3_f32 v52, v52, v53, v54
	ds_bpermute_b32 v53, v212, v52
	s_waitcnt lgkmcnt(0)
; #define LAS __attribute__((address_space(3)))
; #define LAS __attribute__((address_space(3)))
; __device__ __forceinline__ unsigned pk2(float lo, float hi) { return pg8::cvt_pk_bf16(lo, hi); }
; __device__ __forceinline__ f32x4 mfma16(bf16x8 a, bf16x8 b, f32x4 c) { return __builtin_amdgcn_mfma_f32_16x16x32_bf16(a, b, c, 0, 0, 0); }
; template <int NKT, int VSTR, bool SINK>
; __device__ __forceinline__ void attn_core(LAS const unsigned char* kb_, LAS const unsigned char* vb_, bf16x8 q0, bf16x8 q1, float sk, unsigned mskbits, int fr, f32x4 (&o)[4]) {
;     ...
;     mx = fmaxf(mx, __shfl_xor(mx, 16)); mx = fmaxf(mx, __shfl_xor(mx, 32));
;     if (SINK) mx = fmaxf(mx, sk);
;     float sum = 0.f;
; #pragma unroll
;     for (int kt = 0; kt < NKT; ++kt)
; #pragma unroll
;         for (int r = 0; r < 4; ++r) { const float p = __builtin_amdgcn_exp2f(S[kt][r] - mx); S[kt][r] = p; sum += p; }
;     sum += __shfl_xor(sum, 16); sum += __shfl_xor(sum, 32);
;     if (SINK) sum += __builtin_amdgcn_exp2f(sk - mx);
;     const float inv = 1.0f / sum;
;     bf16x8 pf[NKT / 2];
; #pragma unroll
;     for (int kb = 0; kb < NKT / 2; ++kb) {
;         v4u w; w.x = pk2(S[2 * kb][0], S[2 * kb][1]); w.y = pk2(S[2 * kb][2], S[2 * kb][3]); w.z = pk2(S[2 * kb + 1][0], S[2 * kb + 1][1]); w.w = pk2(S[2 * kb + 1][2], S[2 * kb + 1][3]);
;         pf[kb] = __builtin_bit_cast(bf16x8, w);
;     }
; #pragma unroll
;     for (int dt = 0; dt < 4; ++dt) {
;         f32x4 acc = (f32x4){0.f, 0.f, 0.f, 0.f};
; #pragma unroll
;         for (int kb = 0; kb < NKT / 2; ++kb) {
;             const bf16x8 vf = *(LAS const bf16x8*)(vb_ + dt * 16 * VSTR + kb * 64);
;             acc = mfma16(vf, pf[kb], acc);
;         }
;         o[dt] = acc * inv;
;     }
	v_max_f32_e32 v53, v53, v53
	v_max_f32_e32 v52, v52, v53
	ds_bpermute_b32 v53, v176, v52
	s_waitcnt lgkmcnt(0)
	v_max3_f32 v52, v52, v53, v109
	v_sub_f32_e32 v53, v96, v52
	v_exp_f32_e32 v53, v53
	v_sub_f32_e32 v55, v97, v52
	v_exp_f32_e32 v55, v55
	v_sub_f32_e32 v96, v98, v52
	v_exp_f32_e32 v96, v96
	v_sub_f32_e32 v97, v99, v52
	v_exp_f32_e32 v97, v97
	v_sub_f32_e32 v92, v92, v52
	v_add_f32_e32 v54, 0, v53
	v_exp_f32_e32 v92, v92
	v_sub_f32_e32 v93, v93, v52
	v_add_f32_e32 v54, v55, v54
	v_exp_f32_e32 v93, v93
	v_sub_f32_e32 v94, v94, v52
	v_add_f32_e32 v54, v96, v54
	v_exp_f32_e32 v94, v94
	v_sub_f32_e32 v95, v95, v52
	v_add_f32_e32 v54, v97, v54
	v_exp_f32_e32 v95, v95
	v_sub_f32_e32 v88, v88, v52
	v_add_f32_e32 v54, v92, v54
	v_exp_f32_e32 v88, v88
	v_sub_f32_e32 v89, v89, v52
	v_add_f32_e32 v54, v93, v54
	v_exp_f32_e32 v89, v89
	v_sub_f32_e32 v90, v90, v52
	v_add_f32_e32 v54, v94, v54
	v_exp_f32_e32 v90, v90
	v_sub_f32_e32 v91, v91, v52
	v_add_f32_e32 v54, v95, v54
	v_exp_f32_e32 v91, v91
	v_sub_f32_e32 v84, v84, v52
	v_add_f32_e32 v54, v88, v54
	v_exp_f32_e32 v84, v84
	v_sub_f32_e32 v85, v85, v52
	v_add_f32_e32 v54, v89, v54
	v_exp_f32_e32 v85, v85
	v_sub_f32_e32 v86, v86, v52
	v_add_f32_e32 v54, v90, v54
	v_exp_f32_e32 v86, v86
	v_sub_f32_e32 v87, v87, v52
	v_add_f32_e32 v54, v91, v54
	v_exp_f32_e32 v87, v87
	v_sub_f32_e32 v80, v80, v52
	v_add_f32_e32 v54, v84, v54
	v_exp_f32_e32 v80, v80
	v_sub_f32_e32 v81, v81, v52
	v_add_f32_e32 v54, v85, v54
	v_exp_f32_e32 v81, v81
	v_sub_f32_e32 v82, v82, v52
	v_add_f32_e32 v54, v86, v54
	v_exp_f32_e32 v82, v82
	v_sub_f32_e32 v83, v83, v52
	v_add_f32_e32 v54, v87, v54
	v_exp_f32_e32 v83, v83
	v_sub_f32_e32 v76, v76, v52
	v_add_f32_e32 v54, v80, v54
	v_exp_f32_e32 v76, v76
	v_sub_f32_e32 v77, v77, v52
	v_add_f32_e32 v54, v81, v54
	v_exp_f32_e32 v77, v77
	v_sub_f32_e32 v78, v78, v52
	v_add_f32_e32 v54, v82, v54
	v_exp_f32_e32 v78, v78
	v_sub_f32_e32 v79, v79, v52
	v_add_f32_e32 v54, v83, v54
	v_exp_f32_e32 v79, v79
	v_sub_f32_e32 v72, v72, v52
	v_add_f32_e32 v54, v76, v54
	v_exp_f32_e32 v72, v72
	v_sub_f32_e32 v73, v73, v52
	v_add_f32_e32 v54, v77, v54
	v_exp_f32_e32 v73, v73
	v_sub_f32_e32 v74, v74, v52
	v_add_f32_e32 v54, v78, v54
	v_exp_f32_e32 v74, v74
	v_sub_f32_e32 v75, v75, v52
	v_add_f32_e32 v54, v79, v54
	v_exp_f32_e32 v75, v75
	v_sub_f32_e32 v68, v68, v52
	v_add_f32_e32 v54, v72, v54
	v_exp_f32_e32 v98, v68
	v_sub_f32_e32 v68, v69, v52
	v_add_f32_e32 v54, v73, v54
	v_exp_f32_e32 v99, v68
	v_sub_f32_e32 v68, v70, v52
	v_add_f32_e32 v54, v74, v54
	v_exp_f32_e32 v109, v68
	v_sub_f32_e32 v68, v71, v52
	v_add_f32_e32 v54, v75, v54
	v_exp_f32_e32 v110, v68
	v_sub_f32_e32 v64, v64, v52
	v_add_f32_e32 v54, v98, v54
	v_exp_f32_e32 v111, v64
	v_sub_f32_e32 v64, v65, v52
	v_add_f32_e32 v54, v99, v54
	v_exp_f32_e32 v112, v64
	v_sub_f32_e32 v64, v66, v52
	v_add_f32_e32 v54, v109, v54
	v_exp_f32_e32 v113, v64
	v_sub_f32_e32 v64, v67, v52
	v_add_f32_e32 v54, v110, v54
	v_exp_f32_e32 v114, v64
	v_sub_f32_e32 v60, v60, v52
	v_add_f32_e32 v54, v111, v54
	v_exp_f32_e32 v115, v60
	v_sub_f32_e32 v60, v61, v52
	v_add_f32_e32 v54, v112, v54
	v_exp_f32_e32 v116, v60
	v_sub_f32_e32 v60, v62, v52
	v_add_f32_e32 v54, v113, v54
	v_exp_f32_e32 v117, v60
	v_sub_f32_e32 v60, v63, v52
	v_add_f32_e32 v54, v114, v54
	v_exp_f32_e32 v118, v60
	v_sub_f32_e32 v56, v56, v52
	v_add_f32_e32 v54, v115, v54
	v_exp_f32_e32 v119, v56
	v_sub_f32_e32 v56, v57, v52
	v_add_f32_e32 v54, v116, v54
	v_exp_f32_e32 v120, v56
	v_sub_f32_e32 v56, v58, v52
	v_add_f32_e32 v54, v117, v54
	v_exp_f32_e32 v121, v56
	v_sub_f32_e32 v56, v59, v52
	v_add_f32_e32 v54, v118, v54
	v_exp_f32_e32 v122, v56
	v_sub_f32_e32 v48, v48, v52
	v_add_f32_e32 v54, v119, v54
	v_exp_f32_e32 v123, v48
	v_sub_f32_e32 v49, v49, v52
	v_add_f32_e32 v54, v120, v54
	v_exp_f32_e32 v124, v49
	v_sub_f32_e32 v49, v50, v52
	v_add_f32_e32 v54, v121, v54
	v_exp_f32_e32 v125, v49
	v_sub_f32_e32 v49, v51, v52
	v_add_f32_e32 v54, v122, v54
	v_exp_f32_e32 v51, v49
	v_add_f32_e32 v48, v123, v54
	v_add_f32_e32 v48, v124, v48
	v_add_f32_e32 v48, v125, v48
	v_add_f32_e32 v48, v51, v48
	ds_bpermute_b32 v49, v212, v48
	v_cvt_pk_bf16_f32 v68, v53, v55
	v_cvt_pk_bf16_f32 v69, v96, v97
	v_cvt_pk_bf16_f32 v70, v92, v93
	v_cvt_pk_bf16_f32 v71, v94, v95
	s_waitcnt lgkmcnt(0)
	v_add_f32_e32 v48, v48, v49
	ds_bpermute_b32 v49, v176, v48
	v_cvt_pk_bf16_f32 v64, v88, v89
	v_cvt_pk_bf16_f32 v65, v90, v91
	v_cvt_pk_bf16_f32 v66, v84, v85
	v_cvt_pk_bf16_f32 v67, v86, v87
	s_waitcnt lgkmcnt(0)
	v_add_f32_e32 v48, v48, v49
	v_fma_f32 v49, v108, s2, -v52
	v_exp_f32_e32 v49, v49
	v_cvt_pk_bf16_f32 v60, v80, v81
	v_cvt_pk_bf16_f32 v61, v82, v83
	v_cvt_pk_bf16_f32 v62, v76, v77
	v_cvt_pk_bf16_f32 v63, v78, v79
	v_cvt_pk_bf16_f32 v56, v72, v73
	s_nop 0
	v_add_f32_e32 v108, v49, v48
	v_div_scale_f32 v72, s[0:1], v108, v108, 1.0
	v_rcp_f32_e32 v73, v72
	v_cvt_pk_bf16_f32 v57, v74, v75
	v_cvt_pk_bf16_f32 v58, v98, v99
	v_cvt_pk_bf16_f32 v59, v109, v110
	v_cvt_pk_bf16_f32 v52, v111, v112
	v_cvt_pk_bf16_f32 v53, v113, v114
	s_nop 0
	v_fma_f32 v74, -v72, v73, 1.0
	v_fmac_f32_e32 v73, v74, v73
	v_div_scale_f32 v74, vcc, 1.0, v108, 1.0
	v_mul_f32_e32 v75, v74, v73
	v_fma_f32 v76, -v72, v75, v74
	v_fmac_f32_e32 v75, v76, v73
	v_fma_f32 v72, -v72, v75, v74
	v_cvt_pk_bf16_f32 v54, v115, v116
	v_cvt_pk_bf16_f32 v55, v117, v118
	v_cvt_pk_bf16_f32 v48, v119, v120
	v_cvt_pk_bf16_f32 v49, v121, v122
	v_cvt_pk_bf16_f32 v50, v123, v124
	v_cvt_pk_bf16_f32 v51, v125, v51
	v_div_fmas_f32 v72, v72, v73, v75
	s_waitcnt lgkmcnt(0)
; #define LAS __attribute__((address_space(3)))
; #define LAS __attribute__((address_space(3)))
; template <int NKT, int VSTR, bool SINK>
; __device__ __forceinline__ void attn_core(LAS const unsigned char* kb_, LAS const unsigned char* vb_, bf16x8 q0, bf16x8 q1, float sk, unsigned mskbits, int fr, f32x4 (&o)[4]) {
;     ...
;     for (int kt = 0; kt < NKT; ++kt) {
;         const int key = (kt >> 1) * 32 + ((kt & 1) << 2) + krow;
;         LAS const unsigned char* kp = kb_ + key * 144;
;         const bf16x8 a0 = *(LAS const bf16x8*)kp, a1 = *(LAS const bf16x8*)(kp + 64);
;         const float bias = ((mskbits >> (kt >> 2)) & 1u) ? -1e30f : 0.f;
;         f32x4 s = mfma16(a0, q0, (f32x4){bias, bias, bias, bias});
;         s = mfma16(a1, q1, s);
;         S[kt] = s;
;     }
;     float mx = S[0][0];
; #pragma unroll
;     for (int kt = 0; kt < NKT; ++kt) mx = fmaxf(fmaxf(mx, fmaxf(S[kt][0], S[kt][1])), fmaxf(S[kt][2], S[kt][3]));
;     mx = fmaxf(mx, __shfl_xor(mx, 16)); mx = fmaxf(mx, __shfl_xor(mx, 32));
;     if (SINK) mx = fmaxf(mx, sk);
;     float sum = 0.f;
; #pragma unroll
;     for (int kt = 0; kt < NKT; ++kt)
; #pragma unroll
;         for (int r = 0; r < 4; ++r) { const float p = __builtin_amdgcn_exp2f(S[kt][r] - mx); S[kt][r] = p; sum += p; }
;     sum += __shfl_xor(sum, 16); sum += __shfl_xor(sum, 32);
;     if (SINK) sum += __builtin_amdgcn_exp2f(sk - mx);
;     const float inv = 1.0f / sum;
;     bf16x8 pf[NKT / 2];
; #pragma unroll
;     for (int kb = 0; kb < NKT / 2; ++kb) {
;         v4u w; w.x = pk2(S[2 * kb][0], S[2 * kb][1]); w.y = pk2(S[2 * kb][2], S[2 * kb][3]); w.z = pk2(S[2 * kb + 1][0], S[2 * kb + 1][1]); w.w = pk2(S[2 * kb + 1][2], S[2 * kb + 1][3]);
;         pf[kb] = __builtin_bit_cast(bf16x8, w);
;     }
; #pragma unroll
;     for (int dt = 0; dt < 4; ++dt) {
;         f32x4 acc = (f32x4){0.f, 0.f, 0.f, 0.f};
; #pragma unroll
;         for (int kb = 0; kb < NKT / 2; ++kb) {
;             const bf16x8 vf = *(LAS const bf16x8*)(vb_ + dt * 16 * VSTR + kb * 64);
;             acc = mfma16(vf, pf[kb], acc);
;         }
;         o[dt] = acc * inv;
;     }
; template <bool DO_SWA, bool DO_MEM>
; __device__ __forceinline__ void attn_unit(const Args& a, unsigned char* ws, LAS unsigned char* lds, int l, int tid_in, int lane_in, int wave, int unit) {
;     ...
;                 const float sk = a.in[12][l * 8 + h] * LOG2E;
;                 f32x4 o[4];
	ds_read_b128 v[128:131], v106 offset:55296
	ds_read_b128 v[132:135], v106 offset:55360
	ds_read_b128 v[136:139], v106 offset:61760
	ds_read_b128 v[140:143], v105 offset:12864
	ds_read_b128 v[144:147], v106 offset:55424
	ds_read_b128 v[160:163], v106 offset:55488
	ds_read_b128 v[164:167], v106 offset:55552
	ds_read_b128 v[168:171], v106 offset:55616
	ds_read_b128 v[172:175], v106 offset:61696
	ds_read_b128 v[180:183], v106 offset:61824
	ds_read_b128 v[196:199], v106 offset:61888
	ds_read_b128 v[200:203], v106 offset:61952
	ds_read_b128 v[204:207], v106 offset:62016
	ds_read_b128 v[224:227], v105 offset:12800
	s_waitcnt lgkmcnt(13)
	v_mfma_f32_16x16x32_bf16 v[74:77], v[128:131], v[68:71], 0
	ds_read_b128 v[228:231], v105 offset:12928
	v_div_fixup_f32 v72, v72, v108, 1.0
	s_waitcnt lgkmcnt(13)
	v_mfma_f32_16x16x32_bf16 v[74:77], v[132:135], v[64:67], v[74:77]
	ds_read_b128 v[232:235], v105 offset:12992
	s_waitcnt lgkmcnt(11)
	v_mfma_f32_16x16x32_bf16 v[74:77], v[144:147], v[60:63], v[74:77]
	ds_read_b128 v[236:239], v105 offset:13056
	ds_read_b128 v[240:243], v105 offset:13120
	s_waitcnt lgkmcnt(12)
	v_mfma_f32_16x16x32_bf16 v[74:77], v[160:163], v[56:59], v[74:77]
	ds_read_b128 v[244:247], v105 offset:19200
	s_waitcnt lgkmcnt(12)
	v_mfma_f32_16x16x32_bf16 v[74:77], v[164:167], v[52:55], v[74:77]
	ds_read_b128 v[128:131], v105 offset:19264
	s_waitcnt lgkmcnt(12)
	v_mfma_f32_16x16x32_bf16 v[76:79], v[168:171], v[48:51], v[74:77]
	s_nop 7
	v_pk_mul_f32 v[74:75], v[78:79], v[72:73] op_sel_hi:[1,0]
	ds_read_b128 v[132:135], v105 offset:19328
	s_waitcnt lgkmcnt(12)
	v_mfma_f32_16x16x32_bf16 v[78:81], v[172:175], v[68:71], 0
	v_mul_f32_e64 v76, v76, v72
	v_mul_f32_e64 v77, v77, v72
	v_mfma_f32_16x16x32_bf16 v[78:81], v[136:139], v[64:67], v[78:81]
	ds_read_b128 v[144:147], v105 offset:19392
	s_waitcnt lgkmcnt(12)
	v_mfma_f32_16x16x32_bf16 v[78:81], v[180:183], v[60:63], v[78:81]
	ds_read_b128 v[160:163], v105 offset:19456
	s_waitcnt lgkmcnt(12)
	v_mfma_f32_16x16x32_bf16 v[78:81], v[196:199], v[56:59], v[78:81]
	ds_read_b128 v[164:167], v105 offset:19520
	s_waitcnt lgkmcnt(12)
	v_mfma_f32_16x16x32_bf16 v[78:81], v[200:203], v[52:55], v[78:81]
	s_waitcnt lgkmcnt(11)
	v_mfma_f32_16x16x32_bf16 v[80:83], v[204:207], v[48:51], v[78:81]
	s_nop 7
	v_pk_mul_f32 v[78:79], v[82:83], v[72:73] op_sel_hi:[1,0]
	s_waitcnt lgkmcnt(10)
	v_mfma_f32_16x16x32_bf16 v[82:85], v[224:227], v[68:71], 0
	v_mul_f32_e64 v80, v80, v72
	v_mul_f32_e64 v81, v81, v72
	v_mfma_f32_16x16x32_bf16 v[82:85], v[140:143], v[64:67], v[82:85]
	s_waitcnt lgkmcnt(9)
	v_mfma_f32_16x16x32_bf16 v[82:85], v[228:231], v[60:63], v[82:85]
	s_waitcnt lgkmcnt(8)
	v_mfma_f32_16x16x32_bf16 v[82:85], v[232:235], v[56:59], v[82:85]
	s_waitcnt lgkmcnt(7)
	v_mfma_f32_16x16x32_bf16 v[82:85], v[236:239], v[52:55], v[82:85]
	s_waitcnt lgkmcnt(6)
	v_mfma_f32_16x16x32_bf16 v[84:87], v[240:243], v[48:51], v[82:85]
	s_nop 7
	v_pk_mul_f32 v[82:83], v[72:73], v[86:87] op_sel_hi:[0,1]
	s_waitcnt lgkmcnt(5)
	v_mfma_f32_16x16x32_bf16 v[68:71], v[244:247], v[68:71], 0
	v_pk_mul_f32 v[84:85], v[72:73], v[84:85] op_sel_hi:[0,1]
	s_waitcnt lgkmcnt(4)
	v_mfma_f32_16x16x32_bf16 v[64:67], v[128:131], v[64:67], v[68:71]
	s_waitcnt lgkmcnt(3)
	v_mfma_f32_16x16x32_bf16 v[60:63], v[132:135], v[60:63], v[64:67]
	s_waitcnt lgkmcnt(2)
	v_mfma_f32_16x16x32_bf16 v[56:59], v[144:147], v[56:59], v[60:63]
	s_waitcnt lgkmcnt(1)
	v_mfma_f32_16x16x32_bf16 v[52:55], v[160:163], v[52:55], v[56:59]
	v_cvt_pk_bf16_f32 v93, v76, v77
	v_cvt_pk_bf16_f32 v92, v74, v75
	s_waitcnt lgkmcnt(0)
	v_mfma_f32_16x16x32_bf16 v[48:51], v[164:167], v[48:51], v[52:55]
	s_nop 2
	v_mul_f32_e32 v52, v77, v77
	v_mul_f32_e32 v53, v75, v75
	v_fmac_f32_e32 v52, v76, v76
	v_fmac_f32_e32 v53, v74, v74
	v_add_f32_e32 v52, v52, v53
	v_mul_f32_e32 v53, v81, v81
	v_mul_f32_e32 v54, v79, v79
	v_fmac_f32_e32 v53, v80, v80
	v_fmac_f32_e32 v54, v78, v78
	v_add_f32_e32 v53, v53, v54
	v_add_f32_e32 v52, v52, v53
	v_mul_f32_e32 v53, v85, v85
	v_mul_f32_e32 v54, v83, v83
	v_fmac_f32_e32 v53, v84, v84
	v_fmac_f32_e32 v54, v82, v82
	v_pk_mul_f32 v[50:51], v[72:73], v[50:51] op_sel_hi:[0,1]
	v_pk_mul_f32 v[48:49], v[72:73], v[48:49] op_sel_hi:[0,1]
	v_add_f32_e32 v53, v53, v54
	v_add_f32_e32 v52, v53, v52
	v_mul_f32_e32 v53, v49, v49
	v_mul_f32_e32 v54, v51, v51
	v_fmac_f32_e32 v53, v48, v48
	v_fmac_f32_e32 v54, v50, v50
	v_add_f32_e32 v53, v53, v54
	v_cvt_pk_bf16_f32 v95, v80, v81
	v_cvt_pk_bf16_f32 v94, v78, v79
	v_cvt_pk_bf16_f32 v97, v84, v85
	v_cvt_pk_bf16_f32 v96, v82, v83
	v_add_f32_e32 v108, v52, v53
	v_cvt_pk_bf16_f32 v99, v48, v49
	v_cvt_pk_bf16_f32 v98, v50, v51
	global_load_dword v109, v185, s[12:13] offset:4
	s_waitcnt lgkmcnt(0)
	ds_read_b128 v[120:123], v107
	ds_read_b128 v[124:127], v107 offset:64
	ds_read_b128 v[128:131], v107 offset:576
	ds_read_b128 v[132:135], v107 offset:640
	ds_read_b128 v[136:139], v107 offset:4608
	ds_read_b128 v[140:143], v107 offset:4672
	ds_read_b128 v[144:147], v107 offset:5184
	ds_read_b128 v[160:163], v107 offset:5248
	ds_read_b128 v[164:167], v107 offset:9216
	ds_read_b128 v[168:171], v107 offset:9280
	ds_read_b128 v[172:175], v107 offset:9792
	ds_read_b128 v[180:183], v107 offset:9856
	ds_read_b128 v[196:199], v107 offset:13824
	ds_read_b128 v[200:203], v107 offset:13888
	s_waitcnt lgkmcnt(13)
	v_mfma_f32_16x16x32_bf16 v[48:51], v[120:123], v[44:47], v[28:31]
	s_waitcnt vmcnt(0)
	v_mul_f32_e32 v118, 0x3fb8aa3b, v109
	s_waitcnt lgkmcnt(12)
	v_mfma_f32_16x16x32_bf16 v[88:91], v[124:127], v[40:43], v[48:51]
	ds_read_b128 v[204:207], v107 offset:14400
	ds_read_b128 v[224:227], v107 offset:14464
	s_waitcnt lgkmcnt(13)
; #define LAS __attribute__((address_space(3)))
; #define LAS __attribute__((address_space(3)))
; __device__ __forceinline__ f32x4 mfma16(bf16x8 a, bf16x8 b, f32x4 c) { return __builtin_amdgcn_mfma_f32_16x16x32_bf16(a, b, c, 0, 0, 0); }
; template <int NKT, int VSTR, bool SINK>
; __device__ __forceinline__ void attn_core(LAS const unsigned char* kb_, LAS const unsigned char* vb_, bf16x8 q0, bf16x8 q1, float sk, unsigned mskbits, int fr, f32x4 (&o)[4]) {
;     ...
;     for (int kt = 0; kt < NKT; ++kt) {
;         const int key = (kt >> 1) * 32 + ((kt & 1) << 2) + krow;
;         LAS const unsigned char* kp = kb_ + key * 144;
;         const bf16x8 a0 = *(LAS const bf16x8*)kp, a1 = *(LAS const bf16x8*)(kp + 64);
;         const float bias = ((mskbits >> (kt >> 2)) & 1u) ? -1e30f : 0.f;
;         f32x4 s = mfma16(a0, q0, (f32x4){bias, bias, bias, bias});
;         s = mfma16(a1, q1, s);
;         S[kt] = s;
;     }
;     float mx = S[0][0];
; #pragma unroll
;     for (int kt = 0; kt < NKT; ++kt) mx = fmaxf(fmaxf(mx, fmaxf(S[kt][0], S[kt][1])), fmaxf(S[kt][2], S[kt][3]));
;     mx = fmaxf(mx, __shfl_xor(mx, 16)); mx = fmaxf(mx, __shfl_xor(mx, 32));
	v_mfma_f32_16x16x32_bf16 v[48:51], v[128:131], v[44:47], v[28:31]
	s_waitcnt lgkmcnt(12)
	v_mfma_f32_16x16x32_bf16 v[84:87], v[132:135], v[40:43], v[48:51]
	ds_read_b128 v[228:231], v107 offset:18432
	ds_read_b128 v[232:235], v107 offset:18496
	s_waitcnt lgkmcnt(13)
	v_mfma_f32_16x16x32_bf16 v[48:51], v[136:139], v[44:47], v[28:31]
	s_waitcnt lgkmcnt(12)
	v_mfma_f32_16x16x32_bf16 v[80:83], v[140:143], v[40:43], v[48:51]
	ds_read_b128 v[236:239], v107 offset:19008
	ds_read_b128 v[240:243], v107 offset:19072
	s_waitcnt lgkmcnt(13)
	v_mfma_f32_16x16x32_bf16 v[48:51], v[144:147], v[44:47], v[28:31]
	s_waitcnt lgkmcnt(12)
	v_mfma_f32_16x16x32_bf16 v[76:79], v[160:163], v[40:43], v[48:51]
	ds_read_b128 v[244:247], v107 offset:23040
	ds_read_b128 v[120:123], v107 offset:23104
	s_waitcnt lgkmcnt(13)
	v_mfma_f32_16x16x32_bf16 v[48:51], v[164:167], v[44:47], v[24:27]
	s_waitcnt lgkmcnt(12)
	v_mfma_f32_16x16x32_bf16 v[72:75], v[168:171], v[40:43], v[48:51]
	ds_read_b128 v[124:127], v107 offset:23616
	ds_read_b128 v[128:131], v107 offset:23680
	s_waitcnt lgkmcnt(13)
	v_mfma_f32_16x16x32_bf16 v[48:51], v[172:175], v[44:47], v[24:27]
	s_waitcnt lgkmcnt(12)
	v_mfma_f32_16x16x32_bf16 v[68:71], v[180:183], v[40:43], v[48:51]
	s_waitcnt lgkmcnt(11)
	v_mfma_f32_16x16x32_bf16 v[48:51], v[196:199], v[44:47], v[24:27]
	s_waitcnt lgkmcnt(10)
	v_mfma_f32_16x16x32_bf16 v[64:67], v[200:203], v[40:43], v[48:51]
	s_waitcnt lgkmcnt(9)
	v_mfma_f32_16x16x32_bf16 v[48:51], v[204:207], v[44:47], v[24:27]
	s_waitcnt lgkmcnt(8)
	v_mfma_f32_16x16x32_bf16 v[60:63], v[224:227], v[40:43], v[48:51]
	s_waitcnt lgkmcnt(7)
	v_mfma_f32_16x16x32_bf16 v[48:51], v[228:231], v[44:47], 0
	s_waitcnt lgkmcnt(6)
	v_mfma_f32_16x16x32_bf16 v[56:59], v[232:235], v[40:43], v[48:51]
	s_waitcnt lgkmcnt(5)
	v_mfma_f32_16x16x32_bf16 v[48:51], v[236:239], v[44:47], 0
	s_waitcnt lgkmcnt(4)
	v_mfma_f32_16x16x32_bf16 v[52:55], v[240:243], v[40:43], v[48:51]
	s_waitcnt lgkmcnt(3)
	v_mfma_f32_16x16x32_bf16 v[48:51], v[244:247], v[44:47], 0
	s_waitcnt lgkmcnt(2)
	v_mfma_f32_16x16x32_bf16 v[48:51], v[120:123], v[40:43], v[48:51]
	s_waitcnt lgkmcnt(1)
	v_mfma_f32_16x16x32_bf16 v[44:47], v[124:127], v[44:47], 0
	s_waitcnt lgkmcnt(0)
	v_mfma_f32_16x16x32_bf16 v[40:43], v[128:131], v[40:43], v[44:47]
	s_nop 5
	v_max_f32_e32 v44, v91, v91
	v_max_f32_e32 v45, v90, v90
	v_max_f32_e32 v44, v45, v44
	v_max_f32_e32 v45, v85, v85
	v_max_f32_e32 v46, v84, v84
	v_max_f32_e32 v45, v46, v45
	v_max_f32_e32 v46, v87, v87
	v_max_f32_e32 v47, v86, v86
	v_max3_f32 v44, v88, v89, v44
	v_max_f32_e32 v46, v47, v46
	v_max3_f32 v44, v44, v45, v46
	v_max_f32_e32 v45, v81, v81
	v_max_f32_e32 v46, v80, v80
	v_max_f32_e32 v45, v46, v45
	v_max_f32_e32 v46, v83, v83
	v_max_f32_e32 v47, v82, v82
	v_max_f32_e32 v46, v47, v46
	v_max3_f32 v44, v44, v45, v46
	v_max_f32_e32 v45, v77, v77
	v_max_f32_e32 v46, v76, v76
	v_max_f32_e32 v45, v46, v45
	v_max_f32_e32 v46, v79, v79
	v_max_f32_e32 v47, v78, v78
	v_max_f32_e32 v46, v47, v46
	v_max3_f32 v44, v44, v45, v46
	v_max_f32_e32 v45, v73, v73
	v_max_f32_e32 v46, v72, v72
	v_max_f32_e32 v45, v46, v45
	v_max_f32_e32 v46, v75, v75
	v_max_f32_e32 v47, v74, v74
	v_max_f32_e32 v46, v47, v46
	v_max3_f32 v44, v44, v45, v46
	v_max_f32_e32 v45, v69, v69
	v_max_f32_e32 v46, v68, v68
	v_max_f32_e32 v45, v46, v45
	v_max_f32_e32 v46, v71, v71
	v_max_f32_e32 v47, v70, v70
	v_max_f32_e32 v46, v47, v46
	v_max3_f32 v44, v44, v45, v46
	v_max_f32_e32 v45, v65, v65
	v_max_f32_e32 v46, v64, v64
	v_max_f32_e32 v45, v46, v45
	v_max_f32_e32 v46, v67, v67
	v_max_f32_e32 v47, v66, v66
	v_max_f32_e32 v46, v47, v46
	v_max3_f32 v44, v44, v45, v46
	v_max_f32_e32 v45, v61, v61
	v_max_f32_e32 v46, v60, v60
	v_max_f32_e32 v45, v46, v45
	v_max_f32_e32 v46, v63, v63
	v_max_f32_e32 v47, v62, v62
	v_max_f32_e32 v46, v47, v46
	v_max3_f32 v44, v44, v45, v46
	v_max_f32_e32 v45, v57, v57
	v_max_f32_e32 v46, v56, v56
	v_max_f32_e32 v45, v46, v45
	v_max_f32_e32 v46, v59, v59
	v_max_f32_e32 v47, v58, v58
	v_max_f32_e32 v46, v47, v46
	v_max3_f32 v44, v44, v45, v46
	v_max_f32_e32 v45, v53, v53
	v_max_f32_e32 v46, v52, v52
	v_max_f32_e32 v45, v46, v45
	v_max_f32_e32 v46, v55, v55
	v_max_f32_e32 v47, v54, v54
	v_max_f32_e32 v46, v47, v46
	v_max3_f32 v44, v44, v45, v46
	v_max_f32_e32 v45, v49, v49
	v_max_f32_e32 v46, v48, v48
	v_max_f32_e32 v45, v46, v45
	v_max_f32_e32 v46, v51, v51
	v_max_f32_e32 v47, v50, v50
	v_max_f32_e32 v46, v47, v46
	v_max3_f32 v44, v44, v45, v46
	v_max_f32_e32 v45, v41, v41
	v_max_f32_e32 v46, v40, v40
	v_max_f32_e32 v45, v46, v45
	v_max_f32_e32 v46, v43, v43
	v_max_f32_e32 v47, v42, v42
	v_max_f32_e32 v46, v47, v46
	v_max3_f32 v44, v44, v45, v46
	ds_bpermute_b32 v45, v212, v44
	s_waitcnt lgkmcnt(0)
	v_max_f32_e32 v45, v45, v45
	v_max_f32_e32 v44, v44, v45
	ds_bpermute_b32 v45, v176, v44
	s_waitcnt lgkmcnt(0)
; #define LAS __attribute__((address_space(3)))
; #define LAS __attribute__((address_space(3)))
; __device__ __forceinline__ unsigned pk2(float lo, float hi) { return pg8::cvt_pk_bf16(lo, hi); }
; template <int NKT, int VSTR, bool SINK>
; __device__ __forceinline__ void attn_core(LAS const unsigned char* kb_, LAS const unsigned char* vb_, bf16x8 q0, bf16x8 q1, float sk, unsigned mskbits, int fr, f32x4 (&o)[4]) {
;     ...
;     float mx = S[0][0];
; #pragma unroll
;     for (int kt = 0; kt < NKT; ++kt) mx = fmaxf(fmaxf(mx, fmaxf(S[kt][0], S[kt][1])), fmaxf(S[kt][2], S[kt][3]));
;     mx = fmaxf(mx, __shfl_xor(mx, 16)); mx = fmaxf(mx, __shfl_xor(mx, 32));
;     if (SINK) mx = fmaxf(mx, sk);
;     float sum = 0.f;
; #pragma unroll
;     for (int kt = 0; kt < NKT; ++kt)
; #pragma unroll
;         for (int r = 0; r < 4; ++r) { const float p = __builtin_amdgcn_exp2f(S[kt][r] - mx); S[kt][r] = p; sum += p; }
;     sum += __shfl_xor(sum, 16); sum += __shfl_xor(sum, 32);
;     if (SINK) sum += __builtin_amdgcn_exp2f(sk - mx);
;     const float inv = 1.0f / sum;
;     bf16x8 pf[NKT / 2];
; #pragma unroll
;     for (int kb = 0; kb < NKT / 2; ++kb) {
;         v4u w; w.x = pk2(S[2 * kb][0], S[2 * kb][1]); w.y = pk2(S[2 * kb][2], S[2 * kb][3]); w.z = pk2(S[2 * kb + 1][0], S[2 * kb + 1][1]); w.w = pk2(S[2 * kb + 1][2], S[2 * kb + 1][3]);
;         pf[kb] = __builtin_bit_cast(bf16x8, w);
;     }
; #pragma unroll
;     for (int dt = 0; dt < 4; ++dt) {
;         f32x4 acc = (f32x4){0.f, 0.f, 0.f, 0.f};
; #pragma unroll
;         for (int kb = 0; kb < NKT / 2; ++kb) {
;             const bf16x8 vf = *(LAS const bf16x8*)(vb_ + dt * 16 * VSTR + kb * 64);
	v_max3_f32 v44, v44, v45, v118
	v_sub_f32_e32 v45, v88, v44
	v_exp_f32_e32 v45, v45
	v_sub_f32_e32 v47, v89, v44
	v_exp_f32_e32 v47, v47
	v_sub_f32_e32 v88, v90, v44
	v_exp_f32_e32 v88, v88
	v_sub_f32_e32 v89, v91, v44
	v_exp_f32_e32 v89, v89
	v_sub_f32_e32 v84, v84, v44
	v_add_f32_e32 v46, 0, v45
	v_exp_f32_e32 v84, v84
	v_sub_f32_e32 v85, v85, v44
	v_add_f32_e32 v46, v47, v46
	v_exp_f32_e32 v85, v85
	v_sub_f32_e32 v86, v86, v44
	v_add_f32_e32 v46, v88, v46
	v_exp_f32_e32 v86, v86
	v_sub_f32_e32 v87, v87, v44
	v_add_f32_e32 v46, v89, v46
	v_exp_f32_e32 v87, v87
	v_sub_f32_e32 v80, v80, v44
	v_add_f32_e32 v46, v84, v46
	v_exp_f32_e32 v80, v80
	v_sub_f32_e32 v81, v81, v44
	v_add_f32_e32 v46, v85, v46
	v_exp_f32_e32 v81, v81
	v_sub_f32_e32 v82, v82, v44
	v_add_f32_e32 v46, v86, v46
	v_exp_f32_e32 v82, v82
	v_sub_f32_e32 v83, v83, v44
	v_add_f32_e32 v46, v87, v46
	v_exp_f32_e32 v83, v83
	v_sub_f32_e32 v76, v76, v44
	v_add_f32_e32 v46, v80, v46
	v_exp_f32_e32 v76, v76
	v_sub_f32_e32 v77, v77, v44
	v_add_f32_e32 v46, v81, v46
	v_exp_f32_e32 v77, v77
	v_sub_f32_e32 v78, v78, v44
	v_add_f32_e32 v46, v82, v46
	v_exp_f32_e32 v78, v78
	v_sub_f32_e32 v79, v79, v44
	v_add_f32_e32 v46, v83, v46
	v_exp_f32_e32 v79, v79
	v_sub_f32_e32 v72, v72, v44
	v_add_f32_e32 v46, v76, v46
	v_exp_f32_e32 v72, v72
	v_sub_f32_e32 v73, v73, v44
	v_add_f32_e32 v46, v77, v46
	v_exp_f32_e32 v73, v73
	v_sub_f32_e32 v74, v74, v44
	v_add_f32_e32 v46, v78, v46
	v_exp_f32_e32 v74, v74
	v_sub_f32_e32 v75, v75, v44
	v_add_f32_e32 v46, v79, v46
	v_exp_f32_e32 v75, v75
	v_sub_f32_e32 v68, v68, v44
	v_add_f32_e32 v46, v72, v46
	v_exp_f32_e32 v68, v68
	v_sub_f32_e32 v69, v69, v44
	v_add_f32_e32 v46, v73, v46
	v_exp_f32_e32 v69, v69
	v_sub_f32_e32 v70, v70, v44
	v_add_f32_e32 v46, v74, v46
	v_exp_f32_e32 v70, v70
	v_sub_f32_e32 v71, v71, v44
	v_add_f32_e32 v46, v75, v46
	v_exp_f32_e32 v71, v71
	v_sub_f32_e32 v64, v64, v44
	v_add_f32_e32 v46, v68, v46
	v_exp_f32_e32 v64, v64
	v_sub_f32_e32 v65, v65, v44
	v_add_f32_e32 v46, v69, v46
	v_exp_f32_e32 v65, v65
	v_sub_f32_e32 v66, v66, v44
	v_add_f32_e32 v46, v70, v46
	v_exp_f32_e32 v66, v66
	v_sub_f32_e32 v67, v67, v44
	v_add_f32_e32 v46, v71, v46
	v_exp_f32_e32 v67, v67
	v_sub_f32_e32 v60, v60, v44
	v_add_f32_e32 v46, v64, v46
	v_exp_f32_e32 v90, v60
	v_sub_f32_e32 v60, v61, v44
	v_add_f32_e32 v46, v65, v46
	v_exp_f32_e32 v91, v60
	v_sub_f32_e32 v60, v62, v44
	v_add_f32_e32 v46, v66, v46
	v_exp_f32_e32 v110, v60
	v_sub_f32_e32 v60, v63, v44
	v_add_f32_e32 v46, v67, v46
	v_exp_f32_e32 v111, v60
	v_sub_f32_e32 v56, v56, v44
	v_add_f32_e32 v46, v90, v46
	v_exp_f32_e32 v112, v56
	v_sub_f32_e32 v56, v57, v44
	v_add_f32_e32 v46, v91, v46
	v_exp_f32_e32 v113, v56
	v_sub_f32_e32 v56, v58, v44
	v_add_f32_e32 v46, v110, v46
	v_exp_f32_e32 v114, v56
	v_sub_f32_e32 v56, v59, v44
	v_add_f32_e32 v46, v111, v46
	v_exp_f32_e32 v115, v56
	v_sub_f32_e32 v52, v52, v44
	v_add_f32_e32 v46, v112, v46
	v_exp_f32_e32 v116, v52
	v_sub_f32_e32 v52, v53, v44
	v_add_f32_e32 v46, v113, v46
	v_exp_f32_e32 v117, v52
	v_sub_f32_e32 v52, v54, v44
	v_add_f32_e32 v46, v114, v46
	v_exp_f32_e32 v118, v52
	v_sub_f32_e32 v52, v55, v44
	v_add_f32_e32 v46, v115, v46
	v_exp_f32_e32 v119, v52
	v_sub_f32_e32 v48, v48, v44
	v_add_f32_e32 v46, v116, v46
	v_exp_f32_e32 v120, v48
	v_sub_f32_e32 v48, v49, v44
	v_add_f32_e32 v46, v117, v46
	v_exp_f32_e32 v121, v48
	v_sub_f32_e32 v48, v50, v44
	v_add_f32_e32 v46, v118, v46
	v_exp_f32_e32 v122, v48
	v_sub_f32_e32 v48, v51, v44
	v_add_f32_e32 v46, v119, v46
	v_exp_f32_e32 v123, v48
	v_sub_f32_e32 v40, v40, v44
	v_add_f32_e32 v46, v120, v46
	v_exp_f32_e32 v124, v40
	v_sub_f32_e32 v41, v41, v44
	v_add_f32_e32 v46, v121, v46
	v_exp_f32_e32 v125, v41
	v_sub_f32_e32 v41, v42, v44
	v_add_f32_e32 v46, v122, v46
	v_exp_f32_e32 v126, v41
	v_sub_f32_e32 v41, v43, v44
	v_add_f32_e32 v46, v123, v46
	v_exp_f32_e32 v43, v41
	v_add_f32_e32 v40, v124, v46
	v_add_f32_e32 v40, v125, v40
	v_add_f32_e32 v40, v126, v40
	v_add_f32_e32 v40, v43, v40
	ds_bpermute_b32 v41, v212, v40
	v_cvt_pk_bf16_f32 v60, v45, v47
	v_cvt_pk_bf16_f32 v61, v88, v89
	v_cvt_pk_bf16_f32 v62, v84, v85
	v_cvt_pk_bf16_f32 v63, v86, v87
	s_waitcnt lgkmcnt(0)
	v_add_f32_e32 v40, v40, v41
	ds_bpermute_b32 v41, v176, v40
	v_cvt_pk_bf16_f32 v56, v80, v81
	v_cvt_pk_bf16_f32 v57, v82, v83
	v_cvt_pk_bf16_f32 v58, v76, v77
	v_cvt_pk_bf16_f32 v59, v78, v79
	s_waitcnt lgkmcnt(0)
	v_add_f32_e32 v40, v40, v41
	v_fma_f32 v41, v109, s2, -v44
	v_exp_f32_e32 v41, v41
	v_cvt_pk_bf16_f32 v52, v72, v73
	v_cvt_pk_bf16_f32 v53, v74, v75
	v_cvt_pk_bf16_f32 v54, v68, v69
	v_cvt_pk_bf16_f32 v55, v70, v71
	v_cvt_pk_bf16_f32 v48, v64, v65
	s_nop 0
	v_add_f32_e32 v109, v41, v40
	v_div_scale_f32 v64, s[0:1], v109, v109, 1.0
	v_rcp_f32_e32 v65, v64
	v_cvt_pk_bf16_f32 v49, v66, v67
	v_cvt_pk_bf16_f32 v50, v90, v91
	v_cvt_pk_bf16_f32 v51, v110, v111
	v_cvt_pk_bf16_f32 v44, v112, v113
	v_cvt_pk_bf16_f32 v45, v114, v115
	s_nop 0
	v_fma_f32 v66, -v64, v65, 1.0
	v_fmac_f32_e32 v65, v66, v65
	v_div_scale_f32 v66, vcc, 1.0, v109, 1.0
	v_mul_f32_e32 v67, v66, v65
	v_fma_f32 v68, -v64, v67, v66
	v_fmac_f32_e32 v67, v68, v65
	v_fma_f32 v64, -v64, v67, v66
	v_cvt_pk_bf16_f32 v46, v116, v117
	v_cvt_pk_bf16_f32 v47, v118, v119
	v_cvt_pk_bf16_f32 v40, v120, v121
	v_cvt_pk_bf16_f32 v41, v122, v123
	v_cvt_pk_bf16_f32 v42, v124, v125
	v_cvt_pk_bf16_f32 v43, v126, v43
	v_div_fmas_f32 v64, v64, v65, v67
	s_waitcnt lgkmcnt(0)
; #define LAS __attribute__((address_space(3)))
; #define LAS __attribute__((address_space(3)))
; __device__ __forceinline__ f32x4 mfma16(bf16x8 a, bf16x8 b, f32x4 c) { return __builtin_amdgcn_mfma_f32_16x16x32_bf16(a, b, c, 0, 0, 0); }
; template <int NKT, int VSTR, bool SINK>
; __device__ __forceinline__ void attn_core(LAS const unsigned char* kb_, LAS const unsigned char* vb_, bf16x8 q0, bf16x8 q1, float sk, unsigned mskbits, int fr, f32x4 (&o)[4]) {
;     ...
;     for (int kt = 0; kt < NKT; ++kt) {
;         const int key = (kt >> 1) * 32 + ((kt & 1) << 2) + krow;
;         LAS const unsigned char* kp = kb_ + key * 144;
;         const bf16x8 a0 = *(LAS const bf16x8*)kp, a1 = *(LAS const bf16x8*)(kp + 64);
;         const float bias = ((mskbits >> (kt >> 2)) & 1u) ? -1e30f : 0.f;
;         f32x4 s = mfma16(a0, q0, (f32x4){bias, bias, bias, bias});
;         s = mfma16(a1, q1, s);
;         S[kt] = s;
;     ...
; #pragma unroll
;     for (int dt = 0; dt < 4; ++dt) {
;         f32x4 acc = (f32x4){0.f, 0.f, 0.f, 0.f};
; #pragma unroll
;         for (int kb = 0; kb < NKT / 2; ++kb) {
;             const bf16x8 vf = *(LAS const bf16x8*)(vb_ + dt * 16 * VSTR + kb * 64);
;             acc = mfma16(vf, pf[kb], acc);
;         }
;         o[dt] = acc * inv;
;     }
	ds_read_b128 v[128:131], v106 offset:55296
	ds_read_b128 v[132:135], v106 offset:55360
	ds_read_b128 v[136:139], v106 offset:61760
	ds_read_b128 v[140:143], v105 offset:12864
	ds_read_b128 v[144:147], v106 offset:55424
	ds_read_b128 v[160:163], v106 offset:55488
	ds_read_b128 v[164:167], v106 offset:55552
	ds_read_b128 v[168:171], v106 offset:55616
	ds_read_b128 v[172:175], v106 offset:61696
	ds_read_b128 v[180:183], v106 offset:61824
	ds_read_b128 v[196:199], v106 offset:61888
	ds_read_b128 v[200:203], v106 offset:61952
	ds_read_b128 v[204:207], v106 offset:62016
	ds_read_b128 v[224:227], v105 offset:12800
	s_waitcnt lgkmcnt(13)
	v_mfma_f32_16x16x32_bf16 v[66:69], v[128:131], v[60:63], 0
	ds_read_b128 v[228:231], v105 offset:12928
	v_div_fixup_f32 v64, v64, v109, 1.0
	s_waitcnt lgkmcnt(13)
	v_mfma_f32_16x16x32_bf16 v[66:69], v[132:135], v[56:59], v[66:69]
	ds_read_b128 v[232:235], v105 offset:12992
	s_waitcnt lgkmcnt(11)
	v_mfma_f32_16x16x32_bf16 v[66:69], v[144:147], v[52:55], v[66:69]
	ds_read_b128 v[236:239], v105 offset:13056
	ds_read_b128 v[240:243], v105 offset:13120
	s_waitcnt lgkmcnt(12)
	v_mfma_f32_16x16x32_bf16 v[66:69], v[160:163], v[48:51], v[66:69]
	ds_read_b128 v[244:247], v105 offset:19200
	s_waitcnt lgkmcnt(12)
	v_mfma_f32_16x16x32_bf16 v[66:69], v[164:167], v[44:47], v[66:69]
	ds_read_b128 v[128:131], v105 offset:19264
	s_waitcnt lgkmcnt(12)
	v_mfma_f32_16x16x32_bf16 v[68:71], v[168:171], v[40:43], v[66:69]
	s_nop 7
	v_pk_mul_f32 v[66:67], v[70:71], v[64:65] op_sel_hi:[1,0]
	ds_read_b128 v[132:135], v105 offset:19328
	s_waitcnt lgkmcnt(12)
	v_mfma_f32_16x16x32_bf16 v[70:73], v[172:175], v[60:63], 0
	v_mul_f32_e64 v68, v68, v64
	v_mul_f32_e64 v69, v69, v64
	v_mfma_f32_16x16x32_bf16 v[70:73], v[136:139], v[56:59], v[70:73]
	ds_read_b128 v[144:147], v105 offset:19392
	s_waitcnt lgkmcnt(12)
	v_mfma_f32_16x16x32_bf16 v[70:73], v[180:183], v[52:55], v[70:73]
	ds_read_b128 v[160:163], v105 offset:19456
	s_waitcnt lgkmcnt(12)
	v_mfma_f32_16x16x32_bf16 v[70:73], v[196:199], v[48:51], v[70:73]
	ds_read_b128 v[164:167], v105 offset:19520
	s_waitcnt lgkmcnt(12)
	v_mfma_f32_16x16x32_bf16 v[70:73], v[200:203], v[44:47], v[70:73]
	s_waitcnt lgkmcnt(11)
	v_mfma_f32_16x16x32_bf16 v[72:75], v[204:207], v[40:43], v[70:73]
	s_nop 7
	v_pk_mul_f32 v[70:71], v[74:75], v[64:65] op_sel_hi:[1,0]
	s_waitcnt lgkmcnt(10)
	v_mfma_f32_16x16x32_bf16 v[74:77], v[224:227], v[60:63], 0
	v_mul_f32_e64 v72, v72, v64
	v_mul_f32_e64 v73, v73, v64
	v_mfma_f32_16x16x32_bf16 v[74:77], v[140:143], v[56:59], v[74:77]
	s_waitcnt lgkmcnt(9)
	v_mfma_f32_16x16x32_bf16 v[74:77], v[228:231], v[52:55], v[74:77]
	s_waitcnt lgkmcnt(8)
	v_mfma_f32_16x16x32_bf16 v[74:77], v[232:235], v[48:51], v[74:77]
	s_waitcnt lgkmcnt(7)
	v_mfma_f32_16x16x32_bf16 v[74:77], v[236:239], v[44:47], v[74:77]
	s_waitcnt lgkmcnt(6)
	v_mfma_f32_16x16x32_bf16 v[76:79], v[240:243], v[40:43], v[74:77]
	s_nop 7
	v_pk_mul_f32 v[74:75], v[64:65], v[78:79] op_sel_hi:[0,1]
	s_waitcnt lgkmcnt(5)
	v_mfma_f32_16x16x32_bf16 v[60:63], v[244:247], v[60:63], 0
	v_pk_mul_f32 v[76:77], v[64:65], v[76:77] op_sel_hi:[0,1]
	s_waitcnt lgkmcnt(4)
	v_mfma_f32_16x16x32_bf16 v[56:59], v[128:131], v[56:59], v[60:63]
	s_waitcnt lgkmcnt(3)
	v_mfma_f32_16x16x32_bf16 v[52:55], v[132:135], v[52:55], v[56:59]
	s_waitcnt lgkmcnt(2)
	v_mfma_f32_16x16x32_bf16 v[48:51], v[144:147], v[48:51], v[52:55]
	s_waitcnt lgkmcnt(1)
	v_mfma_f32_16x16x32_bf16 v[44:47], v[160:163], v[44:47], v[48:51]
	v_cvt_pk_bf16_f32 v85, v68, v69
	v_cvt_pk_bf16_f32 v84, v66, v67
	s_waitcnt lgkmcnt(0)
	v_mfma_f32_16x16x32_bf16 v[40:43], v[164:167], v[40:43], v[44:47]
	s_nop 2
	v_mul_f32_e32 v44, v69, v69
	v_mul_f32_e32 v45, v67, v67
	v_fmac_f32_e32 v44, v68, v68
	v_fmac_f32_e32 v45, v66, v66
	v_add_f32_e32 v44, v44, v45
	v_mul_f32_e32 v45, v73, v73
	v_mul_f32_e32 v46, v71, v71
	v_fmac_f32_e32 v45, v72, v72
	v_fmac_f32_e32 v46, v70, v70
	v_add_f32_e32 v44, v108, v44
	v_add_f32_e32 v45, v45, v46
	v_add_f32_e32 v44, v45, v44
	v_mul_f32_e32 v45, v77, v77
	v_mul_f32_e32 v46, v75, v75
	v_fmac_f32_e32 v45, v76, v76
	v_fmac_f32_e32 v46, v74, v74
	v_pk_mul_f32 v[42:43], v[64:65], v[42:43] op_sel_hi:[0,1]
	v_pk_mul_f32 v[40:41], v[64:65], v[40:41] op_sel_hi:[0,1]
	v_add_f32_e32 v45, v45, v46
	v_add_f32_e32 v44, v45, v44
	v_mul_f32_e32 v45, v41, v41
	v_mul_f32_e32 v46, v43, v43
	v_fmac_f32_e32 v45, v40, v40
	v_fmac_f32_e32 v46, v42, v42
	v_add_f32_e32 v45, v45, v46
	v_cvt_pk_bf16_f32 v87, v72, v73
	v_cvt_pk_bf16_f32 v86, v70, v71
	v_cvt_pk_bf16_f32 v89, v76, v77
	v_cvt_pk_bf16_f32 v88, v74, v75
	v_add_f32_e32 v108, v44, v45
	v_cvt_pk_bf16_f32 v91, v40, v41
	v_cvt_pk_bf16_f32 v90, v42, v43
	global_load_dword v109, v185, s[12:13] offset:8
	s_waitcnt lgkmcnt(0)
	ds_read_b128 v[120:123], v107
	ds_read_b128 v[124:127], v107 offset:64
	ds_read_b128 v[128:131], v107 offset:576
	ds_read_b128 v[132:135], v107 offset:640
	ds_read_b128 v[136:139], v107 offset:4608
	ds_read_b128 v[140:143], v107 offset:4672
	ds_read_b128 v[144:147], v107 offset:5184
	ds_read_b128 v[160:163], v107 offset:5248
	ds_read_b128 v[164:167], v107 offset:9216
	ds_read_b128 v[168:171], v107 offset:9280
	ds_read_b128 v[172:175], v107 offset:9792
	ds_read_b128 v[180:183], v107 offset:9856
	ds_read_b128 v[196:199], v107 offset:13824
	ds_read_b128 v[200:203], v107 offset:13888
	s_waitcnt lgkmcnt(13)
	v_mfma_f32_16x16x32_bf16 v[40:43], v[120:123], v[36:39], v[28:31]
	s_waitcnt vmcnt(0)
	v_mul_f32_e32 v118, 0x3fb8aa3b, v109
	s_waitcnt lgkmcnt(12)
	v_mfma_f32_16x16x32_bf16 v[80:83], v[124:127], v[32:35], v[40:43]
	ds_read_b128 v[204:207], v107 offset:14400
	ds_read_b128 v[224:227], v107 offset:14464
	s_waitcnt lgkmcnt(13)
; #define LAS __attribute__((address_space(3)))
; #define LAS __attribute__((address_space(3)))
; __device__ __forceinline__ f32x4 mfma16(bf16x8 a, bf16x8 b, f32x4 c) { return __builtin_amdgcn_mfma_f32_16x16x32_bf16(a, b, c, 0, 0, 0); }
; template <int NKT, int VSTR, bool SINK>
; __device__ __forceinline__ void attn_core(LAS const unsigned char* kb_, LAS const unsigned char* vb_, bf16x8 q0, bf16x8 q1, float sk, unsigned mskbits, int fr, f32x4 (&o)[4]) {
;     ...
;     for (int kt = 0; kt < NKT; ++kt) {
;         const int key = (kt >> 1) * 32 + ((kt & 1) << 2) + krow;
;         LAS const unsigned char* kp = kb_ + key * 144;
;         const bf16x8 a0 = *(LAS const bf16x8*)kp, a1 = *(LAS const bf16x8*)(kp + 64);
;         const float bias = ((mskbits >> (kt >> 2)) & 1u) ? -1e30f : 0.f;
;         f32x4 s = mfma16(a0, q0, (f32x4){bias, bias, bias, bias});
;         s = mfma16(a1, q1, s);
;         S[kt] = s;
;     }
;     float mx = S[0][0];
; #pragma unroll
;     for (int kt = 0; kt < NKT; ++kt) mx = fmaxf(fmaxf(mx, fmaxf(S[kt][0], S[kt][1])), fmaxf(S[kt][2], S[kt][3]));
;     mx = fmaxf(mx, __shfl_xor(mx, 16)); mx = fmaxf(mx, __shfl_xor(mx, 32));
	v_mfma_f32_16x16x32_bf16 v[40:43], v[128:131], v[36:39], v[28:31]
	s_waitcnt lgkmcnt(12)
	v_mfma_f32_16x16x32_bf16 v[76:79], v[132:135], v[32:35], v[40:43]
	ds_read_b128 v[228:231], v107 offset:18432
	ds_read_b128 v[232:235], v107 offset:18496
	s_waitcnt lgkmcnt(13)
	v_mfma_f32_16x16x32_bf16 v[40:43], v[136:139], v[36:39], v[28:31]
	s_waitcnt lgkmcnt(12)
	v_mfma_f32_16x16x32_bf16 v[72:75], v[140:143], v[32:35], v[40:43]
	ds_read_b128 v[236:239], v107 offset:19008
	ds_read_b128 v[240:243], v107 offset:19072
	s_waitcnt lgkmcnt(13)
	v_mfma_f32_16x16x32_bf16 v[40:43], v[144:147], v[36:39], v[28:31]
	s_waitcnt lgkmcnt(12)
	v_mfma_f32_16x16x32_bf16 v[68:71], v[160:163], v[32:35], v[40:43]
	ds_read_b128 v[244:247], v107 offset:23040
	ds_read_b128 v[120:123], v107 offset:23104
	s_waitcnt lgkmcnt(13)
	v_mfma_f32_16x16x32_bf16 v[40:43], v[164:167], v[36:39], v[24:27]
	s_waitcnt lgkmcnt(12)
	v_mfma_f32_16x16x32_bf16 v[64:67], v[168:171], v[32:35], v[40:43]
	ds_read_b128 v[124:127], v107 offset:23616
	ds_read_b128 v[128:131], v107 offset:23680
	s_waitcnt lgkmcnt(13)
	v_mfma_f32_16x16x32_bf16 v[40:43], v[172:175], v[36:39], v[24:27]
	s_waitcnt lgkmcnt(12)
	v_mfma_f32_16x16x32_bf16 v[60:63], v[180:183], v[32:35], v[40:43]
	s_waitcnt lgkmcnt(11)
	v_mfma_f32_16x16x32_bf16 v[40:43], v[196:199], v[36:39], v[24:27]
	s_waitcnt lgkmcnt(10)
	v_mfma_f32_16x16x32_bf16 v[56:59], v[200:203], v[32:35], v[40:43]
	s_waitcnt lgkmcnt(9)
	v_mfma_f32_16x16x32_bf16 v[40:43], v[204:207], v[36:39], v[24:27]
	s_waitcnt lgkmcnt(8)
	v_mfma_f32_16x16x32_bf16 v[52:55], v[224:227], v[32:35], v[40:43]
	s_waitcnt lgkmcnt(7)
	v_mfma_f32_16x16x32_bf16 v[40:43], v[228:231], v[36:39], 0
	s_waitcnt lgkmcnt(6)
	v_mfma_f32_16x16x32_bf16 v[48:51], v[232:235], v[32:35], v[40:43]
	s_waitcnt lgkmcnt(5)
	v_mfma_f32_16x16x32_bf16 v[40:43], v[236:239], v[36:39], 0
	s_waitcnt lgkmcnt(4)
	v_mfma_f32_16x16x32_bf16 v[44:47], v[240:243], v[32:35], v[40:43]
	s_waitcnt lgkmcnt(3)
	v_mfma_f32_16x16x32_bf16 v[40:43], v[244:247], v[36:39], 0
	s_waitcnt lgkmcnt(2)
	v_mfma_f32_16x16x32_bf16 v[40:43], v[120:123], v[32:35], v[40:43]
	s_waitcnt lgkmcnt(1)
	v_mfma_f32_16x16x32_bf16 v[36:39], v[124:127], v[36:39], 0
	s_waitcnt lgkmcnt(0)
	v_mfma_f32_16x16x32_bf16 v[32:35], v[128:131], v[32:35], v[36:39]
	s_nop 5
	v_max_f32_e32 v36, v83, v83
	v_max_f32_e32 v37, v82, v82
	v_max_f32_e32 v36, v37, v36
	v_max_f32_e32 v37, v77, v77
	v_max_f32_e32 v38, v76, v76
	v_max_f32_e32 v37, v38, v37
	v_max_f32_e32 v38, v79, v79
	v_max_f32_e32 v39, v78, v78
	v_max3_f32 v36, v80, v81, v36
	v_max_f32_e32 v38, v39, v38
	v_max3_f32 v36, v36, v37, v38
	v_max_f32_e32 v37, v73, v73
	v_max_f32_e32 v38, v72, v72
	v_max_f32_e32 v37, v38, v37
	v_max_f32_e32 v38, v75, v75
	v_max_f32_e32 v39, v74, v74
	v_max_f32_e32 v38, v39, v38
	v_max3_f32 v36, v36, v37, v38
	v_max_f32_e32 v37, v69, v69
	v_max_f32_e32 v38, v68, v68
	v_max_f32_e32 v37, v38, v37
	v_max_f32_e32 v38, v71, v71
	v_max_f32_e32 v39, v70, v70
	v_max_f32_e32 v38, v39, v38
	v_max3_f32 v36, v36, v37, v38
	v_max_f32_e32 v37, v65, v65
	v_max_f32_e32 v38, v64, v64
	v_max_f32_e32 v37, v38, v37
	v_max_f32_e32 v38, v67, v67
	v_max_f32_e32 v39, v66, v66
	v_max_f32_e32 v38, v39, v38
	v_max3_f32 v36, v36, v37, v38
	v_max_f32_e32 v37, v61, v61
	v_max_f32_e32 v38, v60, v60
	v_max_f32_e32 v37, v38, v37
	v_max_f32_e32 v38, v63, v63
	v_max_f32_e32 v39, v62, v62
	v_max_f32_e32 v38, v39, v38
	v_max3_f32 v36, v36, v37, v38
	v_max_f32_e32 v37, v57, v57
	v_max_f32_e32 v38, v56, v56
	v_max_f32_e32 v37, v38, v37
	v_max_f32_e32 v38, v59, v59
	v_max_f32_e32 v39, v58, v58
	v_max_f32_e32 v38, v39, v38
	v_max3_f32 v36, v36, v37, v38
	v_max_f32_e32 v37, v53, v53
	v_max_f32_e32 v38, v52, v52
	v_max_f32_e32 v37, v38, v37
	v_max_f32_e32 v38, v55, v55
	v_max_f32_e32 v39, v54, v54
	v_max_f32_e32 v38, v39, v38
	v_max3_f32 v36, v36, v37, v38
	v_max_f32_e32 v37, v49, v49
	v_max_f32_e32 v38, v48, v48
	v_max_f32_e32 v37, v38, v37
	v_max_f32_e32 v38, v51, v51
	v_max_f32_e32 v39, v50, v50
	v_max_f32_e32 v38, v39, v38
	v_max3_f32 v36, v36, v37, v38
	v_max_f32_e32 v37, v45, v45
	v_max_f32_e32 v38, v44, v44
	v_max_f32_e32 v37, v38, v37
	v_max_f32_e32 v38, v47, v47
	v_max_f32_e32 v39, v46, v46
	v_max_f32_e32 v38, v39, v38
	v_max3_f32 v36, v36, v37, v38
	v_max_f32_e32 v37, v41, v41
	v_max_f32_e32 v38, v40, v40
	v_max_f32_e32 v37, v38, v37
	v_max_f32_e32 v38, v43, v43
	v_max_f32_e32 v39, v42, v42
	v_max_f32_e32 v38, v39, v38
	v_max3_f32 v36, v36, v37, v38
	v_max_f32_e32 v37, v33, v33
	v_max_f32_e32 v38, v32, v32
	v_max_f32_e32 v37, v38, v37
	v_max_f32_e32 v38, v35, v35
	v_max_f32_e32 v39, v34, v34
	v_max_f32_e32 v38, v39, v38
	v_max3_f32 v36, v36, v37, v38
	ds_bpermute_b32 v37, v212, v36
	s_waitcnt lgkmcnt(0)
	v_max_f32_e32 v37, v37, v37
	v_max_f32_e32 v36, v36, v37
	ds_bpermute_b32 v37, v176, v36
	s_waitcnt lgkmcnt(0)
; #define LAS __attribute__((address_space(3)))
; #define LAS __attribute__((address_space(3)))
; __device__ __forceinline__ unsigned pk2(float lo, float hi) { return pg8::cvt_pk_bf16(lo, hi); }
; template <int NKT, int VSTR, bool SINK>
; __device__ __forceinline__ void attn_core(LAS const unsigned char* kb_, LAS const unsigned char* vb_, bf16x8 q0, bf16x8 q1, float sk, unsigned mskbits, int fr, f32x4 (&o)[4]) {
;     ...
;     float mx = S[0][0];
; #pragma unroll
;     for (int kt = 0; kt < NKT; ++kt) mx = fmaxf(fmaxf(mx, fmaxf(S[kt][0], S[kt][1])), fmaxf(S[kt][2], S[kt][3]));
;     mx = fmaxf(mx, __shfl_xor(mx, 16)); mx = fmaxf(mx, __shfl_xor(mx, 32));
;     if (SINK) mx = fmaxf(mx, sk);
;     float sum = 0.f;
; #pragma unroll
;     for (int kt = 0; kt < NKT; ++kt)
; #pragma unroll
;         for (int r = 0; r < 4; ++r) { const float p = __builtin_amdgcn_exp2f(S[kt][r] - mx); S[kt][r] = p; sum += p; }
;     sum += __shfl_xor(sum, 16); sum += __shfl_xor(sum, 32);
;     if (SINK) sum += __builtin_amdgcn_exp2f(sk - mx);
;     const float inv = 1.0f / sum;
;     bf16x8 pf[NKT / 2];
; #pragma unroll
;     for (int kb = 0; kb < NKT / 2; ++kb) {
;         v4u w; w.x = pk2(S[2 * kb][0], S[2 * kb][1]); w.y = pk2(S[2 * kb][2], S[2 * kb][3]); w.z = pk2(S[2 * kb + 1][0], S[2 * kb + 1][1]); w.w = pk2(S[2 * kb + 1][2], S[2 * kb + 1][3]);
;         pf[kb] = __builtin_bit_cast(bf16x8, w);
;     }
; #pragma unroll
;     for (int dt = 0; dt < 4; ++dt) {
;         f32x4 acc = (f32x4){0.f, 0.f, 0.f, 0.f};
; #pragma unroll
;         for (int kb = 0; kb < NKT / 2; ++kb) {
;             const bf16x8 vf = *(LAS const bf16x8*)(vb_ + dt * 16 * VSTR + kb * 64);
	v_max3_f32 v36, v36, v37, v118
	v_sub_f32_e32 v37, v80, v36
	v_exp_f32_e32 v37, v37
	v_sub_f32_e32 v39, v81, v36
	v_exp_f32_e32 v39, v39
	v_sub_f32_e32 v80, v82, v36
	v_exp_f32_e32 v80, v80
	v_sub_f32_e32 v81, v83, v36
	v_exp_f32_e32 v81, v81
	v_sub_f32_e32 v76, v76, v36
	v_add_f32_e32 v38, 0, v37
	v_exp_f32_e32 v76, v76
	v_sub_f32_e32 v77, v77, v36
	v_add_f32_e32 v38, v39, v38
	v_exp_f32_e32 v77, v77
	v_sub_f32_e32 v78, v78, v36
	v_add_f32_e32 v38, v80, v38
	v_exp_f32_e32 v78, v78
	v_sub_f32_e32 v79, v79, v36
	v_add_f32_e32 v38, v81, v38
	v_exp_f32_e32 v79, v79
	v_sub_f32_e32 v72, v72, v36
	v_add_f32_e32 v38, v76, v38
	v_exp_f32_e32 v72, v72
	v_sub_f32_e32 v73, v73, v36
	v_add_f32_e32 v38, v77, v38
	v_exp_f32_e32 v73, v73
	v_sub_f32_e32 v74, v74, v36
	v_add_f32_e32 v38, v78, v38
	v_exp_f32_e32 v74, v74
	v_sub_f32_e32 v75, v75, v36
	v_add_f32_e32 v38, v79, v38
	v_exp_f32_e32 v75, v75
	v_sub_f32_e32 v68, v68, v36
	v_add_f32_e32 v38, v72, v38
	v_exp_f32_e32 v68, v68
	v_sub_f32_e32 v69, v69, v36
	v_add_f32_e32 v38, v73, v38
	v_exp_f32_e32 v69, v69
	v_sub_f32_e32 v70, v70, v36
	v_add_f32_e32 v38, v74, v38
	v_exp_f32_e32 v70, v70
	v_sub_f32_e32 v71, v71, v36
	v_add_f32_e32 v38, v75, v38
	v_exp_f32_e32 v71, v71
	v_sub_f32_e32 v64, v64, v36
	v_add_f32_e32 v38, v68, v38
	v_exp_f32_e32 v64, v64
	v_sub_f32_e32 v65, v65, v36
	v_add_f32_e32 v38, v69, v38
	v_exp_f32_e32 v65, v65
	v_sub_f32_e32 v66, v66, v36
	v_add_f32_e32 v38, v70, v38
	v_exp_f32_e32 v66, v66
	v_sub_f32_e32 v67, v67, v36
	v_add_f32_e32 v38, v71, v38
	v_exp_f32_e32 v67, v67
	v_sub_f32_e32 v60, v60, v36
	v_add_f32_e32 v38, v64, v38
	v_exp_f32_e32 v60, v60
	v_sub_f32_e32 v61, v61, v36
	v_add_f32_e32 v38, v65, v38
	v_exp_f32_e32 v61, v61
	v_sub_f32_e32 v62, v62, v36
	v_add_f32_e32 v38, v66, v38
	v_exp_f32_e32 v62, v62
	v_sub_f32_e32 v63, v63, v36
	v_add_f32_e32 v38, v67, v38
	v_exp_f32_e32 v63, v63
	v_sub_f32_e32 v56, v56, v36
	v_add_f32_e32 v38, v60, v38
	v_exp_f32_e32 v56, v56
	v_sub_f32_e32 v57, v57, v36
	v_add_f32_e32 v38, v61, v38
	v_exp_f32_e32 v57, v57
	v_sub_f32_e32 v58, v58, v36
	v_add_f32_e32 v38, v62, v38
	v_exp_f32_e32 v58, v58
	v_sub_f32_e32 v59, v59, v36
	v_add_f32_e32 v38, v63, v38
	v_exp_f32_e32 v59, v59
	v_sub_f32_e32 v52, v52, v36
	v_add_f32_e32 v38, v56, v38
	v_exp_f32_e32 v82, v52
	v_sub_f32_e32 v52, v53, v36
	v_add_f32_e32 v38, v57, v38
	v_exp_f32_e32 v83, v52
	v_sub_f32_e32 v52, v54, v36
	v_add_f32_e32 v38, v58, v38
	v_exp_f32_e32 v110, v52
	v_sub_f32_e32 v52, v55, v36
	v_add_f32_e32 v38, v59, v38
	v_exp_f32_e32 v111, v52
	v_sub_f32_e32 v48, v48, v36
	v_add_f32_e32 v38, v82, v38
	v_exp_f32_e32 v112, v48
	v_sub_f32_e32 v48, v49, v36
	v_add_f32_e32 v38, v83, v38
	v_exp_f32_e32 v113, v48
	v_sub_f32_e32 v48, v50, v36
	v_add_f32_e32 v38, v110, v38
	v_exp_f32_e32 v114, v48
	v_sub_f32_e32 v48, v51, v36
	v_add_f32_e32 v38, v111, v38
	v_exp_f32_e32 v115, v48
	v_sub_f32_e32 v44, v44, v36
	v_add_f32_e32 v38, v112, v38
	v_exp_f32_e32 v116, v44
	v_sub_f32_e32 v44, v45, v36
	v_add_f32_e32 v38, v113, v38
	v_exp_f32_e32 v117, v44
	v_sub_f32_e32 v44, v46, v36
	v_add_f32_e32 v38, v114, v38
	v_exp_f32_e32 v118, v44
	v_sub_f32_e32 v44, v47, v36
	v_add_f32_e32 v38, v115, v38
	v_exp_f32_e32 v119, v44
	v_sub_f32_e32 v40, v40, v36
	v_add_f32_e32 v38, v116, v38
	v_exp_f32_e32 v120, v40
	v_sub_f32_e32 v40, v41, v36
	v_add_f32_e32 v38, v117, v38
	v_exp_f32_e32 v121, v40
	v_sub_f32_e32 v40, v42, v36
	v_add_f32_e32 v38, v118, v38
	v_exp_f32_e32 v122, v40
	v_sub_f32_e32 v40, v43, v36
	v_add_f32_e32 v38, v119, v38
	v_exp_f32_e32 v123, v40
	v_sub_f32_e32 v32, v32, v36
	v_add_f32_e32 v38, v120, v38
	v_exp_f32_e32 v124, v32
	v_sub_f32_e32 v33, v33, v36
	v_add_f32_e32 v38, v121, v38
	v_exp_f32_e32 v125, v33
	v_sub_f32_e32 v33, v34, v36
	v_add_f32_e32 v38, v122, v38
	v_exp_f32_e32 v126, v33
	v_sub_f32_e32 v33, v35, v36
	v_add_f32_e32 v38, v123, v38
	v_exp_f32_e32 v35, v33
	v_add_f32_e32 v32, v124, v38
	v_add_f32_e32 v32, v125, v32
	v_add_f32_e32 v32, v126, v32
	v_add_f32_e32 v32, v35, v32
	ds_bpermute_b32 v33, v212, v32
	v_cvt_pk_bf16_f32 v52, v37, v39
	v_cvt_pk_bf16_f32 v53, v80, v81
	v_cvt_pk_bf16_f32 v54, v76, v77
	v_cvt_pk_bf16_f32 v55, v78, v79
	s_waitcnt lgkmcnt(0)
	v_add_f32_e32 v32, v32, v33
	ds_bpermute_b32 v33, v176, v32
	v_cvt_pk_bf16_f32 v48, v72, v73
	v_cvt_pk_bf16_f32 v49, v74, v75
	v_cvt_pk_bf16_f32 v50, v68, v69
	v_cvt_pk_bf16_f32 v51, v70, v71
	s_waitcnt lgkmcnt(0)
	v_add_f32_e32 v32, v32, v33
	v_fma_f32 v33, v109, s2, -v36
	v_exp_f32_e32 v33, v33
	v_cvt_pk_bf16_f32 v44, v64, v65
	v_cvt_pk_bf16_f32 v45, v66, v67
	v_cvt_pk_bf16_f32 v46, v60, v61
	v_cvt_pk_bf16_f32 v47, v62, v63
	v_cvt_pk_bf16_f32 v40, v56, v57
	s_nop 0
	v_add_f32_e32 v109, v33, v32
	v_div_scale_f32 v56, s[0:1], v109, v109, 1.0
	v_rcp_f32_e32 v57, v56
	v_cvt_pk_bf16_f32 v41, v58, v59
	v_cvt_pk_bf16_f32 v42, v82, v83
	v_cvt_pk_bf16_f32 v43, v110, v111
	v_cvt_pk_bf16_f32 v36, v112, v113
	v_cvt_pk_bf16_f32 v37, v114, v115
	s_nop 0
	v_fma_f32 v58, -v56, v57, 1.0
	v_fmac_f32_e32 v57, v58, v57
	v_div_scale_f32 v58, vcc, 1.0, v109, 1.0
	v_mul_f32_e32 v59, v58, v57
	v_fma_f32 v60, -v56, v59, v58
	v_fmac_f32_e32 v59, v60, v57
	v_fma_f32 v56, -v56, v59, v58
	v_cvt_pk_bf16_f32 v38, v116, v117
	v_cvt_pk_bf16_f32 v39, v118, v119
	v_cvt_pk_bf16_f32 v32, v120, v121
	v_cvt_pk_bf16_f32 v33, v122, v123
	v_cvt_pk_bf16_f32 v34, v124, v125
	v_cvt_pk_bf16_f32 v35, v126, v35
	v_div_fmas_f32 v56, v56, v57, v59
	s_waitcnt lgkmcnt(0)
; #define LAS __attribute__((address_space(3)))
; #define LAS __attribute__((address_space(3)))
; __device__ __forceinline__ f32x4 mfma16(bf16x8 a, bf16x8 b, f32x4 c) { return __builtin_amdgcn_mfma_f32_16x16x32_bf16(a, b, c, 0, 0, 0); }
; template <int NKT, int VSTR, bool SINK>
; __device__ __forceinline__ void attn_core(LAS const unsigned char* kb_, LAS const unsigned char* vb_, bf16x8 q0, bf16x8 q1, float sk, unsigned mskbits, int fr, f32x4 (&o)[4]) {
;     ...
;     for (int kt = 0; kt < NKT; ++kt) {
;         const int key = (kt >> 1) * 32 + ((kt & 1) << 2) + krow;
;         LAS const unsigned char* kp = kb_ + key * 144;
;         const bf16x8 a0 = *(LAS const bf16x8*)kp, a1 = *(LAS const bf16x8*)(kp + 64);
;         const float bias = ((mskbits >> (kt >> 2)) & 1u) ? -1e30f : 0.f;
;         f32x4 s = mfma16(a0, q0, (f32x4){bias, bias, bias, bias});
;         s = mfma16(a1, q1, s);
;         S[kt] = s;
;     ...
; #pragma unroll
;     for (int dt = 0; dt < 4; ++dt) {
;         f32x4 acc = (f32x4){0.f, 0.f, 0.f, 0.f};
; #pragma unroll
;         for (int kb = 0; kb < NKT / 2; ++kb) {
;             const bf16x8 vf = *(LAS const bf16x8*)(vb_ + dt * 16 * VSTR + kb * 64);
;             acc = mfma16(vf, pf[kb], acc);
;         }
;         o[dt] = acc * inv;
;     }
	ds_read_b128 v[76:79], v106 offset:55296
	ds_read_b128 v[128:131], v106 offset:55360
	ds_read_b128 v[132:135], v106 offset:61760
	ds_read_b128 v[136:139], v105 offset:12864
	ds_read_b128 v[140:143], v106 offset:55424
	ds_read_b128 v[144:147], v106 offset:55488
	ds_read_b128 v[160:163], v106 offset:55552
	ds_read_b128 v[164:167], v106 offset:55616
	ds_read_b128 v[168:171], v106 offset:61696
	ds_read_b128 v[172:175], v106 offset:61824
	ds_read_b128 v[180:183], v106 offset:61888
	ds_read_b128 v[196:199], v106 offset:61952
	ds_read_b128 v[200:203], v106 offset:62016
	ds_read_b128 v[204:207], v105 offset:12800
	s_waitcnt lgkmcnt(13)
	v_mfma_f32_16x16x32_bf16 v[58:61], v[76:79], v[52:55], 0
	ds_read_b128 v[224:227], v105 offset:12928
	v_div_fixup_f32 v56, v56, v109, 1.0
	s_waitcnt lgkmcnt(13)
	v_mfma_f32_16x16x32_bf16 v[58:61], v[128:131], v[48:51], v[58:61]
	ds_read_b128 v[228:231], v105 offset:12992
	s_waitcnt lgkmcnt(11)
	v_mfma_f32_16x16x32_bf16 v[58:61], v[140:143], v[44:47], v[58:61]
	ds_read_b128 v[232:235], v105 offset:13056
	ds_read_b128 v[236:239], v105 offset:13120
	s_waitcnt lgkmcnt(12)
	v_mfma_f32_16x16x32_bf16 v[58:61], v[144:147], v[40:43], v[58:61]
	ds_read_b128 v[240:243], v105 offset:19200
	s_waitcnt lgkmcnt(12)
	v_mfma_f32_16x16x32_bf16 v[58:61], v[160:163], v[36:39], v[58:61]
	ds_read_b128 v[244:247], v105 offset:19264
	s_waitcnt lgkmcnt(12)
	v_mfma_f32_16x16x32_bf16 v[60:63], v[164:167], v[32:35], v[58:61]
	s_nop 7
	v_pk_mul_f32 v[58:59], v[62:63], v[56:57] op_sel_hi:[1,0]
	ds_read_b128 v[76:79], v105 offset:19328
	s_waitcnt lgkmcnt(12)
	v_mfma_f32_16x16x32_bf16 v[62:65], v[168:171], v[52:55], 0
	v_mul_f32_e64 v60, v60, v56
	v_mul_f32_e64 v61, v61, v56
	v_mfma_f32_16x16x32_bf16 v[62:65], v[132:135], v[48:51], v[62:65]
	ds_read_b128 v[128:131], v105 offset:19392
	s_waitcnt lgkmcnt(12)
	v_mfma_f32_16x16x32_bf16 v[62:65], v[172:175], v[44:47], v[62:65]
	ds_read_b128 v[140:143], v105 offset:19456
	s_waitcnt lgkmcnt(12)
	v_mfma_f32_16x16x32_bf16 v[62:65], v[180:183], v[40:43], v[62:65]
	ds_read_b128 v[144:147], v105 offset:19520
	s_waitcnt lgkmcnt(12)
	v_mfma_f32_16x16x32_bf16 v[62:65], v[196:199], v[36:39], v[62:65]
	s_waitcnt lgkmcnt(11)
	v_mfma_f32_16x16x32_bf16 v[64:67], v[200:203], v[32:35], v[62:65]
	s_nop 7
	v_pk_mul_f32 v[62:63], v[66:67], v[56:57] op_sel_hi:[1,0]
	s_waitcnt lgkmcnt(10)
	v_mfma_f32_16x16x32_bf16 v[66:69], v[204:207], v[52:55], 0
	v_mul_f32_e64 v64, v64, v56
	v_mul_f32_e64 v65, v65, v56
	v_mfma_f32_16x16x32_bf16 v[66:69], v[136:139], v[48:51], v[66:69]
	s_waitcnt lgkmcnt(9)
	v_mfma_f32_16x16x32_bf16 v[66:69], v[224:227], v[44:47], v[66:69]
	s_waitcnt lgkmcnt(8)
	v_mfma_f32_16x16x32_bf16 v[66:69], v[228:231], v[40:43], v[66:69]
	s_waitcnt lgkmcnt(7)
	v_mfma_f32_16x16x32_bf16 v[66:69], v[232:235], v[36:39], v[66:69]
	s_waitcnt lgkmcnt(6)
	v_mfma_f32_16x16x32_bf16 v[68:71], v[236:239], v[32:35], v[66:69]
	s_nop 7
	v_pk_mul_f32 v[66:67], v[56:57], v[70:71] op_sel_hi:[0,1]
	s_waitcnt lgkmcnt(5)
	v_mfma_f32_16x16x32_bf16 v[52:55], v[240:243], v[52:55], 0
	v_pk_mul_f32 v[68:69], v[56:57], v[68:69] op_sel_hi:[0,1]
	s_waitcnt lgkmcnt(4)
	v_mfma_f32_16x16x32_bf16 v[48:51], v[244:247], v[48:51], v[52:55]
	s_waitcnt lgkmcnt(3)
	v_mfma_f32_16x16x32_bf16 v[44:47], v[76:79], v[44:47], v[48:51]
	s_waitcnt lgkmcnt(2)
	v_mfma_f32_16x16x32_bf16 v[40:43], v[128:131], v[40:43], v[44:47]
	s_waitcnt lgkmcnt(1)
	v_mfma_f32_16x16x32_bf16 v[36:39], v[140:143], v[36:39], v[40:43]
	v_cvt_pk_bf16_f32 v81, v60, v61
	v_cvt_pk_bf16_f32 v80, v58, v59
	s_waitcnt lgkmcnt(0)
	v_mfma_f32_16x16x32_bf16 v[32:35], v[144:147], v[32:35], v[36:39]
	s_nop 2
	v_mul_f32_e32 v36, v61, v61
	v_mul_f32_e32 v37, v59, v59
	v_fmac_f32_e32 v36, v60, v60
	v_fmac_f32_e32 v37, v58, v58
	v_add_f32_e32 v36, v36, v37
	v_mul_f32_e32 v37, v65, v65
	v_mul_f32_e32 v38, v63, v63
	v_fmac_f32_e32 v37, v64, v64
	v_fmac_f32_e32 v38, v62, v62
	v_add_f32_e32 v36, v108, v36
	v_add_f32_e32 v37, v37, v38
	v_add_f32_e32 v36, v37, v36
	v_mul_f32_e32 v37, v69, v69
	v_mul_f32_e32 v38, v67, v67
	v_fmac_f32_e32 v37, v68, v68
	v_fmac_f32_e32 v38, v66, v66
	v_pk_mul_f32 v[34:35], v[56:57], v[34:35] op_sel_hi:[0,1]
	v_pk_mul_f32 v[32:33], v[56:57], v[32:33] op_sel_hi:[0,1]
	v_add_f32_e32 v37, v37, v38
	v_add_f32_e32 v36, v37, v36
	v_mul_f32_e32 v37, v33, v33
	v_mul_f32_e32 v38, v35, v35
	v_fmac_f32_e32 v37, v32, v32
	v_fmac_f32_e32 v38, v34, v34
	v_add_f32_e32 v37, v37, v38
	v_cvt_pk_bf16_f32 v83, v64, v65
	v_cvt_pk_bf16_f32 v82, v62, v63
	v_cvt_pk_bf16_f32 v109, v68, v69
	v_cvt_pk_bf16_f32 v108, v66, v67
	v_add_f32_e32 v68, v36, v37
	v_cvt_pk_bf16_f32 v111, v32, v33
	v_cvt_pk_bf16_f32 v110, v34, v35
	global_load_dword v69, v185, s[12:13] offset:12
	s_waitcnt lgkmcnt(0)
	ds_read_b128 v[112:115], v107
	ds_read_b128 v[116:119], v107 offset:64
	ds_read_b128 v[120:123], v107 offset:576
	ds_read_b128 v[124:127], v107 offset:640
	ds_read_b128 v[128:131], v107 offset:4608
	ds_read_b128 v[132:135], v107 offset:4672
	ds_read_b128 v[136:139], v107 offset:5184
	ds_read_b128 v[140:143], v107 offset:5248
	ds_read_b128 v[144:147], v107 offset:9216
	ds_read_b128 v[160:163], v107 offset:9280
	ds_read_b128 v[164:167], v107 offset:9792
	ds_read_b128 v[168:171], v107 offset:9856
	ds_read_b128 v[172:175], v107 offset:13824
	ds_read_b128 v[180:183], v107 offset:13888
	s_waitcnt lgkmcnt(13)
	v_mfma_f32_16x16x32_bf16 v[32:35], v[112:115], v[20:23], v[28:31]
	s_waitcnt vmcnt(0)
	v_mul_f32_e32 v70, 0x3fb8aa3b, v69
	s_waitcnt lgkmcnt(12)
	v_mfma_f32_16x16x32_bf16 v[52:55], v[116:119], v[16:19], v[32:35]
	ds_read_b128 v[196:199], v107 offset:14400
	ds_read_b128 v[200:203], v107 offset:14464
	s_waitcnt lgkmcnt(13)
; #define LAS __attribute__((address_space(3)))
; #define LAS __attribute__((address_space(3)))
; __device__ __forceinline__ f32x4 mfma16(bf16x8 a, bf16x8 b, f32x4 c) { return __builtin_amdgcn_mfma_f32_16x16x32_bf16(a, b, c, 0, 0, 0); }
; template <int NKT, int VSTR, bool SINK>
; __device__ __forceinline__ void attn_core(LAS const unsigned char* kb_, LAS const unsigned char* vb_, bf16x8 q0, bf16x8 q1, float sk, unsigned mskbits, int fr, f32x4 (&o)[4]) {
;     ...
;     for (int kt = 0; kt < NKT; ++kt) {
;         const int key = (kt >> 1) * 32 + ((kt & 1) << 2) + krow;
;         LAS const unsigned char* kp = kb_ + key * 144;
;         const bf16x8 a0 = *(LAS const bf16x8*)kp, a1 = *(LAS const bf16x8*)(kp + 64);
;         const float bias = ((mskbits >> (kt >> 2)) & 1u) ? -1e30f : 0.f;
;         f32x4 s = mfma16(a0, q0, (f32x4){bias, bias, bias, bias});
;         s = mfma16(a1, q1, s);
;         S[kt] = s;
;     }
;     float mx = S[0][0];
; #pragma unroll
;     for (int kt = 0; kt < NKT; ++kt) mx = fmaxf(fmaxf(mx, fmaxf(S[kt][0], S[kt][1])), fmaxf(S[kt][2], S[kt][3]));
;     mx = fmaxf(mx, __shfl_xor(mx, 16)); mx = fmaxf(mx, __shfl_xor(mx, 32));
	v_mfma_f32_16x16x32_bf16 v[32:35], v[120:123], v[20:23], v[28:31]
	s_waitcnt lgkmcnt(12)
	v_mfma_f32_16x16x32_bf16 v[48:51], v[124:127], v[16:19], v[32:35]
	ds_read_b128 v[204:207], v107 offset:18432
	ds_read_b128 v[224:227], v107 offset:18496
	s_waitcnt lgkmcnt(13)
	v_mfma_f32_16x16x32_bf16 v[32:35], v[128:131], v[20:23], v[28:31]
	s_waitcnt lgkmcnt(12)
	v_mfma_f32_16x16x32_bf16 v[40:43], v[132:135], v[16:19], v[32:35]
	ds_read_b128 v[228:231], v107 offset:19008
	ds_read_b128 v[232:235], v107 offset:19072
	s_waitcnt lgkmcnt(13)
	v_mfma_f32_16x16x32_bf16 v[28:31], v[136:139], v[20:23], v[28:31]
	s_waitcnt lgkmcnt(12)
	v_mfma_f32_16x16x32_bf16 v[32:35], v[140:143], v[16:19], v[28:31]
	ds_read_b128 v[236:239], v107 offset:23040
	ds_read_b128 v[240:243], v107 offset:23104
	s_waitcnt lgkmcnt(13)
	v_mfma_f32_16x16x32_bf16 v[28:31], v[144:147], v[20:23], v[24:27]
	s_waitcnt lgkmcnt(12)
	v_mfma_f32_16x16x32_bf16 v[28:31], v[160:163], v[16:19], v[28:31]
	ds_read_b128 v[244:247], v107 offset:23616
	ds_read_b128 v[112:115], v107 offset:23680
	s_waitcnt lgkmcnt(13)
	v_mfma_f32_16x16x32_bf16 v[36:39], v[164:167], v[20:23], v[24:27]
	s_waitcnt lgkmcnt(12)
	v_mfma_f32_16x16x32_bf16 v[36:39], v[168:171], v[16:19], v[36:39]
	s_waitcnt lgkmcnt(11)
	v_mfma_f32_16x16x32_bf16 v[44:47], v[172:175], v[20:23], v[24:27]
	s_waitcnt lgkmcnt(10)
	v_mfma_f32_16x16x32_bf16 v[44:47], v[180:183], v[16:19], v[44:47]
	s_waitcnt lgkmcnt(9)
	v_mfma_f32_16x16x32_bf16 v[24:27], v[196:199], v[20:23], v[24:27]
	s_waitcnt lgkmcnt(8)
	v_mfma_f32_16x16x32_bf16 v[24:27], v[200:203], v[16:19], v[24:27]
	s_waitcnt lgkmcnt(7)
	v_mfma_f32_16x16x32_bf16 v[56:59], v[204:207], v[20:23], 0
	s_waitcnt lgkmcnt(6)
	v_mfma_f32_16x16x32_bf16 v[56:59], v[224:227], v[16:19], v[56:59]
	s_waitcnt lgkmcnt(5)
	v_mfma_f32_16x16x32_bf16 v[60:63], v[228:231], v[20:23], 0
	s_waitcnt lgkmcnt(4)
	v_mfma_f32_16x16x32_bf16 v[60:63], v[232:235], v[16:19], v[60:63]
	s_waitcnt lgkmcnt(3)
	v_mfma_f32_16x16x32_bf16 v[64:67], v[236:239], v[20:23], 0
	s_waitcnt lgkmcnt(2)
	v_mfma_f32_16x16x32_bf16 v[64:67], v[240:243], v[16:19], v[64:67]
	s_waitcnt lgkmcnt(1)
	v_mfma_f32_16x16x32_bf16 v[20:23], v[244:247], v[20:23], 0
	s_waitcnt lgkmcnt(0)
	v_mfma_f32_16x16x32_bf16 v[16:19], v[112:115], v[16:19], v[20:23]
	s_nop 5
	v_max_f32_e32 v20, v55, v55
	v_max_f32_e32 v21, v54, v54
	v_max_f32_e32 v20, v21, v20
	v_max_f32_e32 v21, v49, v49
	v_max_f32_e32 v22, v48, v48
	v_max_f32_e32 v21, v22, v21
	v_max_f32_e32 v22, v51, v51
	v_max_f32_e32 v23, v50, v50
	v_max3_f32 v20, v52, v53, v20
	v_max_f32_e32 v22, v23, v22
	v_max3_f32 v20, v20, v21, v22
	v_max_f32_e32 v21, v41, v41
	v_max_f32_e32 v22, v40, v40
	v_max_f32_e32 v21, v22, v21
	v_max_f32_e32 v22, v43, v43
	v_max_f32_e32 v23, v42, v42
	v_max_f32_e32 v22, v23, v22
	v_max3_f32 v20, v20, v21, v22
	v_max_f32_e32 v21, v33, v33
	v_max_f32_e32 v22, v32, v32
	v_max_f32_e32 v21, v22, v21
	v_max_f32_e32 v22, v35, v35
	v_max_f32_e32 v23, v34, v34
	v_max_f32_e32 v22, v23, v22
	v_max3_f32 v20, v20, v21, v22
	v_max_f32_e32 v21, v29, v29
	v_max_f32_e32 v22, v28, v28
	v_max_f32_e32 v21, v22, v21
	v_max_f32_e32 v22, v31, v31
	v_max_f32_e32 v23, v30, v30
	v_max_f32_e32 v22, v23, v22
	v_max3_f32 v20, v20, v21, v22
	v_max_f32_e32 v21, v37, v37
	v_max_f32_e32 v22, v36, v36
	v_max_f32_e32 v21, v22, v21
	v_max_f32_e32 v22, v39, v39
	v_max_f32_e32 v23, v38, v38
	v_max_f32_e32 v22, v23, v22
	v_max3_f32 v20, v20, v21, v22
	v_max_f32_e32 v21, v45, v45
	v_max_f32_e32 v22, v44, v44
	v_max_f32_e32 v21, v22, v21
	v_max_f32_e32 v22, v47, v47
	v_max_f32_e32 v23, v46, v46
	v_max_f32_e32 v22, v23, v22
	v_max3_f32 v20, v20, v21, v22
	v_max_f32_e32 v21, v25, v25
	v_max_f32_e32 v22, v24, v24
	v_max_f32_e32 v21, v22, v21
	v_max_f32_e32 v22, v27, v27
	v_max_f32_e32 v23, v26, v26
	v_max_f32_e32 v22, v23, v22
	v_max3_f32 v20, v20, v21, v22
	v_max_f32_e32 v21, v57, v57
	v_max_f32_e32 v22, v56, v56
	v_max_f32_e32 v21, v22, v21
	v_max_f32_e32 v22, v59, v59
	v_max_f32_e32 v23, v58, v58
	v_max_f32_e32 v22, v23, v22
	v_max3_f32 v20, v20, v21, v22
	v_max_f32_e32 v21, v61, v61
	v_max_f32_e32 v22, v60, v60
	v_max_f32_e32 v21, v22, v21
	v_max_f32_e32 v22, v63, v63
	v_max_f32_e32 v23, v62, v62
	v_max_f32_e32 v22, v23, v22
	v_max3_f32 v20, v20, v21, v22
	v_max_f32_e32 v21, v65, v65
	v_max_f32_e32 v22, v64, v64
	v_max_f32_e32 v21, v22, v21
	v_max_f32_e32 v22, v67, v67
	v_max_f32_e32 v23, v66, v66
	v_max_f32_e32 v22, v23, v22
	v_max3_f32 v20, v20, v21, v22
	v_max_f32_e32 v21, v17, v17
	v_max_f32_e32 v22, v16, v16
	v_max_f32_e32 v21, v22, v21
	v_max_f32_e32 v22, v19, v19
	v_max_f32_e32 v23, v18, v18
	v_max_f32_e32 v22, v23, v22
	v_max3_f32 v20, v20, v21, v22
	ds_bpermute_b32 v21, v212, v20
	s_waitcnt lgkmcnt(0)
	v_max_f32_e32 v21, v21, v21
	v_max_f32_e32 v20, v20, v21
	ds_bpermute_b32 v21, v176, v20
	s_waitcnt lgkmcnt(0)
; #define LAS __attribute__((address_space(3)))
; #define LAS __attribute__((address_space(3)))
; __device__ __forceinline__ unsigned pk2(float lo, float hi) { return pg8::cvt_pk_bf16(lo, hi); }
; template <int NKT, int VSTR, bool SINK>
; __device__ __forceinline__ void attn_core(LAS const unsigned char* kb_, LAS const unsigned char* vb_, bf16x8 q0, bf16x8 q1, float sk, unsigned mskbits, int fr, f32x4 (&o)[4]) {
;     ...
;     float mx = S[0][0];
; #pragma unroll
;     for (int kt = 0; kt < NKT; ++kt) mx = fmaxf(fmaxf(mx, fmaxf(S[kt][0], S[kt][1])), fmaxf(S[kt][2], S[kt][3]));
;     mx = fmaxf(mx, __shfl_xor(mx, 16)); mx = fmaxf(mx, __shfl_xor(mx, 32));
;     if (SINK) mx = fmaxf(mx, sk);
;     float sum = 0.f;
; #pragma unroll
;     for (int kt = 0; kt < NKT; ++kt)
; #pragma unroll
;         for (int r = 0; r < 4; ++r) { const float p = __builtin_amdgcn_exp2f(S[kt][r] - mx); S[kt][r] = p; sum += p; }
;     sum += __shfl_xor(sum, 16); sum += __shfl_xor(sum, 32);
;     if (SINK) sum += __builtin_amdgcn_exp2f(sk - mx);
;     const float inv = 1.0f / sum;
;     bf16x8 pf[NKT / 2];
; #pragma unroll
;     for (int kb = 0; kb < NKT / 2; ++kb) {
;         v4u w; w.x = pk2(S[2 * kb][0], S[2 * kb][1]); w.y = pk2(S[2 * kb][2], S[2 * kb][3]); w.z = pk2(S[2 * kb + 1][0], S[2 * kb + 1][1]); w.w = pk2(S[2 * kb + 1][2], S[2 * kb + 1][3]);
;         pf[kb] = __builtin_bit_cast(bf16x8, w);
;     }
; #pragma unroll
;     for (int dt = 0; dt < 4; ++dt) {
;         f32x4 acc = (f32x4){0.f, 0.f, 0.f, 0.f};
; #pragma unroll
;         for (int kb = 0; kb < NKT / 2; ++kb) {
;             const bf16x8 vf = *(LAS const bf16x8*)(vb_ + dt * 16 * VSTR + kb * 64);
	v_max3_f32 v20, v20, v21, v70
	v_sub_f32_e32 v21, v52, v20
	v_exp_f32_e32 v21, v21
	v_sub_f32_e32 v23, v53, v20
	v_exp_f32_e32 v23, v23
	v_sub_f32_e32 v52, v54, v20
	v_exp_f32_e32 v52, v52
	v_sub_f32_e32 v53, v55, v20
	v_exp_f32_e32 v53, v53
	v_sub_f32_e32 v48, v48, v20
	v_add_f32_e32 v22, 0, v21
	v_exp_f32_e32 v48, v48
	v_sub_f32_e32 v49, v49, v20
	v_add_f32_e32 v22, v23, v22
	v_exp_f32_e32 v49, v49
	v_sub_f32_e32 v50, v50, v20
	v_add_f32_e32 v22, v52, v22
	v_exp_f32_e32 v50, v50
	v_sub_f32_e32 v51, v51, v20
	v_add_f32_e32 v22, v53, v22
	v_exp_f32_e32 v51, v51
	v_sub_f32_e32 v40, v40, v20
	v_add_f32_e32 v22, v48, v22
	v_exp_f32_e32 v40, v40
	v_sub_f32_e32 v41, v41, v20
	v_add_f32_e32 v22, v49, v22
	v_exp_f32_e32 v41, v41
	v_sub_f32_e32 v42, v42, v20
	v_add_f32_e32 v22, v50, v22
	v_exp_f32_e32 v42, v42
	v_sub_f32_e32 v43, v43, v20
	v_add_f32_e32 v22, v51, v22
	v_exp_f32_e32 v43, v43
	v_sub_f32_e32 v32, v32, v20
	v_add_f32_e32 v22, v40, v22
	v_exp_f32_e32 v54, v32
	v_sub_f32_e32 v32, v33, v20
	v_add_f32_e32 v22, v41, v22
	v_exp_f32_e32 v55, v32
	v_sub_f32_e32 v32, v34, v20
	v_add_f32_e32 v22, v42, v22
	v_exp_f32_e32 v70, v32
	v_sub_f32_e32 v32, v35, v20
	v_add_f32_e32 v22, v43, v22
	v_exp_f32_e32 v35, v32
	v_sub_f32_e32 v28, v28, v20
	v_add_f32_e32 v22, v54, v22
	v_exp_f32_e32 v28, v28
	v_sub_f32_e32 v29, v29, v20
	v_add_f32_e32 v22, v55, v22
	v_exp_f32_e32 v29, v29
	v_sub_f32_e32 v30, v30, v20
	v_add_f32_e32 v22, v70, v22
	v_exp_f32_e32 v30, v30
	v_sub_f32_e32 v31, v31, v20
	v_add_f32_e32 v22, v35, v22
	v_exp_f32_e32 v31, v31
	v_sub_f32_e32 v32, v36, v20
	v_add_f32_e32 v22, v28, v22
	v_exp_f32_e32 v71, v32
	v_sub_f32_e32 v32, v37, v20
	v_add_f32_e32 v22, v29, v22
	v_exp_f32_e32 v72, v32
	v_sub_f32_e32 v32, v38, v20
	v_add_f32_e32 v22, v30, v22
	v_exp_f32_e32 v73, v32
	v_sub_f32_e32 v32, v39, v20
	v_add_f32_e32 v22, v31, v22
	v_exp_f32_e32 v74, v32
	v_sub_f32_e32 v32, v44, v20
	v_add_f32_e32 v22, v71, v22
	v_exp_f32_e32 v44, v32
	v_sub_f32_e32 v32, v45, v20
	v_add_f32_e32 v22, v72, v22
	v_exp_f32_e32 v45, v32
	v_sub_f32_e32 v32, v46, v20
	v_add_f32_e32 v22, v73, v22
	v_exp_f32_e32 v46, v32
	v_sub_f32_e32 v32, v47, v20
	v_add_f32_e32 v22, v74, v22
	v_exp_f32_e32 v47, v32
	v_sub_f32_e32 v24, v24, v20
	v_add_f32_e32 v22, v44, v22
	v_exp_f32_e32 v75, v24
	v_sub_f32_e32 v24, v25, v20
	v_add_f32_e32 v22, v45, v22
	v_exp_f32_e32 v76, v24
	v_sub_f32_e32 v24, v26, v20
	v_add_f32_e32 v22, v46, v22
	v_exp_f32_e32 v77, v24
	v_sub_f32_e32 v24, v27, v20
	v_add_f32_e32 v22, v47, v22
	v_exp_f32_e32 v27, v24
	v_sub_f32_e32 v24, v56, v20
	v_add_f32_e32 v22, v75, v22
	v_exp_f32_e32 v56, v24
	v_sub_f32_e32 v24, v57, v20
	v_add_f32_e32 v22, v76, v22
	v_exp_f32_e32 v57, v24
	v_sub_f32_e32 v24, v58, v20
	v_add_f32_e32 v22, v77, v22
	v_exp_f32_e32 v58, v24
	v_sub_f32_e32 v24, v59, v20
	v_add_f32_e32 v22, v27, v22
	v_exp_f32_e32 v59, v24
	v_sub_f32_e32 v24, v60, v20
	v_add_f32_e32 v22, v56, v22
	v_exp_f32_e32 v60, v24
	v_sub_f32_e32 v24, v61, v20
	v_add_f32_e32 v22, v57, v22
	v_exp_f32_e32 v61, v24
	v_sub_f32_e32 v24, v62, v20
	v_add_f32_e32 v22, v58, v22
	v_exp_f32_e32 v62, v24
	v_sub_f32_e32 v24, v63, v20
	v_add_f32_e32 v22, v59, v22
	v_exp_f32_e32 v63, v24
	v_sub_f32_e32 v24, v64, v20
	v_add_f32_e32 v22, v60, v22
	v_exp_f32_e32 v64, v24
	v_sub_f32_e32 v24, v65, v20
	v_add_f32_e32 v22, v61, v22
	v_exp_f32_e32 v65, v24
	v_sub_f32_e32 v24, v66, v20
	v_add_f32_e32 v22, v62, v22
	v_exp_f32_e32 v66, v24
	v_sub_f32_e32 v24, v67, v20
	v_add_f32_e32 v22, v63, v22
	v_exp_f32_e32 v67, v24
	v_sub_f32_e32 v16, v16, v20
	v_add_f32_e32 v22, v64, v22
	v_exp_f32_e32 v78, v16
	v_sub_f32_e32 v17, v17, v20
	v_add_f32_e32 v22, v65, v22
	v_exp_f32_e32 v79, v17
	v_sub_f32_e32 v17, v18, v20
	v_add_f32_e32 v22, v66, v22
	v_exp_f32_e32 v107, v17
	v_sub_f32_e32 v17, v19, v20
	v_add_f32_e32 v22, v67, v22
	v_exp_f32_e32 v19, v17
	v_add_f32_e32 v16, v78, v22
	v_add_f32_e32 v16, v79, v16
	v_add_f32_e32 v16, v107, v16
	v_add_f32_e32 v16, v19, v16
	ds_bpermute_b32 v17, v212, v16
	v_cvt_pk_bf16_f32 v36, v21, v23
	v_cvt_pk_bf16_f32 v37, v52, v53
	v_cvt_pk_bf16_f32 v38, v48, v49
	v_cvt_pk_bf16_f32 v39, v50, v51
	s_waitcnt lgkmcnt(0)
	v_add_f32_e32 v16, v16, v17
	ds_bpermute_b32 v17, v176, v16
	v_cvt_pk_bf16_f32 v32, v40, v41
	v_cvt_pk_bf16_f32 v33, v42, v43
	v_cvt_pk_bf16_f32 v34, v54, v55
	v_cvt_pk_bf16_f32 v35, v70, v35
	s_waitcnt lgkmcnt(0)
	v_add_f32_e32 v16, v16, v17
	v_fma_f32 v17, v69, s2, -v20
	v_exp_f32_e32 v17, v17
	v_cvt_pk_bf16_f32 v28, v28, v29
	v_cvt_pk_bf16_f32 v29, v30, v31
	v_cvt_pk_bf16_f32 v30, v71, v72
	v_cvt_pk_bf16_f32 v31, v73, v74
	v_cvt_pk_bf16_f32 v24, v44, v45
	s_nop 0
	v_add_f32_e32 v69, v17, v16
	v_div_scale_f32 v40, s[0:1], v69, v69, 1.0
	v_rcp_f32_e32 v41, v40
	v_cvt_pk_bf16_f32 v25, v46, v47
	v_cvt_pk_bf16_f32 v26, v75, v76
	v_cvt_pk_bf16_f32 v27, v77, v27
	v_cvt_pk_bf16_f32 v20, v56, v57
	v_cvt_pk_bf16_f32 v21, v58, v59
	s_nop 0
	v_fma_f32 v42, -v40, v41, 1.0
	v_fmac_f32_e32 v41, v42, v41
	v_div_scale_f32 v42, vcc, 1.0, v69, 1.0
	v_mul_f32_e32 v43, v42, v41
	v_fma_f32 v44, -v40, v43, v42
	v_fmac_f32_e32 v43, v44, v41
	v_fma_f32 v40, -v40, v43, v42
	v_cvt_pk_bf16_f32 v22, v60, v61
	v_cvt_pk_bf16_f32 v23, v62, v63
	v_cvt_pk_bf16_f32 v16, v64, v65
	v_cvt_pk_bf16_f32 v17, v66, v67
	v_cvt_pk_bf16_f32 v18, v78, v79
	v_cvt_pk_bf16_f32 v19, v107, v19
	v_div_fmas_f32 v40, v40, v41, v43
	s_waitcnt lgkmcnt(0)
; #define LAS __attribute__((address_space(3)))
; __device__ __forceinline__ float quad_sum(float s) { s += __shfl_xor(s, 16); s += __shfl_xor(s, 32); return s; }
; __device__ __forceinline__ float sq4(const f32x4 a) { return (a[0] * a[0] + a[1] * a[1]) + (a[2] * a[2] + a[3] * a[3]); }
; #define LAS __attribute__((address_space(3)))
; __device__ __forceinline__ unsigned pk2(float lo, float hi) { return pg8::cvt_pk_bf16(lo, hi); }
; __device__ __forceinline__ f32x4 mfma16(bf16x8 a, bf16x8 b, f32x4 c) { return __builtin_amdgcn_mfma_f32_16x16x32_bf16(a, b, c, 0, 0, 0); }
; template <int NKT, int VSTR, bool SINK>
; __device__ __forceinline__ void attn_core(LAS const unsigned char* kb_, LAS const unsigned char* vb_, bf16x8 q0, bf16x8 q1, float sk, unsigned mskbits, int fr, f32x4 (&o)[4]) {
;     ...
; #pragma unroll
;     for (int dt = 0; dt < 4; ++dt) {
;         f32x4 acc = (f32x4){0.f, 0.f, 0.f, 0.f};
; #pragma unroll
;         for (int kb = 0; kb < NKT / 2; ++kb) {
;             const bf16x8 vf = *(LAS const bf16x8*)(vb_ + dt * 16 * VSTR + kb * 64);
;             acc = mfma16(vf, pf[kb], acc);
;         }
;         o[dt] = acc * inv;
;     }
; template <bool DO_SWA, bool DO_MEM>
; __device__ __forceinline__ void attn_unit(const Args& a, unsigned char* ws, LAS unsigned char* lds, int l, int tid_in, int lane_in, int wave, int unit) {
;     ...
;                 for (int dt = 0; dt < 4; ++dt) { ssq += pg8::sq4(o[dt]); osv[hh][dt] = (v2u){pk2(o[dt][0], o[dt][1]), pk2(o[dt][2], o[dt][3])}; }
;             }
;             ssq = pg8::quad_sum(ssq);
;             if (fq == 0) red_a[g * 64 + qs * 16 + fr] = ssq;
	ds_read_b128 v[112:115], v106 offset:55296
	ds_read_b128 v[116:119], v106 offset:55360
	ds_read_b128 v[120:123], v106 offset:61760
	ds_read_b128 v[124:127], v105 offset:12864
	ds_read_b128 v[128:131], v106 offset:55424
	ds_read_b128 v[132:135], v106 offset:55488
	ds_read_b128 v[136:139], v106 offset:55552
	ds_read_b128 v[140:143], v106 offset:55616
	ds_read_b128 v[144:147], v106 offset:61696
	ds_read_b128 v[160:163], v106 offset:61824
	ds_read_b128 v[164:167], v106 offset:61888
	ds_read_b128 v[168:171], v106 offset:61952
	ds_read_b128 v[172:175], v106 offset:62016
	ds_read_b128 v[180:183], v105 offset:12800
	s_waitcnt lgkmcnt(13)
	v_mfma_f32_16x16x32_bf16 v[42:45], v[112:115], v[36:39], 0
	ds_read_b128 v[196:199], v105 offset:12928
	v_div_fixup_f32 v40, v40, v69, 1.0
	s_waitcnt lgkmcnt(13)
	v_mfma_f32_16x16x32_bf16 v[42:45], v[116:119], v[32:35], v[42:45]
	ds_read_b128 v[200:203], v105 offset:12992
	s_waitcnt lgkmcnt(11)
	v_mfma_f32_16x16x32_bf16 v[42:45], v[128:131], v[28:31], v[42:45]
	ds_read_b128 v[204:207], v105 offset:13056
	ds_read_b128 v[224:227], v105 offset:13120
	s_waitcnt lgkmcnt(12)
	v_mfma_f32_16x16x32_bf16 v[42:45], v[132:135], v[24:27], v[42:45]
	ds_read_b128 v[228:231], v105 offset:19200
	s_waitcnt lgkmcnt(12)
	v_mfma_f32_16x16x32_bf16 v[42:45], v[136:139], v[20:23], v[42:45]
	ds_read_b128 v[232:235], v105 offset:19264
	s_waitcnt lgkmcnt(12)
	v_mfma_f32_16x16x32_bf16 v[44:47], v[140:143], v[16:19], v[42:45]
	s_nop 7
	v_pk_mul_f32 v[42:43], v[46:47], v[40:41] op_sel_hi:[1,0]
	ds_read_b128 v[236:239], v105 offset:19328
	s_waitcnt lgkmcnt(12)
	v_mfma_f32_16x16x32_bf16 v[46:49], v[144:147], v[36:39], 0
	v_mul_f32_e64 v44, v44, v40
	v_mul_f32_e64 v45, v45, v40
	v_mfma_f32_16x16x32_bf16 v[46:49], v[120:123], v[32:35], v[46:49]
	ds_read_b128 v[240:243], v105 offset:19392
	s_waitcnt lgkmcnt(12)
	v_mfma_f32_16x16x32_bf16 v[46:49], v[160:163], v[28:31], v[46:49]
	ds_read_b128 v[244:247], v105 offset:19456
	s_waitcnt lgkmcnt(12)
	v_mfma_f32_16x16x32_bf16 v[46:49], v[164:167], v[24:27], v[46:49]
	ds_read_b128 v[112:115], v105 offset:19520
	s_waitcnt lgkmcnt(12)
	v_mfma_f32_16x16x32_bf16 v[46:49], v[168:171], v[20:23], v[46:49]
	s_waitcnt lgkmcnt(11)
	v_mfma_f32_16x16x32_bf16 v[48:51], v[172:175], v[16:19], v[46:49]
	s_nop 7
	v_pk_mul_f32 v[46:47], v[50:51], v[40:41] op_sel_hi:[1,0]
	s_waitcnt lgkmcnt(10)
	v_mfma_f32_16x16x32_bf16 v[50:53], v[180:183], v[36:39], 0
	v_mul_f32_e64 v48, v48, v40
	v_mul_f32_e64 v49, v49, v40
	v_mfma_f32_16x16x32_bf16 v[50:53], v[124:127], v[32:35], v[50:53]
	s_waitcnt lgkmcnt(9)
	v_mfma_f32_16x16x32_bf16 v[50:53], v[196:199], v[28:31], v[50:53]
	s_waitcnt lgkmcnt(8)
	v_mfma_f32_16x16x32_bf16 v[50:53], v[200:203], v[24:27], v[50:53]
	s_waitcnt lgkmcnt(7)
	v_mfma_f32_16x16x32_bf16 v[50:53], v[204:207], v[20:23], v[50:53]
	s_waitcnt lgkmcnt(6)
	v_mfma_f32_16x16x32_bf16 v[50:53], v[224:227], v[16:19], v[50:53]
	s_nop 7
	v_pk_mul_f32 v[54:55], v[40:41], v[52:53] op_sel_hi:[0,1]
	v_pk_mul_f32 v[56:57], v[40:41], v[50:51] op_sel_hi:[0,1]
	s_waitcnt lgkmcnt(5)
	v_mfma_f32_16x16x32_bf16 v[36:39], v[228:231], v[36:39], 0
	s_waitcnt lgkmcnt(4)
	v_mfma_f32_16x16x32_bf16 v[32:35], v[232:235], v[32:35], v[36:39]
	s_waitcnt lgkmcnt(3)
	v_mfma_f32_16x16x32_bf16 v[28:31], v[236:239], v[28:31], v[32:35]
	s_waitcnt lgkmcnt(2)
	v_mfma_f32_16x16x32_bf16 v[24:27], v[240:243], v[24:27], v[28:31]
	s_waitcnt lgkmcnt(1)
	v_mfma_f32_16x16x32_bf16 v[20:23], v[244:247], v[20:23], v[24:27]
	v_cvt_pk_bf16_f32 v106, v44, v45
	v_cvt_pk_bf16_f32 v105, v42, v43
	s_waitcnt lgkmcnt(0)
	v_mfma_f32_16x16x32_bf16 v[16:19], v[112:115], v[16:19], v[20:23]
	s_nop 2
	v_mul_f32_e32 v20, v45, v45
	v_mul_f32_e32 v21, v43, v43
	v_fmac_f32_e32 v20, v44, v44
	v_fmac_f32_e32 v21, v42, v42
	v_add_f32_e32 v20, v20, v21
	v_mul_f32_e32 v21, v49, v49
	v_mul_f32_e32 v22, v47, v47
	v_fmac_f32_e32 v21, v48, v48
	v_fmac_f32_e32 v22, v46, v46
	v_add_f32_e32 v20, v68, v20
	v_add_f32_e32 v21, v21, v22
	v_add_f32_e32 v20, v21, v20
	v_mul_f32_e32 v21, v57, v57
	v_mul_f32_e32 v22, v55, v55
	v_fmac_f32_e32 v21, v56, v56
	v_fmac_f32_e32 v22, v54, v54
	v_pk_mul_f32 v[18:19], v[40:41], v[18:19] op_sel_hi:[0,1]
	v_pk_mul_f32 v[16:17], v[40:41], v[16:17] op_sel_hi:[0,1]
	v_add_f32_e32 v21, v21, v22
	v_add_f32_e32 v20, v21, v20
	v_mul_f32_e32 v21, v17, v17
	v_mul_f32_e32 v22, v19, v19
	v_fmac_f32_e32 v21, v16, v16
	v_fmac_f32_e32 v22, v18, v18
	v_add_f32_e32 v21, v21, v22
	v_add_f32_e32 v20, v20, v21
	v_cvt_pk_bf16_f32 v112, v48, v49
	v_cvt_pk_bf16_f32 v107, v46, v47
	v_cvt_pk_bf16_f32 v114, v56, v57
	v_cvt_pk_bf16_f32 v113, v54, v55
	v_cvt_pk_bf16_f32 v116, v16, v17
	ds_bpermute_b32 v16, v212, v20
	v_cvt_pk_bf16_f32 v115, v18, v19
	s_waitcnt lgkmcnt(0)
	v_add_f32_e32 v16, v20, v16
	ds_bpermute_b32 v17, v176, v16
	s_and_saveexec_b64 s[0:1], s[36:37]
	s_cbranch_execz .LBB0_292
	v_readlane_b32 s2, v251, 30
	s_waitcnt lgkmcnt(0)
	v_add_f32_e32 v16, v16, v17
	v_lshl_add_u32 v18, v210, 2, s2
	ds_write_b32 v18, v16
; template <bool DO_SWA, bool DO_MEM>
; __device__ __forceinline__ void attn_unit(const Args& a, unsigned char* ws, LAS unsigned char* lds, int l, int tid_in, int lane_in, int wave, int unit) {
;     ...
;         if constexpr (DO_MEM) {
; #pragma unroll
;             for (int i = 0; i < 8; ++i) {
;                 const int chn = tid + 512 * i;
;                 mkst[i] = DO_SWA ? *(const v4u*)(MKb + (size_t)(chn >> 4) * 256 + (chn & 15) * 8) : __builtin_nontemporal_load((const v4u*)(MKb + (size_t)(chn >> 4) * 256 + (chn & 15) * 8));
;                 mvst[i] = DO_SWA ? *(const v4u*)(MVTb + (size_t)(chn >> 5) * 256 + (chn & 31) * 8) : __builtin_nontemporal_load((const v4u*)(MVTb + (size_t)(chn >> 5) * 256 + (chn & 31) * 8));
;             }
;         }
;         __syncthreads();
.LBB0_292:
	s_or_b64 exec, exec, s[0:1]
	s_add_i32 s0, s95, s25
	s_ashr_i32 s1, s0, 31
	s_lshl_b64 s[2:3], s[0:1], 17
	s_add_u32 s0, s7, s2
	s_addc_u32 s1, s24, s3
	v_add_u32_e32 v30, 0x400, v213
	s_add_u32 s2, s26, s2
	v_ashrrev_i32_e32 v224, 5, v30
	s_addc_u32 s3, s27, s3
	v_ashrrev_i32_e32 v225, 31, v224
	v_lshl_add_u64 v[18:19], s[2:3], 0, v[184:185]
	v_ashrrev_i32_e32 v182, 4, v30
	v_lshlrev_b64 v[30:31], 9, v[224:225]
	v_lshl_add_u64 v[34:35], v[18:19], 0, v[30:31]
	v_add_u32_e32 v30, 0x600, v213
	v_ashrrev_i32_e32 v234, 5, v30
	v_ashrrev_i32_e32 v235, 31, v234
	v_ashrrev_i32_e32 v232, 4, v30
	v_lshlrev_b64 v[30:31], 9, v[234:235]
	v_lshl_add_u64 v[42:43], v[18:19], 0, v[30:31]
	v_add_u32_e32 v30, 0x800, v213
	v_ashrrev_i32_e32 v238, 5, v30
	v_ashrrev_i32_e32 v239, 31, v238
	v_ashrrev_i32_e32 v236, 4, v30
	v_lshlrev_b64 v[30:31], 9, v[238:239]
	v_mov_b32_e32 v151, v185
	v_lshl_add_u64 v[50:51], v[18:19], 0, v[30:31]
	v_add_u32_e32 v30, 0xa00, v213
	s_waitcnt lgkmcnt(0)
	v_lshl_add_u64 v[16:17], s[0:1], 0, v[150:151]
	v_lshlrev_b64 v[20:21], 9, v[148:149]
	v_ashrrev_i32_e32 v157, 31, v156
	v_ashrrev_i32_e32 v174, 5, v215
	v_ashrrev_i32_e32 v242, 5, v30
	v_lshl_add_u64 v[22:23], v[16:17], 0, v[20:21]
	v_lshlrev_b64 v[24:25], 9, v[156:157]
	v_lshlrev_b64 v[26:27], 9, v[152:153]
	v_ashrrev_i32_e32 v175, 31, v174
	v_ashrrev_i32_e32 v183, 31, v182
	v_ashrrev_i32_e32 v243, 31, v242
	v_lshl_add_u64 v[24:25], v[18:19], 0, v[24:25]
	global_load_dwordx4 v[118:121], v[22:23], off
	global_load_dwordx4 v[122:125], v[24:25], off
	v_lshl_add_u64 v[22:23], v[16:17], 0, v[26:27]
	v_lshlrev_b64 v[28:29], 9, v[174:175]
	v_lshlrev_b64 v[32:33], 9, v[182:183]
	v_ashrrev_i32_e32 v233, 31, v232
	v_ashrrev_i32_e32 v240, 4, v30
	v_lshlrev_b64 v[30:31], 9, v[242:243]
	v_lshl_add_u64 v[28:29], v[18:19], 0, v[28:29]
	global_load_dwordx4 v[126:129], v[22:23], off
	global_load_dwordx4 v[130:133], v[28:29], off
	v_lshl_add_u64 v[22:23], v[16:17], 0, v[32:33]
	v_lshlrev_b64 v[40:41], 9, v[232:233]
	v_ashrrev_i32_e32 v237, 31, v236
	v_lshl_add_u64 v[58:59], v[18:19], 0, v[30:31]
	v_add_u32_e32 v30, 0xc00, v213
	global_load_dwordx4 v[134:137], v[22:23], off
	global_load_dwordx4 v[138:141], v[34:35], off
	v_lshl_add_u64 v[22:23], v[16:17], 0, v[40:41]
	v_lshlrev_b64 v[48:49], 9, v[236:237]
	v_ashrrev_i32_e32 v241, 31, v240
	v_ashrrev_i32_e32 v244, 4, v30
	global_load_dwordx4 v[158:161], v[22:23], off
	global_load_dwordx4 v[162:165], v[42:43], off
	v_lshl_add_u64 v[22:23], v[16:17], 0, v[48:49]
	v_lshlrev_b64 v[56:57], 9, v[240:241]
	v_ashrrev_i32_e32 v245, 31, v244
	v_ashrrev_i32_e32 v246, 5, v30
	global_load_dwordx4 v[166:169], v[22:23], off
	global_load_dwordx4 v[170:173], v[50:51], off
	v_lshl_add_u64 v[22:23], v[16:17], 0, v[56:57]
	v_lshlrev_b64 v[64:65], 9, v[244:245]
	v_ashrrev_i32_e32 v247, 31, v246
	global_load_dwordx4 v[178:181], v[22:23], off
	global_load_dwordx4 v[194:197], v[58:59], off
	v_lshl_add_u64 v[22:23], v[16:17], 0, v[64:65]
	v_lshlrev_b64 v[30:31], 9, v[246:247]
	v_lshl_add_u64 v[66:67], v[18:19], 0, v[30:31]
	global_load_dwordx4 v[198:201], v[22:23], off
	global_load_dwordx4 v[202:205], v[66:67], off
	v_add_u32_e32 v22, 0xe00, v213
	v_ashrrev_i32_e32 v248, 4, v22
	v_ashrrev_i32_e32 v249, 31, v248
	v_ashrrev_i32_e32 v226, 5, v22
	v_lshlrev_b64 v[72:73], 9, v[248:249]
	v_ashrrev_i32_e32 v227, 31, v226
	v_lshl_add_u64 v[16:17], v[16:17], 0, v[72:73]
	v_lshlrev_b64 v[22:23], 9, v[226:227]
	s_mov_b32 s2, 0x10000
	v_lshl_add_u64 v[74:75], v[18:19], 0, v[22:23]
	global_load_dwordx4 v[206:209], v[16:17], off
	global_load_dwordx4 v[228:231], v[74:75], off
	v_lshl_add_u64 v[16:17], s[0:1], 0, v[20:21]
	v_add_co_u32_e32 v20, vcc, s2, v24
	v_lshl_add_u64 v[32:33], s[0:1], 0, v[32:33]
	s_nop 0
	v_addc_co_u32_e32 v21, vcc, 0, v25, vcc
	v_add_co_u32_e32 v28, vcc, s2, v28
	v_lshl_add_u64 v[24:25], s[0:1], 0, v[26:27]
	s_nop 0
	v_addc_co_u32_e32 v29, vcc, 0, v29, vcc
	v_add_co_u32_e32 v36, vcc, s2, v34
	v_lshl_add_u64 v[40:41], s[0:1], 0, v[40:41]
	s_nop 0
	v_addc_co_u32_e32 v37, vcc, 0, v35, vcc
	v_add_co_u32_e32 v44, vcc, s2, v42
	v_lshl_add_u64 v[48:49], s[0:1], 0, v[48:49]
	s_nop 0
	v_addc_co_u32_e32 v45, vcc, 0, v43, vcc
	v_add_co_u32_e32 v52, vcc, s2, v50
	v_lshl_add_u64 v[56:57], s[0:1], 0, v[56:57]
	s_nop 0
	v_addc_co_u32_e32 v53, vcc, 0, v51, vcc
	v_add_co_u32_e32 v60, vcc, s2, v58
	v_lshl_add_u64 v[64:65], s[0:1], 0, v[64:65]
	s_nop 0
	v_addc_co_u32_e32 v61, vcc, 0, v59, vcc
	v_add_co_u32_e32 v68, vcc, s2, v66
	v_lshl_add_u64 v[72:73], s[0:1], 0, v[72:73]
	s_nop 0
	v_addc_co_u32_e32 v69, vcc, 0, v67, vcc
	v_add_co_u32_e32 v76, vcc, s2, v74
	v_lshl_add_u64 v[16:17], v[16:17], 0, v[150:151]
	v_lshl_add_u64 v[24:25], v[24:25], 0, v[150:151]
	v_lshl_add_u64 v[32:33], v[32:33], 0, v[150:151]
	v_lshl_add_u64 v[40:41], v[40:41], 0, v[150:151]
	v_lshl_add_u64 v[48:49], v[48:49], 0, v[150:151]
	v_lshl_add_u64 v[56:57], v[56:57], 0, v[150:151]
	v_lshl_add_u64 v[64:65], v[64:65], 0, v[150:151]
	v_lshl_add_u64 v[72:73], v[72:73], 0, v[150:151]
	v_addc_co_u32_e32 v77, vcc, 0, v75, vcc
	s_barrier
; #define LAS __attribute__((address_space(3)))
; #define LAS __attribute__((address_space(3)))
; __device__ __forceinline__ unsigned pk2(float lo, float hi) { return pg8::cvt_pk_bf16(lo, hi); }
; template <bool DO_SWA, bool DO_MEM>
; __device__ __forceinline__ void attn_unit(const Args& a, unsigned char* ws, LAS unsigned char* lds, int l, int tid_in, int lane_in, int wave, int unit) {
;     ...
;         if constexpr (DO_MEM)
; #pragma unroll
;         for (int i = 0; i < 8; ++i) {
;             const int chn = tid + 512 * i;
;             { const int key = chn >> 4, c16 = chn & 15; *(LAS v4u*)(lds + A_KS + ((c16 >> 3) * 256 + key) * 144 + (c16 & 7) * 16) = mkst[i]; }
;             { const int col = chn >> 5, kc = chn & 31; *(LAS v4u*)(lds + A_VT2 + col * 528 + kc * 16) = mvst[i]; }
;         }
;         if constexpr (DO_MEM)
; #pragma unroll
;         for (int i = 0; i < 8; ++i) {
;             const int chn = tid + 512 * i;
;             mkst[i] = DO_SWA ? *(const v4u*)(MKb + (size_t)(chn >> 4) * 256 + 128 + (chn & 15) * 8) : __builtin_nontemporal_load((const v4u*)(MKb + (size_t)(chn >> 4) * 256 + 128 + (chn & 15) * 8));
;             mvst[i] = DO_SWA ? *(const v4u*)(MVTb + (size_t)(128 + (chn >> 5)) * 256 + (chn & 31) * 8) : __builtin_nontemporal_load((const v4u*)(MVTb + (size_t)(128 + (chn >> 5)) * 256 + (chn & 31) * 8));
;         }
;         __builtin_amdgcn_sched_barrier(0);
;         if constexpr (DO_SWA) {
;             const float tot = red_a[qs * 16 + fr] + red_a[64 + qs * 16 + fr];
;             const float rs = 1.0f / sqrtf(tot * (1.0f / 512.0f) + EPS);
; #pragma unroll
;             for (int hh = 0; hh < 4; ++hh)
; #pragma unroll
;                 for (int dt = 0; dt < 4; ++dt) {
;                     const v2u p = osv[hh][dt];
;                     v2u w; w.x = pk2(__uint_as_float(p.x << 16) * rs, __uint_as_float(p.x & 0xffff0000u) * rs); w.y = pk2(__uint_as_float(p.y << 16) * rs, __uint_as_float(p.y & 0xffff0000u) * rs);
;                     *(v2u*)(MIX + qrow * D + (g * 4 + hh) * 64 + dt * 16 + 4 * fq) = w;
;                 }
	global_load_dwordx4 v[16:19], v[16:17], off offset:256
	s_nop 0
	global_load_dwordx4 v[20:23], v[20:21], off
	s_nop 0
	global_load_dwordx4 v[24:27], v[24:25], off offset:256
	s_nop 0
	global_load_dwordx4 v[28:31], v[28:29], off
	s_nop 0
	global_load_dwordx4 v[32:35], v[32:33], off offset:256
	s_nop 0
	global_load_dwordx4 v[36:39], v[36:37], off
	s_nop 0
	global_load_dwordx4 v[40:43], v[40:41], off offset:256
	s_nop 0
	global_load_dwordx4 v[44:47], v[44:45], off
	s_nop 0
	global_load_dwordx4 v[48:51], v[48:49], off offset:256
	s_nop 0
	global_load_dwordx4 v[52:55], v[52:53], off
	s_nop 0
	global_load_dwordx4 v[56:59], v[56:57], off offset:256
	s_nop 0
	global_load_dwordx4 v[60:63], v[60:61], off
	s_nop 0
	global_load_dwordx4 v[64:67], v[64:65], off offset:256
	s_nop 0
	global_load_dwordx4 v[68:71], v[68:69], off
	s_nop 0
	global_load_dwordx4 v[72:75], v[72:73], off offset:256
	s_nop 0
	global_load_dwordx4 v[76:79], v[76:77], off
	v_lshlrev_b32_e32 v117, 5, v213
	v_and_b32_e32 v117, 0x100, v117
	v_add_u32_e32 v142, v117, v148
	s_movk_i32 s3, 0x90
	v_mad_u64_u32 v[142:143], s[0:1], v142, s3, v[100:101]
	s_waitcnt vmcnt(31)
	ds_write_b128 v142, v[118:121]
	v_add_u32_e32 v118, v152, v117
	v_and_b32_e32 v104, 0x1f0, v104
	s_add_i32 s2, 0, 0x12000
	v_mad_u64_u32 v[146:147], s[0:1], v118, s3, v[100:101]
	v_add_u32_e32 v118, v182, v117
	v_add_u32_e32 v104, s2, v104
	s_movk_i32 s4, 0x210
	v_mad_u64_u32 v[150:151], s[0:1], v118, s3, v[100:101]
	v_add_u32_e32 v118, v232, v117
	v_mad_u64_u32 v[144:145], s[0:1], v156, s4, v[104:105]
	v_mad_u64_u32 v[148:149], s[0:1], v174, s4, v[104:105]
	v_mad_u64_u32 v[152:153], s[0:1], v224, s4, v[104:105]
	v_mad_u64_u32 v[156:157], s[0:1], v118, s3, v[100:101]
	v_add_u32_e32 v118, v236, v117
	s_waitcnt vmcnt(30)
	ds_write_b128 v144, v[122:125]
	s_waitcnt vmcnt(29)
	ds_write_b128 v146, v[126:129]
	s_waitcnt vmcnt(28)
	ds_write_b128 v148, v[130:133]
	s_waitcnt vmcnt(27)
	ds_write_b128 v150, v[134:137]
	s_waitcnt vmcnt(26)
	ds_write_b128 v152, v[138:141]
	s_waitcnt vmcnt(25)
	ds_write_b128 v156, v[158:161]
	v_mad_u64_u32 v[158:159], s[0:1], v234, s4, v[104:105]
	v_mad_u64_u32 v[160:161], s[0:1], v118, s3, v[100:101]
	v_add_u32_e32 v118, v240, v117
	s_waitcnt vmcnt(24)
	ds_write_b128 v158, v[162:165]
	v_mad_u64_u32 v[162:163], s[0:1], v238, s4, v[104:105]
	v_mad_u64_u32 v[164:165], s[0:1], v118, s3, v[100:101]
	v_add_u32_e32 v118, v244, v117
	v_add_u32_e32 v117, v248, v117
	s_waitcnt vmcnt(23)
	ds_write_b128 v160, v[166:169]
	s_waitcnt vmcnt(22)
	ds_write_b128 v162, v[170:173]
	v_mad_u64_u32 v[166:167], s[0:1], v242, s4, v[104:105]
	v_mad_u64_u32 v[168:169], s[0:1], v118, s3, v[100:101]
	v_mad_u64_u32 v[170:171], s[0:1], v246, s4, v[104:105]
	v_mad_u64_u32 v[172:173], s[0:1], v117, s3, v[100:101]
	v_mad_u64_u32 v[174:175], s[0:1], v226, s4, v[104:105]
	s_waitcnt vmcnt(21)
	ds_write_b128 v164, v[178:181]
	s_waitcnt vmcnt(20)
	ds_write_b128 v166, v[194:197]
	s_waitcnt vmcnt(19)
	ds_write_b128 v168, v[198:201]
	s_waitcnt vmcnt(18)
	ds_write_b128 v170, v[202:205]
	s_waitcnt vmcnt(17)
	ds_write_b128 v172, v[206:209]
	s_waitcnt vmcnt(16)
	ds_write_b128 v174, v[228:231]
	s_add_i32 s0, 0, 0x22800
	v_or_b32_e32 v143, 64, v211
	v_lshl_add_u32 v100, v211, 2, s0
	v_lshl_add_u32 v104, v143, 2, s0
	ds_read_b32 v100, v100
	ds_read_b32 v104, v104
	s_mov_b32 s0, 0xf800000
	s_waitcnt lgkmcnt(0)
	v_add_f32_e32 v100, v100, v104
	v_fmamk_f32 v100, v100, 0x3b000000, v218
	v_cmp_gt_f32_e32 vcc, s0, v100
	v_mul_f32_e32 v104, 0x4f800000, v100
	s_nop 0
	v_cndmask_b32_e32 v100, v100, v104, vcc
	v_sqrt_f32_e32 v104, v100
	s_nop 0
	v_add_u32_e32 v117, -1, v104
	v_fma_f32 v118, -v117, v104, v100
	v_cmp_ge_f32_e64 s[0:1], 0, v118
	v_add_u32_e32 v118, 1, v104
	s_nop 0
	v_cndmask_b32_e64 v117, v104, v117, s[0:1]
	v_fma_f32 v104, -v118, v104, v100
	v_cmp_lt_f32_e64 s[0:1], 0, v104
	s_nop 1
	v_cndmask_b32_e64 v104, v117, v118, s[0:1]
	v_mul_f32_e32 v117, 0x37800000, v104
	v_cndmask_b32_e32 v104, v104, v117, vcc
	v_cmp_class_f32_e32 vcc, v100, v219
	s_nop 1
	v_cndmask_b32_e32 v100, v104, v100, vcc
	v_div_scale_f32 v104, s[0:1], v100, v100, 1.0
	v_rcp_f32_e32 v117, v104
	v_readlane_b32 s0, v253, 49
	v_readlane_b32 s1, v253, 50
	v_fma_f32 v118, -v104, v117, 1.0
	v_fmac_f32_e32 v117, v118, v117
	v_div_scale_f32 v118, vcc, 1.0, v100, 1.0
	v_mul_f32_e32 v119, v118, v117
	v_fma_f32 v120, -v104, v119, v118
	v_fmac_f32_e32 v119, v120, v117
	v_fma_f32 v104, -v104, v119, v118
	v_div_fmas_f32 v104, v104, v117, v119
	v_div_fixup_f32 v100, v104, v100, 1.0
	v_lshlrev_b64 v[118:119], 11, v[154:155]
	v_lshlrev_b32_e32 v120, 2, v214
	v_lshlrev_b32_e32 v104, 16, v93
	v_and_b32_e32 v93, 0xffff0000, v93
	v_lshl_add_u64 v[118:119], s[20:21], 0, v[118:119]
	v_ashrrev_i32_e32 v121, 31, v120
	v_mul_f32_e32 v93, v100, v93
	v_lshl_add_u64 v[140:141], v[120:121], 1, v[118:119]
	v_mul_f32_e32 v104, v100, v104
	v_cvt_pk_bf16_f32 v120, v104, v93
	v_lshlrev_b32_e32 v93, 16, v92
	v_and_b32_e32 v92, 0xffff0000, v92
	v_mul_f32_e32 v93, v100, v93
	v_mul_f32_e32 v92, v100, v92
	v_cvt_pk_bf16_f32 v121, v93, v92
	v_lshlrev_b32_e32 v92, 16, v95
	v_and_b32_e32 v93, 0xffff0000, v95
	v_lshl_add_u64 v[118:119], v[140:141], 0, s[34:35]
	v_mul_f32_e32 v92, v100, v92
	v_mul_f32_e32 v93, v100, v93
	global_store_dwordx2 v[118:119], v[120:121], off
	v_cvt_pk_bf16_f32 v92, v92, v93
	v_lshlrev_b32_e32 v93, 16, v94
	v_mul_f32_e32 v93, v100, v93
	v_and_b32_e32 v94, 0xffff0000, v94
	v_mul_f32_e32 v94, v100, v94
	v_cvt_pk_bf16_f32 v93, v93, v94
	global_store_dwordx2 v[118:119], v[92:93], off offset:32
	v_lshlrev_b32_e32 v92, 16, v97
	v_and_b32_e32 v93, 0xffff0000, v97
	v_mul_f32_e32 v92, v100, v92
; __device__ __forceinline__ unsigned pk2(float lo, float hi) { return pg8::cvt_pk_bf16(lo, hi); }
; template <bool DO_SWA, bool DO_MEM>
; __device__ __forceinline__ void attn_unit(const Args& a, unsigned char* ws, LAS unsigned char* lds, int l, int tid_in, int lane_in, int wave, int unit) {
;     ...
;         if constexpr (DO_SWA) {
;             const float tot = red_a[qs * 16 + fr] + red_a[64 + qs * 16 + fr];
;             const float rs = 1.0f / sqrtf(tot * (1.0f / 512.0f) + EPS);
; #pragma unroll
;             for (int hh = 0; hh < 4; ++hh)
; #pragma unroll
;                 for (int dt = 0; dt < 4; ++dt) {
;                     const v2u p = osv[hh][dt];
;                     v2u w; w.x = pk2(__uint_as_float(p.x << 16) * rs, __uint_as_float(p.x & 0xffff0000u) * rs); w.y = pk2(__uint_as_float(p.y << 16) * rs, __uint_as_float(p.y & 0xffff0000u) * rs);
;                     *(v2u*)(MIX + qrow * D + (g * 4 + hh) * 64 + dt * 16 + 4 * fq) = w;
;                 }
;         }
;         __syncthreads();
	v_mul_f32_e32 v93, v100, v93
	v_cvt_pk_bf16_f32 v92, v92, v93
	v_lshlrev_b32_e32 v93, 16, v96
	v_mul_f32_e32 v93, v100, v93
	v_and_b32_e32 v94, 0xffff0000, v96
	v_mul_f32_e32 v94, v100, v94
	v_cvt_pk_bf16_f32 v93, v93, v94
	global_store_dwordx2 v[118:119], v[92:93], off offset:64
	v_lshlrev_b32_e32 v92, 16, v99
	v_and_b32_e32 v93, 0xffff0000, v99
	v_mul_f32_e32 v92, v100, v92
	v_mul_f32_e32 v93, v100, v93
	v_cvt_pk_bf16_f32 v92, v92, v93
	v_lshlrev_b32_e32 v93, 16, v98
	v_mul_f32_e32 v93, v100, v93
	v_and_b32_e32 v94, 0xffff0000, v98
	v_mul_f32_e32 v94, v100, v94
	v_cvt_pk_bf16_f32 v93, v93, v94
	global_store_dwordx2 v[118:119], v[92:93], off offset:96
	v_lshlrev_b32_e32 v92, 16, v85
	v_and_b32_e32 v85, 0xffff0000, v85
	v_mul_f32_e32 v92, v100, v92
	v_mul_f32_e32 v85, v100, v85
	v_cvt_pk_bf16_f32 v92, v92, v85
	v_lshlrev_b32_e32 v85, 16, v84
	v_and_b32_e32 v84, 0xffff0000, v84
	v_mul_f32_e32 v85, v100, v85
	v_mul_f32_e32 v84, v100, v84
	v_cvt_pk_bf16_f32 v93, v85, v84
	v_lshlrev_b32_e32 v84, 16, v87
	v_and_b32_e32 v85, 0xffff0000, v87
	v_mul_f32_e32 v84, v100, v84
	v_mul_f32_e32 v85, v100, v85
	global_store_dwordx2 v[118:119], v[92:93], off offset:128
	v_cvt_pk_bf16_f32 v84, v84, v85
	v_lshlrev_b32_e32 v85, 16, v86
	v_mul_f32_e32 v85, v100, v85
	v_and_b32_e32 v86, 0xffff0000, v86
	v_mul_f32_e32 v86, v100, v86
	v_cvt_pk_bf16_f32 v85, v85, v86
	global_store_dwordx2 v[118:119], v[84:85], off offset:160
	v_lshlrev_b32_e32 v84, 16, v89
	v_and_b32_e32 v85, 0xffff0000, v89
	v_mul_f32_e32 v84, v100, v84
	v_mul_f32_e32 v85, v100, v85
	v_cvt_pk_bf16_f32 v84, v84, v85
	v_lshlrev_b32_e32 v85, 16, v88
	v_mul_f32_e32 v85, v100, v85
	v_and_b32_e32 v86, 0xffff0000, v88
	v_mul_f32_e32 v86, v100, v86
	v_cvt_pk_bf16_f32 v85, v85, v86
	global_store_dwordx2 v[118:119], v[84:85], off offset:192
	v_lshlrev_b32_e32 v84, 16, v91
	v_and_b32_e32 v85, 0xffff0000, v91
	v_mul_f32_e32 v84, v100, v84
	v_mul_f32_e32 v85, v100, v85
	v_cvt_pk_bf16_f32 v84, v84, v85
	v_lshlrev_b32_e32 v85, 16, v90
	v_mul_f32_e32 v85, v100, v85
	v_and_b32_e32 v86, 0xffff0000, v90
	v_mul_f32_e32 v86, v100, v86
	v_cvt_pk_bf16_f32 v85, v85, v86
	global_store_dwordx2 v[118:119], v[84:85], off offset:224
	v_lshlrev_b32_e32 v84, 16, v81
	v_and_b32_e32 v81, 0xffff0000, v81
	v_mul_f32_e32 v84, v100, v84
	v_mul_f32_e32 v81, v100, v81
	v_cvt_pk_bf16_f32 v84, v84, v81
	v_lshlrev_b32_e32 v81, 16, v80
	v_and_b32_e32 v80, 0xffff0000, v80
	v_mul_f32_e32 v81, v100, v81
	v_mul_f32_e32 v80, v100, v80
	v_cvt_pk_bf16_f32 v85, v81, v80
	v_lshlrev_b32_e32 v80, 16, v83
	v_and_b32_e32 v81, 0xffff0000, v83
	v_mul_f32_e32 v80, v100, v80
	v_mul_f32_e32 v81, v100, v81
	global_store_dwordx2 v[118:119], v[84:85], off offset:256
	v_cvt_pk_bf16_f32 v80, v80, v81
	v_lshlrev_b32_e32 v81, 16, v82
	v_mul_f32_e32 v81, v100, v81
	v_and_b32_e32 v82, 0xffff0000, v82
	v_mul_f32_e32 v82, v100, v82
	v_cvt_pk_bf16_f32 v81, v81, v82
	global_store_dwordx2 v[118:119], v[80:81], off offset:288
	v_lshlrev_b32_e32 v80, 16, v109
	v_and_b32_e32 v81, 0xffff0000, v109
	v_mul_f32_e32 v80, v100, v80
	v_mul_f32_e32 v81, v100, v81
	v_cvt_pk_bf16_f32 v80, v80, v81
	v_lshlrev_b32_e32 v81, 16, v108
	v_mul_f32_e32 v81, v100, v81
	v_and_b32_e32 v82, 0xffff0000, v108
	v_mul_f32_e32 v82, v100, v82
	v_cvt_pk_bf16_f32 v81, v81, v82
	global_store_dwordx2 v[118:119], v[80:81], off offset:320
	v_lshlrev_b32_e32 v80, 16, v111
	v_and_b32_e32 v81, 0xffff0000, v111
	v_mul_f32_e32 v80, v100, v80
	v_mul_f32_e32 v81, v100, v81
	v_cvt_pk_bf16_f32 v80, v80, v81
	v_lshlrev_b32_e32 v81, 16, v110
	v_and_b32_e32 v82, 0xffff0000, v110
	v_mul_f32_e32 v81, v100, v81
	v_mul_f32_e32 v82, v100, v82
	v_cvt_pk_bf16_f32 v81, v81, v82
	v_lshlrev_b32_e32 v82, 16, v106
	v_and_b32_e32 v83, 0xffff0000, v106
	v_mul_f32_e32 v82, v100, v82
	v_mul_f32_e32 v83, v100, v83
	global_store_dwordx2 v[118:119], v[80:81], off offset:352
	v_cvt_pk_bf16_f32 v82, v82, v83
	v_lshlrev_b32_e32 v83, 16, v105
	v_mul_f32_e32 v83, v100, v83
	v_and_b32_e32 v84, 0xffff0000, v105
	v_lshl_add_u64 v[80:81], s[0:1], 1, v[140:141]
	v_mul_f32_e32 v84, v100, v84
	v_cvt_pk_bf16_f32 v83, v83, v84
	global_store_dwordx2 v[80:81], v[82:83], off offset:384
	v_lshlrev_b32_e32 v82, 16, v112
	v_and_b32_e32 v83, 0xffff0000, v112
	v_mul_f32_e32 v82, v100, v82
	v_mul_f32_e32 v83, v100, v83
	v_cvt_pk_bf16_f32 v82, v82, v83
	v_lshlrev_b32_e32 v83, 16, v107
	v_mul_f32_e32 v83, v100, v83
	v_and_b32_e32 v84, 0xffff0000, v107
	v_mul_f32_e32 v84, v100, v84
	v_cvt_pk_bf16_f32 v83, v83, v84
	global_store_dwordx2 v[80:81], v[82:83], off offset:416
	v_lshlrev_b32_e32 v82, 16, v114
	v_and_b32_e32 v83, 0xffff0000, v114
	v_mul_f32_e32 v82, v100, v82
	v_mul_f32_e32 v83, v100, v83
	v_cvt_pk_bf16_f32 v82, v82, v83
	v_lshlrev_b32_e32 v83, 16, v113
	v_mul_f32_e32 v83, v100, v83
	v_and_b32_e32 v84, 0xffff0000, v113
	v_mul_f32_e32 v84, v100, v84
	v_cvt_pk_bf16_f32 v83, v83, v84
	global_store_dwordx2 v[80:81], v[82:83], off offset:448
	v_lshlrev_b32_e32 v82, 16, v116
	v_and_b32_e32 v83, 0xffff0000, v116
	v_mul_f32_e32 v82, v100, v82
	v_mul_f32_e32 v83, v100, v83
	v_cvt_pk_bf16_f32 v82, v82, v83
	v_lshlrev_b32_e32 v83, 16, v115
	v_mul_f32_e32 v83, v100, v83
	v_and_b32_e32 v84, 0xffff0000, v115
	v_readlane_b32 s0, v251, 23
	v_mul_f32_e32 v84, v100, v84
	v_cvt_pk_bf16_f32 v83, v83, v84
	global_store_dwordx2 v[80:81], v[82:83], off offset:480
	v_mul_lo_u32 v80, v102, s4
	v_add3_u32 v147, s0, v101, v103
	s_barrier
; #define LAS __attribute__((address_space(3)))
; #define LAS __attribute__((address_space(3)))
; __device__ __forceinline__ f32x4 mfma16(bf16x8 a, bf16x8 b, f32x4 c) { return __builtin_amdgcn_mfma_f32_16x16x32_bf16(a, b, c, 0, 0, 0); }
; template <int NKT, int VSTR, bool SINK>
; __device__ __forceinline__ void attn_core(LAS const unsigned char* kb_, LAS const unsigned char* vb_, bf16x8 q0, bf16x8 q1, float sk, unsigned mskbits, int fr, f32x4 (&o)[4]) {
;     ...
;     for (int kt = 0; kt < NKT; ++kt) {
;         const int key = (kt >> 1) * 32 + ((kt & 1) << 2) + krow;
;         LAS const unsigned char* kp = kb_ + key * 144;
;         const bf16x8 a0 = *(LAS const bf16x8*)kp, a1 = *(LAS const bf16x8*)(kp + 64);
;         const float bias = ((mskbits >> (kt >> 2)) & 1u) ? -1e30f : 0.f;
;         f32x4 s = mfma16(a0, q0, (f32x4){bias, bias, bias, bias});
;         s = mfma16(a1, q1, s);
;         S[kt] = s;
;     }
;     float mx = S[0][0];
; #pragma unroll
;     for (int kt = 0; kt < NKT; ++kt) mx = fmaxf(fmaxf(mx, fmaxf(S[kt][0], S[kt][1])), fmaxf(S[kt][2], S[kt][3]));
;     mx = fmaxf(mx, __shfl_xor(mx, 16)); mx = fmaxf(mx, __shfl_xor(mx, 32));
; template <bool DO_SWA, bool DO_MEM>
; __device__ __forceinline__ void attn_unit(const Args& a, unsigned char* ws, LAS unsigned char* lds, int l, int tid_in, int lane_in, int wave, int unit) {
;     ...
;         if constexpr (DO_MEM) attn_core<16, 528, false>(lds + A_KS + g * 256 * 144 + fq * 16, lds + A_VT2 + (g * 64 + fr) * 528 + fq * 16, qmm[0][0], qmm[0][1], 0.f, 0u, fr, omem[0]);
	v_add3_u32 v145, s2, v80, v101
	s_waitcnt lgkmcnt(0)
	ds_read_b128 v[200:203], v147
	ds_read_b128 v[204:207], v147 offset:64
	ds_read_b128 v[228:231], v147 offset:576
	ds_read_b128 v[232:235], v147 offset:640
	ds_read_b128 v[236:239], v147 offset:4608
	ds_read_b128 v[240:243], v147 offset:4672
	ds_read_b128 v[244:247], v147 offset:5184
	s_waitcnt lgkmcnt(6)
	v_mfma_f32_16x16x32_bf16 v[80:83], v[200:203], v[12:15], 0
	s_waitcnt lgkmcnt(5)
	v_mfma_f32_16x16x32_bf16 v[136:139], v[204:207], v[8:11], v[80:83]
	ds_read_b128 v[200:203], v147 offset:5248
	ds_read_b128 v[204:207], v147 offset:9216
	s_waitcnt lgkmcnt(6)
	v_mfma_f32_16x16x32_bf16 v[80:83], v[228:231], v[12:15], 0
	s_waitcnt lgkmcnt(5)
	v_mfma_f32_16x16x32_bf16 v[132:135], v[232:235], v[8:11], v[80:83]
	ds_read_b128 v[228:231], v147 offset:9280
	ds_read_b128 v[232:235], v147 offset:9792
	s_waitcnt lgkmcnt(6)
	v_mfma_f32_16x16x32_bf16 v[80:83], v[236:239], v[12:15], 0
	s_waitcnt lgkmcnt(5)
	v_mfma_f32_16x16x32_bf16 v[128:131], v[240:243], v[8:11], v[80:83]
	ds_read_b128 v[236:239], v147 offset:9856
	ds_read_b128 v[240:243], v147 offset:13824
	s_waitcnt lgkmcnt(6)
	v_mfma_f32_16x16x32_bf16 v[80:83], v[244:247], v[12:15], 0
	s_waitcnt lgkmcnt(5)
	v_mfma_f32_16x16x32_bf16 v[124:127], v[200:203], v[8:11], v[80:83]
	ds_read_b128 v[244:247], v147 offset:13888
	ds_read_b128 v[200:203], v147 offset:14400
	s_waitcnt lgkmcnt(6)
	v_mfma_f32_16x16x32_bf16 v[80:83], v[204:207], v[12:15], 0
	s_waitcnt lgkmcnt(5)
	v_mfma_f32_16x16x32_bf16 v[120:123], v[228:231], v[8:11], v[80:83]
	ds_read_b128 v[204:207], v147 offset:14464
	ds_read_b128 v[228:231], v147 offset:18432
	s_waitcnt lgkmcnt(6)
	v_mfma_f32_16x16x32_bf16 v[80:83], v[232:235], v[12:15], 0
	s_waitcnt lgkmcnt(5)
	v_mfma_f32_16x16x32_bf16 v[116:119], v[236:239], v[8:11], v[80:83]
	ds_read_b128 v[232:235], v147 offset:18496
	ds_read_b128 v[236:239], v147 offset:19008
	s_waitcnt lgkmcnt(6)
	v_mfma_f32_16x16x32_bf16 v[80:83], v[240:243], v[12:15], 0
	s_waitcnt lgkmcnt(5)
	v_mfma_f32_16x16x32_bf16 v[112:115], v[244:247], v[8:11], v[80:83]
	ds_read_b128 v[240:243], v147 offset:19072
	ds_read_b128 v[244:247], v147 offset:23040
	s_waitcnt lgkmcnt(6)
	v_mfma_f32_16x16x32_bf16 v[80:83], v[200:203], v[12:15], 0
	s_waitcnt lgkmcnt(5)
	v_mfma_f32_16x16x32_bf16 v[108:111], v[204:207], v[8:11], v[80:83]
	ds_read_b128 v[200:203], v147 offset:23104
	ds_read_b128 v[204:207], v147 offset:23616
	s_waitcnt lgkmcnt(6)
	v_mfma_f32_16x16x32_bf16 v[80:83], v[228:231], v[12:15], 0
	s_waitcnt lgkmcnt(5)
	v_mfma_f32_16x16x32_bf16 v[104:107], v[232:235], v[8:11], v[80:83]
	ds_read_b128 v[228:231], v147 offset:23680
	ds_read_b128 v[232:235], v147 offset:27648
	s_waitcnt lgkmcnt(6)
	v_mfma_f32_16x16x32_bf16 v[80:83], v[236:239], v[12:15], 0
	s_waitcnt lgkmcnt(5)
	v_mfma_f32_16x16x32_bf16 v[100:103], v[240:243], v[8:11], v[80:83]
	ds_read_b128 v[236:239], v147 offset:27712
	ds_read_b128 v[240:243], v147 offset:28224
	s_waitcnt lgkmcnt(6)
	v_mfma_f32_16x16x32_bf16 v[80:83], v[244:247], v[12:15], 0
	s_waitcnt lgkmcnt(5)
	v_mfma_f32_16x16x32_bf16 v[96:99], v[200:203], v[8:11], v[80:83]
	ds_read_b128 v[244:247], v147 offset:28288
	ds_read_b128 v[200:203], v147 offset:32256
	s_waitcnt lgkmcnt(6)
	v_mfma_f32_16x16x32_bf16 v[80:83], v[204:207], v[12:15], 0
	s_waitcnt lgkmcnt(5)
	v_mfma_f32_16x16x32_bf16 v[92:95], v[228:231], v[8:11], v[80:83]
	ds_read_b128 v[204:207], v147 offset:32320
	ds_read_b128 v[228:231], v147 offset:32832
	s_waitcnt lgkmcnt(6)
	v_mfma_f32_16x16x32_bf16 v[80:83], v[232:235], v[12:15], 0
	s_waitcnt lgkmcnt(5)
	v_mfma_f32_16x16x32_bf16 v[88:91], v[236:239], v[8:11], v[80:83]
	ds_read_b128 v[232:235], v147 offset:32896
	s_waitcnt lgkmcnt(5)
	v_mfma_f32_16x16x32_bf16 v[80:83], v[240:243], v[12:15], 0
	s_waitcnt lgkmcnt(4)
	v_mfma_f32_16x16x32_bf16 v[84:87], v[244:247], v[8:11], v[80:83]
	s_waitcnt lgkmcnt(3)
	v_mfma_f32_16x16x32_bf16 v[80:83], v[200:203], v[12:15], 0
	s_waitcnt lgkmcnt(2)
	v_mfma_f32_16x16x32_bf16 v[80:83], v[204:207], v[8:11], v[80:83]
	s_waitcnt lgkmcnt(1)
	v_mfma_f32_16x16x32_bf16 v[12:15], v[228:231], v[12:15], 0
	s_waitcnt lgkmcnt(0)
	v_mfma_f32_16x16x32_bf16 v[8:11], v[232:235], v[8:11], v[12:15]
	s_nop 5
	v_max_f32_e32 v12, v139, v139
	v_max_f32_e32 v13, v138, v138
	v_max_f32_e32 v12, v13, v12
	v_max_f32_e32 v13, v133, v133
	v_max_f32_e32 v14, v132, v132
	v_max_f32_e32 v13, v14, v13
	v_max_f32_e32 v14, v135, v135
	v_max_f32_e32 v15, v134, v134
	v_max3_f32 v12, v136, v137, v12
	v_max_f32_e32 v14, v15, v14
	v_max3_f32 v12, v12, v13, v14
	v_max_f32_e32 v13, v129, v129
	v_max_f32_e32 v14, v128, v128
	v_max_f32_e32 v13, v14, v13
	v_max_f32_e32 v14, v131, v131
	v_max_f32_e32 v15, v130, v130
	v_max_f32_e32 v14, v15, v14
	v_max3_f32 v12, v12, v13, v14
	v_max_f32_e32 v13, v125, v125
	v_max_f32_e32 v14, v124, v124
	v_max_f32_e32 v13, v14, v13
	v_max_f32_e32 v14, v127, v127
	v_max_f32_e32 v15, v126, v126
	v_max_f32_e32 v14, v15, v14
	v_max3_f32 v12, v12, v13, v14
	v_max_f32_e32 v13, v121, v121
	v_max_f32_e32 v14, v120, v120
	v_max_f32_e32 v13, v14, v13
	v_max_f32_e32 v14, v123, v123
	v_max_f32_e32 v15, v122, v122
	v_max_f32_e32 v14, v15, v14
	v_max3_f32 v12, v12, v13, v14
	v_max_f32_e32 v13, v117, v117
	v_max_f32_e32 v14, v116, v116
	v_max_f32_e32 v13, v14, v13
	v_max_f32_e32 v14, v119, v119
	v_max_f32_e32 v15, v118, v118
	v_max_f32_e32 v14, v15, v14
	v_max3_f32 v12, v12, v13, v14
	v_max_f32_e32 v13, v113, v113
	v_max_f32_e32 v14, v112, v112
	v_max_f32_e32 v13, v14, v13
	v_max_f32_e32 v14, v115, v115
	v_max_f32_e32 v15, v114, v114
	v_max_f32_e32 v14, v15, v14
	v_max3_f32 v12, v12, v13, v14
	v_max_f32_e32 v13, v109, v109
	v_max_f32_e32 v14, v108, v108
; template <int NKT, int VSTR, bool SINK>
; __device__ __forceinline__ void attn_core(LAS const unsigned char* kb_, LAS const unsigned char* vb_, bf16x8 q0, bf16x8 q1, float sk, unsigned mskbits, int fr, f32x4 (&o)[4]) {
;     ...
;     float mx = S[0][0];
; #pragma unroll
;     for (int kt = 0; kt < NKT; ++kt) mx = fmaxf(fmaxf(mx, fmaxf(S[kt][0], S[kt][1])), fmaxf(S[kt][2], S[kt][3]));
;     mx = fmaxf(mx, __shfl_xor(mx, 16)); mx = fmaxf(mx, __shfl_xor(mx, 32));
;     if (SINK) mx = fmaxf(mx, sk);
;     float sum = 0.f;
; #pragma unroll
;     for (int kt = 0; kt < NKT; ++kt)
; #pragma unroll
;         for (int r = 0; r < 4; ++r) { const float p = __builtin_amdgcn_exp2f(S[kt][r] - mx); S[kt][r] = p; sum += p; }
;     sum += __shfl_xor(sum, 16); sum += __shfl_xor(sum, 32);
	v_max_f32_e32 v13, v14, v13
	v_max_f32_e32 v14, v111, v111
	v_max_f32_e32 v15, v110, v110
	v_max_f32_e32 v14, v15, v14
	v_max3_f32 v12, v12, v13, v14
	v_max_f32_e32 v13, v105, v105
	v_max_f32_e32 v14, v104, v104
	v_max_f32_e32 v13, v14, v13
	v_max_f32_e32 v14, v107, v107
	v_max_f32_e32 v15, v106, v106
	v_max_f32_e32 v14, v15, v14
	v_max3_f32 v12, v12, v13, v14
	v_max_f32_e32 v13, v101, v101
	v_max_f32_e32 v14, v100, v100
	v_max_f32_e32 v13, v14, v13
	v_max_f32_e32 v14, v103, v103
	v_max_f32_e32 v15, v102, v102
	v_max_f32_e32 v14, v15, v14
	v_max3_f32 v12, v12, v13, v14
	v_max_f32_e32 v13, v97, v97
	v_max_f32_e32 v14, v96, v96
	v_max_f32_e32 v13, v14, v13
	v_max_f32_e32 v14, v99, v99
	v_max_f32_e32 v15, v98, v98
	v_max_f32_e32 v14, v15, v14
	v_max3_f32 v12, v12, v13, v14
	v_max_f32_e32 v13, v93, v93
	v_max_f32_e32 v14, v92, v92
	v_max_f32_e32 v13, v14, v13
	v_max_f32_e32 v14, v95, v95
	v_max_f32_e32 v15, v94, v94
	v_max_f32_e32 v14, v15, v14
	v_max3_f32 v12, v12, v13, v14
	v_max_f32_e32 v13, v89, v89
	v_max_f32_e32 v14, v88, v88
	v_max_f32_e32 v13, v14, v13
	v_max_f32_e32 v14, v91, v91
	v_max_f32_e32 v15, v90, v90
	v_max_f32_e32 v14, v15, v14
	v_max3_f32 v12, v12, v13, v14
	v_max_f32_e32 v13, v85, v85
	v_max_f32_e32 v14, v84, v84
	v_max_f32_e32 v13, v14, v13
	v_max_f32_e32 v14, v87, v87
	v_max_f32_e32 v15, v86, v86
	v_max_f32_e32 v14, v15, v14
	v_max3_f32 v12, v12, v13, v14
	v_max_f32_e32 v13, v81, v81
	v_max_f32_e32 v14, v80, v80
	v_max_f32_e32 v13, v14, v13
	v_max_f32_e32 v14, v83, v83
	v_max_f32_e32 v15, v82, v82
	v_max_f32_e32 v14, v15, v14
	v_max3_f32 v12, v12, v13, v14
	v_max_f32_e32 v13, v9, v9
	v_max_f32_e32 v14, v8, v8
	v_max_f32_e32 v13, v14, v13
	v_max_f32_e32 v14, v11, v11
	v_max_f32_e32 v15, v10, v10
	v_max_f32_e32 v14, v15, v14
	v_max3_f32 v12, v12, v13, v14
	ds_bpermute_b32 v13, v212, v12
	s_waitcnt lgkmcnt(0)
	v_max_f32_e32 v13, v13, v13
	v_max_f32_e32 v12, v12, v13
	ds_bpermute_b32 v13, v176, v12
	s_waitcnt lgkmcnt(0)
	v_max_f32_e32 v13, v13, v13
	v_max_f32_e32 v149, v12, v13
	v_sub_f32_e32 v12, v136, v149
	v_exp_f32_e32 v12, v12
	v_sub_f32_e32 v13, v137, v149
	v_exp_f32_e32 v13, v13
	v_sub_f32_e32 v132, v132, v149
	v_add_f32_e32 v14, 0, v12
	v_exp_f32_e32 v132, v132
	v_add_f32_e32 v15, v13, v14
	v_sub_f32_e32 v14, v138, v149
	v_exp_f32_e32 v14, v14
	v_sub_f32_e32 v133, v133, v149
	v_exp_f32_e32 v133, v133
	v_sub_f32_e32 v134, v134, v149
	v_add_f32_e32 v136, v14, v15
	v_sub_f32_e32 v15, v139, v149
	v_exp_f32_e32 v15, v15
	v_exp_f32_e32 v134, v134
	v_sub_f32_e32 v135, v135, v149
	v_exp_f32_e32 v135, v135
	v_add_f32_e32 v136, v15, v136
	v_sub_f32_e32 v128, v128, v149
	v_add_f32_e32 v136, v132, v136
	v_exp_f32_e32 v128, v128
	v_sub_f32_e32 v129, v129, v149
	v_add_f32_e32 v136, v133, v136
	v_exp_f32_e32 v129, v129
	v_sub_f32_e32 v130, v130, v149
	v_add_f32_e32 v136, v134, v136
	v_exp_f32_e32 v130, v130
	v_sub_f32_e32 v131, v131, v149
	v_add_f32_e32 v136, v135, v136
	v_exp_f32_e32 v131, v131
	v_sub_f32_e32 v124, v124, v149
	v_add_f32_e32 v136, v128, v136
	v_exp_f32_e32 v124, v124
	v_sub_f32_e32 v125, v125, v149
	v_add_f32_e32 v136, v129, v136
	v_exp_f32_e32 v125, v125
	v_sub_f32_e32 v126, v126, v149
	v_add_f32_e32 v136, v130, v136
	v_exp_f32_e32 v126, v126
	v_sub_f32_e32 v127, v127, v149
	v_add_f32_e32 v136, v131, v136
	v_exp_f32_e32 v127, v127
	v_sub_f32_e32 v120, v120, v149
	v_add_f32_e32 v136, v124, v136
	v_exp_f32_e32 v120, v120
	v_sub_f32_e32 v121, v121, v149
	v_add_f32_e32 v136, v125, v136
	v_exp_f32_e32 v121, v121
	v_sub_f32_e32 v122, v122, v149
	v_add_f32_e32 v136, v126, v136
	v_exp_f32_e32 v122, v122
	v_sub_f32_e32 v123, v123, v149
	v_add_f32_e32 v136, v127, v136
	v_exp_f32_e32 v123, v123
	v_sub_f32_e32 v116, v116, v149
	v_add_f32_e32 v136, v120, v136
	v_exp_f32_e32 v116, v116
	v_sub_f32_e32 v117, v117, v149
	v_add_f32_e32 v136, v121, v136
	v_exp_f32_e32 v117, v117
	v_sub_f32_e32 v118, v118, v149
	v_add_f32_e32 v136, v122, v136
	v_exp_f32_e32 v118, v118
	v_sub_f32_e32 v119, v119, v149
	v_add_f32_e32 v136, v123, v136
	v_exp_f32_e32 v119, v119
	v_sub_f32_e32 v112, v112, v149
	v_add_f32_e32 v136, v116, v136
	v_exp_f32_e32 v112, v112
	v_sub_f32_e32 v113, v113, v149
	v_add_f32_e32 v136, v117, v136
	v_exp_f32_e32 v113, v113
	v_sub_f32_e32 v114, v114, v149
	v_add_f32_e32 v136, v118, v136
	v_exp_f32_e32 v114, v114
	v_sub_f32_e32 v115, v115, v149
	v_add_f32_e32 v136, v119, v136
	v_exp_f32_e32 v115, v115
	v_sub_f32_e32 v108, v108, v149
	v_add_f32_e32 v136, v112, v136
	v_exp_f32_e32 v108, v108
	v_sub_f32_e32 v109, v109, v149
	v_add_f32_e32 v136, v113, v136
	v_exp_f32_e32 v109, v109
	v_sub_f32_e32 v110, v110, v149
	v_add_f32_e32 v136, v114, v136
	v_exp_f32_e32 v110, v110
	v_sub_f32_e32 v111, v111, v149
	v_add_f32_e32 v136, v115, v136
	v_exp_f32_e32 v111, v111
	v_sub_f32_e32 v104, v104, v149
	v_add_f32_e32 v136, v108, v136
	v_exp_f32_e32 v104, v104
	v_sub_f32_e32 v105, v105, v149
	v_add_f32_e32 v136, v109, v136
	v_exp_f32_e32 v105, v105
	v_sub_f32_e32 v106, v106, v149
	v_add_f32_e32 v136, v110, v136
	v_exp_f32_e32 v106, v106
	v_sub_f32_e32 v107, v107, v149
	v_add_f32_e32 v136, v111, v136
	v_exp_f32_e32 v107, v107
	v_sub_f32_e32 v100, v100, v149
	v_add_f32_e32 v136, v104, v136
	v_exp_f32_e32 v100, v100
	v_sub_f32_e32 v101, v101, v149
	v_add_f32_e32 v136, v105, v136
	v_exp_f32_e32 v101, v101
	v_sub_f32_e32 v102, v102, v149
	v_add_f32_e32 v136, v106, v136
	v_exp_f32_e32 v102, v102
	v_sub_f32_e32 v103, v103, v149
	v_add_f32_e32 v136, v107, v136
	v_exp_f32_e32 v103, v103
	v_sub_f32_e32 v96, v96, v149
	v_add_f32_e32 v136, v100, v136
	v_exp_f32_e32 v96, v96
	v_sub_f32_e32 v97, v97, v149
	v_add_f32_e32 v136, v101, v136
	v_exp_f32_e32 v97, v97
; #define LAS __attribute__((address_space(3)))
; #define LAS __attribute__((address_space(3)))
; __device__ __forceinline__ unsigned pk2(float lo, float hi) { return pg8::cvt_pk_bf16(lo, hi); }
; __device__ __forceinline__ f32x4 mfma16(bf16x8 a, bf16x8 b, f32x4 c) { return __builtin_amdgcn_mfma_f32_16x16x32_bf16(a, b, c, 0, 0, 0); }
; template <int NKT, int VSTR, bool SINK>
; __device__ __forceinline__ void attn_core(LAS const unsigned char* kb_, LAS const unsigned char* vb_, bf16x8 q0, bf16x8 q1, float sk, unsigned mskbits, int fr, f32x4 (&o)[4]) {
;     ...
;     sum += __shfl_xor(sum, 16); sum += __shfl_xor(sum, 32);
;     if (SINK) sum += __builtin_amdgcn_exp2f(sk - mx);
;     const float inv = 1.0f / sum;
;     bf16x8 pf[NKT / 2];
; #pragma unroll
;     for (int kb = 0; kb < NKT / 2; ++kb) {
;         v4u w; w.x = pk2(S[2 * kb][0], S[2 * kb][1]); w.y = pk2(S[2 * kb][2], S[2 * kb][3]); w.z = pk2(S[2 * kb + 1][0], S[2 * kb + 1][1]); w.w = pk2(S[2 * kb + 1][2], S[2 * kb + 1][3]);
;         pf[kb] = __builtin_bit_cast(bf16x8, w);
;     }
; #pragma unroll
;     for (int dt = 0; dt < 4; ++dt) {
;         f32x4 acc = (f32x4){0.f, 0.f, 0.f, 0.f};
; #pragma unroll
;         for (int kb = 0; kb < NKT / 2; ++kb) {
;             const bf16x8 vf = *(LAS const bf16x8*)(vb_ + dt * 16 * VSTR + kb * 64);
;             acc = mfma16(vf, pf[kb], acc);
;         }
;         o[dt] = acc * inv;
;     }
	v_sub_f32_e32 v98, v98, v149
	v_add_f32_e32 v136, v102, v136
	v_exp_f32_e32 v98, v98
	v_sub_f32_e32 v99, v99, v149
	v_add_f32_e32 v136, v103, v136
	v_exp_f32_e32 v99, v99
	v_sub_f32_e32 v92, v92, v149
	v_add_f32_e32 v136, v96, v136
	v_exp_f32_e32 v137, v92
	v_add_f32_e32 v136, v97, v136
	v_add_f32_e32 v136, v98, v136
	v_add_f32_e32 v136, v99, v136
	v_sub_f32_e32 v93, v93, v149
	v_add_f32_e32 v92, v137, v136
	v_exp_f32_e32 v136, v93
	v_sub_f32_e32 v93, v94, v149
	v_exp_f32_e32 v138, v93
	v_sub_f32_e32 v93, v95, v149
	v_exp_f32_e32 v95, v93
	v_sub_f32_e32 v88, v88, v149
	v_exp_f32_e32 v139, v88
	v_sub_f32_e32 v89, v89, v149
	v_add_f32_e32 v92, v136, v92
	v_exp_f32_e32 v151, v89
	v_sub_f32_e32 v89, v90, v149
	v_add_f32_e32 v92, v138, v92
	v_exp_f32_e32 v153, v89
	v_sub_f32_e32 v89, v91, v149
	v_add_f32_e32 v92, v95, v92
	v_exp_f32_e32 v154, v89
	v_sub_f32_e32 v84, v84, v149
	v_add_f32_e32 v88, v139, v92
	v_exp_f32_e32 v155, v84
	v_sub_f32_e32 v85, v85, v149
	v_add_f32_e32 v88, v151, v88
	v_exp_f32_e32 v157, v85
	v_sub_f32_e32 v85, v86, v149
	v_add_f32_e32 v88, v153, v88
	v_exp_f32_e32 v159, v85
	v_sub_f32_e32 v85, v87, v149
	v_add_f32_e32 v88, v154, v88
	v_exp_f32_e32 v161, v85
	v_sub_f32_e32 v80, v80, v149
	v_add_f32_e32 v84, v155, v88
	v_exp_f32_e32 v163, v80
	v_sub_f32_e32 v81, v81, v149
	v_add_f32_e32 v84, v157, v84
	v_exp_f32_e32 v165, v81
	v_sub_f32_e32 v81, v82, v149
	v_add_f32_e32 v84, v159, v84
	v_exp_f32_e32 v167, v81
	v_sub_f32_e32 v81, v83, v149
	v_add_f32_e32 v84, v161, v84
	v_exp_f32_e32 v169, v81
	v_sub_f32_e32 v8, v8, v149
	v_add_f32_e32 v80, v163, v84
	v_exp_f32_e32 v171, v8
	v_sub_f32_e32 v9, v9, v149
	v_add_f32_e32 v80, v165, v80
	v_exp_f32_e32 v173, v9
	v_sub_f32_e32 v9, v10, v149
	v_add_f32_e32 v80, v167, v80
	v_exp_f32_e32 v175, v9
	v_sub_f32_e32 v9, v11, v149
	v_add_f32_e32 v80, v169, v80
	v_exp_f32_e32 v149, v9
	v_add_f32_e32 v8, v171, v80
	v_add_f32_e32 v8, v173, v8
	v_add_f32_e32 v8, v175, v8
	v_add_f32_e32 v8, v149, v8
	ds_bpermute_b32 v9, v212, v8
	v_cvt_pk_bf16_f32 v84, v12, v13
	v_cvt_pk_bf16_f32 v85, v14, v15
	v_cvt_pk_bf16_f32 v86, v132, v133
	v_cvt_pk_bf16_f32 v87, v134, v135
	s_waitcnt lgkmcnt(0)
	v_add_f32_e32 v8, v8, v9
	ds_bpermute_b32 v9, v176, v8
	v_cvt_pk_bf16_f32 v80, v128, v129
	v_cvt_pk_bf16_f32 v81, v130, v131
	v_cvt_pk_bf16_f32 v82, v124, v125
	v_cvt_pk_bf16_f32 v83, v126, v127
	s_waitcnt lgkmcnt(0)
	v_add_f32_e32 v177, v8, v9
	v_cvt_pk_bf16_f32 v12, v120, v121
	v_cvt_pk_bf16_f32 v13, v122, v123
	v_cvt_pk_bf16_f32 v14, v116, v117
	v_cvt_pk_bf16_f32 v15, v118, v119
	v_cvt_pk_bf16_f32 v8, v112, v113
	v_cvt_pk_bf16_f32 v9, v114, v115
	v_cvt_pk_bf16_f32 v10, v108, v109
	v_cvt_pk_bf16_f32 v11, v110, v111
	v_cvt_pk_bf16_f32 v88, v104, v105
	v_div_scale_f32 v104, s[0:1], v177, v177, 1.0
	v_rcp_f32_e32 v105, v104
	v_cvt_pk_bf16_f32 v89, v106, v107
	v_cvt_pk_bf16_f32 v90, v100, v101
	v_cvt_pk_bf16_f32 v91, v102, v103
	v_cvt_pk_bf16_f32 v92, v96, v97
	v_cvt_pk_bf16_f32 v93, v98, v99
	s_nop 0
	v_fma_f32 v106, -v104, v105, 1.0
	v_fmac_f32_e32 v105, v106, v105
	v_div_scale_f32 v106, vcc, 1.0, v177, 1.0
	v_mul_f32_e32 v107, v106, v105
	v_fma_f32 v108, -v104, v107, v106
	v_fmac_f32_e32 v107, v108, v105
	v_fma_f32 v104, -v104, v107, v106
	v_div_fmas_f32 v104, v104, v105, v107
	v_cvt_pk_bf16_f32 v94, v137, v136
	v_cvt_pk_bf16_f32 v95, v138, v95
	v_cvt_pk_bf16_f32 v96, v139, v151
	v_cvt_pk_bf16_f32 v97, v153, v154
	v_cvt_pk_bf16_f32 v98, v155, v157
	v_cvt_pk_bf16_f32 v99, v159, v161
	v_cvt_pk_bf16_f32 v100, v163, v165
	v_cvt_pk_bf16_f32 v101, v167, v169
	v_cvt_pk_bf16_f32 v102, v171, v173
	v_cvt_pk_bf16_f32 v103, v175, v149
	v_div_fixup_f32 v116, v104, v177, 1.0
	ds_read_b128 v[104:107], v145
	ds_read_b128 v[108:111], v145 offset:64
	s_waitcnt lgkmcnt(1)
	v_mfma_f32_16x16x32_bf16 v[104:107], v[104:107], v[84:87], 0
	ds_read_b128 v[112:115], v145 offset:8512
	ds_read_b128 v[118:121], v145 offset:16960
	s_waitcnt lgkmcnt(2)
	v_mfma_f32_16x16x32_bf16 v[104:107], v[108:111], v[80:83], v[104:107]
	ds_read_b128 v[108:111], v145 offset:128
	s_waitcnt lgkmcnt(0)
	v_mfma_f32_16x16x32_bf16 v[104:107], v[108:111], v[12:15], v[104:107]
	ds_read_b128 v[108:111], v145 offset:192
	s_waitcnt lgkmcnt(0)
	v_mfma_f32_16x16x32_bf16 v[104:107], v[108:111], v[8:11], v[104:107]
	ds_read_b128 v[108:111], v145 offset:256
	s_waitcnt lgkmcnt(0)
	v_mfma_f32_16x16x32_bf16 v[104:107], v[108:111], v[88:91], v[104:107]
	ds_read_b128 v[108:111], v145 offset:320
	s_waitcnt lgkmcnt(0)
	v_mfma_f32_16x16x32_bf16 v[104:107], v[108:111], v[92:95], v[104:107]
	ds_read_b128 v[108:111], v145 offset:384
	s_waitcnt lgkmcnt(0)
	v_mfma_f32_16x16x32_bf16 v[104:107], v[108:111], v[96:99], v[104:107]
	ds_read_b128 v[108:111], v145 offset:448
	s_waitcnt lgkmcnt(0)
	v_mfma_f32_16x16x32_bf16 v[106:109], v[108:111], v[100:103], v[104:107]
	s_nop 7
	v_pk_mul_f32 v[104:105], v[108:109], v[116:117] op_sel_hi:[1,0]
	ds_read_b128 v[108:111], v145 offset:8448
	s_waitcnt lgkmcnt(0)
	v_mfma_f32_16x16x32_bf16 v[108:111], v[108:111], v[84:87], 0
	v_mul_f32_e64 v106, v106, v116
	v_mul_f32_e64 v107, v107, v116
	v_mfma_f32_16x16x32_bf16 v[108:111], v[112:115], v[80:83], v[108:111]
	ds_read_b128 v[112:115], v145 offset:8576
	s_waitcnt lgkmcnt(0)
	v_mfma_f32_16x16x32_bf16 v[108:111], v[112:115], v[12:15], v[108:111]
	ds_read_b128 v[112:115], v145 offset:8640
	s_waitcnt lgkmcnt(0)
	v_mfma_f32_16x16x32_bf16 v[108:111], v[112:115], v[8:11], v[108:111]
	ds_read_b128 v[112:115], v145 offset:8704
	s_waitcnt lgkmcnt(0)
	v_mfma_f32_16x16x32_bf16 v[108:111], v[112:115], v[88:91], v[108:111]
	ds_read_b128 v[112:115], v145 offset:8768
	s_waitcnt lgkmcnt(0)
; #define LAS __attribute__((address_space(3)))
; #define LAS __attribute__((address_space(3)))
; __device__ __forceinline__ f32x4 mfma16(bf16x8 a, bf16x8 b, f32x4 c) { return __builtin_amdgcn_mfma_f32_16x16x32_bf16(a, b, c, 0, 0, 0); }
; template <int NKT, int VSTR, bool SINK>
; __device__ __forceinline__ void attn_core(LAS const unsigned char* kb_, LAS const unsigned char* vb_, bf16x8 q0, bf16x8 q1, float sk, unsigned mskbits, int fr, f32x4 (&o)[4]) {
;     ...
;     for (int kt = 0; kt < NKT; ++kt) {
;         const int key = (kt >> 1) * 32 + ((kt & 1) << 2) + krow;
;         LAS const unsigned char* kp = kb_ + key * 144;
;         const bf16x8 a0 = *(LAS const bf16x8*)kp, a1 = *(LAS const bf16x8*)(kp + 64);
;         const float bias = ((mskbits >> (kt >> 2)) & 1u) ? -1e30f : 0.f;
;         f32x4 s = mfma16(a0, q0, (f32x4){bias, bias, bias, bias});
;         s = mfma16(a1, q1, s);
;         S[kt] = s;
; template <bool DO_SWA, bool DO_MEM>
; __device__ __forceinline__ void attn_unit(const Args& a, unsigned char* ws, LAS unsigned char* lds, int l, int tid_in, int lane_in, int wave, int unit) {
;     ...
;         if constexpr (DO_MEM) attn_core<16, 528, false>(lds + A_KS + g * 256 * 144 + fq * 16, lds + A_VT2 + (g * 64 + fr) * 528 + fq * 16, qmm[0][0], qmm[0][1], 0.f, 0u, fr, omem[0]);
;         __syncthreads();
;         if constexpr (DO_MEM)
; #pragma unroll
;         for (int i = 0; i < 8; ++i) {
;             const int chn = tid + 512 * i;
;             { const int key = chn >> 4, c16 = chn & 15; *(LAS v4u*)(lds + A_KS + ((c16 >> 3) * 256 + key) * 144 + (c16 & 7) * 16) = mkst[i]; }
;             { const int col = chn >> 5, kc = chn & 31; *(LAS v4u*)(lds + A_VT2 + col * 528 + kc * 16) = mvst[i]; }
;         }
;         __syncthreads();
;         if constexpr (DO_MEM) {
;             attn_core<16, 528, false>(lds + A_KS + g * 256 * 144 + fq * 16, lds + A_VT2 + (g * 64 + fr) * 528 + fq * 16, qmm[1][0], qmm[1][1], 0.f, 0u, fr, omem[1]);
	v_mfma_f32_16x16x32_bf16 v[108:111], v[112:115], v[92:95], v[108:111]
	ds_read_b128 v[112:115], v145 offset:8832
	s_waitcnt lgkmcnt(0)
	v_mfma_f32_16x16x32_bf16 v[108:111], v[112:115], v[96:99], v[108:111]
	ds_read_b128 v[112:115], v145 offset:8896
	s_waitcnt lgkmcnt(0)
	v_mfma_f32_16x16x32_bf16 v[110:113], v[112:115], v[100:103], v[108:111]
	s_nop 7
	v_pk_mul_f32 v[108:109], v[112:113], v[116:117] op_sel_hi:[1,0]
	ds_read_b128 v[112:115], v145 offset:16896
	s_waitcnt lgkmcnt(0)
	v_mfma_f32_16x16x32_bf16 v[112:115], v[112:115], v[84:87], 0
	v_mul_f32_e64 v110, v110, v116
	v_mul_f32_e64 v111, v111, v116
	v_mfma_f32_16x16x32_bf16 v[112:115], v[118:121], v[80:83], v[112:115]
	ds_read_b128 v[118:121], v145 offset:17024
	s_waitcnt lgkmcnt(0)
	v_mfma_f32_16x16x32_bf16 v[112:115], v[118:121], v[12:15], v[112:115]
	ds_read_b128 v[118:121], v145 offset:17088
	s_waitcnt lgkmcnt(0)
	v_mfma_f32_16x16x32_bf16 v[112:115], v[118:121], v[8:11], v[112:115]
	ds_read_b128 v[118:121], v145 offset:17152
	s_waitcnt lgkmcnt(0)
	v_mfma_f32_16x16x32_bf16 v[112:115], v[118:121], v[88:91], v[112:115]
	ds_read_b128 v[118:121], v145 offset:17216
	s_waitcnt lgkmcnt(0)
	v_mfma_f32_16x16x32_bf16 v[112:115], v[118:121], v[92:95], v[112:115]
	ds_read_b128 v[118:121], v145 offset:17280
	s_waitcnt lgkmcnt(0)
	v_mfma_f32_16x16x32_bf16 v[112:115], v[118:121], v[96:99], v[112:115]
	ds_read_b128 v[118:121], v145 offset:17344
	s_waitcnt lgkmcnt(0)
	v_mfma_f32_16x16x32_bf16 v[118:121], v[118:121], v[100:103], v[112:115]
	s_nop 7
	v_pk_mul_f32 v[112:113], v[116:117], v[120:121] op_sel_hi:[0,1]
	v_pk_mul_f32 v[114:115], v[116:117], v[118:119] op_sel_hi:[0,1]
	ds_read_b128 v[118:121], v145 offset:25344
	s_waitcnt lgkmcnt(0)
	v_mfma_f32_16x16x32_bf16 v[84:87], v[118:121], v[84:87], 0
	ds_read_b128 v[118:121], v145 offset:25408
	s_waitcnt lgkmcnt(0)
	v_mfma_f32_16x16x32_bf16 v[80:83], v[118:121], v[80:83], v[84:87]
	s_nop 4
	ds_read_b128 v[84:87], v145 offset:25472
	s_waitcnt lgkmcnt(0)
	v_mfma_f32_16x16x32_bf16 v[12:15], v[84:87], v[12:15], v[80:83]
	s_nop 2
	ds_read_b128 v[80:83], v145 offset:25536
	s_waitcnt lgkmcnt(0)
	v_mfma_f32_16x16x32_bf16 v[8:11], v[80:83], v[8:11], v[12:15]
	s_nop 2
	ds_read_b128 v[12:15], v145 offset:25600
	s_waitcnt lgkmcnt(0)
	v_mfma_f32_16x16x32_bf16 v[8:11], v[12:15], v[88:91], v[8:11]
	ds_read_b128 v[12:15], v145 offset:25664
	s_waitcnt lgkmcnt(0)
	v_mfma_f32_16x16x32_bf16 v[8:11], v[12:15], v[92:95], v[8:11]
	ds_read_b128 v[12:15], v145 offset:25728
	s_waitcnt lgkmcnt(0)
	v_mfma_f32_16x16x32_bf16 v[8:11], v[12:15], v[96:99], v[8:11]
	ds_read_b128 v[12:15], v145 offset:25792
	s_waitcnt lgkmcnt(0)
	s_barrier
	v_mfma_f32_16x16x32_bf16 v[8:11], v[12:15], v[100:103], v[8:11]
	s_waitcnt vmcnt(31)
	ds_write_b128 v142, v[16:19]
	s_waitcnt vmcnt(30)
	ds_write_b128 v144, v[20:23]
	s_waitcnt vmcnt(29)
	ds_write_b128 v146, v[24:27]
	s_waitcnt vmcnt(28)
	ds_write_b128 v148, v[28:31]
	s_waitcnt vmcnt(27)
	ds_write_b128 v150, v[32:35]
	s_waitcnt vmcnt(26)
	ds_write_b128 v152, v[36:39]
	s_waitcnt vmcnt(25)
	ds_write_b128 v156, v[40:43]
	s_waitcnt vmcnt(24)
	ds_write_b128 v158, v[44:47]
	s_waitcnt vmcnt(23)
	ds_write_b128 v160, v[48:51]
	s_waitcnt vmcnt(22)
	ds_write_b128 v162, v[52:55]
	s_waitcnt vmcnt(21)
	ds_write_b128 v164, v[56:59]
	s_waitcnt vmcnt(20)
	ds_write_b128 v166, v[60:63]
	s_waitcnt vmcnt(19)
	ds_write_b128 v168, v[64:67]
	s_waitcnt vmcnt(18)
	ds_write_b128 v170, v[68:71]
	s_waitcnt vmcnt(17)
	ds_write_b128 v172, v[72:75]
	s_waitcnt vmcnt(16)
	ds_write_b128 v174, v[76:79]
	s_waitcnt lgkmcnt(0)
	v_pk_mul_f32 v[80:81], v[116:117], v[10:11] op_sel_hi:[0,1]
	v_pk_mul_f32 v[82:83], v[116:117], v[8:9] op_sel_hi:[0,1]
	s_barrier
	s_waitcnt lgkmcnt(0)
	ds_read_b128 v[84:87], v147
	ds_read_b128 v[88:91], v147 offset:64
	ds_read_b128 v[92:95], v147 offset:576
	ds_read_b128 v[196:199], v147 offset:640
	ds_read_b128 v[200:203], v147 offset:4608
	ds_read_b128 v[204:207], v147 offset:4672
	ds_read_b128 v[228:231], v147 offset:5184
	ds_read_b128 v[232:235], v147 offset:5248
	ds_read_b128 v[236:239], v147 offset:9216
	ds_read_b128 v[240:243], v147 offset:9280
	ds_read_b128 v[244:247], v147 offset:9792
	s_waitcnt lgkmcnt(10)
	v_mfma_f32_16x16x32_bf16 v[8:11], v[84:87], v[4:7], 0
	s_waitcnt lgkmcnt(9)
	v_mfma_f32_16x16x32_bf16 v[64:67], v[88:91], v[0:3], v[8:11]
	ds_read_b128 v[84:87], v147 offset:9856
	ds_read_b128 v[88:91], v147 offset:13824
	s_waitcnt lgkmcnt(10)
	v_mfma_f32_16x16x32_bf16 v[8:11], v[92:95], v[4:7], 0
	s_waitcnt lgkmcnt(9)
	v_mfma_f32_16x16x32_bf16 v[60:63], v[196:199], v[0:3], v[8:11]
	ds_read_b128 v[92:95], v147 offset:13888
	ds_read_b128 v[196:199], v147 offset:14400
	s_waitcnt lgkmcnt(10)
	v_mfma_f32_16x16x32_bf16 v[8:11], v[200:203], v[4:7], 0
	s_waitcnt lgkmcnt(9)
	v_mfma_f32_16x16x32_bf16 v[20:23], v[204:207], v[0:3], v[8:11]
	ds_read_b128 v[200:203], v147 offset:14464
	ds_read_b128 v[204:207], v147 offset:18432
	s_waitcnt lgkmcnt(10)
	v_mfma_f32_16x16x32_bf16 v[8:11], v[228:231], v[4:7], 0
	s_waitcnt lgkmcnt(9)
	v_mfma_f32_16x16x32_bf16 v[12:15], v[232:235], v[0:3], v[8:11]
	ds_read_b128 v[228:231], v147 offset:18496
	ds_read_b128 v[232:235], v147 offset:19008
	s_waitcnt lgkmcnt(10)
	v_mfma_f32_16x16x32_bf16 v[8:11], v[236:239], v[4:7], 0
	s_waitcnt lgkmcnt(9)
	v_mfma_f32_16x16x32_bf16 v[8:11], v[240:243], v[0:3], v[8:11]
	ds_read_b128 v[236:239], v147 offset:19072
	ds_read_b128 v[240:243], v147 offset:23040
	s_waitcnt lgkmcnt(10)
	v_mfma_f32_16x16x32_bf16 v[16:19], v[244:247], v[4:7], 0
	s_waitcnt lgkmcnt(9)
	v_mfma_f32_16x16x32_bf16 v[16:19], v[84:87], v[0:3], v[16:19]
	ds_read_b128 v[244:247], v147 offset:23104
	ds_read_b128 v[84:87], v147 offset:23616
	s_waitcnt lgkmcnt(10)
; #define LAS __attribute__((address_space(3)))
; #define LAS __attribute__((address_space(3)))
; __device__ __forceinline__ f32x4 mfma16(bf16x8 a, bf16x8 b, f32x4 c) { return __builtin_amdgcn_mfma_f32_16x16x32_bf16(a, b, c, 0, 0, 0); }
; template <int NKT, int VSTR, bool SINK>
; __device__ __forceinline__ void attn_core(LAS const unsigned char* kb_, LAS const unsigned char* vb_, bf16x8 q0, bf16x8 q1, float sk, unsigned mskbits, int fr, f32x4 (&o)[4]) {
;     ...
;     for (int kt = 0; kt < NKT; ++kt) {
;         const int key = (kt >> 1) * 32 + ((kt & 1) << 2) + krow;
;         LAS const unsigned char* kp = kb_ + key * 144;
;         const bf16x8 a0 = *(LAS const bf16x8*)kp, a1 = *(LAS const bf16x8*)(kp + 64);
;         const float bias = ((mskbits >> (kt >> 2)) & 1u) ? -1e30f : 0.f;
;         f32x4 s = mfma16(a0, q0, (f32x4){bias, bias, bias, bias});
;         s = mfma16(a1, q1, s);
;         S[kt] = s;
;     }
;     float mx = S[0][0];
; #pragma unroll
;     for (int kt = 0; kt < NKT; ++kt) mx = fmaxf(fmaxf(mx, fmaxf(S[kt][0], S[kt][1])), fmaxf(S[kt][2], S[kt][3]));
;     mx = fmaxf(mx, __shfl_xor(mx, 16)); mx = fmaxf(mx, __shfl_xor(mx, 32));
	v_mfma_f32_16x16x32_bf16 v[24:27], v[88:91], v[4:7], 0
	s_waitcnt lgkmcnt(9)
	v_mfma_f32_16x16x32_bf16 v[24:27], v[92:95], v[0:3], v[24:27]
	ds_read_b128 v[88:91], v147 offset:23680
	ds_read_b128 v[92:95], v147 offset:27648
	s_waitcnt lgkmcnt(10)
	v_mfma_f32_16x16x32_bf16 v[28:31], v[196:199], v[4:7], 0
	s_waitcnt lgkmcnt(9)
	v_mfma_f32_16x16x32_bf16 v[28:31], v[200:203], v[0:3], v[28:31]
	ds_read_b128 v[196:199], v147 offset:27712
	ds_read_b128 v[200:203], v147 offset:28224
	s_waitcnt lgkmcnt(10)
	v_mfma_f32_16x16x32_bf16 v[32:35], v[204:207], v[4:7], 0
	s_waitcnt lgkmcnt(9)
	v_mfma_f32_16x16x32_bf16 v[32:35], v[228:231], v[0:3], v[32:35]
	ds_read_b128 v[204:207], v147 offset:28288
	ds_read_b128 v[228:231], v147 offset:32256
	s_waitcnt lgkmcnt(10)
	v_mfma_f32_16x16x32_bf16 v[36:39], v[232:235], v[4:7], 0
	s_waitcnt lgkmcnt(9)
	v_mfma_f32_16x16x32_bf16 v[36:39], v[236:239], v[0:3], v[36:39]
	ds_read_b128 v[232:235], v147 offset:32320
	ds_read_b128 v[236:239], v147 offset:32832
	s_waitcnt lgkmcnt(10)
	v_mfma_f32_16x16x32_bf16 v[40:43], v[240:243], v[4:7], 0
	s_waitcnt lgkmcnt(9)
	v_mfma_f32_16x16x32_bf16 v[40:43], v[244:247], v[0:3], v[40:43]
	ds_read_b128 v[240:243], v147 offset:32896
	s_waitcnt lgkmcnt(9)
	v_mfma_f32_16x16x32_bf16 v[44:47], v[84:87], v[4:7], 0
	s_waitcnt lgkmcnt(8)
	v_mfma_f32_16x16x32_bf16 v[48:51], v[88:91], v[0:3], v[44:47]
	s_waitcnt lgkmcnt(7)
	v_mfma_f32_16x16x32_bf16 v[44:47], v[92:95], v[4:7], 0
	s_waitcnt lgkmcnt(6)
	v_mfma_f32_16x16x32_bf16 v[52:55], v[196:199], v[0:3], v[44:47]
	s_waitcnt lgkmcnt(5)
	v_mfma_f32_16x16x32_bf16 v[44:47], v[200:203], v[4:7], 0
	s_waitcnt lgkmcnt(4)
	v_mfma_f32_16x16x32_bf16 v[56:59], v[204:207], v[0:3], v[44:47]
	s_waitcnt lgkmcnt(3)
	v_mfma_f32_16x16x32_bf16 v[44:47], v[228:231], v[4:7], 0
	s_waitcnt lgkmcnt(2)
	v_mfma_f32_16x16x32_bf16 v[44:47], v[232:235], v[0:3], v[44:47]
	s_waitcnt lgkmcnt(1)
	v_mfma_f32_16x16x32_bf16 v[4:7], v[236:239], v[4:7], 0
	s_waitcnt lgkmcnt(0)
	v_mfma_f32_16x16x32_bf16 v[0:3], v[240:243], v[0:3], v[4:7]
	s_nop 5
	v_max_f32_e32 v4, v67, v67
	v_max_f32_e32 v5, v66, v66
	v_max_f32_e32 v4, v5, v4
	v_max_f32_e32 v5, v61, v61
	v_max_f32_e32 v6, v60, v60
	v_max_f32_e32 v5, v6, v5
	v_max_f32_e32 v6, v63, v63
	v_max_f32_e32 v7, v62, v62
	v_max3_f32 v4, v64, v65, v4
	v_max_f32_e32 v6, v7, v6
	v_max3_f32 v4, v4, v5, v6
	v_max_f32_e32 v5, v21, v21
	v_max_f32_e32 v6, v20, v20
	v_max_f32_e32 v5, v6, v5
	v_max_f32_e32 v6, v23, v23
	v_max_f32_e32 v7, v22, v22
	v_max_f32_e32 v6, v7, v6
	v_max3_f32 v4, v4, v5, v6
	v_max_f32_e32 v5, v13, v13
	v_max_f32_e32 v6, v12, v12
	v_max_f32_e32 v5, v6, v5
	v_max_f32_e32 v6, v15, v15
	v_max_f32_e32 v7, v14, v14
	v_max_f32_e32 v6, v7, v6
	v_max3_f32 v4, v4, v5, v6
	v_max_f32_e32 v5, v9, v9
	v_max_f32_e32 v6, v8, v8
	v_max_f32_e32 v5, v6, v5
	v_max_f32_e32 v6, v11, v11
	v_max_f32_e32 v7, v10, v10
	v_max_f32_e32 v6, v7, v6
	v_max3_f32 v4, v4, v5, v6
	v_max_f32_e32 v5, v17, v17
	v_max_f32_e32 v6, v16, v16
	v_max_f32_e32 v5, v6, v5
	v_max_f32_e32 v6, v19, v19
	v_max_f32_e32 v7, v18, v18
	v_max_f32_e32 v6, v7, v6
	v_max3_f32 v4, v4, v5, v6
	v_max_f32_e32 v5, v25, v25
	v_max_f32_e32 v6, v24, v24
	v_max_f32_e32 v5, v6, v5
	v_max_f32_e32 v6, v27, v27
	v_max_f32_e32 v7, v26, v26
	v_max_f32_e32 v6, v7, v6
	v_max3_f32 v4, v4, v5, v6
	v_max_f32_e32 v5, v29, v29
	v_max_f32_e32 v6, v28, v28
	v_max_f32_e32 v5, v6, v5
	v_max_f32_e32 v6, v31, v31
	v_max_f32_e32 v7, v30, v30
	v_max_f32_e32 v6, v7, v6
	v_max3_f32 v4, v4, v5, v6
	v_max_f32_e32 v5, v33, v33
	v_max_f32_e32 v6, v32, v32
	v_max_f32_e32 v5, v6, v5
	v_max_f32_e32 v6, v35, v35
	v_max_f32_e32 v7, v34, v34
	v_max_f32_e32 v6, v7, v6
	v_max3_f32 v4, v4, v5, v6
	v_max_f32_e32 v5, v37, v37
	v_max_f32_e32 v6, v36, v36
	v_max_f32_e32 v5, v6, v5
	v_max_f32_e32 v6, v39, v39
	v_max_f32_e32 v7, v38, v38
	v_max_f32_e32 v6, v7, v6
	v_max3_f32 v4, v4, v5, v6
	v_max_f32_e32 v5, v41, v41
	v_max_f32_e32 v6, v40, v40
	v_max_f32_e32 v5, v6, v5
	v_max_f32_e32 v6, v43, v43
	v_max_f32_e32 v7, v42, v42
	v_max_f32_e32 v6, v7, v6
	v_max3_f32 v4, v4, v5, v6
	v_max_f32_e32 v5, v49, v49
	v_max_f32_e32 v6, v48, v48
	v_max_f32_e32 v5, v6, v5
	v_max_f32_e32 v6, v51, v51
	v_max_f32_e32 v7, v50, v50
	v_max_f32_e32 v6, v7, v6
	v_max3_f32 v4, v4, v5, v6
	v_max_f32_e32 v5, v53, v53
	v_max_f32_e32 v6, v52, v52
	v_max_f32_e32 v5, v6, v5
	v_max_f32_e32 v6, v55, v55
	v_max_f32_e32 v7, v54, v54
	v_max_f32_e32 v6, v7, v6
	v_max3_f32 v4, v4, v5, v6
	v_max_f32_e32 v5, v57, v57
	v_max_f32_e32 v6, v56, v56
	v_max_f32_e32 v5, v6, v5
	v_max_f32_e32 v6, v59, v59
	v_max_f32_e32 v7, v58, v58
	v_max_f32_e32 v6, v7, v6
	v_max3_f32 v4, v4, v5, v6
	v_max_f32_e32 v5, v45, v45
	v_max_f32_e32 v6, v44, v44
	v_max_f32_e32 v5, v6, v5
	v_max_f32_e32 v6, v47, v47
	v_max_f32_e32 v7, v46, v46
	v_max_f32_e32 v6, v7, v6
	v_max3_f32 v4, v4, v5, v6
	v_max_f32_e32 v5, v1, v1
	v_max_f32_e32 v6, v0, v0
	v_max_f32_e32 v5, v6, v5
	v_max_f32_e32 v6, v3, v3
	v_max_f32_e32 v7, v2, v2
	v_max_f32_e32 v6, v7, v6
	v_max3_f32 v4, v4, v5, v6
	ds_bpermute_b32 v5, v212, v4
	s_waitcnt lgkmcnt(0)
	v_max_f32_e32 v5, v5, v5
	v_max_f32_e32 v4, v4, v5
	ds_bpermute_b32 v5, v176, v4
	s_waitcnt lgkmcnt(0)
; template <int NKT, int VSTR, bool SINK>
; __device__ __forceinline__ void attn_core(LAS const unsigned char* kb_, LAS const unsigned char* vb_, bf16x8 q0, bf16x8 q1, float sk, unsigned mskbits, int fr, f32x4 (&o)[4]) {
;     ...
;     if (SINK) mx = fmaxf(mx, sk);
;     float sum = 0.f;
; #pragma unroll
;     for (int kt = 0; kt < NKT; ++kt)
; #pragma unroll
;         for (int r = 0; r < 4; ++r) { const float p = __builtin_amdgcn_exp2f(S[kt][r] - mx); S[kt][r] = p; sum += p; }
;     sum += __shfl_xor(sum, 16); sum += __shfl_xor(sum, 32);
;     if (SINK) sum += __builtin_amdgcn_exp2f(sk - mx);
;     const float inv = 1.0f / sum;
	v_max_f32_e32 v5, v5, v5
	v_max_f32_e32 v7, v4, v5
	v_sub_f32_e32 v4, v64, v7
	v_exp_f32_e32 v4, v4
	v_sub_f32_e32 v5, v65, v7
	v_exp_f32_e32 v5, v5
	v_sub_f32_e32 v60, v60, v7
	v_add_f32_e32 v6, 0, v4
	v_exp_f32_e32 v60, v60
	v_add_f32_e32 v64, v5, v6
	v_sub_f32_e32 v6, v66, v7
	v_exp_f32_e32 v6, v6
	v_sub_f32_e32 v61, v61, v7
	v_exp_f32_e32 v61, v61
	v_sub_f32_e32 v62, v62, v7
	v_add_f32_e32 v65, v6, v64
	v_sub_f32_e32 v64, v67, v7
	v_exp_f32_e32 v64, v64
	v_exp_f32_e32 v62, v62
	v_sub_f32_e32 v63, v63, v7
	v_exp_f32_e32 v63, v63
	v_add_f32_e32 v65, v64, v65
	v_sub_f32_e32 v20, v20, v7
	v_add_f32_e32 v65, v60, v65
	v_exp_f32_e32 v20, v20
	v_sub_f32_e32 v21, v21, v7
	v_add_f32_e32 v65, v61, v65
	v_exp_f32_e32 v21, v21
	v_sub_f32_e32 v22, v22, v7
	v_add_f32_e32 v65, v62, v65
	v_exp_f32_e32 v22, v22
	v_sub_f32_e32 v23, v23, v7
	v_add_f32_e32 v65, v63, v65
	v_exp_f32_e32 v23, v23
	v_sub_f32_e32 v12, v12, v7
	v_add_f32_e32 v65, v20, v65
	v_exp_f32_e32 v12, v12
	v_sub_f32_e32 v13, v13, v7
	v_add_f32_e32 v65, v21, v65
	v_exp_f32_e32 v13, v13
	v_sub_f32_e32 v14, v14, v7
	v_add_f32_e32 v65, v22, v65
	v_exp_f32_e32 v14, v14
	v_sub_f32_e32 v15, v15, v7
	v_add_f32_e32 v65, v23, v65
	v_exp_f32_e32 v15, v15
	v_sub_f32_e32 v8, v8, v7
	v_add_f32_e32 v65, v12, v65
	v_exp_f32_e32 v8, v8
	v_sub_f32_e32 v9, v9, v7
	v_add_f32_e32 v65, v13, v65
	v_exp_f32_e32 v9, v9
	v_sub_f32_e32 v10, v10, v7
	v_add_f32_e32 v65, v14, v65
	v_exp_f32_e32 v10, v10
	v_sub_f32_e32 v11, v11, v7
	v_add_f32_e32 v65, v15, v65
	v_exp_f32_e32 v11, v11
	v_sub_f32_e32 v16, v16, v7
	v_add_f32_e32 v65, v8, v65
	v_exp_f32_e32 v16, v16
	v_sub_f32_e32 v17, v17, v7
	v_add_f32_e32 v65, v9, v65
	v_exp_f32_e32 v17, v17
	v_sub_f32_e32 v18, v18, v7
	v_add_f32_e32 v65, v10, v65
	v_exp_f32_e32 v18, v18
	v_sub_f32_e32 v19, v19, v7
	v_add_f32_e32 v65, v11, v65
	v_exp_f32_e32 v19, v19
	v_sub_f32_e32 v24, v24, v7
	v_add_f32_e32 v65, v16, v65
	v_exp_f32_e32 v66, v24
	v_add_f32_e32 v65, v17, v65
	v_add_f32_e32 v65, v18, v65
	v_add_f32_e32 v65, v19, v65
	v_sub_f32_e32 v25, v25, v7
	v_add_f32_e32 v24, v66, v65
	v_exp_f32_e32 v65, v25
	v_sub_f32_e32 v25, v26, v7
	v_exp_f32_e32 v67, v25
	v_sub_f32_e32 v25, v27, v7
	v_exp_f32_e32 v68, v25
	v_sub_f32_e32 v25, v28, v7
	v_exp_f32_e32 v69, v25
	v_sub_f32_e32 v25, v29, v7
	v_add_f32_e32 v24, v65, v24
	v_exp_f32_e32 v70, v25
	v_sub_f32_e32 v25, v30, v7
	v_add_f32_e32 v24, v67, v24
	v_exp_f32_e32 v71, v25
	v_sub_f32_e32 v25, v31, v7
	v_add_f32_e32 v24, v68, v24
	v_exp_f32_e32 v72, v25
	v_sub_f32_e32 v25, v32, v7
	v_add_f32_e32 v24, v69, v24
	v_exp_f32_e32 v32, v25
	v_sub_f32_e32 v25, v33, v7
	v_add_f32_e32 v24, v70, v24
	v_exp_f32_e32 v33, v25
	v_sub_f32_e32 v25, v34, v7
	v_add_f32_e32 v24, v71, v24
	v_exp_f32_e32 v34, v25
	v_sub_f32_e32 v25, v35, v7
	v_add_f32_e32 v24, v72, v24
	v_exp_f32_e32 v35, v25
	v_sub_f32_e32 v25, v36, v7
	v_add_f32_e32 v24, v32, v24
	v_exp_f32_e32 v36, v25
	v_sub_f32_e32 v25, v37, v7
	v_add_f32_e32 v24, v33, v24
	v_exp_f32_e32 v37, v25
	v_sub_f32_e32 v25, v38, v7
	v_add_f32_e32 v24, v34, v24
	v_exp_f32_e32 v38, v25
	v_sub_f32_e32 v25, v39, v7
	v_add_f32_e32 v24, v35, v24
	v_exp_f32_e32 v39, v25
	v_sub_f32_e32 v25, v40, v7
	v_add_f32_e32 v24, v36, v24
	v_exp_f32_e32 v40, v25
	v_sub_f32_e32 v25, v41, v7
	v_add_f32_e32 v24, v37, v24
	v_exp_f32_e32 v41, v25
	v_sub_f32_e32 v25, v42, v7
	v_add_f32_e32 v24, v38, v24
	v_exp_f32_e32 v42, v25
	v_sub_f32_e32 v25, v43, v7
	v_add_f32_e32 v24, v39, v24
	v_exp_f32_e32 v43, v25
	v_sub_f32_e32 v25, v48, v7
	v_add_f32_e32 v24, v40, v24
	v_exp_f32_e32 v48, v25
	v_sub_f32_e32 v25, v49, v7
	v_add_f32_e32 v24, v41, v24
	v_exp_f32_e32 v49, v25
	v_sub_f32_e32 v25, v50, v7
	v_add_f32_e32 v24, v42, v24
	v_exp_f32_e32 v50, v25
	v_sub_f32_e32 v25, v51, v7
	v_add_f32_e32 v24, v43, v24
	v_exp_f32_e32 v51, v25
	v_sub_f32_e32 v25, v52, v7
	v_add_f32_e32 v24, v48, v24
	v_exp_f32_e32 v52, v25
	v_sub_f32_e32 v25, v53, v7
	v_add_f32_e32 v24, v49, v24
	v_exp_f32_e32 v53, v25
	v_sub_f32_e32 v25, v54, v7
	v_add_f32_e32 v24, v50, v24
	v_exp_f32_e32 v54, v25
	v_sub_f32_e32 v25, v55, v7
	v_add_f32_e32 v24, v51, v24
	v_exp_f32_e32 v55, v25
	v_sub_f32_e32 v25, v56, v7
	v_add_f32_e32 v24, v52, v24
	v_exp_f32_e32 v56, v25
	v_sub_f32_e32 v25, v57, v7
	v_add_f32_e32 v24, v53, v24
	v_exp_f32_e32 v57, v25
	v_sub_f32_e32 v25, v58, v7
	v_add_f32_e32 v24, v54, v24
	v_exp_f32_e32 v58, v25
	v_sub_f32_e32 v25, v59, v7
	v_add_f32_e32 v24, v55, v24
	v_exp_f32_e32 v59, v25
	v_sub_f32_e32 v25, v44, v7
	v_add_f32_e32 v24, v56, v24
	v_exp_f32_e32 v44, v25
	v_sub_f32_e32 v25, v45, v7
	v_add_f32_e32 v24, v57, v24
	v_exp_f32_e32 v45, v25
	v_sub_f32_e32 v25, v46, v7
	v_add_f32_e32 v24, v58, v24
	v_exp_f32_e32 v46, v25
	v_sub_f32_e32 v25, v47, v7
	v_add_f32_e32 v24, v59, v24
	v_exp_f32_e32 v47, v25
	v_sub_f32_e32 v0, v0, v7
	v_add_f32_e32 v24, v44, v24
	v_exp_f32_e32 v73, v0
	v_sub_f32_e32 v1, v1, v7
	v_add_f32_e32 v24, v45, v24
	v_exp_f32_e32 v74, v1
	v_sub_f32_e32 v1, v2, v7
	v_add_f32_e32 v24, v46, v24
	v_exp_f32_e32 v75, v1
	v_sub_f32_e32 v1, v3, v7
	v_add_f32_e32 v24, v47, v24
	v_exp_f32_e32 v3, v1
	v_add_f32_e32 v0, v73, v24
	v_add_f32_e32 v0, v74, v0
	v_add_f32_e32 v0, v75, v0
	v_add_f32_e32 v0, v3, v0
	ds_bpermute_b32 v1, v212, v0
	v_cvt_pk_bf16_f32 v28, v4, v5
	v_cvt_pk_bf16_f32 v29, v6, v64
	v_cvt_pk_bf16_f32 v30, v60, v61
	v_cvt_pk_bf16_f32 v31, v62, v63
	s_waitcnt lgkmcnt(0)
	v_add_f32_e32 v0, v0, v1
	ds_bpermute_b32 v1, v176, v0
	v_cvt_pk_bf16_f32 v24, v20, v21
	v_cvt_pk_bf16_f32 v25, v22, v23
	v_cvt_pk_bf16_f32 v26, v12, v13
	v_cvt_pk_bf16_f32 v27, v14, v15
	s_waitcnt lgkmcnt(0)
; #define LAS __attribute__((address_space(3)))
; #define LAS __attribute__((address_space(3)))
; __device__ __forceinline__ unsigned pk2(float lo, float hi) { return pg8::cvt_pk_bf16(lo, hi); }
; __device__ __forceinline__ f32x4 mfma16(bf16x8 a, bf16x8 b, f32x4 c) { return __builtin_amdgcn_mfma_f32_16x16x32_bf16(a, b, c, 0, 0, 0); }
; template <int NKT, int VSTR, bool SINK>
; __device__ __forceinline__ void attn_core(LAS const unsigned char* kb_, LAS const unsigned char* vb_, bf16x8 q0, bf16x8 q1, float sk, unsigned mskbits, int fr, f32x4 (&o)[4]) {
;     ...
;     const float inv = 1.0f / sum;
;     bf16x8 pf[NKT / 2];
; #pragma unroll
;     for (int kb = 0; kb < NKT / 2; ++kb) {
;         v4u w; w.x = pk2(S[2 * kb][0], S[2 * kb][1]); w.y = pk2(S[2 * kb][2], S[2 * kb][3]); w.z = pk2(S[2 * kb + 1][0], S[2 * kb + 1][1]); w.w = pk2(S[2 * kb + 1][2], S[2 * kb + 1][3]);
;         pf[kb] = __builtin_bit_cast(bf16x8, w);
;     }
; #pragma unroll
;     for (int dt = 0; dt < 4; ++dt) {
;         f32x4 acc = (f32x4){0.f, 0.f, 0.f, 0.f};
; #pragma unroll
;         for (int kb = 0; kb < NKT / 2; ++kb) {
;             const bf16x8 vf = *(LAS const bf16x8*)(vb_ + dt * 16 * VSTR + kb * 64);
;             acc = mfma16(vf, pf[kb], acc);
;         }
;         o[dt] = acc * inv;
;     }
	v_add_f32_e32 v76, v0, v1
	v_cvt_pk_bf16_f32 v20, v8, v9
	v_cvt_pk_bf16_f32 v21, v10, v11
	v_cvt_pk_bf16_f32 v22, v16, v17
	v_cvt_pk_bf16_f32 v23, v18, v19
	v_cvt_pk_bf16_f32 v16, v66, v65
	v_cvt_pk_bf16_f32 v17, v67, v68
	v_cvt_pk_bf16_f32 v18, v69, v70
	v_cvt_pk_bf16_f32 v19, v71, v72
	v_cvt_pk_bf16_f32 v12, v32, v33
	v_div_scale_f32 v32, s[0:1], v76, v76, 1.0
	v_rcp_f32_e32 v33, v32
	v_cvt_pk_bf16_f32 v13, v34, v35
	v_cvt_pk_bf16_f32 v14, v36, v37
	v_cvt_pk_bf16_f32 v15, v38, v39
	v_cvt_pk_bf16_f32 v8, v40, v41
	v_cvt_pk_bf16_f32 v9, v42, v43
	s_nop 0
	v_fma_f32 v34, -v32, v33, 1.0
	v_fmac_f32_e32 v33, v34, v33
	v_div_scale_f32 v34, vcc, 1.0, v76, 1.0
	v_mul_f32_e32 v35, v34, v33
	v_fma_f32 v36, -v32, v35, v34
	v_fmac_f32_e32 v35, v36, v33
	v_fma_f32 v32, -v32, v35, v34
	v_div_fmas_f32 v32, v32, v33, v35
	v_cvt_pk_bf16_f32 v10, v48, v49
	v_cvt_pk_bf16_f32 v11, v50, v51
	v_cvt_pk_bf16_f32 v4, v52, v53
	v_cvt_pk_bf16_f32 v5, v54, v55
	v_cvt_pk_bf16_f32 v6, v56, v57
	v_cvt_pk_bf16_f32 v7, v58, v59
	v_cvt_pk_bf16_f32 v0, v44, v45
	v_cvt_pk_bf16_f32 v1, v46, v47
	v_cvt_pk_bf16_f32 v2, v73, v74
	v_cvt_pk_bf16_f32 v3, v75, v3
	v_div_fixup_f32 v36, v32, v76, 1.0
	s_waitcnt lgkmcnt(0)
	ds_read_b128 v[60:63], v145
	ds_read_b128 v[64:67], v145 offset:64
	ds_read_b128 v[68:71], v145 offset:8512
	ds_read_b128 v[84:87], v145 offset:16960
	ds_read_b128 v[88:91], v145 offset:128
	ds_read_b128 v[92:95], v145 offset:192
	ds_read_b128 v[196:199], v145 offset:256
	ds_read_b128 v[200:203], v145 offset:320
	ds_read_b128 v[204:207], v145 offset:384
	ds_read_b128 v[228:231], v145 offset:448
	ds_read_b128 v[232:235], v145 offset:8448
	ds_read_b128 v[236:239], v145 offset:8576
	ds_read_b128 v[240:243], v145 offset:8640
	ds_read_b128 v[244:247], v145 offset:8704
	s_waitcnt lgkmcnt(13)
	v_mfma_f32_16x16x32_bf16 v[32:35], v[60:63], v[28:31], 0
	ds_read_b128 v[60:63], v145 offset:8768
	s_waitcnt lgkmcnt(13)
	v_mfma_f32_16x16x32_bf16 v[32:35], v[64:67], v[24:27], v[32:35]
	ds_read_b128 v[64:67], v145 offset:8832
	s_waitcnt lgkmcnt(11)
	v_mfma_f32_16x16x32_bf16 v[32:35], v[88:91], v[20:23], v[32:35]
	ds_read_b128 v[88:91], v145 offset:8896
	s_waitcnt lgkmcnt(11)
	v_mfma_f32_16x16x32_bf16 v[32:35], v[92:95], v[16:19], v[32:35]
	ds_read_b128 v[92:95], v145 offset:16896
	s_waitcnt lgkmcnt(11)
	v_mfma_f32_16x16x32_bf16 v[32:35], v[196:199], v[12:15], v[32:35]
	ds_read_b128 v[196:199], v145 offset:17024
	s_waitcnt lgkmcnt(11)
	v_mfma_f32_16x16x32_bf16 v[32:35], v[200:203], v[8:11], v[32:35]
	ds_read_b128 v[200:203], v145 offset:17088
	s_waitcnt lgkmcnt(11)
	v_mfma_f32_16x16x32_bf16 v[32:35], v[204:207], v[4:7], v[32:35]
	ds_read_b128 v[204:207], v145 offset:17152
	s_waitcnt lgkmcnt(11)
	v_mfma_f32_16x16x32_bf16 v[38:41], v[228:231], v[0:3], v[32:35]
	ds_read_b128 v[228:231], v145 offset:17216
	s_nop 7
	v_pk_mul_f32 v[32:33], v[40:41], v[36:37] op_sel_hi:[1,0]
	v_pk_mul_f32 v[34:35], v[38:39], v[36:37] op_sel_hi:[1,0]
	s_waitcnt lgkmcnt(11)
	v_mfma_f32_16x16x32_bf16 v[38:41], v[232:235], v[28:31], 0
	ds_read_b128 v[232:235], v145 offset:17280
	v_mfma_f32_16x16x32_bf16 v[38:41], v[68:71], v[24:27], v[38:41]
	ds_read_b128 v[68:71], v145 offset:17344
	s_waitcnt lgkmcnt(12)
	v_mfma_f32_16x16x32_bf16 v[38:41], v[236:239], v[20:23], v[38:41]
	ds_read_b128 v[236:239], v145 offset:25344
	s_waitcnt lgkmcnt(12)
	v_mfma_f32_16x16x32_bf16 v[38:41], v[240:243], v[16:19], v[38:41]
	ds_read_b128 v[240:243], v145 offset:25408
	s_waitcnt lgkmcnt(12)
	v_mfma_f32_16x16x32_bf16 v[38:41], v[244:247], v[12:15], v[38:41]
	ds_read_b128 v[244:247], v145 offset:25472
	s_waitcnt lgkmcnt(12)
	v_mfma_f32_16x16x32_bf16 v[38:41], v[60:63], v[8:11], v[38:41]
	ds_read_b128 v[60:63], v145 offset:25536
	s_waitcnt lgkmcnt(12)
; #define LAS __attribute__((address_space(3)))
; __device__ __forceinline__ float quad_sum(float s) { s += __shfl_xor(s, 16); s += __shfl_xor(s, 32); return s; }
; __device__ __forceinline__ float sq4(const f32x4 a) { return (a[0] * a[0] + a[1] * a[1]) + (a[2] * a[2] + a[3] * a[3]); }
; #define LAS __attribute__((address_space(3)))
; __device__ __forceinline__ f32x4 mfma16(bf16x8 a, bf16x8 b, f32x4 c) { return __builtin_amdgcn_mfma_f32_16x16x32_bf16(a, b, c, 0, 0, 0); }
; template <int NKT, int VSTR, bool SINK>
; __device__ __forceinline__ void attn_core(LAS const unsigned char* kb_, LAS const unsigned char* vb_, bf16x8 q0, bf16x8 q1, float sk, unsigned mskbits, int fr, f32x4 (&o)[4]) {
;     ...
; #pragma unroll
;     for (int dt = 0; dt < 4; ++dt) {
;         f32x4 acc = (f32x4){0.f, 0.f, 0.f, 0.f};
; #pragma unroll
;         for (int kb = 0; kb < NKT / 2; ++kb) {
;             const bf16x8 vf = *(LAS const bf16x8*)(vb_ + dt * 16 * VSTR + kb * 64);
;             acc = mfma16(vf, pf[kb], acc);
;         }
;         o[dt] = acc * inv;
;     }
; template <bool DO_SWA, bool DO_MEM>
; __device__ __forceinline__ void attn_unit(const Args& a, unsigned char* ws, LAS unsigned char* lds, int l, int tid_in, int lane_in, int wave, int unit) {
;     ...
;             float ssq = 0.f;
; #pragma unroll
;             for (int hp = 0; hp < 2; ++hp)
; #pragma unroll
;                 for (int dt = 0; dt < 4; ++dt) ssq += pg8::sq4(omem[hp][dt]);
;             ssq = pg8::quad_sum(ssq);
;             if (fq == 0) red_m[g * 64 + qs * 16 + fr] = ssq;
	v_mfma_f32_16x16x32_bf16 v[38:41], v[64:67], v[4:7], v[38:41]
	ds_read_b128 v[64:67], v145 offset:25600
	s_waitcnt lgkmcnt(12)
	v_mfma_f32_16x16x32_bf16 v[40:43], v[88:91], v[0:3], v[38:41]
	s_nop 7
	v_pk_mul_f32 v[38:39], v[42:43], v[36:37] op_sel_hi:[1,0]
	ds_read_b128 v[88:91], v145 offset:25664
	s_waitcnt lgkmcnt(12)
	v_mfma_f32_16x16x32_bf16 v[42:45], v[92:95], v[28:31], 0
	v_mul_f32_e64 v40, v40, v36
	v_mul_f32_e64 v41, v41, v36
	v_mfma_f32_16x16x32_bf16 v[42:45], v[84:87], v[24:27], v[42:45]
	ds_read_b128 v[92:95], v145 offset:25728
	s_waitcnt lgkmcnt(12)
	v_mfma_f32_16x16x32_bf16 v[42:45], v[196:199], v[20:23], v[42:45]
	ds_read_b128 v[84:87], v145 offset:25792
	s_waitcnt lgkmcnt(12)
	v_mfma_f32_16x16x32_bf16 v[42:45], v[200:203], v[16:19], v[42:45]
	s_waitcnt lgkmcnt(11)
	v_mfma_f32_16x16x32_bf16 v[42:45], v[204:207], v[12:15], v[42:45]
	s_waitcnt lgkmcnt(10)
	v_mfma_f32_16x16x32_bf16 v[42:45], v[228:231], v[8:11], v[42:45]
	s_waitcnt lgkmcnt(9)
	v_mfma_f32_16x16x32_bf16 v[42:45], v[232:235], v[4:7], v[42:45]
	s_waitcnt lgkmcnt(8)
	v_mfma_f32_16x16x32_bf16 v[44:47], v[68:71], v[0:3], v[42:45]
	s_nop 7
	v_pk_mul_f32 v[42:43], v[36:37], v[46:47] op_sel_hi:[0,1]
	s_waitcnt lgkmcnt(7)
	v_mfma_f32_16x16x32_bf16 v[28:31], v[236:239], v[28:31], 0
	v_pk_mul_f32 v[44:45], v[36:37], v[44:45] op_sel_hi:[0,1]
	s_waitcnt lgkmcnt(6)
	v_mfma_f32_16x16x32_bf16 v[24:27], v[240:243], v[24:27], v[28:31]
	s_waitcnt lgkmcnt(5)
	v_mfma_f32_16x16x32_bf16 v[20:23], v[244:247], v[20:23], v[24:27]
	s_waitcnt lgkmcnt(4)
	v_mfma_f32_16x16x32_bf16 v[16:19], v[60:63], v[16:19], v[20:23]
	s_waitcnt lgkmcnt(3)
	v_mfma_f32_16x16x32_bf16 v[12:15], v[64:67], v[12:15], v[16:19]
	s_waitcnt lgkmcnt(2)
	v_mfma_f32_16x16x32_bf16 v[8:11], v[88:91], v[8:11], v[12:15]
	s_waitcnt lgkmcnt(1)
	v_mfma_f32_16x16x32_bf16 v[4:7], v[92:95], v[4:7], v[8:11]
	s_waitcnt lgkmcnt(0)
	v_mfma_f32_16x16x32_bf16 v[2:5], v[84:87], v[0:3], v[4:7]
	s_nop 2
	v_mul_f32_e32 v6, v109, v109
	v_fmac_f32_e32 v6, v108, v108
	s_nop 2
	v_pk_mul_f32 v[0:1], v[36:37], v[4:5] op_sel_hi:[0,1]
	v_mul_f32_e32 v4, v107, v107
	v_mul_f32_e32 v5, v105, v105
	v_fmac_f32_e32 v4, v106, v106
	v_fmac_f32_e32 v5, v104, v104
	v_add_f32_e32 v4, v4, v5
	v_mul_f32_e32 v5, v111, v111
	v_fmac_f32_e32 v5, v110, v110
	v_add_f32_e32 v5, v5, v6
	v_add_f32_e32 v4, v4, v5
	v_mul_f32_e32 v5, v115, v115
	v_mul_f32_e32 v6, v113, v113
	v_fmac_f32_e32 v5, v114, v114
	v_fmac_f32_e32 v6, v112, v112
	v_add_f32_e32 v5, v5, v6
	v_add_f32_e32 v4, v4, v5
	v_mul_f32_e32 v5, v83, v83
	v_mul_f32_e32 v6, v81, v81
	v_fmac_f32_e32 v5, v82, v82
	v_fmac_f32_e32 v6, v80, v80
	v_add_f32_e32 v5, v5, v6
	v_add_f32_e32 v4, v4, v5
	v_mul_f32_e32 v5, v35, v35
	v_mul_f32_e32 v6, v33, v33
	v_fmac_f32_e32 v5, v34, v34
	v_fmac_f32_e32 v6, v32, v32
	v_add_f32_e32 v5, v5, v6
	v_add_f32_e32 v4, v4, v5
	v_mul_f32_e32 v5, v41, v41
	v_mul_f32_e32 v6, v39, v39
	v_fmac_f32_e32 v5, v40, v40
	v_fmac_f32_e32 v6, v38, v38
	v_add_f32_e32 v5, v5, v6
	v_add_f32_e32 v4, v5, v4
	v_mul_f32_e32 v5, v45, v45
	v_mul_f32_e32 v6, v43, v43
	v_fmac_f32_e32 v5, v44, v44
	v_fmac_f32_e32 v6, v42, v42
	v_pk_mul_f32 v[2:3], v[36:37], v[2:3] op_sel_hi:[0,1]
	v_add_f32_e32 v5, v5, v6
	v_add_f32_e32 v4, v4, v5
	v_mul_f32_e32 v5, v3, v3
	v_mul_f32_e32 v6, v1, v1
	v_fmac_f32_e32 v5, v2, v2
	v_fmac_f32_e32 v6, v0, v0
	v_add_f32_e32 v5, v5, v6
	v_add_f32_e32 v4, v4, v5
	ds_bpermute_b32 v5, v212, v4
	s_waitcnt lgkmcnt(0)
	v_add_f32_e32 v4, v4, v5
	ds_bpermute_b32 v5, v176, v4
	s_and_saveexec_b64 s[0:1], s[36:37]
	s_cbranch_execz .LBB0_255
	v_readlane_b32 s2, v251, 26
	s_waitcnt lgkmcnt(0)
	v_add_f32_e32 v4, v4, v5
	v_lshl_add_u32 v6, v210, 2, s2
	ds_write_b32 v6, v4
	s_branch .LBB0_255
